# hazard-clean build: part-a MFMA result to VALU read distance padded to 12 wait states on every path; U-pass token sorts emitted pairwise
# baseline (speedup 1.0000x reference)
; #define MFMA32(a, b, c) __builtin_amdgcn_mfma_f32_32x32x16_bf16((a), (b), (c), 0, 0, 0)
; DI void hsync() { hsync_impl(false); }
; DI void peer_top16(const u16* __restrict__ PQrow, const u16* __restrict__ SK, unsigned (&top)[16], int lr, int hh) {
;   bf16x8 qf[8];
; #pragma unroll
;   for (int ks = 0; ks < 8; ++ks) qf[ks] = *(const bf16x8*)(PQrow + ks * 16 + hh * 8);
;   unsigned g[4][16];
; #pragma unroll
;   for (int kt = 0; kt < 4; ++kt) {
;     f32x16 acc;
; #pragma unroll
;     for (int e = 0; e < 16; ++e) acc[e] = 0.f;
; #pragma unroll
;     for (int ks = 0; ks < 8; ++ks) {
;       bf16x8 a = *(const bf16x8*)(SK + (size_t)(kt * 32 + lr) * 128 + ks * 16 + hh * 8);
;       acc = MFMA32(a, qf[ks], acc);
; template <bool STORE>
; DI void peer_item(const Params& p, int item, char* smem) {
;     ...
;   hsync();
;   for (int hq = 0; hq < 2; ++hq) {
;     const int hd = wave * 2 + hq;
;     unsigned top1[16], top2[16];
;     const u16* pqrow = PQ + (size_t)(tok0 + lr) * 2048 + hd * 256;
;     peer_top16(pqrow, SUBK + (size_t)(hd * 2 + 0) * 128 * 128, top1, lr, hh);
;     peer_top16(pqrow + 128, SUBK + (size_t)(hd * 2 + 1) * 128 * 128, top2, lr, hh);
.LBB0_1045:
	s_or_b64 exec, exec, s[0:1]
	v_writelane_b32 v254, s6, 0
	v_writelane_b32 v254, s7, 1
	v_writelane_b32 v254, s12, 2
	v_writelane_b32 v254, s13, 3
	v_writelane_b32 v254, s14, 4
	v_writelane_b32 v254, s15, 5
	v_writelane_b32 v254, s16, 6
	v_writelane_b32 v254, s17, 7
	v_writelane_b32 v254, s18, 8
	v_writelane_b32 v254, s19, 9
	v_writelane_b32 v254, s20, 10
	v_writelane_b32 v254, s21, 11
	v_writelane_b32 v254, s22, 12
	v_writelane_b32 v254, s23, 13
	v_writelane_b32 v254, s24, 14
	v_writelane_b32 v254, s25, 15
	v_writelane_b32 v254, s26, 16
	v_writelane_b32 v254, s27, 17
	v_writelane_b32 v254, s28, 18
	v_writelane_b32 v254, s29, 19
	v_writelane_b32 v254, s30, 20
	v_writelane_b32 v254, s31, 21
	v_writelane_b32 v254, s33, 22
	v_writelane_b32 v254, s34, 23
	v_writelane_b32 v254, s35, 24
	v_writelane_b32 v254, s36, 25
	v_writelane_b32 v254, s37, 26
	v_writelane_b32 v254, s38, 27
	v_writelane_b32 v254, s39, 28
	v_writelane_b32 v254, s40, 29
	v_writelane_b32 v254, s41, 30
	v_writelane_b32 v254, s42, 31
	v_writelane_b32 v254, s44, 32
	v_writelane_b32 v254, s45, 33
	v_writelane_b32 v254, s48, 34
	v_writelane_b32 v254, s49, 35
	v_writelane_b32 v254, s50, 36
	v_writelane_b32 v254, s51, 37
	v_writelane_b32 v254, s52, 38
	v_writelane_b32 v254, s53, 39
	v_writelane_b32 v254, s55, 40
	v_writelane_b32 v254, s60, 41
	v_writelane_b32 v254, s61, 42
	v_writelane_b32 v254, s62, 43
	v_writelane_b32 v254, s63, 44
	v_writelane_b32 v254, s66, 45
	v_writelane_b32 v254, s67, 46
	v_writelane_b32 v254, s68, 47
	v_writelane_b32 v254, s69, 48
	v_writelane_b32 v254, s74, 49
	v_writelane_b32 v254, s75, 50
	v_writelane_b32 v254, s76, 51
	v_writelane_b32 v254, s77, 52
	v_writelane_b32 v254, s78, 53
	v_writelane_b32 v254, s79, 54
	v_writelane_b32 v254, s88, 55
	s_mov_b32 s16, s33
	s_lshl_b32 s19, s6, 5
	v_readlane_b32 s56, v253, 48
	v_readlane_b32 s57, v253, 49
	v_readfirstlane_b32 s13, v211
	v_mbcnt_lo_u32_b32 v235, -1, 0
	v_mbcnt_hi_u32_b32 v235, -1, v235
	s_nop 3
	s_bfe_u32 s17, s13, 0x20006
	s_add_u32 s0, s56, 0x1180000
	s_addc_u32 s1, s57, 0
	s_add_u32 s2, s56, 0xac80200
	s_addc_u32 s3, s57, 0
	s_lshl_b32 s15, s19, 12
	s_add_u32 s2, s2, s15
	s_addc_u32 s3, s3, 0
	s_lshl_b32 s15, s17, 10
	s_add_u32 s2, s2, s15
	s_addc_u32 s3, s3, 0
	s_lshl_b32 s15, s17, 17
	s_add_u32 s0, s0, s15
	s_addc_u32 s1, s1, 0
	s_mul_i32 s18, s17, 7168
	s_add_u32 s18, s18, s16
	s_add_u32 s18, s18, 49152
	v_and_b32_e32 v236, 31, v235
	v_lshrrev_b32_e32 v237, 5, v235
	v_lshlrev_b32_e32 v243, 2, v235
	v_add_u32_e32 v240, s18, v243
	ds_write_b32 v240, v3 offset:512
	ds_write_b32 v240, v53 offset:768
	ds_write_b32 v240, v64 offset:1024
	ds_write_b32 v240, v65 offset:1280
	ds_write_b32 v240, v66 offset:1536
	ds_write_b32 v240, v67 offset:1792
	ds_write_b32 v240, v68 offset:2048
	ds_write_b32 v240, v69 offset:2304
	ds_write_b32 v240, v70 offset:2560
	ds_write_b32 v240, v71 offset:2816
	ds_write_b32 v240, v72 offset:3072
	ds_write_b32 v240, v73 offset:3328
	ds_write_b32 v240, v74 offset:3584
	ds_write_b32 v240, v75 offset:3840
	ds_write_b32 v240, v76 offset:4096
	ds_write_b32 v240, v77 offset:4352
	ds_write_b32 v240, v78 offset:4608
	ds_write_b32 v240, v79 offset:4864
	ds_write_b32 v240, v80 offset:5120
	ds_write_b32 v240, v81 offset:5376
	ds_write_b32 v240, v82 offset:5632
	ds_write_b32 v240, v83 offset:5888
	ds_write_b32 v240, v84 offset:6144
	ds_write_b32 v240, v96 offset:6400
	v_lshlrev_b32_e32 v244, 4, v237
	v_lshl_add_u32 v238, v236, 8, v244
	v_lshl_add_u32 v239, v236, 12, v244
	s_lshl_b32 s15, s17, 11
	s_add_u32 s15, s15, s16
	s_add_u32 s15, s15, 32768
	v_lshl_add_u32 v241, v235, 5, s15
	s_lshl_b32 s15, s17, 7
	s_add_u32 s15, s15, s16
	v_lshl_add_u32 v242, v236, 9, s15
	v_lshl_add_u32 v242, v237, 6, v242
	s_waitcnt lgkmcnt(0)
	global_load_dwordx4 v[176:179], v239, s[2:3] offset:0
	global_load_dwordx4 v[180:183], v239, s[2:3] offset:32
	global_load_dwordx4 v[184:187], v239, s[2:3] offset:64
	global_load_dwordx4 v[188:191], v239, s[2:3] offset:96
	global_load_dwordx4 v[192:195], v239, s[2:3] offset:128
	global_load_dwordx4 v[196:199], v239, s[2:3] offset:160
	global_load_dwordx4 v[200:203], v239, s[2:3] offset:192
	global_load_dwordx4 v[204:207], v239, s[2:3] offset:224
	s_add_u32 s4, s0, 0
	s_addc_u32 s5, s1, 0
	global_load_dwordx4 v[144:147], v238, s[4:5] offset:0
	global_load_dwordx4 v[148:151], v238, s[4:5] offset:32
	global_load_dwordx4 v[152:155], v238, s[4:5] offset:64
	global_load_dwordx4 v[156:159], v238, s[4:5] offset:96
	global_load_dwordx4 v[160:163], v238, s[4:5] offset:128
	global_load_dwordx4 v[164:167], v238, s[4:5] offset:160
	global_load_dwordx4 v[168:171], v238, s[4:5] offset:192
	global_load_dwordx4 v[172:175], v238, s[4:5] offset:224
	v_lshlrev_b32_e32 v245, 2, v237
	v_sub_u32_e32 v213, 127, v245
	v_sub_u32_e32 v214, 126, v245
	v_sub_u32_e32 v215, 125, v245
	v_sub_u32_e32 v216, 124, v245
	v_sub_u32_e32 v217, 119, v245
	v_sub_u32_e32 v218, 118, v245
	v_sub_u32_e32 v219, 117, v245
	v_sub_u32_e32 v220, 116, v245
	v_sub_u32_e32 v221, 111, v245
	v_sub_u32_e32 v222, 110, v245
	v_sub_u32_e32 v223, 109, v245
	v_sub_u32_e32 v224, 108, v245
	v_sub_u32_e32 v225, 103, v245
	v_sub_u32_e32 v226, 102, v245
	v_sub_u32_e32 v227, 101, v245
	v_sub_u32_e32 v228, 100, v245
	s_waitcnt vmcnt(7)
	v_mfma_f32_32x32x16_bf16 v[128:143], v[144:147], v[176:179], 0
	s_waitcnt vmcnt(6)
	v_mfma_f32_32x32x16_bf16 v[128:143], v[148:151], v[180:183], v[128:143]
	s_waitcnt vmcnt(5)
	v_mfma_f32_32x32x16_bf16 v[128:143], v[152:155], v[184:187], v[128:143]
	s_waitcnt vmcnt(4)
	v_mfma_f32_32x32x16_bf16 v[128:143], v[156:159], v[188:191], v[128:143]
	s_waitcnt vmcnt(3)
; #define MFMA32(a, b, c) __builtin_amdgcn_mfma_f32_32x32x16_bf16((a), (b), (c), 0, 0, 0)
; DI int crow(int i, int hh) { return (i & 3) + 8 * (i >> 2) + 4 * hh; }
; template <int LOGN>
; DI void bitonic_sort_desc(unsigned (&a)[1 << LOGN]) {
;   constexpr int N = 1 << LOGN;
; #pragma unroll
;   for (int ks = 1; ks <= LOGN; ++ks)
; #pragma unroll
;     ...
; #pragma unroll
;       for (int i = 0; i < N; ++i) {
;         const int k = 1 << ks, j = 1 << js, l = i ^ j;
;         if (l > i) {
;           const bool desc = ((i & k) == 0) || (ks == LOGN);
;           const unsigned x = a[i], y = a[l];
;           const unsigned hi = max(x, y), lo = min(x, y);
;           a[i] = desc ? hi : lo;
;           a[l] = desc ? lo : hi;
;         }
;       }
; DI void peer_top16(const u16* __restrict__ PQrow, const u16* __restrict__ SK, unsigned (&top)[16], int lr, int hh) {
;     ...
;     for (int ks = 0; ks < 8; ++ks) {
;       bf16x8 a = *(const bf16x8*)(SK + (size_t)(kt * 32 + lr) * 128 + ks * 16 + hh * 8);
;       acc = MFMA32(a, qf[ks], acc);
;     }
; #pragma unroll
;     for (int e = 0; e < 16; ++e) {
;       int kidx = kt * 32 + crow(e, hh);
;       g[kt][e] = (f2ord(acc[e]) & ~127u) | (unsigned)(127 - kidx);
;     }
;     bitonic_sort_desc<4>(g[kt]);
	v_mfma_f32_32x32x16_bf16 v[128:143], v[160:163], v[192:195], v[128:143]
	s_waitcnt vmcnt(2)
	v_mfma_f32_32x32x16_bf16 v[128:143], v[164:167], v[196:199], v[128:143]
	s_waitcnt vmcnt(1)
	v_mfma_f32_32x32x16_bf16 v[128:143], v[168:171], v[200:203], v[128:143]
	s_waitcnt vmcnt(0)
	v_mfma_f32_32x32x16_bf16 v[128:143], v[172:175], v[204:207], v[128:143]
	s_add_u32 s4, s0, 8192
	s_addc_u32 s5, s1, 0
	global_load_dwordx4 v[144:147], v238, s[4:5] offset:0
	global_load_dwordx4 v[148:151], v238, s[4:5] offset:32
	global_load_dwordx4 v[152:155], v238, s[4:5] offset:64
	global_load_dwordx4 v[156:159], v238, s[4:5] offset:96
	global_load_dwordx4 v[160:163], v238, s[4:5] offset:128
	global_load_dwordx4 v[164:167], v238, s[4:5] offset:160
	global_load_dwordx4 v[168:171], v238, s[4:5] offset:192
	global_load_dwordx4 v[172:175], v238, s[4:5] offset:224
	s_nop 7
	s_nop 3
	v_ashrrev_i32_e32 v230, 31, v128
	v_or_b32_e32 v230, 0x80000000, v230
	v_xor_b32_e32 v229, v230, v128
	v_and_b32_e32 v229, 0xffffff80, v229
	v_or_b32_e32 v117, v229, v213
	v_ashrrev_i32_e32 v230, 31, v129
	v_or_b32_e32 v230, 0x80000000, v230
	v_xor_b32_e32 v229, v230, v129
	v_and_b32_e32 v229, 0xffffff80, v229
	v_or_b32_e32 v116, v229, v214
	v_ashrrev_i32_e32 v230, 31, v130
	v_or_b32_e32 v230, 0x80000000, v230
	v_xor_b32_e32 v229, v230, v130
	v_and_b32_e32 v229, 0xffffff80, v229
	v_or_b32_e32 v115, v229, v215
	v_ashrrev_i32_e32 v230, 31, v131
	v_or_b32_e32 v230, 0x80000000, v230
	v_xor_b32_e32 v229, v230, v131
	v_and_b32_e32 v229, 0xffffff80, v229
	v_or_b32_e32 v114, v229, v216
	v_ashrrev_i32_e32 v230, 31, v132
	v_or_b32_e32 v230, 0x80000000, v230
	v_xor_b32_e32 v229, v230, v132
	v_and_b32_e32 v229, 0xffffff80, v229
	v_or_b32_e32 v113, v229, v217
	v_ashrrev_i32_e32 v230, 31, v133
	v_or_b32_e32 v230, 0x80000000, v230
	v_xor_b32_e32 v229, v230, v133
	v_and_b32_e32 v229, 0xffffff80, v229
	v_or_b32_e32 v112, v229, v218
	v_ashrrev_i32_e32 v230, 31, v134
	v_or_b32_e32 v230, 0x80000000, v230
	v_xor_b32_e32 v229, v230, v134
	v_and_b32_e32 v229, 0xffffff80, v229
	v_or_b32_e32 v111, v229, v219
	v_ashrrev_i32_e32 v230, 31, v135
	v_or_b32_e32 v230, 0x80000000, v230
	v_xor_b32_e32 v229, v230, v135
	v_and_b32_e32 v229, 0xffffff80, v229
	v_or_b32_e32 v110, v229, v220
	v_ashrrev_i32_e32 v230, 31, v136
	v_or_b32_e32 v230, 0x80000000, v230
	v_xor_b32_e32 v229, v230, v136
	v_and_b32_e32 v229, 0xffffff80, v229
	v_or_b32_e32 v109, v229, v221
	v_ashrrev_i32_e32 v230, 31, v137
	v_or_b32_e32 v230, 0x80000000, v230
	v_xor_b32_e32 v229, v230, v137
	v_and_b32_e32 v229, 0xffffff80, v229
	v_or_b32_e32 v108, v229, v222
	v_ashrrev_i32_e32 v230, 31, v138
	v_or_b32_e32 v230, 0x80000000, v230
	v_xor_b32_e32 v229, v230, v138
	v_and_b32_e32 v229, 0xffffff80, v229
	v_or_b32_e32 v107, v229, v223
	v_ashrrev_i32_e32 v230, 31, v139
	v_or_b32_e32 v230, 0x80000000, v230
	v_xor_b32_e32 v229, v230, v139
	v_and_b32_e32 v229, 0xffffff80, v229
	v_or_b32_e32 v106, v229, v224
	v_ashrrev_i32_e32 v230, 31, v140
	v_or_b32_e32 v230, 0x80000000, v230
	v_xor_b32_e32 v229, v230, v140
	v_and_b32_e32 v229, 0xffffff80, v229
	v_or_b32_e32 v105, v229, v225
	v_ashrrev_i32_e32 v230, 31, v141
	v_or_b32_e32 v230, 0x80000000, v230
	v_xor_b32_e32 v229, v230, v141
	v_and_b32_e32 v229, 0xffffff80, v229
	v_or_b32_e32 v104, v229, v226
	v_ashrrev_i32_e32 v230, 31, v142
	v_or_b32_e32 v230, 0x80000000, v230
	v_xor_b32_e32 v229, v230, v142
	v_and_b32_e32 v229, 0xffffff80, v229
	v_or_b32_e32 v103, v229, v227
	v_ashrrev_i32_e32 v230, 31, v143
	v_or_b32_e32 v230, 0x80000000, v230
	v_xor_b32_e32 v229, v230, v143
	v_and_b32_e32 v229, 0xffffff80, v229
	v_or_b32_e32 v102, v229, v228
	v_subrev_u32_e32 v213, 32, v213
	v_subrev_u32_e32 v214, 32, v214
	v_subrev_u32_e32 v215, 32, v215
	v_subrev_u32_e32 v216, 32, v216
	v_subrev_u32_e32 v217, 32, v217
	v_subrev_u32_e32 v218, 32, v218
	v_subrev_u32_e32 v219, 32, v219
	v_subrev_u32_e32 v220, 32, v220
	v_subrev_u32_e32 v221, 32, v221
	v_subrev_u32_e32 v222, 32, v222
	v_subrev_u32_e32 v223, 32, v223
	v_subrev_u32_e32 v224, 32, v224
	v_subrev_u32_e32 v225, 32, v225
	v_subrev_u32_e32 v226, 32, v226
	v_subrev_u32_e32 v227, 32, v227
	v_subrev_u32_e32 v228, 32, v228
	v_max_u32_e32 v101, v117, v116
	v_min_u32_e32 v116, v117, v116
	v_min_u32_e32 v117, v115, v114
	v_max_u32_e32 v114, v115, v114
	v_max_u32_e32 v115, v113, v112
	v_min_u32_e32 v112, v113, v112
	v_min_u32_e32 v113, v111, v110
	v_max_u32_e32 v110, v111, v110
	v_max_u32_e32 v111, v109, v108
	v_min_u32_e32 v108, v109, v108
	v_min_u32_e32 v109, v107, v106
	v_max_u32_e32 v106, v107, v106
	v_max_u32_e32 v107, v105, v104
	v_min_u32_e32 v104, v105, v104
	v_min_u32_e32 v105, v103, v102
	v_max_u32_e32 v102, v103, v102
	v_max_u32_e32 v103, v101, v117
	v_min_u32_e32 v117, v101, v117
	v_max_u32_e32 v101, v116, v114
	v_min_u32_e32 v114, v116, v114
	v_min_u32_e32 v116, v115, v113
	v_max_u32_e32 v113, v115, v113
	v_min_u32_e32 v115, v112, v110
	v_max_u32_e32 v110, v112, v110
	v_max_u32_e32 v112, v111, v109
	v_min_u32_e32 v109, v111, v109
	v_max_u32_e32 v111, v108, v106
	v_min_u32_e32 v106, v108, v106
	v_min_u32_e32 v108, v107, v105
	v_max_u32_e32 v105, v107, v105
	v_min_u32_e32 v107, v104, v102
	v_max_u32_e32 v102, v104, v102
	v_max_u32_e32 v104, v103, v101
	v_min_u32_e32 v101, v103, v101
	v_max_u32_e32 v103, v117, v114
	v_min_u32_e32 v114, v117, v114
	v_min_u32_e32 v117, v116, v115
	v_max_u32_e32 v115, v116, v115
	v_min_u32_e32 v116, v113, v110
	v_max_u32_e32 v110, v113, v110
	v_max_u32_e32 v113, v112, v111
	v_min_u32_e32 v111, v112, v111
	v_max_u32_e32 v112, v109, v106
	v_min_u32_e32 v106, v109, v106
	v_min_u32_e32 v109, v108, v107
	v_max_u32_e32 v107, v108, v107
	v_min_u32_e32 v108, v105, v102
; #define MFMA32(a, b, c) __builtin_amdgcn_mfma_f32_32x32x16_bf16((a), (b), (c), 0, 0, 0)
; template <int LOGN>
; DI void bitonic_sort_desc(unsigned (&a)[1 << LOGN]) {
;   constexpr int N = 1 << LOGN;
; #pragma unroll
;   for (int ks = 1; ks <= LOGN; ++ks)
; #pragma unroll
;     ...
; #pragma unroll
;       for (int i = 0; i < N; ++i) {
;         const int k = 1 << ks, j = 1 << js, l = i ^ j;
;         if (l > i) {
;           const bool desc = ((i & k) == 0) || (ks == LOGN);
;           const unsigned x = a[i], y = a[l];
;           const unsigned hi = max(x, y), lo = min(x, y);
;           a[i] = desc ? hi : lo;
;           a[l] = desc ? lo : hi;
;         }
;       }
; DI void peer_top16(const u16* __restrict__ PQrow, const u16* __restrict__ SK, unsigned (&top)[16], int lr, int hh) {
;     ...
;     for (int ks = 0; ks < 8; ++ks) {
;       bf16x8 a = *(const bf16x8*)(SK + (size_t)(kt * 32 + lr) * 128 + ks * 16 + hh * 8);
;       acc = MFMA32(a, qf[ks], acc);
	v_max_u32_e32 v102, v105, v102
	v_max_u32_e32 v105, v104, v117
	v_min_u32_e32 v117, v104, v117
	v_max_u32_e32 v104, v101, v115
	v_min_u32_e32 v115, v101, v115
	v_max_u32_e32 v101, v103, v116
	v_min_u32_e32 v116, v103, v116
	v_max_u32_e32 v103, v114, v110
	v_min_u32_e32 v110, v114, v110
	v_min_u32_e32 v114, v113, v109
	v_max_u32_e32 v109, v113, v109
	v_min_u32_e32 v113, v111, v107
	v_max_u32_e32 v107, v111, v107
	v_min_u32_e32 v111, v112, v108
	v_max_u32_e32 v108, v112, v108
	v_min_u32_e32 v112, v106, v102
	v_max_u32_e32 v102, v106, v102
	v_max_u32_e32 v106, v105, v101
	v_min_u32_e32 v101, v105, v101
	v_max_u32_e32 v105, v104, v103
	v_min_u32_e32 v103, v104, v103
	v_max_u32_e32 v104, v117, v116
	v_min_u32_e32 v116, v117, v116
	v_max_u32_e32 v117, v115, v110
	v_min_u32_e32 v110, v115, v110
	v_min_u32_e32 v115, v114, v111
	v_max_u32_e32 v111, v114, v111
	v_min_u32_e32 v114, v113, v112
	v_max_u32_e32 v112, v113, v112
	v_min_u32_e32 v113, v109, v108
	v_max_u32_e32 v108, v109, v108
	v_min_u32_e32 v109, v107, v102
	v_max_u32_e32 v102, v107, v102
	v_max_u32_e32 v107, v106, v105
	v_min_u32_e32 v105, v106, v105
	v_max_u32_e32 v106, v101, v103
	v_min_u32_e32 v103, v101, v103
	v_max_u32_e32 v101, v104, v117
	v_min_u32_e32 v117, v104, v117
	v_max_u32_e32 v104, v116, v110
	v_min_u32_e32 v110, v116, v110
	v_min_u32_e32 v116, v115, v114
	v_max_u32_e32 v114, v115, v114
	v_min_u32_e32 v115, v111, v112
	v_max_u32_e32 v112, v111, v112
	v_min_u32_e32 v111, v113, v109
	v_max_u32_e32 v109, v113, v109
	v_min_u32_e32 v113, v108, v102
	v_max_u32_e32 v102, v108, v102
	v_max_u32_e32 v108, v107, v116
	v_min_u32_e32 v116, v107, v116
	v_max_u32_e32 v107, v105, v114
	v_min_u32_e32 v114, v105, v114
	v_max_u32_e32 v105, v106, v115
	v_min_u32_e32 v115, v106, v115
	v_max_u32_e32 v106, v103, v112
	v_min_u32_e32 v112, v103, v112
	v_max_u32_e32 v103, v101, v111
	v_min_u32_e32 v111, v101, v111
	v_max_u32_e32 v101, v117, v109
	v_min_u32_e32 v109, v117, v109
	v_max_u32_e32 v117, v104, v113
	v_min_u32_e32 v113, v104, v113
	v_max_u32_e32 v104, v110, v102
	v_min_u32_e32 v102, v110, v102
	v_max_u32_e32 v110, v108, v103
	v_min_u32_e32 v103, v108, v103
	v_max_u32_e32 v108, v107, v101
	v_min_u32_e32 v101, v107, v101
	v_max_u32_e32 v107, v105, v117
	v_min_u32_e32 v117, v105, v117
	v_max_u32_e32 v105, v106, v104
	v_min_u32_e32 v104, v106, v104
	v_max_u32_e32 v106, v116, v111
	v_min_u32_e32 v111, v116, v111
	v_max_u32_e32 v116, v114, v109
	v_min_u32_e32 v109, v114, v109
	v_max_u32_e32 v114, v115, v113
	v_min_u32_e32 v113, v115, v113
	v_max_u32_e32 v115, v112, v102
	v_min_u32_e32 v102, v112, v102
	v_max_u32_e32 v112, v110, v107
	v_min_u32_e32 v107, v110, v107
	v_max_u32_e32 v110, v108, v105
	v_min_u32_e32 v105, v108, v105
	v_max_u32_e32 v108, v103, v117
	v_min_u32_e32 v117, v103, v117
	v_max_u32_e32 v103, v101, v104
	v_min_u32_e32 v104, v101, v104
	v_max_u32_e32 v101, v106, v114
	v_min_u32_e32 v114, v106, v114
	v_max_u32_e32 v106, v116, v115
	v_min_u32_e32 v115, v116, v115
	v_max_u32_e32 v116, v111, v113
	v_min_u32_e32 v113, v111, v113
	v_max_u32_e32 v111, v109, v102
	v_min_u32_e32 v102, v109, v102
	v_max_u32_e32 v109, v112, v110
	v_min_u32_e32 v110, v112, v110
	v_max_u32_e32 v112, v107, v105
	v_min_u32_e32 v105, v107, v105
	v_max_u32_e32 v107, v108, v103
	v_min_u32_e32 v103, v108, v103
	v_max_u32_e32 v108, v117, v104
	v_min_u32_e32 v104, v117, v104
	v_max_u32_e32 v117, v101, v106
	v_min_u32_e32 v106, v101, v106
	v_max_u32_e32 v101, v114, v115
	v_min_u32_e32 v115, v114, v115
	v_max_u32_e32 v114, v116, v111
	v_min_u32_e32 v111, v116, v111
	v_max_u32_e32 v116, v113, v102
	v_min_u32_e32 v102, v113, v102
	s_waitcnt vmcnt(7)
	v_mfma_f32_32x32x16_bf16 v[128:143], v[144:147], v[176:179], 0
	s_waitcnt vmcnt(6)
	v_mfma_f32_32x32x16_bf16 v[128:143], v[148:151], v[180:183], v[128:143]
	s_waitcnt vmcnt(5)
	v_mfma_f32_32x32x16_bf16 v[128:143], v[152:155], v[184:187], v[128:143]
	s_waitcnt vmcnt(4)
	v_mfma_f32_32x32x16_bf16 v[128:143], v[156:159], v[188:191], v[128:143]
	s_waitcnt vmcnt(3)
	v_mfma_f32_32x32x16_bf16 v[128:143], v[160:163], v[192:195], v[128:143]
	s_waitcnt vmcnt(2)
	v_mfma_f32_32x32x16_bf16 v[128:143], v[164:167], v[196:199], v[128:143]
	s_waitcnt vmcnt(1)
	v_mfma_f32_32x32x16_bf16 v[128:143], v[168:171], v[200:203], v[128:143]
	s_waitcnt vmcnt(0)
; #define MFMA32(a, b, c) __builtin_amdgcn_mfma_f32_32x32x16_bf16((a), (b), (c), 0, 0, 0)
; DI int crow(int i, int hh) { return (i & 3) + 8 * (i >> 2) + 4 * hh; }
; template <int LOGN>
; DI void bitonic_sort_desc(unsigned (&a)[1 << LOGN]) {
;   constexpr int N = 1 << LOGN;
; #pragma unroll
;   for (int ks = 1; ks <= LOGN; ++ks)
; #pragma unroll
;     ...
; #pragma unroll
;       for (int i = 0; i < N; ++i) {
;         const int k = 1 << ks, j = 1 << js, l = i ^ j;
;         if (l > i) {
;           const bool desc = ((i & k) == 0) || (ks == LOGN);
;           const unsigned x = a[i], y = a[l];
;           const unsigned hi = max(x, y), lo = min(x, y);
;           a[i] = desc ? hi : lo;
;           a[l] = desc ? lo : hi;
;         }
;       }
; DI void peer_top16(const u16* __restrict__ PQrow, const u16* __restrict__ SK, unsigned (&top)[16], int lr, int hh) {
;     ...
;     for (int ks = 0; ks < 8; ++ks) {
;       bf16x8 a = *(const bf16x8*)(SK + (size_t)(kt * 32 + lr) * 128 + ks * 16 + hh * 8);
;       acc = MFMA32(a, qf[ks], acc);
;     }
; #pragma unroll
;     for (int e = 0; e < 16; ++e) {
;       int kidx = kt * 32 + crow(e, hh);
;       g[kt][e] = (f2ord(acc[e]) & ~127u) | (unsigned)(127 - kidx);
;     }
;     bitonic_sort_desc<4>(g[kt]);
	v_mfma_f32_32x32x16_bf16 v[128:143], v[172:175], v[204:207], v[128:143]
	s_add_u32 s4, s0, 16384
	s_addc_u32 s5, s1, 0
	global_load_dwordx4 v[144:147], v238, s[4:5] offset:0
	global_load_dwordx4 v[148:151], v238, s[4:5] offset:32
	global_load_dwordx4 v[152:155], v238, s[4:5] offset:64
	global_load_dwordx4 v[156:159], v238, s[4:5] offset:96
	global_load_dwordx4 v[160:163], v238, s[4:5] offset:128
	global_load_dwordx4 v[164:167], v238, s[4:5] offset:160
	global_load_dwordx4 v[168:171], v238, s[4:5] offset:192
	global_load_dwordx4 v[172:175], v238, s[4:5] offset:224
	s_nop 7
	s_nop 3
	v_ashrrev_i32_e32 v230, 31, v128
	v_or_b32_e32 v230, 0x80000000, v230
	v_xor_b32_e32 v229, v230, v128
	v_and_b32_e32 v229, 0xffffff80, v229
	v_or_b32_e32 v113, v229, v213
	v_ashrrev_i32_e32 v230, 31, v129
	v_or_b32_e32 v230, 0x80000000, v230
	v_xor_b32_e32 v229, v230, v129
	v_and_b32_e32 v229, 0xffffff80, v229
	v_or_b32_e32 v100, v229, v214
	v_ashrrev_i32_e32 v230, 31, v130
	v_or_b32_e32 v230, 0x80000000, v230
	v_xor_b32_e32 v229, v230, v130
	v_and_b32_e32 v229, 0xffffff80, v229
	v_or_b32_e32 v99, v229, v215
	v_ashrrev_i32_e32 v230, 31, v131
	v_or_b32_e32 v230, 0x80000000, v230
	v_xor_b32_e32 v229, v230, v131
	v_and_b32_e32 v229, 0xffffff80, v229
	v_or_b32_e32 v98, v229, v216
	v_ashrrev_i32_e32 v230, 31, v132
	v_or_b32_e32 v230, 0x80000000, v230
	v_xor_b32_e32 v229, v230, v132
	v_and_b32_e32 v229, 0xffffff80, v229
	v_or_b32_e32 v97, v229, v217
	v_ashrrev_i32_e32 v230, 31, v133
	v_or_b32_e32 v230, 0x80000000, v230
	v_xor_b32_e32 v229, v230, v133
	v_and_b32_e32 v229, 0xffffff80, v229
	v_or_b32_e32 v96, v229, v218
	v_ashrrev_i32_e32 v230, 31, v134
	v_or_b32_e32 v230, 0x80000000, v230
	v_xor_b32_e32 v229, v230, v134
	v_and_b32_e32 v229, 0xffffff80, v229
	v_or_b32_e32 v95, v229, v219
	v_ashrrev_i32_e32 v230, 31, v135
	v_or_b32_e32 v230, 0x80000000, v230
	v_xor_b32_e32 v229, v230, v135
	v_and_b32_e32 v229, 0xffffff80, v229
	v_or_b32_e32 v94, v229, v220
	v_ashrrev_i32_e32 v230, 31, v136
	v_or_b32_e32 v230, 0x80000000, v230
	v_xor_b32_e32 v229, v230, v136
	v_and_b32_e32 v229, 0xffffff80, v229
	v_or_b32_e32 v93, v229, v221
	v_ashrrev_i32_e32 v230, 31, v137
	v_or_b32_e32 v230, 0x80000000, v230
	v_xor_b32_e32 v229, v230, v137
	v_and_b32_e32 v229, 0xffffff80, v229
	v_or_b32_e32 v92, v229, v222
	v_ashrrev_i32_e32 v230, 31, v138
	v_or_b32_e32 v230, 0x80000000, v230
	v_xor_b32_e32 v229, v230, v138
	v_and_b32_e32 v229, 0xffffff80, v229
	v_or_b32_e32 v91, v229, v223
	v_ashrrev_i32_e32 v230, 31, v139
	v_or_b32_e32 v230, 0x80000000, v230
	v_xor_b32_e32 v229, v230, v139
	v_and_b32_e32 v229, 0xffffff80, v229
	v_or_b32_e32 v90, v229, v224
	v_ashrrev_i32_e32 v230, 31, v140
	v_or_b32_e32 v230, 0x80000000, v230
	v_xor_b32_e32 v229, v230, v140
	v_and_b32_e32 v229, 0xffffff80, v229
	v_or_b32_e32 v89, v229, v225
	v_ashrrev_i32_e32 v230, 31, v141
	v_or_b32_e32 v230, 0x80000000, v230
	v_xor_b32_e32 v229, v230, v141
	v_and_b32_e32 v229, 0xffffff80, v229
	v_or_b32_e32 v88, v229, v226
	v_ashrrev_i32_e32 v230, 31, v142
	v_or_b32_e32 v230, 0x80000000, v230
	v_xor_b32_e32 v229, v230, v142
	v_and_b32_e32 v229, 0xffffff80, v229
	v_or_b32_e32 v87, v229, v227
	v_ashrrev_i32_e32 v230, 31, v143
	v_or_b32_e32 v230, 0x80000000, v230
	v_xor_b32_e32 v229, v230, v143
	v_and_b32_e32 v229, 0xffffff80, v229
	v_or_b32_e32 v86, v229, v228
	v_subrev_u32_e32 v213, 32, v213
	v_subrev_u32_e32 v214, 32, v214
	v_subrev_u32_e32 v215, 32, v215
	v_subrev_u32_e32 v216, 32, v216
	v_subrev_u32_e32 v217, 32, v217
	v_subrev_u32_e32 v218, 32, v218
	v_subrev_u32_e32 v219, 32, v219
	v_subrev_u32_e32 v220, 32, v220
	v_subrev_u32_e32 v221, 32, v221
	v_subrev_u32_e32 v222, 32, v222
	v_subrev_u32_e32 v223, 32, v223
	v_subrev_u32_e32 v224, 32, v224
	v_subrev_u32_e32 v225, 32, v225
	v_subrev_u32_e32 v226, 32, v226
	v_subrev_u32_e32 v227, 32, v227
	v_subrev_u32_e32 v228, 32, v228
	v_max_u32_e32 v85, v113, v100
	v_min_u32_e32 v100, v113, v100
	v_min_u32_e32 v113, v99, v98
	v_max_u32_e32 v98, v99, v98
	v_max_u32_e32 v99, v97, v96
	v_min_u32_e32 v96, v97, v96
	v_min_u32_e32 v97, v95, v94
	v_max_u32_e32 v94, v95, v94
	v_max_u32_e32 v95, v93, v92
	v_min_u32_e32 v92, v93, v92
	v_min_u32_e32 v93, v91, v90
	v_max_u32_e32 v90, v91, v90
	v_max_u32_e32 v91, v89, v88
	v_min_u32_e32 v88, v89, v88
	v_min_u32_e32 v89, v87, v86
	v_max_u32_e32 v86, v87, v86
	v_max_u32_e32 v87, v85, v113
	v_min_u32_e32 v113, v85, v113
	v_max_u32_e32 v85, v100, v98
	v_min_u32_e32 v98, v100, v98
	v_min_u32_e32 v100, v99, v97
	v_max_u32_e32 v97, v99, v97
	v_min_u32_e32 v99, v96, v94
	v_max_u32_e32 v94, v96, v94
	v_max_u32_e32 v96, v95, v93
	v_min_u32_e32 v93, v95, v93
	v_max_u32_e32 v95, v92, v90
	v_min_u32_e32 v90, v92, v90
	v_min_u32_e32 v92, v91, v89
	v_max_u32_e32 v89, v91, v89
	v_min_u32_e32 v91, v88, v86
	v_max_u32_e32 v86, v88, v86
	v_max_u32_e32 v88, v87, v85
	v_min_u32_e32 v85, v87, v85
	v_max_u32_e32 v87, v113, v98
	v_min_u32_e32 v98, v113, v98
	v_min_u32_e32 v113, v100, v99
	v_max_u32_e32 v99, v100, v99
	v_min_u32_e32 v100, v97, v94
	v_max_u32_e32 v94, v97, v94
	v_max_u32_e32 v97, v96, v95
	v_min_u32_e32 v95, v96, v95
	v_max_u32_e32 v96, v93, v90
	v_min_u32_e32 v90, v93, v90
	v_min_u32_e32 v93, v92, v91
	v_max_u32_e32 v91, v92, v91
	v_min_u32_e32 v92, v89, v86
	v_max_u32_e32 v86, v89, v86
	v_max_u32_e32 v89, v88, v113
	v_min_u32_e32 v113, v88, v113
	v_max_u32_e32 v88, v85, v99
	v_min_u32_e32 v99, v85, v99
	v_max_u32_e32 v85, v87, v100
	v_min_u32_e32 v100, v87, v100
	v_max_u32_e32 v87, v98, v94
	v_min_u32_e32 v94, v98, v94
	v_min_u32_e32 v98, v97, v93
	v_max_u32_e32 v93, v97, v93
	v_min_u32_e32 v97, v95, v91
	v_max_u32_e32 v91, v95, v91
	v_min_u32_e32 v95, v96, v92
; template <int LOGN>
; DI void bitonic_sort_desc(unsigned (&a)[1 << LOGN]) {
;   constexpr int N = 1 << LOGN;
; #pragma unroll
;   for (int ks = 1; ks <= LOGN; ++ks)
; #pragma unroll
;     ...
; #pragma unroll
;       for (int i = 0; i < N; ++i) {
;         const int k = 1 << ks, j = 1 << js, l = i ^ j;
;         if (l > i) {
;           const bool desc = ((i & k) == 0) || (ks == LOGN);
;           const unsigned x = a[i], y = a[l];
;           const unsigned hi = max(x, y), lo = min(x, y);
;           a[i] = desc ? hi : lo;
;           a[l] = desc ? lo : hi;
;         }
;       }
; }
; DI void merge_top16(unsigned (&a)[16], const unsigned (&b)[16]) {
; #pragma unroll
;   for (int i = 0; i < 16; ++i) a[i] = max(a[i], b[15 - i]);
; #pragma unroll
;     ...
; #pragma unroll
;     for (int i = 0; i < 16; ++i) {
;       const int j = 1 << js, l = i ^ j;
;       if (l > i) {
;         const unsigned x = a[i], y = a[l];
;         a[i] = max(x, y);
;         a[l] = min(x, y);
;       }
;     }
; }
	v_max_u32_e32 v92, v96, v92
	v_min_u32_e32 v96, v90, v86
	v_max_u32_e32 v86, v90, v86
	v_max_u32_e32 v90, v89, v85
	v_min_u32_e32 v85, v89, v85
	v_max_u32_e32 v89, v88, v87
	v_min_u32_e32 v87, v88, v87
	v_max_u32_e32 v88, v113, v100
	v_min_u32_e32 v100, v113, v100
	v_max_u32_e32 v113, v99, v94
	v_min_u32_e32 v94, v99, v94
	v_min_u32_e32 v99, v98, v95
	v_max_u32_e32 v95, v98, v95
	v_min_u32_e32 v98, v97, v96
	v_max_u32_e32 v96, v97, v96
	v_min_u32_e32 v97, v93, v92
	v_max_u32_e32 v92, v93, v92
	v_min_u32_e32 v93, v91, v86
	v_max_u32_e32 v86, v91, v86
	v_max_u32_e32 v91, v90, v89
	v_min_u32_e32 v89, v90, v89
	v_max_u32_e32 v90, v85, v87
	v_min_u32_e32 v87, v85, v87
	v_max_u32_e32 v85, v88, v113
	v_min_u32_e32 v113, v88, v113
	v_max_u32_e32 v88, v100, v94
	v_min_u32_e32 v94, v100, v94
	v_min_u32_e32 v100, v99, v98
	v_max_u32_e32 v98, v99, v98
	v_min_u32_e32 v99, v95, v96
	v_max_u32_e32 v96, v95, v96
	v_min_u32_e32 v95, v97, v93
	v_max_u32_e32 v93, v97, v93
	v_min_u32_e32 v97, v92, v86
	v_max_u32_e32 v86, v92, v86
	v_max_u32_e32 v92, v91, v100
	v_min_u32_e32 v100, v91, v100
	v_max_u32_e32 v91, v89, v98
	v_min_u32_e32 v98, v89, v98
	v_max_u32_e32 v89, v90, v99
	v_min_u32_e32 v99, v90, v99
	v_max_u32_e32 v90, v87, v96
	v_min_u32_e32 v96, v87, v96
	v_max_u32_e32 v87, v85, v95
	v_min_u32_e32 v95, v85, v95
	v_max_u32_e32 v85, v113, v93
	v_min_u32_e32 v93, v113, v93
	v_max_u32_e32 v113, v88, v97
	v_min_u32_e32 v97, v88, v97
	v_max_u32_e32 v88, v94, v86
	v_min_u32_e32 v86, v94, v86
	v_max_u32_e32 v94, v92, v87
	v_min_u32_e32 v87, v92, v87
	v_max_u32_e32 v92, v91, v85
	v_min_u32_e32 v85, v91, v85
	v_max_u32_e32 v91, v89, v113
	v_min_u32_e32 v113, v89, v113
	v_max_u32_e32 v89, v90, v88
	v_min_u32_e32 v88, v90, v88
	v_max_u32_e32 v90, v100, v95
	v_min_u32_e32 v95, v100, v95
	v_max_u32_e32 v100, v98, v93
	v_min_u32_e32 v93, v98, v93
	v_max_u32_e32 v98, v99, v97
	v_min_u32_e32 v97, v99, v97
	v_max_u32_e32 v99, v96, v86
	v_min_u32_e32 v86, v96, v86
	v_max_u32_e32 v96, v94, v91
	v_min_u32_e32 v91, v94, v91
	v_max_u32_e32 v94, v92, v89
	v_min_u32_e32 v89, v92, v89
	v_max_u32_e32 v92, v87, v113
	v_min_u32_e32 v113, v87, v113
	v_max_u32_e32 v87, v85, v88
	v_min_u32_e32 v88, v85, v88
	v_max_u32_e32 v85, v90, v98
	v_min_u32_e32 v98, v90, v98
	v_max_u32_e32 v90, v100, v99
	v_min_u32_e32 v99, v100, v99
	v_max_u32_e32 v100, v95, v97
	v_min_u32_e32 v97, v95, v97
	v_max_u32_e32 v95, v93, v86
	v_min_u32_e32 v86, v93, v86
	v_max_u32_e32 v93, v96, v94
	v_min_u32_e32 v94, v96, v94
	v_max_u32_e32 v96, v91, v89
	v_min_u32_e32 v89, v91, v89
	v_max_u32_e32 v91, v92, v87
	v_min_u32_e32 v87, v92, v87
	v_max_u32_e32 v92, v113, v88
	v_min_u32_e32 v88, v113, v88
	v_max_u32_e32 v113, v85, v90
	v_min_u32_e32 v90, v85, v90
	v_max_u32_e32 v85, v98, v99
	v_min_u32_e32 v99, v98, v99
	v_max_u32_e32 v98, v100, v95
	v_min_u32_e32 v95, v100, v95
	v_max_u32_e32 v100, v97, v86
	v_min_u32_e32 v86, v97, v86
	v_max_u32_e32 v97, v109, v86
	v_max_u32_e32 v109, v110, v100
	v_max_u32_e32 v110, v112, v95
	v_max_u32_e32 v112, v105, v98
	v_max_u32_e32 v105, v107, v99
	v_max_u32_e32 v107, v103, v85
	v_max_u32_e32 v103, v108, v90
	v_max_u32_e32 v108, v104, v113
	v_max_u32_e32 v104, v117, v88
	v_max_u32_e32 v117, v106, v92
	v_max_u32_e32 v106, v101, v87
	v_max_u32_e32 v101, v115, v91
	v_max_u32_e32 v115, v114, v89
	v_max_u32_e32 v114, v111, v96
	v_max_u32_e32 v111, v116, v94
	v_max_u32_e32 v116, v102, v93
	v_max_u32_e32 v86, v97, v104
	v_min_u32_e32 v104, v97, v104
	v_max_u32_e32 v97, v109, v117
	v_min_u32_e32 v117, v109, v117
	v_max_u32_e32 v109, v110, v106
	v_min_u32_e32 v106, v110, v106
	v_max_u32_e32 v110, v112, v101
	v_min_u32_e32 v101, v112, v101
	v_max_u32_e32 v112, v105, v115
	v_min_u32_e32 v115, v105, v115
	v_max_u32_e32 v105, v107, v114
	v_min_u32_e32 v114, v107, v114
	v_max_u32_e32 v107, v103, v111
	v_min_u32_e32 v111, v103, v111
	v_max_u32_e32 v103, v108, v116
	v_min_u32_e32 v116, v108, v116
	v_max_u32_e32 v108, v86, v112
	v_min_u32_e32 v112, v86, v112
	v_max_u32_e32 v86, v97, v105
	v_min_u32_e32 v105, v97, v105
	v_max_u32_e32 v97, v109, v107
	v_min_u32_e32 v107, v109, v107
	v_max_u32_e32 v109, v110, v103
	v_min_u32_e32 v103, v110, v103
	v_max_u32_e32 v110, v104, v115
	v_min_u32_e32 v115, v104, v115
	v_max_u32_e32 v104, v117, v114
	v_min_u32_e32 v114, v117, v114
	v_max_u32_e32 v117, v106, v111
	v_min_u32_e32 v111, v106, v111
	v_max_u32_e32 v106, v101, v116
	v_min_u32_e32 v116, v101, v116
	v_max_u32_e32 v101, v108, v97
	v_min_u32_e32 v97, v108, v97
	v_max_u32_e32 v108, v86, v109
	v_min_u32_e32 v109, v86, v109
	v_max_u32_e32 v86, v112, v107
	v_min_u32_e32 v107, v112, v107
	v_max_u32_e32 v112, v105, v103
	v_min_u32_e32 v103, v105, v103
	v_max_u32_e32 v105, v110, v117
	v_min_u32_e32 v117, v110, v117
	v_max_u32_e32 v110, v104, v106
	v_min_u32_e32 v106, v104, v106
	v_max_u32_e32 v104, v115, v111
	v_min_u32_e32 v111, v115, v111
	v_max_u32_e32 v115, v114, v116
	v_min_u32_e32 v116, v114, v116
	v_max_u32_e32 v114, v101, v108
	v_min_u32_e32 v108, v101, v108
	v_max_u32_e32 v101, v97, v109
	v_min_u32_e32 v109, v97, v109
	v_max_u32_e32 v97, v86, v112
	v_min_u32_e32 v112, v86, v112
	v_max_u32_e32 v86, v107, v103
	v_min_u32_e32 v103, v107, v103
	v_max_u32_e32 v107, v105, v110
	v_min_u32_e32 v110, v105, v110
	v_max_u32_e32 v105, v117, v106
	v_min_u32_e32 v106, v117, v106
	v_max_u32_e32 v117, v104, v115
	v_min_u32_e32 v115, v104, v115
	v_max_u32_e32 v104, v111, v116
	v_min_u32_e32 v116, v111, v116
	s_waitcnt vmcnt(7)
	v_mfma_f32_32x32x16_bf16 v[128:143], v[144:147], v[176:179], 0
	s_waitcnt vmcnt(6)
	v_mfma_f32_32x32x16_bf16 v[128:143], v[148:151], v[180:183], v[128:143]
	s_waitcnt vmcnt(5)
; #define MFMA32(a, b, c) __builtin_amdgcn_mfma_f32_32x32x16_bf16((a), (b), (c), 0, 0, 0)
; DI int crow(int i, int hh) { return (i & 3) + 8 * (i >> 2) + 4 * hh; }
; template <int LOGN>
; DI void bitonic_sort_desc(unsigned (&a)[1 << LOGN]) {
;   constexpr int N = 1 << LOGN;
; #pragma unroll
;   for (int ks = 1; ks <= LOGN; ++ks)
; #pragma unroll
;     ...
; #pragma unroll
;       for (int i = 0; i < N; ++i) {
;         const int k = 1 << ks, j = 1 << js, l = i ^ j;
;         if (l > i) {
;           const bool desc = ((i & k) == 0) || (ks == LOGN);
;           const unsigned x = a[i], y = a[l];
;           const unsigned hi = max(x, y), lo = min(x, y);
;           a[i] = desc ? hi : lo;
;           a[l] = desc ? lo : hi;
;         }
;       }
; DI void peer_top16(const u16* __restrict__ PQrow, const u16* __restrict__ SK, unsigned (&top)[16], int lr, int hh) {
;     ...
;     for (int ks = 0; ks < 8; ++ks) {
;       bf16x8 a = *(const bf16x8*)(SK + (size_t)(kt * 32 + lr) * 128 + ks * 16 + hh * 8);
;       acc = MFMA32(a, qf[ks], acc);
;     }
; #pragma unroll
;     for (int e = 0; e < 16; ++e) {
;       int kidx = kt * 32 + crow(e, hh);
;       g[kt][e] = (f2ord(acc[e]) & ~127u) | (unsigned)(127 - kidx);
;     }
;     bitonic_sort_desc<4>(g[kt]);
	v_mfma_f32_32x32x16_bf16 v[128:143], v[152:155], v[184:187], v[128:143]
	s_waitcnt vmcnt(4)
	v_mfma_f32_32x32x16_bf16 v[128:143], v[156:159], v[188:191], v[128:143]
	s_waitcnt vmcnt(3)
	v_mfma_f32_32x32x16_bf16 v[128:143], v[160:163], v[192:195], v[128:143]
	s_waitcnt vmcnt(2)
	v_mfma_f32_32x32x16_bf16 v[128:143], v[164:167], v[196:199], v[128:143]
	s_waitcnt vmcnt(1)
	v_mfma_f32_32x32x16_bf16 v[128:143], v[168:171], v[200:203], v[128:143]
	s_waitcnt vmcnt(0)
	v_mfma_f32_32x32x16_bf16 v[128:143], v[172:175], v[204:207], v[128:143]
	s_add_u32 s4, s0, 24576
	s_addc_u32 s5, s1, 0
	global_load_dwordx4 v[144:147], v238, s[4:5] offset:0
	global_load_dwordx4 v[148:151], v238, s[4:5] offset:32
	global_load_dwordx4 v[152:155], v238, s[4:5] offset:64
	global_load_dwordx4 v[156:159], v238, s[4:5] offset:96
	global_load_dwordx4 v[160:163], v238, s[4:5] offset:128
	global_load_dwordx4 v[164:167], v238, s[4:5] offset:160
	global_load_dwordx4 v[168:171], v238, s[4:5] offset:192
	global_load_dwordx4 v[172:175], v238, s[4:5] offset:224
	s_nop 7
	s_nop 3
	v_ashrrev_i32_e32 v230, 31, v128
	v_or_b32_e32 v230, 0x80000000, v230
	v_xor_b32_e32 v229, v230, v128
	v_and_b32_e32 v229, 0xffffff80, v229
	v_or_b32_e32 v111, v229, v213
	v_ashrrev_i32_e32 v230, 31, v129
	v_or_b32_e32 v230, 0x80000000, v230
	v_xor_b32_e32 v229, v230, v129
	v_and_b32_e32 v229, 0xffffff80, v229
	v_or_b32_e32 v100, v229, v214
	v_ashrrev_i32_e32 v230, 31, v130
	v_or_b32_e32 v230, 0x80000000, v230
	v_xor_b32_e32 v229, v230, v130
	v_and_b32_e32 v229, 0xffffff80, v229
	v_or_b32_e32 v95, v229, v215
	v_ashrrev_i32_e32 v230, 31, v131
	v_or_b32_e32 v230, 0x80000000, v230
	v_xor_b32_e32 v229, v230, v131
	v_and_b32_e32 v229, 0xffffff80, v229
	v_or_b32_e32 v98, v229, v216
	v_ashrrev_i32_e32 v230, 31, v132
	v_or_b32_e32 v230, 0x80000000, v230
	v_xor_b32_e32 v229, v230, v132
	v_and_b32_e32 v229, 0xffffff80, v229
	v_or_b32_e32 v99, v229, v217
	v_ashrrev_i32_e32 v230, 31, v133
	v_or_b32_e32 v230, 0x80000000, v230
	v_xor_b32_e32 v229, v230, v133
	v_and_b32_e32 v229, 0xffffff80, v229
	v_or_b32_e32 v85, v229, v218
	v_ashrrev_i32_e32 v230, 31, v134
	v_or_b32_e32 v230, 0x80000000, v230
	v_xor_b32_e32 v229, v230, v134
	v_and_b32_e32 v229, 0xffffff80, v229
	v_or_b32_e32 v90, v229, v219
	v_ashrrev_i32_e32 v230, 31, v135
	v_or_b32_e32 v230, 0x80000000, v230
	v_xor_b32_e32 v229, v230, v135
	v_and_b32_e32 v229, 0xffffff80, v229
	v_or_b32_e32 v113, v229, v220
	v_ashrrev_i32_e32 v230, 31, v136
	v_or_b32_e32 v230, 0x80000000, v230
	v_xor_b32_e32 v229, v230, v136
	v_and_b32_e32 v229, 0xffffff80, v229
	v_or_b32_e32 v88, v229, v221
	v_ashrrev_i32_e32 v230, 31, v137
	v_or_b32_e32 v230, 0x80000000, v230
	v_xor_b32_e32 v229, v230, v137
	v_and_b32_e32 v229, 0xffffff80, v229
	v_or_b32_e32 v92, v229, v222
	v_ashrrev_i32_e32 v230, 31, v138
	v_or_b32_e32 v230, 0x80000000, v230
	v_xor_b32_e32 v229, v230, v138
	v_and_b32_e32 v229, 0xffffff80, v229
	v_or_b32_e32 v87, v229, v223
	v_ashrrev_i32_e32 v230, 31, v139
	v_or_b32_e32 v230, 0x80000000, v230
	v_xor_b32_e32 v229, v230, v139
	v_and_b32_e32 v229, 0xffffff80, v229
	v_or_b32_e32 v91, v229, v224
	v_ashrrev_i32_e32 v230, 31, v140
	v_or_b32_e32 v230, 0x80000000, v230
	v_xor_b32_e32 v229, v230, v140
	v_and_b32_e32 v229, 0xffffff80, v229
	v_or_b32_e32 v89, v229, v225
	v_ashrrev_i32_e32 v230, 31, v141
	v_or_b32_e32 v230, 0x80000000, v230
	v_xor_b32_e32 v229, v230, v141
	v_and_b32_e32 v229, 0xffffff80, v229
	v_or_b32_e32 v96, v229, v226
	v_ashrrev_i32_e32 v230, 31, v142
	v_or_b32_e32 v230, 0x80000000, v230
	v_xor_b32_e32 v229, v230, v142
	v_and_b32_e32 v229, 0xffffff80, v229
	v_or_b32_e32 v94, v229, v227
	v_ashrrev_i32_e32 v230, 31, v143
	v_or_b32_e32 v230, 0x80000000, v230
	v_xor_b32_e32 v229, v230, v143
	v_and_b32_e32 v229, 0xffffff80, v229
	v_or_b32_e32 v93, v229, v228
	v_subrev_u32_e32 v213, 32, v213
	v_subrev_u32_e32 v214, 32, v214
	v_subrev_u32_e32 v215, 32, v215
	v_subrev_u32_e32 v216, 32, v216
	v_subrev_u32_e32 v217, 32, v217
	v_subrev_u32_e32 v218, 32, v218
	v_subrev_u32_e32 v219, 32, v219
	v_subrev_u32_e32 v220, 32, v220
	v_subrev_u32_e32 v221, 32, v221
	v_subrev_u32_e32 v222, 32, v222
	v_subrev_u32_e32 v223, 32, v223
	v_subrev_u32_e32 v224, 32, v224
	v_subrev_u32_e32 v225, 32, v225
	v_subrev_u32_e32 v226, 32, v226
	v_subrev_u32_e32 v227, 32, v227
	v_subrev_u32_e32 v228, 32, v228
	v_max_u32_e32 v102, v111, v100
	v_min_u32_e32 v100, v111, v100
	v_min_u32_e32 v111, v95, v98
	v_max_u32_e32 v98, v95, v98
	v_max_u32_e32 v95, v99, v85
	v_min_u32_e32 v85, v99, v85
	v_min_u32_e32 v99, v90, v113
	v_max_u32_e32 v113, v90, v113
	v_max_u32_e32 v90, v88, v92
	v_min_u32_e32 v92, v88, v92
	v_min_u32_e32 v88, v87, v91
	v_max_u32_e32 v91, v87, v91
	v_max_u32_e32 v87, v89, v96
	v_min_u32_e32 v96, v89, v96
	v_min_u32_e32 v89, v94, v93
	v_max_u32_e32 v93, v94, v93
	v_max_u32_e32 v94, v102, v111
	v_min_u32_e32 v111, v102, v111
	v_max_u32_e32 v102, v100, v98
	v_min_u32_e32 v98, v100, v98
	v_min_u32_e32 v100, v95, v99
	v_max_u32_e32 v99, v95, v99
	v_min_u32_e32 v95, v85, v113
	v_max_u32_e32 v113, v85, v113
	v_max_u32_e32 v85, v90, v88
	v_min_u32_e32 v88, v90, v88
	v_max_u32_e32 v90, v92, v91
	v_min_u32_e32 v91, v92, v91
	v_min_u32_e32 v92, v87, v89
	v_max_u32_e32 v89, v87, v89
	v_min_u32_e32 v87, v96, v93
	v_max_u32_e32 v93, v96, v93
	v_max_u32_e32 v96, v94, v102
	v_min_u32_e32 v102, v94, v102
	v_max_u32_e32 v94, v111, v98
	v_min_u32_e32 v98, v111, v98
	v_min_u32_e32 v111, v100, v95
	v_max_u32_e32 v95, v100, v95
	v_min_u32_e32 v100, v99, v113
	v_max_u32_e32 v113, v99, v113
	v_max_u32_e32 v99, v85, v90
	v_min_u32_e32 v90, v85, v90
	v_max_u32_e32 v85, v88, v91
	v_min_u32_e32 v91, v88, v91
; #define MFMA32(a, b, c) __builtin_amdgcn_mfma_f32_32x32x16_bf16((a), (b), (c), 0, 0, 0)
; DI int crow(int i, int hh) { return (i & 3) + 8 * (i >> 2) + 4 * hh; }
; template <int LOGN>
; DI void bitonic_sort_desc(unsigned (&a)[1 << LOGN]) {
;   constexpr int N = 1 << LOGN;
; #pragma unroll
;   for (int ks = 1; ks <= LOGN; ++ks)
; #pragma unroll
;     ...
; #pragma unroll
;       for (int i = 0; i < N; ++i) {
;         const int k = 1 << ks, j = 1 << js, l = i ^ j;
;         if (l > i) {
;           const bool desc = ((i & k) == 0) || (ks == LOGN);
;           const unsigned x = a[i], y = a[l];
;           const unsigned hi = max(x, y), lo = min(x, y);
;           a[i] = desc ? hi : lo;
;           a[l] = desc ? lo : hi;
;         }
;       }
; DI void peer_top16(const u16* __restrict__ PQrow, const u16* __restrict__ SK, unsigned (&top)[16], int lr, int hh) {
;   bf16x8 qf[8];
; #pragma unroll
;   for (int ks = 0; ks < 8; ++ks) qf[ks] = *(const bf16x8*)(PQrow + ks * 16 + hh * 8);
;   unsigned g[4][16];
; #pragma unroll
;   for (int kt = 0; kt < 4; ++kt) {
;     f32x16 acc;
; #pragma unroll
;     for (int e = 0; e < 16; ++e) acc[e] = 0.f;
; #pragma unroll
;     for (int ks = 0; ks < 8; ++ks) {
;       bf16x8 a = *(const bf16x8*)(SK + (size_t)(kt * 32 + lr) * 128 + ks * 16 + hh * 8);
;       acc = MFMA32(a, qf[ks], acc);
;     }
; #pragma unroll
;     for (int e = 0; e < 16; ++e) {
;       int kidx = kt * 32 + crow(e, hh);
;       g[kt][e] = (f2ord(acc[e]) & ~127u) | (unsigned)(127 - kidx);
	v_min_u32_e32 v88, v92, v87
	v_max_u32_e32 v87, v92, v87
	v_min_u32_e32 v92, v89, v93
	v_max_u32_e32 v93, v89, v93
	v_max_u32_e32 v89, v96, v111
	v_min_u32_e32 v111, v96, v111
	v_max_u32_e32 v96, v102, v95
	v_min_u32_e32 v95, v102, v95
	v_max_u32_e32 v102, v94, v100
	v_min_u32_e32 v100, v94, v100
	v_max_u32_e32 v94, v98, v113
	v_min_u32_e32 v113, v98, v113
	v_min_u32_e32 v98, v99, v88
	v_max_u32_e32 v88, v99, v88
	v_min_u32_e32 v99, v90, v87
	v_max_u32_e32 v87, v90, v87
	v_min_u32_e32 v90, v85, v92
	v_max_u32_e32 v92, v85, v92
	v_min_u32_e32 v85, v91, v93
	v_max_u32_e32 v93, v91, v93
	v_max_u32_e32 v91, v89, v102
	v_min_u32_e32 v102, v89, v102
	v_max_u32_e32 v89, v96, v94
	v_min_u32_e32 v94, v96, v94
	v_max_u32_e32 v96, v111, v100
	v_min_u32_e32 v100, v111, v100
	v_max_u32_e32 v111, v95, v113
	v_min_u32_e32 v113, v95, v113
	v_min_u32_e32 v95, v98, v90
	v_max_u32_e32 v90, v98, v90
	v_min_u32_e32 v98, v99, v85
	v_max_u32_e32 v85, v99, v85
	v_min_u32_e32 v99, v88, v92
	v_max_u32_e32 v92, v88, v92
	v_min_u32_e32 v88, v87, v93
	v_max_u32_e32 v93, v87, v93
	v_max_u32_e32 v87, v91, v89
	v_min_u32_e32 v89, v91, v89
	v_max_u32_e32 v91, v102, v94
	v_min_u32_e32 v94, v102, v94
	v_max_u32_e32 v102, v96, v111
	v_min_u32_e32 v111, v96, v111
	v_max_u32_e32 v96, v100, v113
	v_min_u32_e32 v113, v100, v113
	v_min_u32_e32 v100, v95, v98
	v_max_u32_e32 v98, v95, v98
	v_min_u32_e32 v95, v90, v85
	v_max_u32_e32 v85, v90, v85
	v_min_u32_e32 v90, v99, v88
	v_max_u32_e32 v88, v99, v88
	v_min_u32_e32 v99, v92, v93
	v_max_u32_e32 v93, v92, v93
	v_max_u32_e32 v92, v87, v100
	v_min_u32_e32 v100, v87, v100
	v_max_u32_e32 v87, v89, v98
	v_min_u32_e32 v98, v89, v98
	v_max_u32_e32 v89, v91, v95
	v_min_u32_e32 v95, v91, v95
	v_max_u32_e32 v91, v94, v85
	v_min_u32_e32 v85, v94, v85
	v_max_u32_e32 v94, v102, v90
	v_min_u32_e32 v90, v102, v90
	v_max_u32_e32 v102, v111, v88
	v_min_u32_e32 v88, v111, v88
	v_max_u32_e32 v111, v96, v99
	v_min_u32_e32 v99, v96, v99
	v_max_u32_e32 v96, v113, v93
	v_min_u32_e32 v93, v113, v93
	v_max_u32_e32 v113, v92, v94
	v_min_u32_e32 v94, v92, v94
	v_max_u32_e32 v92, v87, v102
	v_min_u32_e32 v102, v87, v102
	v_max_u32_e32 v87, v89, v111
	v_min_u32_e32 v111, v89, v111
	v_max_u32_e32 v89, v91, v96
	v_min_u32_e32 v96, v91, v96
	v_max_u32_e32 v91, v100, v90
	v_min_u32_e32 v90, v100, v90
	v_max_u32_e32 v100, v98, v88
	v_min_u32_e32 v88, v98, v88
	v_max_u32_e32 v98, v95, v99
	v_min_u32_e32 v99, v95, v99
	v_max_u32_e32 v95, v85, v93
	v_min_u32_e32 v93, v85, v93
	v_max_u32_e32 v85, v113, v87
	v_min_u32_e32 v87, v113, v87
	v_max_u32_e32 v113, v92, v89
	v_min_u32_e32 v89, v92, v89
	v_max_u32_e32 v92, v94, v111
	v_min_u32_e32 v111, v94, v111
	v_max_u32_e32 v94, v102, v96
	v_min_u32_e32 v96, v102, v96
	v_max_u32_e32 v102, v91, v98
	v_min_u32_e32 v98, v91, v98
	v_max_u32_e32 v91, v100, v95
	v_min_u32_e32 v95, v100, v95
	v_max_u32_e32 v100, v90, v99
	v_min_u32_e32 v99, v90, v99
	v_max_u32_e32 v90, v88, v93
	v_min_u32_e32 v93, v88, v93
	v_max_u32_e32 v88, v85, v113
	v_min_u32_e32 v113, v85, v113
	v_max_u32_e32 v85, v87, v89
	v_min_u32_e32 v89, v87, v89
	v_max_u32_e32 v87, v92, v94
	v_min_u32_e32 v94, v92, v94
	v_max_u32_e32 v92, v111, v96
	v_min_u32_e32 v96, v111, v96
	v_max_u32_e32 v111, v102, v91
	v_min_u32_e32 v91, v102, v91
	v_max_u32_e32 v102, v98, v95
	v_min_u32_e32 v95, v98, v95
	v_max_u32_e32 v98, v100, v90
	v_min_u32_e32 v90, v100, v90
	v_max_u32_e32 v100, v99, v93
	v_min_u32_e32 v93, v99, v93
	s_waitcnt vmcnt(7)
	v_mfma_f32_32x32x16_bf16 v[128:143], v[144:147], v[176:179], 0
	s_waitcnt vmcnt(6)
	v_mfma_f32_32x32x16_bf16 v[128:143], v[148:151], v[180:183], v[128:143]
	s_waitcnt vmcnt(5)
	v_mfma_f32_32x32x16_bf16 v[128:143], v[152:155], v[184:187], v[128:143]
	s_waitcnt vmcnt(4)
	v_mfma_f32_32x32x16_bf16 v[128:143], v[156:159], v[188:191], v[128:143]
	s_waitcnt vmcnt(3)
	v_mfma_f32_32x32x16_bf16 v[128:143], v[160:163], v[192:195], v[128:143]
	s_waitcnt vmcnt(2)
	v_mfma_f32_32x32x16_bf16 v[128:143], v[164:167], v[196:199], v[128:143]
	s_waitcnt vmcnt(1)
	v_mfma_f32_32x32x16_bf16 v[128:143], v[168:171], v[200:203], v[128:143]
	s_waitcnt vmcnt(0)
	v_mfma_f32_32x32x16_bf16 v[128:143], v[172:175], v[204:207], v[128:143]
	global_load_dwordx4 v[176:179], v239, s[2:3] offset:256
	global_load_dwordx4 v[180:183], v239, s[2:3] offset:288
	global_load_dwordx4 v[184:187], v239, s[2:3] offset:320
	global_load_dwordx4 v[188:191], v239, s[2:3] offset:352
	global_load_dwordx4 v[192:195], v239, s[2:3] offset:384
	global_load_dwordx4 v[196:199], v239, s[2:3] offset:416
	global_load_dwordx4 v[200:203], v239, s[2:3] offset:448
	global_load_dwordx4 v[204:207], v239, s[2:3] offset:480
	s_add_u32 s4, s0, 32768
	s_addc_u32 s5, s1, 0
	global_load_dwordx4 v[144:147], v238, s[4:5] offset:0
	global_load_dwordx4 v[148:151], v238, s[4:5] offset:32
	global_load_dwordx4 v[152:155], v238, s[4:5] offset:64
	global_load_dwordx4 v[156:159], v238, s[4:5] offset:96
	global_load_dwordx4 v[160:163], v238, s[4:5] offset:128
	global_load_dwordx4 v[164:167], v238, s[4:5] offset:160
	global_load_dwordx4 v[168:171], v238, s[4:5] offset:192
	global_load_dwordx4 v[172:175], v238, s[4:5] offset:224
	s_nop 7
	s_nop 3
	v_ashrrev_i32_e32 v230, 31, v128
	v_or_b32_e32 v230, 0x80000000, v230
	v_xor_b32_e32 v229, v230, v128
	v_and_b32_e32 v229, 0xffffff80, v229
	v_or_b32_e32 v99, v229, v213
	v_ashrrev_i32_e32 v230, 31, v129
	v_or_b32_e32 v230, 0x80000000, v230
	v_xor_b32_e32 v229, v230, v129
	v_and_b32_e32 v229, 0xffffff80, v229
	v_or_b32_e32 v84, v229, v214
	v_ashrrev_i32_e32 v230, 31, v130
	v_or_b32_e32 v230, 0x80000000, v230
	v_xor_b32_e32 v229, v230, v130
	v_and_b32_e32 v229, 0xffffff80, v229
; DI int crow(int i, int hh) { return (i & 3) + 8 * (i >> 2) + 4 * hh; }
; template <int LOGN>
; DI void bitonic_sort_desc(unsigned (&a)[1 << LOGN]) {
;   constexpr int N = 1 << LOGN;
; #pragma unroll
;   for (int ks = 1; ks <= LOGN; ++ks)
; #pragma unroll
;     ...
; #pragma unroll
;       for (int i = 0; i < N; ++i) {
;         const int k = 1 << ks, j = 1 << js, l = i ^ j;
;         if (l > i) {
;           const bool desc = ((i & k) == 0) || (ks == LOGN);
;           const unsigned x = a[i], y = a[l];
;           const unsigned hi = max(x, y), lo = min(x, y);
;           a[i] = desc ? hi : lo;
;           a[l] = desc ? lo : hi;
;         }
;       }
; DI void peer_top16(const u16* __restrict__ PQrow, const u16* __restrict__ SK, unsigned (&top)[16], int lr, int hh) {
;     ...
; #pragma unroll
;     for (int e = 0; e < 16; ++e) {
;       int kidx = kt * 32 + crow(e, hh);
;       g[kt][e] = (f2ord(acc[e]) & ~127u) | (unsigned)(127 - kidx);
;     }
;     bitonic_sort_desc<4>(g[kt]);
	v_or_b32_e32 v83, v229, v215
	v_ashrrev_i32_e32 v230, 31, v131
	v_or_b32_e32 v230, 0x80000000, v230
	v_xor_b32_e32 v229, v230, v131
	v_and_b32_e32 v229, 0xffffff80, v229
	v_or_b32_e32 v82, v229, v216
	v_ashrrev_i32_e32 v230, 31, v132
	v_or_b32_e32 v230, 0x80000000, v230
	v_xor_b32_e32 v229, v230, v132
	v_and_b32_e32 v229, 0xffffff80, v229
	v_or_b32_e32 v81, v229, v217
	v_ashrrev_i32_e32 v230, 31, v133
	v_or_b32_e32 v230, 0x80000000, v230
	v_xor_b32_e32 v229, v230, v133
	v_and_b32_e32 v229, 0xffffff80, v229
	v_or_b32_e32 v80, v229, v218
	v_ashrrev_i32_e32 v230, 31, v134
	v_or_b32_e32 v230, 0x80000000, v230
	v_xor_b32_e32 v229, v230, v134
	v_and_b32_e32 v229, 0xffffff80, v229
	v_or_b32_e32 v79, v229, v219
	v_ashrrev_i32_e32 v230, 31, v135
	v_or_b32_e32 v230, 0x80000000, v230
	v_xor_b32_e32 v229, v230, v135
	v_and_b32_e32 v229, 0xffffff80, v229
	v_or_b32_e32 v78, v229, v220
	v_ashrrev_i32_e32 v230, 31, v136
	v_or_b32_e32 v230, 0x80000000, v230
	v_xor_b32_e32 v229, v230, v136
	v_and_b32_e32 v229, 0xffffff80, v229
	v_or_b32_e32 v77, v229, v221
	v_ashrrev_i32_e32 v230, 31, v137
	v_or_b32_e32 v230, 0x80000000, v230
	v_xor_b32_e32 v229, v230, v137
	v_and_b32_e32 v229, 0xffffff80, v229
	v_or_b32_e32 v76, v229, v222
	v_ashrrev_i32_e32 v230, 31, v138
	v_or_b32_e32 v230, 0x80000000, v230
	v_xor_b32_e32 v229, v230, v138
	v_and_b32_e32 v229, 0xffffff80, v229
	v_or_b32_e32 v75, v229, v223
	v_ashrrev_i32_e32 v230, 31, v139
	v_or_b32_e32 v230, 0x80000000, v230
	v_xor_b32_e32 v229, v230, v139
	v_and_b32_e32 v229, 0xffffff80, v229
	v_or_b32_e32 v74, v229, v224
	v_ashrrev_i32_e32 v230, 31, v140
	v_or_b32_e32 v230, 0x80000000, v230
	v_xor_b32_e32 v229, v230, v140
	v_and_b32_e32 v229, 0xffffff80, v229
	v_or_b32_e32 v73, v229, v225
	v_ashrrev_i32_e32 v230, 31, v141
	v_or_b32_e32 v230, 0x80000000, v230
	v_xor_b32_e32 v229, v230, v141
	v_and_b32_e32 v229, 0xffffff80, v229
	v_or_b32_e32 v72, v229, v226
	v_ashrrev_i32_e32 v230, 31, v142
	v_or_b32_e32 v230, 0x80000000, v230
	v_xor_b32_e32 v229, v230, v142
	v_and_b32_e32 v229, 0xffffff80, v229
	v_or_b32_e32 v71, v229, v227
	v_ashrrev_i32_e32 v230, 31, v143
	v_or_b32_e32 v230, 0x80000000, v230
	v_xor_b32_e32 v229, v230, v143
	v_and_b32_e32 v229, 0xffffff80, v229
	v_or_b32_e32 v70, v229, v228
	v_max_u32_e32 v69, v99, v84
	v_min_u32_e32 v84, v99, v84
	v_min_u32_e32 v99, v83, v82
	v_max_u32_e32 v82, v83, v82
	v_max_u32_e32 v83, v81, v80
	v_min_u32_e32 v80, v81, v80
	v_min_u32_e32 v81, v79, v78
	v_max_u32_e32 v78, v79, v78
	v_max_u32_e32 v79, v77, v76
	v_min_u32_e32 v76, v77, v76
	v_min_u32_e32 v77, v75, v74
	v_max_u32_e32 v74, v75, v74
	v_max_u32_e32 v75, v73, v72
	v_min_u32_e32 v72, v73, v72
	v_min_u32_e32 v73, v71, v70
	v_max_u32_e32 v70, v71, v70
	v_max_u32_e32 v71, v69, v99
	v_min_u32_e32 v99, v69, v99
	v_max_u32_e32 v69, v84, v82
	v_min_u32_e32 v82, v84, v82
	v_min_u32_e32 v84, v83, v81
	v_max_u32_e32 v81, v83, v81
	v_min_u32_e32 v83, v80, v78
	v_max_u32_e32 v78, v80, v78
	v_max_u32_e32 v80, v79, v77
	v_min_u32_e32 v77, v79, v77
	v_max_u32_e32 v79, v76, v74
	v_min_u32_e32 v74, v76, v74
	v_min_u32_e32 v76, v75, v73
	v_max_u32_e32 v73, v75, v73
	v_min_u32_e32 v75, v72, v70
	v_max_u32_e32 v70, v72, v70
	v_max_u32_e32 v72, v71, v69
	v_min_u32_e32 v69, v71, v69
	v_max_u32_e32 v71, v99, v82
	v_min_u32_e32 v82, v99, v82
	v_min_u32_e32 v99, v84, v83
	v_max_u32_e32 v83, v84, v83
	v_min_u32_e32 v84, v81, v78
	v_max_u32_e32 v78, v81, v78
	v_max_u32_e32 v81, v80, v79
	v_min_u32_e32 v79, v80, v79
	v_max_u32_e32 v80, v77, v74
	v_min_u32_e32 v74, v77, v74
	v_min_u32_e32 v77, v76, v75
	v_max_u32_e32 v75, v76, v75
	v_min_u32_e32 v76, v73, v70
	v_max_u32_e32 v70, v73, v70
	v_max_u32_e32 v73, v72, v99
	v_min_u32_e32 v99, v72, v99
	v_max_u32_e32 v72, v69, v83
	v_min_u32_e32 v83, v69, v83
	v_max_u32_e32 v69, v71, v84
	v_min_u32_e32 v84, v71, v84
	v_max_u32_e32 v71, v82, v78
	v_min_u32_e32 v78, v82, v78
	v_min_u32_e32 v82, v81, v77
	v_max_u32_e32 v77, v81, v77
	v_min_u32_e32 v81, v79, v75
	v_max_u32_e32 v75, v79, v75
	v_min_u32_e32 v79, v80, v76
	v_max_u32_e32 v76, v80, v76
	v_min_u32_e32 v80, v74, v70
	v_max_u32_e32 v70, v74, v70
	v_max_u32_e32 v74, v73, v69
	v_min_u32_e32 v69, v73, v69
	v_max_u32_e32 v73, v72, v71
	v_min_u32_e32 v71, v72, v71
	v_max_u32_e32 v72, v99, v84
	v_min_u32_e32 v84, v99, v84
	v_max_u32_e32 v99, v83, v78
	v_min_u32_e32 v78, v83, v78
	v_min_u32_e32 v83, v82, v79
	v_max_u32_e32 v79, v82, v79
	v_min_u32_e32 v82, v81, v80
	v_max_u32_e32 v80, v81, v80
	v_min_u32_e32 v81, v77, v76
	v_max_u32_e32 v76, v77, v76
	v_min_u32_e32 v77, v75, v70
	v_max_u32_e32 v70, v75, v70
	v_max_u32_e32 v75, v74, v73
	v_min_u32_e32 v73, v74, v73
	v_max_u32_e32 v74, v69, v71
	v_min_u32_e32 v71, v69, v71
	v_max_u32_e32 v69, v72, v99
	v_min_u32_e32 v99, v72, v99
	v_max_u32_e32 v72, v84, v78
	v_min_u32_e32 v78, v84, v78
	v_min_u32_e32 v84, v83, v82
	v_max_u32_e32 v82, v83, v82
	v_min_u32_e32 v83, v79, v80
	v_max_u32_e32 v80, v79, v80
	v_min_u32_e32 v79, v81, v77
	v_max_u32_e32 v77, v81, v77
	v_min_u32_e32 v81, v76, v70
	v_max_u32_e32 v70, v76, v70
	v_max_u32_e32 v76, v75, v84
	v_min_u32_e32 v84, v75, v84
	v_max_u32_e32 v75, v73, v82
	v_min_u32_e32 v82, v73, v82
	v_max_u32_e32 v73, v74, v83
	v_min_u32_e32 v83, v74, v83
	v_max_u32_e32 v74, v71, v80
	v_min_u32_e32 v80, v71, v80
	v_max_u32_e32 v71, v69, v79
	v_min_u32_e32 v79, v69, v79
	v_max_u32_e32 v69, v99, v77
	v_min_u32_e32 v77, v99, v77
	v_max_u32_e32 v99, v72, v81
	v_min_u32_e32 v81, v72, v81
	v_max_u32_e32 v72, v78, v70
	v_min_u32_e32 v70, v78, v70
	v_max_u32_e32 v78, v76, v71
	v_min_u32_e32 v71, v76, v71
	v_max_u32_e32 v76, v75, v69
	v_min_u32_e32 v69, v75, v69
	v_max_u32_e32 v75, v73, v99
; DI void merge_top16(unsigned (&a)[16], const unsigned (&b)[16]) {
; #pragma unroll
;   for (int i = 0; i < 16; ++i) a[i] = max(a[i], b[15 - i]);
; #pragma unroll
;     ...
; #pragma unroll
;     for (int i = 0; i < 16; ++i) {
;       const int j = 1 << js, l = i ^ j;
;       if (l > i) {
;         const unsigned x = a[i], y = a[l];
;         a[i] = max(x, y);
;         a[l] = min(x, y);
;       }
;     }
; }
; DI void peer_top16(const u16* __restrict__ PQrow, const u16* __restrict__ SK, unsigned (&top)[16], int lr, int hh) {
;     ...
;     bitonic_sort_desc<4>(g[kt]);
;   }
;   merge_top16(g[0], g[1]);
;   merge_top16(g[2], g[3]);
;   merge_top16(g[0], g[2]);
;   unsigned other[16];
; #pragma unroll
;   for (int i = 0; i < 16; ++i) other[i] = (unsigned)__shfl_xor((int)g[0][i], 32);
;   merge_top16(g[0], other);
; #pragma unroll
;   for (int i = 0; i < 16; ++i) top[i] = g[0][i];
	v_min_u32_e32 v99, v73, v99
	v_max_u32_e32 v73, v74, v72
	v_min_u32_e32 v72, v74, v72
	v_max_u32_e32 v74, v84, v79
	v_min_u32_e32 v79, v84, v79
	v_max_u32_e32 v84, v82, v77
	v_min_u32_e32 v77, v82, v77
	v_max_u32_e32 v82, v83, v81
	v_min_u32_e32 v81, v83, v81
	v_max_u32_e32 v83, v80, v70
	v_min_u32_e32 v70, v80, v70
	v_max_u32_e32 v80, v78, v75
	v_min_u32_e32 v75, v78, v75
	v_max_u32_e32 v78, v76, v73
	v_min_u32_e32 v73, v76, v73
	v_max_u32_e32 v76, v71, v99
	v_min_u32_e32 v99, v71, v99
	v_max_u32_e32 v71, v69, v72
	v_min_u32_e32 v72, v69, v72
	v_max_u32_e32 v69, v74, v82
	v_min_u32_e32 v82, v74, v82
	v_max_u32_e32 v74, v84, v83
	v_min_u32_e32 v83, v84, v83
	v_max_u32_e32 v84, v79, v81
	v_min_u32_e32 v81, v79, v81
	v_max_u32_e32 v79, v77, v70
	v_min_u32_e32 v70, v77, v70
	v_max_u32_e32 v77, v80, v78
	v_min_u32_e32 v78, v80, v78
	v_max_u32_e32 v80, v75, v73
	v_min_u32_e32 v73, v75, v73
	v_max_u32_e32 v75, v76, v71
	v_min_u32_e32 v71, v76, v71
	v_max_u32_e32 v76, v99, v72
	v_min_u32_e32 v72, v99, v72
	v_max_u32_e32 v99, v69, v74
	v_min_u32_e32 v74, v69, v74
	v_max_u32_e32 v69, v82, v83
	v_min_u32_e32 v83, v82, v83
	v_max_u32_e32 v82, v84, v79
	v_min_u32_e32 v79, v84, v79
	v_max_u32_e32 v84, v81, v70
	v_min_u32_e32 v70, v81, v70
	v_max_u32_e32 v81, v88, v70
	v_max_u32_e32 v88, v113, v84
	v_max_u32_e32 v113, v85, v79
	v_max_u32_e32 v85, v89, v82
	v_max_u32_e32 v89, v87, v83
	v_max_u32_e32 v87, v94, v69
	v_max_u32_e32 v94, v92, v74
	v_max_u32_e32 v92, v96, v99
	v_max_u32_e32 v96, v111, v72
	v_max_u32_e32 v111, v91, v76
	v_max_u32_e32 v91, v102, v71
	v_max_u32_e32 v102, v95, v75
	v_max_u32_e32 v95, v98, v73
	v_max_u32_e32 v98, v90, v80
	v_max_u32_e32 v90, v100, v78
	v_max_u32_e32 v100, v93, v77
	v_max_u32_e32 v70, v81, v96
	v_min_u32_e32 v96, v81, v96
	v_max_u32_e32 v81, v88, v111
	v_min_u32_e32 v111, v88, v111
	v_max_u32_e32 v88, v113, v91
	v_min_u32_e32 v91, v113, v91
	v_max_u32_e32 v113, v85, v102
	v_min_u32_e32 v102, v85, v102
	v_max_u32_e32 v85, v89, v95
	v_min_u32_e32 v95, v89, v95
	v_max_u32_e32 v89, v87, v98
	v_min_u32_e32 v98, v87, v98
	v_max_u32_e32 v87, v94, v90
	v_min_u32_e32 v90, v94, v90
	v_max_u32_e32 v94, v92, v100
	v_min_u32_e32 v100, v92, v100
	v_max_u32_e32 v92, v70, v85
	v_min_u32_e32 v85, v70, v85
	v_max_u32_e32 v70, v81, v89
	v_min_u32_e32 v89, v81, v89
	v_max_u32_e32 v81, v88, v87
	v_min_u32_e32 v87, v88, v87
	v_max_u32_e32 v88, v113, v94
	v_min_u32_e32 v94, v113, v94
	v_max_u32_e32 v113, v96, v95
	v_min_u32_e32 v95, v96, v95
	v_max_u32_e32 v96, v111, v98
	v_min_u32_e32 v98, v111, v98
	v_max_u32_e32 v111, v91, v90
	v_min_u32_e32 v90, v91, v90
	v_max_u32_e32 v91, v102, v100
	v_min_u32_e32 v100, v102, v100
	v_max_u32_e32 v102, v92, v81
	v_min_u32_e32 v81, v92, v81
	v_max_u32_e32 v92, v70, v88
	v_min_u32_e32 v88, v70, v88
	v_max_u32_e32 v70, v85, v87
	v_min_u32_e32 v87, v85, v87
	v_max_u32_e32 v85, v89, v94
	v_min_u32_e32 v94, v89, v94
	v_max_u32_e32 v89, v113, v111
	v_min_u32_e32 v111, v113, v111
	v_max_u32_e32 v113, v96, v91
	v_min_u32_e32 v91, v96, v91
	v_max_u32_e32 v96, v95, v90
	v_min_u32_e32 v90, v95, v90
	v_max_u32_e32 v95, v98, v100
	v_min_u32_e32 v100, v98, v100
	v_max_u32_e32 v98, v102, v92
	v_min_u32_e32 v92, v102, v92
	v_max_u32_e32 v102, v81, v88
	v_min_u32_e32 v88, v81, v88
	v_max_u32_e32 v81, v70, v85
	v_min_u32_e32 v85, v70, v85
	v_max_u32_e32 v70, v87, v94
	v_min_u32_e32 v94, v87, v94
	v_max_u32_e32 v87, v89, v113
	v_min_u32_e32 v113, v89, v113
	v_max_u32_e32 v89, v111, v91
	v_min_u32_e32 v91, v111, v91
	v_max_u32_e32 v111, v96, v95
	v_min_u32_e32 v95, v96, v95
	v_max_u32_e32 v96, v90, v100
	v_min_u32_e32 v100, v90, v100
	v_max_u32_e32 v90, v114, v100
	v_max_u32_e32 v114, v108, v96
	v_max_u32_e32 v108, v101, v95
	v_max_u32_e32 v101, v109, v111
	v_max_u32_e32 v109, v97, v91
	v_max_u32_e32 v97, v112, v89
	v_max_u32_e32 v112, v86, v113
	v_max_u32_e32 v86, v103, v87
	v_max_u32_e32 v103, v107, v94
	v_max_u32_e32 v107, v110, v70
	v_max_u32_e32 v110, v105, v85
	v_max_u32_e32 v105, v106, v81
	v_max_u32_e32 v106, v117, v88
	v_max_u32_e32 v117, v115, v102
	v_max_u32_e32 v115, v104, v92
	v_max_u32_e32 v104, v116, v98
	v_max_u32_e32 v100, v90, v103
	v_min_u32_e32 v103, v90, v103
	v_max_u32_e32 v90, v114, v107
	v_min_u32_e32 v107, v114, v107
	v_max_u32_e32 v114, v108, v110
	v_min_u32_e32 v110, v108, v110
	v_max_u32_e32 v108, v101, v105
	v_min_u32_e32 v105, v101, v105
	v_max_u32_e32 v101, v109, v106
	v_min_u32_e32 v106, v109, v106
	v_max_u32_e32 v109, v97, v117
	v_min_u32_e32 v117, v97, v117
	v_max_u32_e32 v97, v112, v115
	v_min_u32_e32 v115, v112, v115
	v_max_u32_e32 v112, v86, v104
	v_min_u32_e32 v104, v86, v104
	v_max_u32_e32 v86, v100, v101
	v_min_u32_e32 v101, v100, v101
	v_max_u32_e32 v100, v90, v109
	v_min_u32_e32 v109, v90, v109
	v_max_u32_e32 v90, v114, v97
	v_min_u32_e32 v97, v114, v97
	v_max_u32_e32 v114, v108, v112
	v_min_u32_e32 v112, v108, v112
	v_max_u32_e32 v108, v103, v106
	v_min_u32_e32 v106, v103, v106
	v_max_u32_e32 v103, v107, v117
	v_min_u32_e32 v117, v107, v117
	v_max_u32_e32 v107, v110, v115
	v_min_u32_e32 v115, v110, v115
	v_max_u32_e32 v110, v105, v104
	v_min_u32_e32 v104, v105, v104
	v_max_u32_e32 v105, v86, v90
	v_min_u32_e32 v90, v86, v90
	v_max_u32_e32 v86, v100, v114
	v_min_u32_e32 v114, v100, v114
	v_max_u32_e32 v100, v101, v97
	v_min_u32_e32 v97, v101, v97
	v_max_u32_e32 v101, v109, v112
	v_min_u32_e32 v112, v109, v112
	v_max_u32_e32 v109, v108, v107
	v_min_u32_e32 v107, v108, v107
	v_max_u32_e32 v108, v103, v110
	v_min_u32_e32 v110, v103, v110
	v_max_u32_e32 v103, v106, v115
	v_min_u32_e32 v115, v106, v115
	v_max_u32_e32 v106, v117, v104
	v_min_u32_e32 v104, v117, v104
	v_max_u32_e32 v117, v105, v86
	v_min_u32_e32 v86, v105, v86
	v_max_u32_e32 v105, v90, v114
	v_min_u32_e32 v114, v90, v114
	v_max_u32_e32 v90, v100, v101
	v_min_u32_e32 v101, v100, v101
	v_max_u32_e32 v100, v97, v112
	v_min_u32_e32 v112, v97, v112
	v_max_u32_e32 v97, v109, v108
	v_min_u32_e32 v108, v109, v108
	v_max_u32_e32 v109, v107, v110
	v_min_u32_e32 v110, v107, v110
	v_max_u32_e32 v107, v103, v106
	v_min_u32_e32 v106, v103, v106
	v_max_u32_e32 v103, v115, v104
	v_min_u32_e32 v104, v115, v104
	v_mov_b32_e32 v0, v117
	v_mov_b32_e32 v1, v86
	v_mov_b32_e32 v2, v105
	v_mov_b32_e32 v3, v114
	v_mov_b32_e32 v4, v90
	v_mov_b32_e32 v5, v101
	v_mov_b32_e32 v6, v100
	v_mov_b32_e32 v7, v112
	v_mov_b32_e32 v8, v97
	v_mov_b32_e32 v9, v108
	v_mov_b32_e32 v10, v109
	v_mov_b32_e32 v11, v110
	v_mov_b32_e32 v12, v107
	v_mov_b32_e32 v13, v106
	v_mov_b32_e32 v14, v103
	v_mov_b32_e32 v15, v104
	v_sub_u32_e32 v213, 127, v245
	v_sub_u32_e32 v214, 126, v245
	v_sub_u32_e32 v215, 125, v245
	v_sub_u32_e32 v216, 124, v245
	v_sub_u32_e32 v217, 119, v245
	v_sub_u32_e32 v218, 118, v245
	v_sub_u32_e32 v219, 117, v245
	v_sub_u32_e32 v220, 116, v245
	v_sub_u32_e32 v221, 111, v245
	v_sub_u32_e32 v222, 110, v245
	v_sub_u32_e32 v223, 109, v245
	v_sub_u32_e32 v224, 108, v245
	v_sub_u32_e32 v225, 103, v245
	v_sub_u32_e32 v226, 102, v245
	v_sub_u32_e32 v227, 101, v245
	v_sub_u32_e32 v228, 100, v245
	s_waitcnt vmcnt(7)
; #define MFMA32(a, b, c) __builtin_amdgcn_mfma_f32_32x32x16_bf16((a), (b), (c), 0, 0, 0)
; DI int crow(int i, int hh) { return (i & 3) + 8 * (i >> 2) + 4 * hh; }
; template <int LOGN>
; DI void bitonic_sort_desc(unsigned (&a)[1 << LOGN]) {
;   constexpr int N = 1 << LOGN;
; #pragma unroll
;   for (int ks = 1; ks <= LOGN; ++ks)
; #pragma unroll
;     ...
; #pragma unroll
;       for (int i = 0; i < N; ++i) {
;         const int k = 1 << ks, j = 1 << js, l = i ^ j;
;         if (l > i) {
;           const bool desc = ((i & k) == 0) || (ks == LOGN);
;           const unsigned x = a[i], y = a[l];
;           const unsigned hi = max(x, y), lo = min(x, y);
;           a[i] = desc ? hi : lo;
;           a[l] = desc ? lo : hi;
;         }
;       }
; DI void peer_top16(const u16* __restrict__ PQrow, const u16* __restrict__ SK, unsigned (&top)[16], int lr, int hh) {
;     ...
;     for (int ks = 0; ks < 8; ++ks) {
;       bf16x8 a = *(const bf16x8*)(SK + (size_t)(kt * 32 + lr) * 128 + ks * 16 + hh * 8);
;       acc = MFMA32(a, qf[ks], acc);
;     }
; #pragma unroll
;     for (int e = 0; e < 16; ++e) {
;       int kidx = kt * 32 + crow(e, hh);
;       g[kt][e] = (f2ord(acc[e]) & ~127u) | (unsigned)(127 - kidx);
;     }
;     bitonic_sort_desc<4>(g[kt]);
	v_mfma_f32_32x32x16_bf16 v[128:143], v[144:147], v[176:179], 0
	s_waitcnt vmcnt(6)
	v_mfma_f32_32x32x16_bf16 v[128:143], v[148:151], v[180:183], v[128:143]
	s_waitcnt vmcnt(5)
	v_mfma_f32_32x32x16_bf16 v[128:143], v[152:155], v[184:187], v[128:143]
	s_waitcnt vmcnt(4)
	v_mfma_f32_32x32x16_bf16 v[128:143], v[156:159], v[188:191], v[128:143]
	s_waitcnt vmcnt(3)
	v_mfma_f32_32x32x16_bf16 v[128:143], v[160:163], v[192:195], v[128:143]
	s_waitcnt vmcnt(2)
	v_mfma_f32_32x32x16_bf16 v[128:143], v[164:167], v[196:199], v[128:143]
	s_waitcnt vmcnt(1)
	v_mfma_f32_32x32x16_bf16 v[128:143], v[168:171], v[200:203], v[128:143]
	s_waitcnt vmcnt(0)
	v_mfma_f32_32x32x16_bf16 v[128:143], v[172:175], v[204:207], v[128:143]
	s_add_u32 s4, s0, 40960
	s_addc_u32 s5, s1, 0
	global_load_dwordx4 v[144:147], v238, s[4:5] offset:0
	global_load_dwordx4 v[148:151], v238, s[4:5] offset:32
	global_load_dwordx4 v[152:155], v238, s[4:5] offset:64
	global_load_dwordx4 v[156:159], v238, s[4:5] offset:96
	global_load_dwordx4 v[160:163], v238, s[4:5] offset:128
	global_load_dwordx4 v[164:167], v238, s[4:5] offset:160
	global_load_dwordx4 v[168:171], v238, s[4:5] offset:192
	global_load_dwordx4 v[172:175], v238, s[4:5] offset:224
	s_nop 7
	s_nop 3
	v_ashrrev_i32_e32 v230, 31, v128
	v_or_b32_e32 v230, 0x80000000, v230
	v_xor_b32_e32 v229, v230, v128
	v_and_b32_e32 v229, 0xffffff80, v229
	v_or_b32_e32 v104, v229, v213
	v_ashrrev_i32_e32 v230, 31, v129
	v_or_b32_e32 v230, 0x80000000, v230
	v_xor_b32_e32 v229, v230, v129
	v_and_b32_e32 v229, 0xffffff80, v229
	v_or_b32_e32 v103, v229, v214
	v_ashrrev_i32_e32 v230, 31, v130
	v_or_b32_e32 v230, 0x80000000, v230
	v_xor_b32_e32 v229, v230, v130
	v_and_b32_e32 v229, 0xffffff80, v229
	v_or_b32_e32 v106, v229, v215
	v_ashrrev_i32_e32 v230, 31, v131
	v_or_b32_e32 v230, 0x80000000, v230
	v_xor_b32_e32 v229, v230, v131
	v_and_b32_e32 v229, 0xffffff80, v229
	v_or_b32_e32 v107, v229, v216
	v_ashrrev_i32_e32 v230, 31, v132
	v_or_b32_e32 v230, 0x80000000, v230
	v_xor_b32_e32 v229, v230, v132
	v_and_b32_e32 v229, 0xffffff80, v229
	v_or_b32_e32 v110, v229, v217
	v_ashrrev_i32_e32 v230, 31, v133
	v_or_b32_e32 v230, 0x80000000, v230
	v_xor_b32_e32 v229, v230, v133
	v_and_b32_e32 v229, 0xffffff80, v229
	v_or_b32_e32 v109, v229, v218
	v_ashrrev_i32_e32 v230, 31, v134
	v_or_b32_e32 v230, 0x80000000, v230
	v_xor_b32_e32 v229, v230, v134
	v_and_b32_e32 v229, 0xffffff80, v229
	v_or_b32_e32 v108, v229, v219
	v_ashrrev_i32_e32 v230, 31, v135
	v_or_b32_e32 v230, 0x80000000, v230
	v_xor_b32_e32 v229, v230, v135
	v_and_b32_e32 v229, 0xffffff80, v229
	v_or_b32_e32 v97, v229, v220
	v_ashrrev_i32_e32 v230, 31, v136
	v_or_b32_e32 v230, 0x80000000, v230
	v_xor_b32_e32 v229, v230, v136
	v_and_b32_e32 v229, 0xffffff80, v229
	v_or_b32_e32 v112, v229, v221
	v_ashrrev_i32_e32 v230, 31, v137
	v_or_b32_e32 v230, 0x80000000, v230
	v_xor_b32_e32 v229, v230, v137
	v_and_b32_e32 v229, 0xffffff80, v229
	v_or_b32_e32 v100, v229, v222
	v_ashrrev_i32_e32 v230, 31, v138
	v_or_b32_e32 v230, 0x80000000, v230
	v_xor_b32_e32 v229, v230, v138
	v_and_b32_e32 v229, 0xffffff80, v229
	v_or_b32_e32 v101, v229, v223
	v_ashrrev_i32_e32 v230, 31, v139
	v_or_b32_e32 v230, 0x80000000, v230
	v_xor_b32_e32 v229, v230, v139
	v_and_b32_e32 v229, 0xffffff80, v229
	v_or_b32_e32 v90, v229, v224
	v_ashrrev_i32_e32 v230, 31, v140
	v_or_b32_e32 v230, 0x80000000, v230
	v_xor_b32_e32 v229, v230, v140
	v_and_b32_e32 v229, 0xffffff80, v229
	v_or_b32_e32 v114, v229, v225
	v_ashrrev_i32_e32 v230, 31, v141
	v_or_b32_e32 v230, 0x80000000, v230
	v_xor_b32_e32 v229, v230, v141
	v_and_b32_e32 v229, 0xffffff80, v229
	v_or_b32_e32 v105, v229, v226
	v_ashrrev_i32_e32 v230, 31, v142
	v_or_b32_e32 v230, 0x80000000, v230
	v_xor_b32_e32 v229, v230, v142
	v_and_b32_e32 v229, 0xffffff80, v229
	v_or_b32_e32 v86, v229, v227
	v_ashrrev_i32_e32 v230, 31, v143
	v_or_b32_e32 v230, 0x80000000, v230
	v_xor_b32_e32 v229, v230, v143
	v_and_b32_e32 v229, 0xffffff80, v229
	v_or_b32_e32 v117, v229, v228
	v_subrev_u32_e32 v213, 32, v213
	v_subrev_u32_e32 v214, 32, v214
	v_subrev_u32_e32 v215, 32, v215
	v_subrev_u32_e32 v216, 32, v216
	v_subrev_u32_e32 v217, 32, v217
	v_subrev_u32_e32 v218, 32, v218
	v_subrev_u32_e32 v219, 32, v219
	v_subrev_u32_e32 v220, 32, v220
	v_subrev_u32_e32 v221, 32, v221
	v_subrev_u32_e32 v222, 32, v222
	v_subrev_u32_e32 v223, 32, v223
	v_subrev_u32_e32 v224, 32, v224
	v_subrev_u32_e32 v225, 32, v225
	v_subrev_u32_e32 v226, 32, v226
	v_subrev_u32_e32 v227, 32, v227
	v_subrev_u32_e32 v228, 32, v228
	v_max_u32_e32 v115, v104, v103
	v_min_u32_e32 v103, v104, v103
	v_min_u32_e32 v104, v106, v107
	v_max_u32_e32 v107, v106, v107
	v_max_u32_e32 v106, v110, v109
	v_min_u32_e32 v109, v110, v109
	v_min_u32_e32 v110, v108, v97
	v_max_u32_e32 v97, v108, v97
	v_max_u32_e32 v108, v112, v100
	v_min_u32_e32 v100, v112, v100
	v_min_u32_e32 v112, v101, v90
	v_max_u32_e32 v90, v101, v90
	v_max_u32_e32 v101, v114, v105
	v_min_u32_e32 v105, v114, v105
	v_min_u32_e32 v114, v86, v117
	v_max_u32_e32 v117, v86, v117
	v_max_u32_e32 v86, v115, v104
	v_min_u32_e32 v104, v115, v104
	v_max_u32_e32 v115, v103, v107
	v_min_u32_e32 v107, v103, v107
	v_min_u32_e32 v103, v106, v110
	v_max_u32_e32 v110, v106, v110
	v_min_u32_e32 v106, v109, v97
	v_max_u32_e32 v97, v109, v97
	v_max_u32_e32 v109, v108, v112
	v_min_u32_e32 v112, v108, v112
	v_max_u32_e32 v108, v100, v90
	v_min_u32_e32 v90, v100, v90
	v_min_u32_e32 v100, v101, v114
	v_max_u32_e32 v114, v101, v114
	v_min_u32_e32 v101, v105, v117
	v_max_u32_e32 v117, v105, v117
	v_max_u32_e32 v105, v86, v115
	v_min_u32_e32 v115, v86, v115
	v_max_u32_e32 v86, v104, v107
	v_min_u32_e32 v107, v104, v107
; #define MFMA32(a, b, c) __builtin_amdgcn_mfma_f32_32x32x16_bf16((a), (b), (c), 0, 0, 0)
; template <int LOGN>
; DI void bitonic_sort_desc(unsigned (&a)[1 << LOGN]) {
;   constexpr int N = 1 << LOGN;
; #pragma unroll
;   for (int ks = 1; ks <= LOGN; ++ks)
; #pragma unroll
;     ...
; #pragma unroll
;       for (int i = 0; i < N; ++i) {
;         const int k = 1 << ks, j = 1 << js, l = i ^ j;
;         if (l > i) {
;           const bool desc = ((i & k) == 0) || (ks == LOGN);
;           const unsigned x = a[i], y = a[l];
;           const unsigned hi = max(x, y), lo = min(x, y);
;           a[i] = desc ? hi : lo;
;           a[l] = desc ? lo : hi;
;         }
;       }
; DI void peer_top16(const u16* __restrict__ PQrow, const u16* __restrict__ SK, unsigned (&top)[16], int lr, int hh) {
;     ...
;     for (int ks = 0; ks < 8; ++ks) {
;       bf16x8 a = *(const bf16x8*)(SK + (size_t)(kt * 32 + lr) * 128 + ks * 16 + hh * 8);
;       acc = MFMA32(a, qf[ks], acc);
	v_min_u32_e32 v104, v103, v106
	v_max_u32_e32 v106, v103, v106
	v_min_u32_e32 v103, v110, v97
	v_max_u32_e32 v97, v110, v97
	v_max_u32_e32 v110, v109, v108
	v_min_u32_e32 v108, v109, v108
	v_max_u32_e32 v109, v112, v90
	v_min_u32_e32 v90, v112, v90
	v_min_u32_e32 v112, v100, v101
	v_max_u32_e32 v101, v100, v101
	v_min_u32_e32 v100, v114, v117
	v_max_u32_e32 v117, v114, v117
	v_max_u32_e32 v114, v105, v104
	v_min_u32_e32 v104, v105, v104
	v_max_u32_e32 v105, v115, v106
	v_min_u32_e32 v106, v115, v106
	v_max_u32_e32 v115, v86, v103
	v_min_u32_e32 v103, v86, v103
	v_max_u32_e32 v86, v107, v97
	v_min_u32_e32 v97, v107, v97
	v_min_u32_e32 v107, v110, v112
	v_max_u32_e32 v112, v110, v112
	v_min_u32_e32 v110, v108, v101
	v_max_u32_e32 v101, v108, v101
	v_min_u32_e32 v108, v109, v100
	v_max_u32_e32 v100, v109, v100
	v_min_u32_e32 v109, v90, v117
	v_max_u32_e32 v117, v90, v117
	v_max_u32_e32 v90, v114, v115
	v_min_u32_e32 v115, v114, v115
	v_max_u32_e32 v114, v105, v86
	v_min_u32_e32 v86, v105, v86
	v_max_u32_e32 v105, v104, v103
	v_min_u32_e32 v103, v104, v103
	v_max_u32_e32 v104, v106, v97
	v_min_u32_e32 v97, v106, v97
	v_min_u32_e32 v106, v107, v108
	v_max_u32_e32 v108, v107, v108
	v_min_u32_e32 v107, v110, v109
	v_max_u32_e32 v109, v110, v109
	v_min_u32_e32 v110, v112, v100
	v_max_u32_e32 v100, v112, v100
	v_min_u32_e32 v112, v101, v117
	v_max_u32_e32 v117, v101, v117
	v_max_u32_e32 v101, v90, v114
	v_min_u32_e32 v114, v90, v114
	v_max_u32_e32 v90, v115, v86
	v_min_u32_e32 v86, v115, v86
	v_max_u32_e32 v115, v105, v104
	v_min_u32_e32 v104, v105, v104
	v_max_u32_e32 v105, v103, v97
	v_min_u32_e32 v97, v103, v97
	v_min_u32_e32 v103, v106, v107
	v_max_u32_e32 v107, v106, v107
	v_min_u32_e32 v106, v108, v109
	v_max_u32_e32 v109, v108, v109
	v_min_u32_e32 v108, v110, v112
	v_max_u32_e32 v112, v110, v112
	v_min_u32_e32 v110, v100, v117
	v_max_u32_e32 v117, v100, v117
	v_max_u32_e32 v100, v101, v103
	v_min_u32_e32 v103, v101, v103
	v_max_u32_e32 v101, v114, v107
	v_min_u32_e32 v107, v114, v107
	v_max_u32_e32 v114, v90, v106
	v_min_u32_e32 v106, v90, v106
	v_max_u32_e32 v90, v86, v109
	v_min_u32_e32 v109, v86, v109
	v_max_u32_e32 v86, v115, v108
	v_min_u32_e32 v108, v115, v108
	v_max_u32_e32 v115, v104, v112
	v_min_u32_e32 v112, v104, v112
	v_max_u32_e32 v104, v105, v110
	v_min_u32_e32 v110, v105, v110
	v_max_u32_e32 v105, v97, v117
	v_min_u32_e32 v117, v97, v117
	v_max_u32_e32 v97, v100, v86
	v_min_u32_e32 v86, v100, v86
	v_max_u32_e32 v100, v101, v115
	v_min_u32_e32 v115, v101, v115
	v_max_u32_e32 v101, v114, v104
	v_min_u32_e32 v104, v114, v104
	v_max_u32_e32 v114, v90, v105
	v_min_u32_e32 v105, v90, v105
	v_max_u32_e32 v90, v103, v108
	v_min_u32_e32 v108, v103, v108
	v_max_u32_e32 v103, v107, v112
	v_min_u32_e32 v112, v107, v112
	v_max_u32_e32 v107, v106, v110
	v_min_u32_e32 v110, v106, v110
	v_max_u32_e32 v106, v109, v117
	v_min_u32_e32 v117, v109, v117
	v_max_u32_e32 v109, v97, v101
	v_min_u32_e32 v101, v97, v101
	v_max_u32_e32 v97, v100, v114
	v_min_u32_e32 v114, v100, v114
	v_max_u32_e32 v100, v86, v104
	v_min_u32_e32 v104, v86, v104
	v_max_u32_e32 v86, v115, v105
	v_min_u32_e32 v105, v115, v105
	v_max_u32_e32 v115, v90, v107
	v_min_u32_e32 v107, v90, v107
	v_max_u32_e32 v90, v103, v106
	v_min_u32_e32 v106, v103, v106
	v_max_u32_e32 v103, v108, v110
	v_min_u32_e32 v110, v108, v110
	v_max_u32_e32 v108, v112, v117
	v_min_u32_e32 v117, v112, v117
	v_max_u32_e32 v112, v109, v97
	v_min_u32_e32 v97, v109, v97
	v_max_u32_e32 v109, v101, v114
	v_min_u32_e32 v114, v101, v114
	v_max_u32_e32 v101, v100, v86
	v_min_u32_e32 v86, v100, v86
	v_max_u32_e32 v100, v104, v105
	v_min_u32_e32 v105, v104, v105
	v_max_u32_e32 v104, v115, v90
	v_min_u32_e32 v90, v115, v90
	v_max_u32_e32 v115, v107, v106
	v_min_u32_e32 v106, v107, v106
	v_max_u32_e32 v107, v103, v108
	v_min_u32_e32 v108, v103, v108
	v_max_u32_e32 v103, v110, v117
	v_min_u32_e32 v117, v110, v117
	s_waitcnt vmcnt(7)
	v_mfma_f32_32x32x16_bf16 v[128:143], v[144:147], v[176:179], 0
	s_waitcnt vmcnt(6)
	v_mfma_f32_32x32x16_bf16 v[128:143], v[148:151], v[180:183], v[128:143]
	s_waitcnt vmcnt(5)
	v_mfma_f32_32x32x16_bf16 v[128:143], v[152:155], v[184:187], v[128:143]
	s_waitcnt vmcnt(4)
	v_mfma_f32_32x32x16_bf16 v[128:143], v[156:159], v[188:191], v[128:143]
	s_waitcnt vmcnt(3)
	v_mfma_f32_32x32x16_bf16 v[128:143], v[160:163], v[192:195], v[128:143]
	s_waitcnt vmcnt(2)
	v_mfma_f32_32x32x16_bf16 v[128:143], v[164:167], v[196:199], v[128:143]
	s_waitcnt vmcnt(1)
	v_mfma_f32_32x32x16_bf16 v[128:143], v[168:171], v[200:203], v[128:143]
	s_waitcnt vmcnt(0)
; #define MFMA32(a, b, c) __builtin_amdgcn_mfma_f32_32x32x16_bf16((a), (b), (c), 0, 0, 0)
; DI int crow(int i, int hh) { return (i & 3) + 8 * (i >> 2) + 4 * hh; }
; template <int LOGN>
; DI void bitonic_sort_desc(unsigned (&a)[1 << LOGN]) {
;   constexpr int N = 1 << LOGN;
; #pragma unroll
;   for (int ks = 1; ks <= LOGN; ++ks)
; #pragma unroll
;     ...
; #pragma unroll
;       for (int i = 0; i < N; ++i) {
;         const int k = 1 << ks, j = 1 << js, l = i ^ j;
;         if (l > i) {
;           const bool desc = ((i & k) == 0) || (ks == LOGN);
;           const unsigned x = a[i], y = a[l];
;           const unsigned hi = max(x, y), lo = min(x, y);
;           a[i] = desc ? hi : lo;
;           a[l] = desc ? lo : hi;
;         }
;       }
; DI void peer_top16(const u16* __restrict__ PQrow, const u16* __restrict__ SK, unsigned (&top)[16], int lr, int hh) {
;     ...
;     for (int ks = 0; ks < 8; ++ks) {
;       bf16x8 a = *(const bf16x8*)(SK + (size_t)(kt * 32 + lr) * 128 + ks * 16 + hh * 8);
;       acc = MFMA32(a, qf[ks], acc);
;     }
; #pragma unroll
;     for (int e = 0; e < 16; ++e) {
;       int kidx = kt * 32 + crow(e, hh);
;       g[kt][e] = (f2ord(acc[e]) & ~127u) | (unsigned)(127 - kidx);
;     }
;     bitonic_sort_desc<4>(g[kt]);
	v_mfma_f32_32x32x16_bf16 v[128:143], v[172:175], v[204:207], v[128:143]
	s_add_u32 s4, s0, 49152
	s_addc_u32 s5, s1, 0
	global_load_dwordx4 v[144:147], v238, s[4:5] offset:0
	global_load_dwordx4 v[148:151], v238, s[4:5] offset:32
	global_load_dwordx4 v[152:155], v238, s[4:5] offset:64
	global_load_dwordx4 v[156:159], v238, s[4:5] offset:96
	global_load_dwordx4 v[160:163], v238, s[4:5] offset:128
	global_load_dwordx4 v[164:167], v238, s[4:5] offset:160
	global_load_dwordx4 v[168:171], v238, s[4:5] offset:192
	global_load_dwordx4 v[172:175], v238, s[4:5] offset:224
	s_nop 7
	s_nop 3
	v_ashrrev_i32_e32 v230, 31, v128
	v_or_b32_e32 v230, 0x80000000, v230
	v_xor_b32_e32 v229, v230, v128
	v_and_b32_e32 v229, 0xffffff80, v229
	v_or_b32_e32 v110, v229, v213
	v_ashrrev_i32_e32 v230, 31, v129
	v_or_b32_e32 v230, 0x80000000, v230
	v_xor_b32_e32 v229, v230, v129
	v_and_b32_e32 v229, 0xffffff80, v229
	v_or_b32_e32 v96, v229, v214
	v_ashrrev_i32_e32 v230, 31, v130
	v_or_b32_e32 v230, 0x80000000, v230
	v_xor_b32_e32 v229, v230, v130
	v_and_b32_e32 v229, 0xffffff80, v229
	v_or_b32_e32 v95, v229, v215
	v_ashrrev_i32_e32 v230, 31, v131
	v_or_b32_e32 v230, 0x80000000, v230
	v_xor_b32_e32 v229, v230, v131
	v_and_b32_e32 v229, 0xffffff80, v229
	v_or_b32_e32 v111, v229, v216
	v_ashrrev_i32_e32 v230, 31, v132
	v_or_b32_e32 v230, 0x80000000, v230
	v_xor_b32_e32 v229, v230, v132
	v_and_b32_e32 v229, 0xffffff80, v229
	v_or_b32_e32 v91, v229, v217
	v_ashrrev_i32_e32 v230, 31, v133
	v_or_b32_e32 v230, 0x80000000, v230
	v_xor_b32_e32 v229, v230, v133
	v_and_b32_e32 v229, 0xffffff80, v229
	v_or_b32_e32 v89, v229, v218
	v_ashrrev_i32_e32 v230, 31, v134
	v_or_b32_e32 v230, 0x80000000, v230
	v_xor_b32_e32 v229, v230, v134
	v_and_b32_e32 v229, 0xffffff80, v229
	v_or_b32_e32 v113, v229, v219
	v_ashrrev_i32_e32 v230, 31, v135
	v_or_b32_e32 v230, 0x80000000, v230
	v_xor_b32_e32 v229, v230, v135
	v_and_b32_e32 v229, 0xffffff80, v229
	v_or_b32_e32 v87, v229, v220
	v_ashrrev_i32_e32 v230, 31, v136
	v_or_b32_e32 v230, 0x80000000, v230
	v_xor_b32_e32 v229, v230, v136
	v_and_b32_e32 v229, 0xffffff80, v229
	v_or_b32_e32 v94, v229, v221
	v_ashrrev_i32_e32 v230, 31, v137
	v_or_b32_e32 v230, 0x80000000, v230
	v_xor_b32_e32 v229, v230, v137
	v_and_b32_e32 v229, 0xffffff80, v229
	v_or_b32_e32 v70, v229, v222
	v_ashrrev_i32_e32 v230, 31, v138
	v_or_b32_e32 v230, 0x80000000, v230
	v_xor_b32_e32 v229, v230, v138
	v_and_b32_e32 v229, 0xffffff80, v229
	v_or_b32_e32 v85, v229, v223
	v_ashrrev_i32_e32 v230, 31, v139
	v_or_b32_e32 v230, 0x80000000, v230
	v_xor_b32_e32 v229, v230, v139
	v_and_b32_e32 v229, 0xffffff80, v229
	v_or_b32_e32 v81, v229, v224
	v_ashrrev_i32_e32 v230, 31, v140
	v_or_b32_e32 v230, 0x80000000, v230
	v_xor_b32_e32 v229, v230, v140
	v_and_b32_e32 v229, 0xffffff80, v229
	v_or_b32_e32 v88, v229, v225
	v_ashrrev_i32_e32 v230, 31, v141
	v_or_b32_e32 v230, 0x80000000, v230
	v_xor_b32_e32 v229, v230, v141
	v_and_b32_e32 v229, 0xffffff80, v229
	v_or_b32_e32 v102, v229, v226
	v_ashrrev_i32_e32 v230, 31, v142
	v_or_b32_e32 v230, 0x80000000, v230
	v_xor_b32_e32 v229, v230, v142
	v_and_b32_e32 v229, 0xffffff80, v229
	v_or_b32_e32 v92, v229, v227
	v_ashrrev_i32_e32 v230, 31, v143
	v_or_b32_e32 v230, 0x80000000, v230
	v_xor_b32_e32 v229, v230, v143
	v_and_b32_e32 v229, 0xffffff80, v229
	v_or_b32_e32 v98, v229, v228
	v_subrev_u32_e32 v213, 32, v213
	v_subrev_u32_e32 v214, 32, v214
	v_subrev_u32_e32 v215, 32, v215
	v_subrev_u32_e32 v216, 32, v216
	v_subrev_u32_e32 v217, 32, v217
	v_subrev_u32_e32 v218, 32, v218
	v_subrev_u32_e32 v219, 32, v219
	v_subrev_u32_e32 v220, 32, v220
	v_subrev_u32_e32 v221, 32, v221
	v_subrev_u32_e32 v222, 32, v222
	v_subrev_u32_e32 v223, 32, v223
	v_subrev_u32_e32 v224, 32, v224
	v_subrev_u32_e32 v225, 32, v225
	v_subrev_u32_e32 v226, 32, v226
	v_subrev_u32_e32 v227, 32, v227
	v_subrev_u32_e32 v228, 32, v228
	v_max_u32_e32 v116, v110, v96
	v_min_u32_e32 v96, v110, v96
	v_min_u32_e32 v110, v95, v111
	v_max_u32_e32 v111, v95, v111
	v_max_u32_e32 v95, v91, v89
	v_min_u32_e32 v89, v91, v89
	v_min_u32_e32 v91, v113, v87
	v_max_u32_e32 v87, v113, v87
	v_max_u32_e32 v113, v94, v70
	v_min_u32_e32 v70, v94, v70
	v_min_u32_e32 v94, v85, v81
	v_max_u32_e32 v81, v85, v81
	v_max_u32_e32 v85, v88, v102
	v_min_u32_e32 v102, v88, v102
	v_min_u32_e32 v88, v92, v98
	v_max_u32_e32 v98, v92, v98
	v_max_u32_e32 v92, v116, v110
	v_min_u32_e32 v110, v116, v110
	v_max_u32_e32 v116, v96, v111
	v_min_u32_e32 v111, v96, v111
	v_min_u32_e32 v96, v95, v91
	v_max_u32_e32 v91, v95, v91
	v_min_u32_e32 v95, v89, v87
	v_max_u32_e32 v87, v89, v87
	v_max_u32_e32 v89, v113, v94
	v_min_u32_e32 v94, v113, v94
	v_max_u32_e32 v113, v70, v81
	v_min_u32_e32 v81, v70, v81
	v_min_u32_e32 v70, v85, v88
	v_max_u32_e32 v88, v85, v88
	v_min_u32_e32 v85, v102, v98
	v_max_u32_e32 v98, v102, v98
	v_max_u32_e32 v102, v92, v116
	v_min_u32_e32 v116, v92, v116
	v_max_u32_e32 v92, v110, v111
	v_min_u32_e32 v111, v110, v111
	v_min_u32_e32 v110, v96, v95
	v_max_u32_e32 v95, v96, v95
	v_min_u32_e32 v96, v91, v87
	v_max_u32_e32 v87, v91, v87
	v_max_u32_e32 v91, v89, v113
	v_min_u32_e32 v113, v89, v113
	v_max_u32_e32 v89, v94, v81
	v_min_u32_e32 v81, v94, v81
	v_min_u32_e32 v94, v70, v85
	v_max_u32_e32 v85, v70, v85
	v_min_u32_e32 v70, v88, v98
	v_max_u32_e32 v98, v88, v98
	v_max_u32_e32 v88, v102, v110
	v_min_u32_e32 v110, v102, v110
	v_max_u32_e32 v102, v116, v95
	v_min_u32_e32 v95, v116, v95
	v_max_u32_e32 v116, v92, v96
	v_min_u32_e32 v96, v92, v96
	v_max_u32_e32 v92, v111, v87
	v_min_u32_e32 v87, v111, v87
	v_min_u32_e32 v111, v91, v94
	v_max_u32_e32 v94, v91, v94
	v_min_u32_e32 v91, v113, v85
	v_max_u32_e32 v85, v113, v85
; template <int LOGN>
; DI void bitonic_sort_desc(unsigned (&a)[1 << LOGN]) {
;   constexpr int N = 1 << LOGN;
; #pragma unroll
;   for (int ks = 1; ks <= LOGN; ++ks)
; #pragma unroll
;     ...
; #pragma unroll
;       for (int i = 0; i < N; ++i) {
;         const int k = 1 << ks, j = 1 << js, l = i ^ j;
;         if (l > i) {
;           const bool desc = ((i & k) == 0) || (ks == LOGN);
;           const unsigned x = a[i], y = a[l];
;           const unsigned hi = max(x, y), lo = min(x, y);
;           a[i] = desc ? hi : lo;
;           a[l] = desc ? lo : hi;
;         }
;       }
; }
; DI void merge_top16(unsigned (&a)[16], const unsigned (&b)[16]) {
; #pragma unroll
;   for (int i = 0; i < 16; ++i) a[i] = max(a[i], b[15 - i]);
; #pragma unroll
;     ...
; #pragma unroll
;     for (int i = 0; i < 16; ++i) {
;       const int j = 1 << js, l = i ^ j;
;       if (l > i) {
;         const unsigned x = a[i], y = a[l];
;         a[i] = max(x, y);
;         a[l] = min(x, y);
;       }
;     }
; }
	v_min_u32_e32 v113, v89, v70
	v_max_u32_e32 v70, v89, v70
	v_min_u32_e32 v89, v81, v98
	v_max_u32_e32 v98, v81, v98
	v_max_u32_e32 v81, v88, v116
	v_min_u32_e32 v116, v88, v116
	v_max_u32_e32 v88, v102, v92
	v_min_u32_e32 v92, v102, v92
	v_max_u32_e32 v102, v110, v96
	v_min_u32_e32 v96, v110, v96
	v_max_u32_e32 v110, v95, v87
	v_min_u32_e32 v87, v95, v87
	v_min_u32_e32 v95, v111, v113
	v_max_u32_e32 v113, v111, v113
	v_min_u32_e32 v111, v91, v89
	v_max_u32_e32 v89, v91, v89
	v_min_u32_e32 v91, v94, v70
	v_max_u32_e32 v70, v94, v70
	v_min_u32_e32 v94, v85, v98
	v_max_u32_e32 v98, v85, v98
	v_max_u32_e32 v85, v81, v88
	v_min_u32_e32 v88, v81, v88
	v_max_u32_e32 v81, v116, v92
	v_min_u32_e32 v92, v116, v92
	v_max_u32_e32 v116, v102, v110
	v_min_u32_e32 v110, v102, v110
	v_max_u32_e32 v102, v96, v87
	v_min_u32_e32 v87, v96, v87
	v_min_u32_e32 v96, v95, v111
	v_max_u32_e32 v111, v95, v111
	v_min_u32_e32 v95, v113, v89
	v_max_u32_e32 v89, v113, v89
	v_min_u32_e32 v113, v91, v94
	v_max_u32_e32 v94, v91, v94
	v_min_u32_e32 v91, v70, v98
	v_max_u32_e32 v98, v70, v98
	v_max_u32_e32 v70, v85, v96
	v_min_u32_e32 v96, v85, v96
	v_max_u32_e32 v85, v88, v111
	v_min_u32_e32 v111, v88, v111
	v_max_u32_e32 v88, v81, v95
	v_min_u32_e32 v95, v81, v95
	v_max_u32_e32 v81, v92, v89
	v_min_u32_e32 v89, v92, v89
	v_max_u32_e32 v92, v116, v113
	v_min_u32_e32 v113, v116, v113
	v_max_u32_e32 v116, v110, v94
	v_min_u32_e32 v94, v110, v94
	v_max_u32_e32 v110, v102, v91
	v_min_u32_e32 v91, v102, v91
	v_max_u32_e32 v102, v87, v98
	v_min_u32_e32 v98, v87, v98
	v_max_u32_e32 v87, v70, v92
	v_min_u32_e32 v92, v70, v92
	v_max_u32_e32 v70, v85, v116
	v_min_u32_e32 v116, v85, v116
	v_max_u32_e32 v85, v88, v110
	v_min_u32_e32 v110, v88, v110
	v_max_u32_e32 v88, v81, v102
	v_min_u32_e32 v102, v81, v102
	v_max_u32_e32 v81, v96, v113
	v_min_u32_e32 v113, v96, v113
	v_max_u32_e32 v96, v111, v94
	v_min_u32_e32 v94, v111, v94
	v_max_u32_e32 v111, v95, v91
	v_min_u32_e32 v91, v95, v91
	v_max_u32_e32 v95, v89, v98
	v_min_u32_e32 v98, v89, v98
	v_max_u32_e32 v89, v87, v85
	v_min_u32_e32 v85, v87, v85
	v_max_u32_e32 v87, v70, v88
	v_min_u32_e32 v88, v70, v88
	v_max_u32_e32 v70, v92, v110
	v_min_u32_e32 v110, v92, v110
	v_max_u32_e32 v92, v116, v102
	v_min_u32_e32 v102, v116, v102
	v_max_u32_e32 v116, v81, v111
	v_min_u32_e32 v111, v81, v111
	v_max_u32_e32 v81, v96, v95
	v_min_u32_e32 v95, v96, v95
	v_max_u32_e32 v96, v113, v91
	v_min_u32_e32 v91, v113, v91
	v_max_u32_e32 v113, v94, v98
	v_min_u32_e32 v98, v94, v98
	v_max_u32_e32 v94, v89, v87
	v_min_u32_e32 v87, v89, v87
	v_max_u32_e32 v89, v85, v88
	v_min_u32_e32 v88, v85, v88
	v_max_u32_e32 v85, v70, v92
	v_min_u32_e32 v92, v70, v92
	v_max_u32_e32 v70, v110, v102
	v_min_u32_e32 v102, v110, v102
	v_max_u32_e32 v110, v116, v81
	v_min_u32_e32 v81, v116, v81
	v_max_u32_e32 v116, v111, v95
	v_min_u32_e32 v95, v111, v95
	v_max_u32_e32 v111, v96, v113
	v_min_u32_e32 v113, v96, v113
	v_max_u32_e32 v96, v91, v98
	v_min_u32_e32 v98, v91, v98
	v_max_u32_e32 v91, v112, v98
	v_max_u32_e32 v112, v97, v96
	v_max_u32_e32 v97, v109, v113
	v_max_u32_e32 v109, v114, v111
	v_max_u32_e32 v114, v101, v95
	v_max_u32_e32 v101, v86, v116
	v_max_u32_e32 v86, v100, v81
	v_max_u32_e32 v100, v105, v110
	v_max_u32_e32 v105, v104, v102
	v_max_u32_e32 v104, v90, v70
	v_max_u32_e32 v90, v115, v92
	v_max_u32_e32 v115, v106, v85
	v_max_u32_e32 v106, v107, v88
	v_max_u32_e32 v107, v108, v89
	v_max_u32_e32 v108, v103, v87
	v_max_u32_e32 v103, v117, v94
	v_max_u32_e32 v98, v91, v105
	v_min_u32_e32 v105, v91, v105
	v_max_u32_e32 v91, v112, v104
	v_min_u32_e32 v104, v112, v104
	v_max_u32_e32 v112, v97, v90
	v_min_u32_e32 v90, v97, v90
	v_max_u32_e32 v97, v109, v115
	v_min_u32_e32 v115, v109, v115
	v_max_u32_e32 v109, v114, v106
	v_min_u32_e32 v106, v114, v106
	v_max_u32_e32 v114, v101, v107
	v_min_u32_e32 v107, v101, v107
	v_max_u32_e32 v101, v86, v108
	v_min_u32_e32 v108, v86, v108
	v_max_u32_e32 v86, v100, v103
	v_min_u32_e32 v103, v100, v103
	v_max_u32_e32 v100, v98, v109
	v_min_u32_e32 v109, v98, v109
	v_max_u32_e32 v98, v91, v114
	v_min_u32_e32 v114, v91, v114
	v_max_u32_e32 v91, v112, v101
	v_min_u32_e32 v101, v112, v101
	v_max_u32_e32 v112, v97, v86
	v_min_u32_e32 v86, v97, v86
	v_max_u32_e32 v97, v105, v106
	v_min_u32_e32 v106, v105, v106
	v_max_u32_e32 v105, v104, v107
	v_min_u32_e32 v107, v104, v107
	v_max_u32_e32 v104, v90, v108
	v_min_u32_e32 v108, v90, v108
	v_max_u32_e32 v90, v115, v103
	v_min_u32_e32 v103, v115, v103
	v_max_u32_e32 v115, v100, v91
	v_min_u32_e32 v91, v100, v91
	v_max_u32_e32 v100, v98, v112
	v_min_u32_e32 v112, v98, v112
	v_max_u32_e32 v98, v109, v101
	v_min_u32_e32 v101, v109, v101
	v_max_u32_e32 v109, v114, v86
	v_min_u32_e32 v86, v114, v86
	v_max_u32_e32 v114, v97, v104
	v_min_u32_e32 v104, v97, v104
	v_max_u32_e32 v97, v105, v90
	v_min_u32_e32 v90, v105, v90
	v_max_u32_e32 v105, v106, v108
	v_min_u32_e32 v108, v106, v108
	v_max_u32_e32 v106, v107, v103
	v_min_u32_e32 v103, v107, v103
	v_max_u32_e32 v107, v115, v100
	v_min_u32_e32 v100, v115, v100
	v_max_u32_e32 v115, v91, v112
	v_min_u32_e32 v112, v91, v112
	v_max_u32_e32 v91, v98, v109
	v_min_u32_e32 v109, v98, v109
	v_max_u32_e32 v98, v101, v86
	v_min_u32_e32 v86, v101, v86
	v_max_u32_e32 v101, v114, v97
	v_min_u32_e32 v97, v114, v97
	v_max_u32_e32 v114, v104, v90
	v_min_u32_e32 v90, v104, v90
	v_max_u32_e32 v104, v105, v106
	v_min_u32_e32 v106, v105, v106
	v_max_u32_e32 v105, v108, v103
	v_min_u32_e32 v103, v108, v103
	s_waitcnt vmcnt(7)
	v_mfma_f32_32x32x16_bf16 v[128:143], v[144:147], v[176:179], 0
	s_waitcnt vmcnt(6)
	v_mfma_f32_32x32x16_bf16 v[128:143], v[148:151], v[180:183], v[128:143]
	s_waitcnt vmcnt(5)
; #define MFMA32(a, b, c) __builtin_amdgcn_mfma_f32_32x32x16_bf16((a), (b), (c), 0, 0, 0)
; DI int crow(int i, int hh) { return (i & 3) + 8 * (i >> 2) + 4 * hh; }
; template <int LOGN>
; DI void bitonic_sort_desc(unsigned (&a)[1 << LOGN]) {
;   constexpr int N = 1 << LOGN;
; #pragma unroll
;   for (int ks = 1; ks <= LOGN; ++ks)
; #pragma unroll
;     ...
; #pragma unroll
;       for (int i = 0; i < N; ++i) {
;         const int k = 1 << ks, j = 1 << js, l = i ^ j;
;         if (l > i) {
;           const bool desc = ((i & k) == 0) || (ks == LOGN);
;           const unsigned x = a[i], y = a[l];
;           const unsigned hi = max(x, y), lo = min(x, y);
;           a[i] = desc ? hi : lo;
;           a[l] = desc ? lo : hi;
;         }
;       }
; DI void peer_top16(const u16* __restrict__ PQrow, const u16* __restrict__ SK, unsigned (&top)[16], int lr, int hh) {
;     ...
;     for (int ks = 0; ks < 8; ++ks) {
;       bf16x8 a = *(const bf16x8*)(SK + (size_t)(kt * 32 + lr) * 128 + ks * 16 + hh * 8);
;       acc = MFMA32(a, qf[ks], acc);
;     }
; #pragma unroll
;     for (int e = 0; e < 16; ++e) {
;       int kidx = kt * 32 + crow(e, hh);
;       g[kt][e] = (f2ord(acc[e]) & ~127u) | (unsigned)(127 - kidx);
;     }
;     bitonic_sort_desc<4>(g[kt]);
	v_mfma_f32_32x32x16_bf16 v[128:143], v[152:155], v[184:187], v[128:143]
	s_waitcnt vmcnt(4)
	v_mfma_f32_32x32x16_bf16 v[128:143], v[156:159], v[188:191], v[128:143]
	s_waitcnt vmcnt(3)
	v_mfma_f32_32x32x16_bf16 v[128:143], v[160:163], v[192:195], v[128:143]
	s_waitcnt vmcnt(2)
	v_mfma_f32_32x32x16_bf16 v[128:143], v[164:167], v[196:199], v[128:143]
	s_waitcnt vmcnt(1)
	v_mfma_f32_32x32x16_bf16 v[128:143], v[168:171], v[200:203], v[128:143]
	s_waitcnt vmcnt(0)
	v_mfma_f32_32x32x16_bf16 v[128:143], v[172:175], v[204:207], v[128:143]
	s_add_u32 s4, s0, 57344
	s_addc_u32 s5, s1, 0
	global_load_dwordx4 v[144:147], v238, s[4:5] offset:0
	global_load_dwordx4 v[148:151], v238, s[4:5] offset:32
	global_load_dwordx4 v[152:155], v238, s[4:5] offset:64
	global_load_dwordx4 v[156:159], v238, s[4:5] offset:96
	global_load_dwordx4 v[160:163], v238, s[4:5] offset:128
	global_load_dwordx4 v[164:167], v238, s[4:5] offset:160
	global_load_dwordx4 v[168:171], v238, s[4:5] offset:192
	global_load_dwordx4 v[172:175], v238, s[4:5] offset:224
	s_nop 7
	s_nop 3
	v_ashrrev_i32_e32 v230, 31, v128
	v_or_b32_e32 v230, 0x80000000, v230
	v_xor_b32_e32 v229, v230, v128
	v_and_b32_e32 v229, 0xffffff80, v229
	v_or_b32_e32 v108, v229, v213
	v_ashrrev_i32_e32 v230, 31, v129
	v_or_b32_e32 v230, 0x80000000, v230
	v_xor_b32_e32 v229, v230, v129
	v_and_b32_e32 v229, 0xffffff80, v229
	v_or_b32_e32 v96, v229, v214
	v_ashrrev_i32_e32 v230, 31, v130
	v_or_b32_e32 v230, 0x80000000, v230
	v_xor_b32_e32 v229, v230, v130
	v_and_b32_e32 v229, 0xffffff80, v229
	v_or_b32_e32 v113, v229, v215
	v_ashrrev_i32_e32 v230, 31, v131
	v_or_b32_e32 v230, 0x80000000, v230
	v_xor_b32_e32 v229, v230, v131
	v_and_b32_e32 v229, 0xffffff80, v229
	v_or_b32_e32 v111, v229, v216
	v_ashrrev_i32_e32 v230, 31, v132
	v_or_b32_e32 v230, 0x80000000, v230
	v_xor_b32_e32 v229, v230, v132
	v_and_b32_e32 v229, 0xffffff80, v229
	v_or_b32_e32 v95, v229, v217
	v_ashrrev_i32_e32 v230, 31, v133
	v_or_b32_e32 v230, 0x80000000, v230
	v_xor_b32_e32 v229, v230, v133
	v_and_b32_e32 v229, 0xffffff80, v229
	v_or_b32_e32 v116, v229, v218
	v_ashrrev_i32_e32 v230, 31, v134
	v_or_b32_e32 v230, 0x80000000, v230
	v_xor_b32_e32 v229, v230, v134
	v_and_b32_e32 v229, 0xffffff80, v229
	v_or_b32_e32 v81, v229, v219
	v_ashrrev_i32_e32 v230, 31, v135
	v_or_b32_e32 v230, 0x80000000, v230
	v_xor_b32_e32 v229, v230, v135
	v_and_b32_e32 v229, 0xffffff80, v229
	v_or_b32_e32 v110, v229, v220
	v_ashrrev_i32_e32 v230, 31, v136
	v_or_b32_e32 v230, 0x80000000, v230
	v_xor_b32_e32 v229, v230, v136
	v_and_b32_e32 v229, 0xffffff80, v229
	v_or_b32_e32 v102, v229, v221
	v_ashrrev_i32_e32 v230, 31, v137
	v_or_b32_e32 v230, 0x80000000, v230
	v_xor_b32_e32 v229, v230, v137
	v_and_b32_e32 v229, 0xffffff80, v229
	v_or_b32_e32 v70, v229, v222
	v_ashrrev_i32_e32 v230, 31, v138
	v_or_b32_e32 v230, 0x80000000, v230
	v_xor_b32_e32 v229, v230, v138
	v_and_b32_e32 v229, 0xffffff80, v229
	v_or_b32_e32 v92, v229, v223
	v_ashrrev_i32_e32 v230, 31, v139
	v_or_b32_e32 v230, 0x80000000, v230
	v_xor_b32_e32 v229, v230, v139
	v_and_b32_e32 v229, 0xffffff80, v229
	v_or_b32_e32 v85, v229, v224
	v_ashrrev_i32_e32 v230, 31, v140
	v_or_b32_e32 v230, 0x80000000, v230
	v_xor_b32_e32 v229, v230, v140
	v_and_b32_e32 v229, 0xffffff80, v229
	v_or_b32_e32 v88, v229, v225
	v_ashrrev_i32_e32 v230, 31, v141
	v_or_b32_e32 v230, 0x80000000, v230
	v_xor_b32_e32 v229, v230, v141
	v_and_b32_e32 v229, 0xffffff80, v229
	v_or_b32_e32 v89, v229, v226
	v_ashrrev_i32_e32 v230, 31, v142
	v_or_b32_e32 v230, 0x80000000, v230
	v_xor_b32_e32 v229, v230, v142
	v_and_b32_e32 v229, 0xffffff80, v229
	v_or_b32_e32 v87, v229, v227
	v_ashrrev_i32_e32 v230, 31, v143
	v_or_b32_e32 v230, 0x80000000, v230
	v_xor_b32_e32 v229, v230, v143
	v_and_b32_e32 v229, 0xffffff80, v229
	v_or_b32_e32 v94, v229, v228
	v_subrev_u32_e32 v213, 32, v213
	v_subrev_u32_e32 v214, 32, v214
	v_subrev_u32_e32 v215, 32, v215
	v_subrev_u32_e32 v216, 32, v216
	v_subrev_u32_e32 v217, 32, v217
	v_subrev_u32_e32 v218, 32, v218
	v_subrev_u32_e32 v219, 32, v219
	v_subrev_u32_e32 v220, 32, v220
	v_subrev_u32_e32 v221, 32, v221
	v_subrev_u32_e32 v222, 32, v222
	v_subrev_u32_e32 v223, 32, v223
	v_subrev_u32_e32 v224, 32, v224
	v_subrev_u32_e32 v225, 32, v225
	v_subrev_u32_e32 v226, 32, v226
	v_subrev_u32_e32 v227, 32, v227
	v_subrev_u32_e32 v228, 32, v228
	v_max_u32_e32 v117, v108, v96
	v_min_u32_e32 v96, v108, v96
	v_min_u32_e32 v108, v113, v111
	v_max_u32_e32 v111, v113, v111
	v_max_u32_e32 v113, v95, v116
	v_min_u32_e32 v116, v95, v116
	v_min_u32_e32 v95, v81, v110
	v_max_u32_e32 v110, v81, v110
	v_max_u32_e32 v81, v102, v70
	v_min_u32_e32 v70, v102, v70
	v_min_u32_e32 v102, v92, v85
	v_max_u32_e32 v85, v92, v85
	v_max_u32_e32 v92, v88, v89
	v_min_u32_e32 v89, v88, v89
	v_min_u32_e32 v88, v87, v94
	v_max_u32_e32 v94, v87, v94
	v_max_u32_e32 v87, v117, v108
	v_min_u32_e32 v108, v117, v108
	v_max_u32_e32 v117, v96, v111
	v_min_u32_e32 v111, v96, v111
	v_min_u32_e32 v96, v113, v95
	v_max_u32_e32 v95, v113, v95
	v_min_u32_e32 v113, v116, v110
	v_max_u32_e32 v110, v116, v110
	v_max_u32_e32 v116, v81, v102
	v_min_u32_e32 v102, v81, v102
	v_max_u32_e32 v81, v70, v85
	v_min_u32_e32 v85, v70, v85
	v_min_u32_e32 v70, v92, v88
	v_max_u32_e32 v88, v92, v88
	v_min_u32_e32 v92, v89, v94
	v_max_u32_e32 v94, v89, v94
	v_max_u32_e32 v89, v87, v117
	v_min_u32_e32 v117, v87, v117
	v_max_u32_e32 v87, v108, v111
	v_min_u32_e32 v111, v108, v111
	v_min_u32_e32 v108, v96, v113
	v_max_u32_e32 v113, v96, v113
	v_min_u32_e32 v96, v95, v110
	v_max_u32_e32 v110, v95, v110
	v_max_u32_e32 v95, v116, v81
	v_min_u32_e32 v81, v116, v81
	v_max_u32_e32 v116, v102, v85
; #define MFMA32(a, b, c) __builtin_amdgcn_mfma_f32_32x32x16_bf16((a), (b), (c), 0, 0, 0)
; DI int crow(int i, int hh) { return (i & 3) + 8 * (i >> 2) + 4 * hh; }
; template <int LOGN>
; DI void bitonic_sort_desc(unsigned (&a)[1 << LOGN]) {
;   constexpr int N = 1 << LOGN;
; #pragma unroll
;   for (int ks = 1; ks <= LOGN; ++ks)
; #pragma unroll
;     ...
; #pragma unroll
;       for (int i = 0; i < N; ++i) {
;         const int k = 1 << ks, j = 1 << js, l = i ^ j;
;         if (l > i) {
;           const bool desc = ((i & k) == 0) || (ks == LOGN);
;           const unsigned x = a[i], y = a[l];
;           const unsigned hi = max(x, y), lo = min(x, y);
;           a[i] = desc ? hi : lo;
;           a[l] = desc ? lo : hi;
;         }
;       }
; DI void peer_top16(const u16* __restrict__ PQrow, const u16* __restrict__ SK, unsigned (&top)[16], int lr, int hh) {
;   bf16x8 qf[8];
; #pragma unroll
;   for (int ks = 0; ks < 8; ++ks) qf[ks] = *(const bf16x8*)(PQrow + ks * 16 + hh * 8);
;   unsigned g[4][16];
; #pragma unroll
;   for (int kt = 0; kt < 4; ++kt) {
;     f32x16 acc;
; #pragma unroll
;     for (int e = 0; e < 16; ++e) acc[e] = 0.f;
; #pragma unroll
;     for (int ks = 0; ks < 8; ++ks) {
;       bf16x8 a = *(const bf16x8*)(SK + (size_t)(kt * 32 + lr) * 128 + ks * 16 + hh * 8);
;       acc = MFMA32(a, qf[ks], acc);
;     }
; #pragma unroll
;     for (int e = 0; e < 16; ++e) {
;       int kidx = kt * 32 + crow(e, hh);
;       g[kt][e] = (f2ord(acc[e]) & ~127u) | (unsigned)(127 - kidx);
	v_min_u32_e32 v85, v102, v85
	v_min_u32_e32 v102, v70, v92
	v_max_u32_e32 v92, v70, v92
	v_min_u32_e32 v70, v88, v94
	v_max_u32_e32 v94, v88, v94
	v_max_u32_e32 v88, v89, v108
	v_min_u32_e32 v108, v89, v108
	v_max_u32_e32 v89, v117, v113
	v_min_u32_e32 v113, v117, v113
	v_max_u32_e32 v117, v87, v96
	v_min_u32_e32 v96, v87, v96
	v_max_u32_e32 v87, v111, v110
	v_min_u32_e32 v110, v111, v110
	v_min_u32_e32 v111, v95, v102
	v_max_u32_e32 v102, v95, v102
	v_min_u32_e32 v95, v81, v92
	v_max_u32_e32 v92, v81, v92
	v_min_u32_e32 v81, v116, v70
	v_max_u32_e32 v70, v116, v70
	v_min_u32_e32 v116, v85, v94
	v_max_u32_e32 v94, v85, v94
	v_max_u32_e32 v85, v88, v117
	v_min_u32_e32 v117, v88, v117
	v_max_u32_e32 v88, v89, v87
	v_min_u32_e32 v87, v89, v87
	v_max_u32_e32 v89, v108, v96
	v_min_u32_e32 v96, v108, v96
	v_max_u32_e32 v108, v113, v110
	v_min_u32_e32 v110, v113, v110
	v_min_u32_e32 v113, v111, v81
	v_max_u32_e32 v81, v111, v81
	v_min_u32_e32 v111, v95, v116
	v_max_u32_e32 v116, v95, v116
	v_min_u32_e32 v95, v102, v70
	v_max_u32_e32 v70, v102, v70
	v_min_u32_e32 v102, v92, v94
	v_max_u32_e32 v94, v92, v94
	v_max_u32_e32 v92, v85, v88
	v_min_u32_e32 v88, v85, v88
	v_max_u32_e32 v85, v117, v87
	v_min_u32_e32 v87, v117, v87
	v_max_u32_e32 v117, v89, v108
	v_min_u32_e32 v108, v89, v108
	v_max_u32_e32 v89, v96, v110
	v_min_u32_e32 v110, v96, v110
	v_min_u32_e32 v96, v113, v111
	v_max_u32_e32 v111, v113, v111
	v_min_u32_e32 v113, v81, v116
	v_max_u32_e32 v116, v81, v116
	v_min_u32_e32 v81, v95, v102
	v_max_u32_e32 v102, v95, v102
	v_min_u32_e32 v95, v70, v94
	v_max_u32_e32 v94, v70, v94
	v_max_u32_e32 v70, v92, v96
	v_min_u32_e32 v96, v92, v96
	v_max_u32_e32 v92, v88, v111
	v_min_u32_e32 v111, v88, v111
	v_max_u32_e32 v88, v85, v113
	v_min_u32_e32 v113, v85, v113
	v_max_u32_e32 v85, v87, v116
	v_min_u32_e32 v116, v87, v116
	v_max_u32_e32 v87, v117, v81
	v_min_u32_e32 v81, v117, v81
	v_max_u32_e32 v117, v108, v102
	v_min_u32_e32 v102, v108, v102
	v_max_u32_e32 v108, v89, v95
	v_min_u32_e32 v95, v89, v95
	v_max_u32_e32 v89, v110, v94
	v_min_u32_e32 v94, v110, v94
	v_max_u32_e32 v110, v70, v87
	v_min_u32_e32 v87, v70, v87
	v_max_u32_e32 v70, v92, v117
	v_min_u32_e32 v117, v92, v117
	v_max_u32_e32 v92, v88, v108
	v_min_u32_e32 v108, v88, v108
	v_max_u32_e32 v88, v85, v89
	v_min_u32_e32 v89, v85, v89
	v_max_u32_e32 v85, v96, v81
	v_min_u32_e32 v81, v96, v81
	v_max_u32_e32 v96, v111, v102
	v_min_u32_e32 v102, v111, v102
	v_max_u32_e32 v111, v113, v95
	v_min_u32_e32 v95, v113, v95
	v_max_u32_e32 v113, v116, v94
	v_min_u32_e32 v94, v116, v94
	v_max_u32_e32 v116, v110, v92
	v_min_u32_e32 v92, v110, v92
	v_max_u32_e32 v110, v70, v88
	v_min_u32_e32 v88, v70, v88
	v_max_u32_e32 v70, v87, v108
	v_min_u32_e32 v108, v87, v108
	v_max_u32_e32 v87, v117, v89
	v_min_u32_e32 v89, v117, v89
	v_max_u32_e32 v117, v85, v111
	v_min_u32_e32 v111, v85, v111
	v_max_u32_e32 v85, v96, v113
	v_min_u32_e32 v113, v96, v113
	v_max_u32_e32 v96, v81, v95
	v_min_u32_e32 v95, v81, v95
	v_max_u32_e32 v81, v102, v94
	v_min_u32_e32 v94, v102, v94
	v_max_u32_e32 v102, v116, v110
	v_min_u32_e32 v110, v116, v110
	v_max_u32_e32 v116, v92, v88
	v_min_u32_e32 v88, v92, v88
	v_max_u32_e32 v92, v70, v87
	v_min_u32_e32 v87, v70, v87
	v_max_u32_e32 v70, v108, v89
	v_min_u32_e32 v89, v108, v89
	v_max_u32_e32 v108, v117, v85
	v_min_u32_e32 v85, v117, v85
	v_max_u32_e32 v117, v111, v113
	v_min_u32_e32 v113, v111, v113
	v_max_u32_e32 v111, v96, v81
	v_min_u32_e32 v81, v96, v81
	v_max_u32_e32 v96, v95, v94
	v_min_u32_e32 v94, v95, v94
	s_waitcnt vmcnt(7)
	v_mfma_f32_32x32x16_bf16 v[128:143], v[144:147], v[176:179], 0
	s_waitcnt vmcnt(6)
	v_mfma_f32_32x32x16_bf16 v[128:143], v[148:151], v[180:183], v[128:143]
	s_waitcnt vmcnt(5)
	v_mfma_f32_32x32x16_bf16 v[128:143], v[152:155], v[184:187], v[128:143]
	s_waitcnt vmcnt(4)
	v_mfma_f32_32x32x16_bf16 v[128:143], v[156:159], v[188:191], v[128:143]
	s_waitcnt vmcnt(3)
	v_mfma_f32_32x32x16_bf16 v[128:143], v[160:163], v[192:195], v[128:143]
	s_waitcnt vmcnt(2)
	v_mfma_f32_32x32x16_bf16 v[128:143], v[164:167], v[196:199], v[128:143]
	s_waitcnt vmcnt(1)
	v_mfma_f32_32x32x16_bf16 v[128:143], v[168:171], v[200:203], v[128:143]
	s_waitcnt vmcnt(0)
	v_mfma_f32_32x32x16_bf16 v[128:143], v[172:175], v[204:207], v[128:143]
	global_load_dwordx4 v[176:179], v239, s[2:3] offset:512
	global_load_dwordx4 v[180:183], v239, s[2:3] offset:544
	global_load_dwordx4 v[184:187], v239, s[2:3] offset:576
	global_load_dwordx4 v[188:191], v239, s[2:3] offset:608
	global_load_dwordx4 v[192:195], v239, s[2:3] offset:640
	global_load_dwordx4 v[196:199], v239, s[2:3] offset:672
	global_load_dwordx4 v[200:203], v239, s[2:3] offset:704
	global_load_dwordx4 v[204:207], v239, s[2:3] offset:736
	s_add_u32 s4, s0, 65536
	s_addc_u32 s5, s1, 0
	global_load_dwordx4 v[144:147], v238, s[4:5] offset:0
	global_load_dwordx4 v[148:151], v238, s[4:5] offset:32
	global_load_dwordx4 v[152:155], v238, s[4:5] offset:64
	global_load_dwordx4 v[156:159], v238, s[4:5] offset:96
	global_load_dwordx4 v[160:163], v238, s[4:5] offset:128
	global_load_dwordx4 v[164:167], v238, s[4:5] offset:160
	global_load_dwordx4 v[168:171], v238, s[4:5] offset:192
	global_load_dwordx4 v[172:175], v238, s[4:5] offset:224
	s_nop 7
	s_nop 3
	v_ashrrev_i32_e32 v230, 31, v128
	v_or_b32_e32 v230, 0x80000000, v230
	v_xor_b32_e32 v229, v230, v128
	v_and_b32_e32 v229, 0xffffff80, v229
	v_or_b32_e32 v95, v229, v213
	v_ashrrev_i32_e32 v230, 31, v129
	v_or_b32_e32 v230, 0x80000000, v230
	v_xor_b32_e32 v229, v230, v129
	v_and_b32_e32 v229, 0xffffff80, v229
	v_or_b32_e32 v84, v229, v214
	v_ashrrev_i32_e32 v230, 31, v130
	v_or_b32_e32 v230, 0x80000000, v230
; DI int crow(int i, int hh) { return (i & 3) + 8 * (i >> 2) + 4 * hh; }
; template <int LOGN>
; DI void bitonic_sort_desc(unsigned (&a)[1 << LOGN]) {
;   constexpr int N = 1 << LOGN;
; #pragma unroll
;   for (int ks = 1; ks <= LOGN; ++ks)
; #pragma unroll
;     ...
; #pragma unroll
;       for (int i = 0; i < N; ++i) {
;         const int k = 1 << ks, j = 1 << js, l = i ^ j;
;         if (l > i) {
;           const bool desc = ((i & k) == 0) || (ks == LOGN);
;           const unsigned x = a[i], y = a[l];
;           const unsigned hi = max(x, y), lo = min(x, y);
;           a[i] = desc ? hi : lo;
;           a[l] = desc ? lo : hi;
;         }
;       }
; DI void peer_top16(const u16* __restrict__ PQrow, const u16* __restrict__ SK, unsigned (&top)[16], int lr, int hh) {
;     ...
; #pragma unroll
;     for (int e = 0; e < 16; ++e) {
;       int kidx = kt * 32 + crow(e, hh);
;       g[kt][e] = (f2ord(acc[e]) & ~127u) | (unsigned)(127 - kidx);
;     }
;     bitonic_sort_desc<4>(g[kt]);
	v_xor_b32_e32 v229, v230, v130
	v_and_b32_e32 v229, 0xffffff80, v229
	v_or_b32_e32 v79, v229, v215
	v_ashrrev_i32_e32 v230, 31, v131
	v_or_b32_e32 v230, 0x80000000, v230
	v_xor_b32_e32 v229, v230, v131
	v_and_b32_e32 v229, 0xffffff80, v229
	v_or_b32_e32 v82, v229, v216
	v_ashrrev_i32_e32 v230, 31, v132
	v_or_b32_e32 v230, 0x80000000, v230
	v_xor_b32_e32 v229, v230, v132
	v_and_b32_e32 v229, 0xffffff80, v229
	v_or_b32_e32 v83, v229, v217
	v_ashrrev_i32_e32 v230, 31, v133
	v_or_b32_e32 v230, 0x80000000, v230
	v_xor_b32_e32 v229, v230, v133
	v_and_b32_e32 v229, 0xffffff80, v229
	v_or_b32_e32 v69, v229, v218
	v_ashrrev_i32_e32 v230, 31, v134
	v_or_b32_e32 v230, 0x80000000, v230
	v_xor_b32_e32 v229, v230, v134
	v_and_b32_e32 v229, 0xffffff80, v229
	v_or_b32_e32 v74, v229, v219
	v_ashrrev_i32_e32 v230, 31, v135
	v_or_b32_e32 v230, 0x80000000, v230
	v_xor_b32_e32 v229, v230, v135
	v_and_b32_e32 v229, 0xffffff80, v229
	v_or_b32_e32 v99, v229, v220
	v_ashrrev_i32_e32 v230, 31, v136
	v_or_b32_e32 v230, 0x80000000, v230
	v_xor_b32_e32 v229, v230, v136
	v_and_b32_e32 v229, 0xffffff80, v229
	v_or_b32_e32 v72, v229, v221
	v_ashrrev_i32_e32 v230, 31, v137
	v_or_b32_e32 v230, 0x80000000, v230
	v_xor_b32_e32 v229, v230, v137
	v_and_b32_e32 v229, 0xffffff80, v229
	v_or_b32_e32 v76, v229, v222
	v_ashrrev_i32_e32 v230, 31, v138
	v_or_b32_e32 v230, 0x80000000, v230
	v_xor_b32_e32 v229, v230, v138
	v_and_b32_e32 v229, 0xffffff80, v229
	v_or_b32_e32 v71, v229, v223
	v_ashrrev_i32_e32 v230, 31, v139
	v_or_b32_e32 v230, 0x80000000, v230
	v_xor_b32_e32 v229, v230, v139
	v_and_b32_e32 v229, 0xffffff80, v229
	v_or_b32_e32 v75, v229, v224
	v_ashrrev_i32_e32 v230, 31, v140
	v_or_b32_e32 v230, 0x80000000, v230
	v_xor_b32_e32 v229, v230, v140
	v_and_b32_e32 v229, 0xffffff80, v229
	v_or_b32_e32 v73, v229, v225
	v_ashrrev_i32_e32 v230, 31, v141
	v_or_b32_e32 v230, 0x80000000, v230
	v_xor_b32_e32 v229, v230, v141
	v_and_b32_e32 v229, 0xffffff80, v229
	v_or_b32_e32 v80, v229, v226
	v_ashrrev_i32_e32 v230, 31, v142
	v_or_b32_e32 v230, 0x80000000, v230
	v_xor_b32_e32 v229, v230, v142
	v_and_b32_e32 v229, 0xffffff80, v229
	v_or_b32_e32 v78, v229, v227
	v_ashrrev_i32_e32 v230, 31, v143
	v_or_b32_e32 v230, 0x80000000, v230
	v_xor_b32_e32 v229, v230, v143
	v_and_b32_e32 v229, 0xffffff80, v229
	v_or_b32_e32 v77, v229, v228
	v_max_u32_e32 v93, v95, v84
	v_min_u32_e32 v84, v95, v84
	v_min_u32_e32 v95, v79, v82
	v_max_u32_e32 v82, v79, v82
	v_max_u32_e32 v79, v83, v69
	v_min_u32_e32 v69, v83, v69
	v_min_u32_e32 v83, v74, v99
	v_max_u32_e32 v99, v74, v99
	v_max_u32_e32 v74, v72, v76
	v_min_u32_e32 v76, v72, v76
	v_min_u32_e32 v72, v71, v75
	v_max_u32_e32 v75, v71, v75
	v_max_u32_e32 v71, v73, v80
	v_min_u32_e32 v80, v73, v80
	v_min_u32_e32 v73, v78, v77
	v_max_u32_e32 v77, v78, v77
	v_max_u32_e32 v78, v93, v95
	v_min_u32_e32 v95, v93, v95
	v_max_u32_e32 v93, v84, v82
	v_min_u32_e32 v82, v84, v82
	v_min_u32_e32 v84, v79, v83
	v_max_u32_e32 v83, v79, v83
	v_min_u32_e32 v79, v69, v99
	v_max_u32_e32 v99, v69, v99
	v_max_u32_e32 v69, v74, v72
	v_min_u32_e32 v72, v74, v72
	v_max_u32_e32 v74, v76, v75
	v_min_u32_e32 v75, v76, v75
	v_min_u32_e32 v76, v71, v73
	v_max_u32_e32 v73, v71, v73
	v_min_u32_e32 v71, v80, v77
	v_max_u32_e32 v77, v80, v77
	v_max_u32_e32 v80, v78, v93
	v_min_u32_e32 v93, v78, v93
	v_max_u32_e32 v78, v95, v82
	v_min_u32_e32 v82, v95, v82
	v_min_u32_e32 v95, v84, v79
	v_max_u32_e32 v79, v84, v79
	v_min_u32_e32 v84, v83, v99
	v_max_u32_e32 v99, v83, v99
	v_max_u32_e32 v83, v69, v74
	v_min_u32_e32 v74, v69, v74
	v_max_u32_e32 v69, v72, v75
	v_min_u32_e32 v75, v72, v75
	v_min_u32_e32 v72, v76, v71
	v_max_u32_e32 v71, v76, v71
	v_min_u32_e32 v76, v73, v77
	v_max_u32_e32 v77, v73, v77
	v_max_u32_e32 v73, v80, v95
	v_min_u32_e32 v95, v80, v95
	v_max_u32_e32 v80, v93, v79
	v_min_u32_e32 v79, v93, v79
	v_max_u32_e32 v93, v78, v84
	v_min_u32_e32 v84, v78, v84
	v_max_u32_e32 v78, v82, v99
	v_min_u32_e32 v99, v82, v99
	v_min_u32_e32 v82, v83, v72
	v_max_u32_e32 v72, v83, v72
	v_min_u32_e32 v83, v74, v71
	v_max_u32_e32 v71, v74, v71
	v_min_u32_e32 v74, v69, v76
	v_max_u32_e32 v76, v69, v76
	v_min_u32_e32 v69, v75, v77
	v_max_u32_e32 v77, v75, v77
	v_max_u32_e32 v75, v73, v93
	v_min_u32_e32 v93, v73, v93
	v_max_u32_e32 v73, v80, v78
	v_min_u32_e32 v78, v80, v78
	v_max_u32_e32 v80, v95, v84
	v_min_u32_e32 v84, v95, v84
	v_max_u32_e32 v95, v79, v99
	v_min_u32_e32 v99, v79, v99
	v_min_u32_e32 v79, v82, v74
	v_max_u32_e32 v74, v82, v74
	v_min_u32_e32 v82, v83, v69
	v_max_u32_e32 v69, v83, v69
	v_min_u32_e32 v83, v72, v76
	v_max_u32_e32 v76, v72, v76
	v_min_u32_e32 v72, v71, v77
	v_max_u32_e32 v77, v71, v77
	v_max_u32_e32 v71, v75, v73
	v_min_u32_e32 v73, v75, v73
	v_max_u32_e32 v75, v93, v78
	v_min_u32_e32 v78, v93, v78
	v_max_u32_e32 v93, v80, v95
	v_min_u32_e32 v95, v80, v95
	v_max_u32_e32 v80, v84, v99
	v_min_u32_e32 v99, v84, v99
	v_min_u32_e32 v84, v79, v82
	v_max_u32_e32 v82, v79, v82
	v_min_u32_e32 v79, v74, v69
	v_max_u32_e32 v69, v74, v69
	v_min_u32_e32 v74, v83, v72
	v_max_u32_e32 v72, v83, v72
	v_min_u32_e32 v83, v76, v77
	v_max_u32_e32 v77, v76, v77
	v_max_u32_e32 v76, v71, v84
	v_min_u32_e32 v84, v71, v84
	v_max_u32_e32 v71, v73, v82
	v_min_u32_e32 v82, v73, v82
	v_max_u32_e32 v73, v75, v79
	v_min_u32_e32 v79, v75, v79
	v_max_u32_e32 v75, v78, v69
	v_min_u32_e32 v69, v78, v69
	v_max_u32_e32 v78, v93, v74
	v_min_u32_e32 v74, v93, v74
	v_max_u32_e32 v93, v95, v72
	v_min_u32_e32 v72, v95, v72
	v_max_u32_e32 v95, v80, v83
	v_min_u32_e32 v83, v80, v83
	v_max_u32_e32 v80, v99, v77
	v_min_u32_e32 v77, v99, v77
	v_max_u32_e32 v99, v76, v78
	v_min_u32_e32 v78, v76, v78
; DI void merge_top16(unsigned (&a)[16], const unsigned (&b)[16]) {
; #pragma unroll
;   for (int i = 0; i < 16; ++i) a[i] = max(a[i], b[15 - i]);
; #pragma unroll
;     ...
; #pragma unroll
;     for (int i = 0; i < 16; ++i) {
;       const int j = 1 << js, l = i ^ j;
;       if (l > i) {
;         const unsigned x = a[i], y = a[l];
;         a[i] = max(x, y);
;         a[l] = min(x, y);
;       }
;     }
; }
; DI void peer_top16(const u16* __restrict__ PQrow, const u16* __restrict__ SK, unsigned (&top)[16], int lr, int hh) {
;     ...
;   merge_top16(g[0], g[1]);
;   merge_top16(g[2], g[3]);
;   merge_top16(g[0], g[2]);
	v_max_u32_e32 v76, v71, v93
	v_min_u32_e32 v93, v71, v93
	v_max_u32_e32 v71, v73, v95
	v_min_u32_e32 v95, v73, v95
	v_max_u32_e32 v73, v75, v80
	v_min_u32_e32 v80, v75, v80
	v_max_u32_e32 v75, v84, v74
	v_min_u32_e32 v74, v84, v74
	v_max_u32_e32 v84, v82, v72
	v_min_u32_e32 v72, v82, v72
	v_max_u32_e32 v82, v79, v83
	v_min_u32_e32 v83, v79, v83
	v_max_u32_e32 v79, v69, v77
	v_min_u32_e32 v77, v69, v77
	v_max_u32_e32 v69, v99, v71
	v_min_u32_e32 v71, v99, v71
	v_max_u32_e32 v99, v76, v73
	v_min_u32_e32 v73, v76, v73
	v_max_u32_e32 v76, v78, v95
	v_min_u32_e32 v95, v78, v95
	v_max_u32_e32 v78, v93, v80
	v_min_u32_e32 v80, v93, v80
	v_max_u32_e32 v93, v75, v82
	v_min_u32_e32 v82, v75, v82
	v_max_u32_e32 v75, v84, v79
	v_min_u32_e32 v79, v84, v79
	v_max_u32_e32 v84, v74, v83
	v_min_u32_e32 v83, v74, v83
	v_max_u32_e32 v74, v72, v77
	v_min_u32_e32 v77, v72, v77
	v_max_u32_e32 v72, v69, v99
	v_min_u32_e32 v99, v69, v99
	v_max_u32_e32 v69, v71, v73
	v_min_u32_e32 v73, v71, v73
	v_max_u32_e32 v71, v76, v78
	v_min_u32_e32 v78, v76, v78
	v_max_u32_e32 v76, v95, v80
	v_min_u32_e32 v80, v95, v80
	v_max_u32_e32 v95, v93, v75
	v_min_u32_e32 v75, v93, v75
	v_max_u32_e32 v93, v82, v79
	v_min_u32_e32 v79, v82, v79
	v_max_u32_e32 v82, v84, v74
	v_min_u32_e32 v74, v84, v74
	v_max_u32_e32 v84, v83, v77
	v_min_u32_e32 v77, v83, v77
	v_max_u32_e32 v83, v102, v77
	v_max_u32_e32 v102, v110, v84
	v_max_u32_e32 v110, v116, v74
	v_max_u32_e32 v116, v88, v82
	v_max_u32_e32 v88, v92, v79
	v_max_u32_e32 v92, v87, v93
	v_max_u32_e32 v87, v70, v75
	v_max_u32_e32 v70, v89, v95
	v_max_u32_e32 v89, v108, v80
	v_max_u32_e32 v108, v85, v76
	v_max_u32_e32 v85, v117, v78
	v_max_u32_e32 v117, v113, v71
	v_max_u32_e32 v113, v111, v73
	v_max_u32_e32 v111, v81, v69
	v_max_u32_e32 v81, v96, v99
	v_max_u32_e32 v96, v94, v72
	v_max_u32_e32 v77, v83, v89
	v_min_u32_e32 v89, v83, v89
	v_max_u32_e32 v83, v102, v108
	v_min_u32_e32 v108, v102, v108
	v_max_u32_e32 v102, v110, v85
	v_min_u32_e32 v85, v110, v85
	v_max_u32_e32 v110, v116, v117
	v_min_u32_e32 v117, v116, v117
	v_max_u32_e32 v116, v88, v113
	v_min_u32_e32 v113, v88, v113
	v_max_u32_e32 v88, v92, v111
	v_min_u32_e32 v111, v92, v111
	v_max_u32_e32 v92, v87, v81
	v_min_u32_e32 v81, v87, v81
	v_max_u32_e32 v87, v70, v96
	v_min_u32_e32 v96, v70, v96
	v_max_u32_e32 v70, v77, v116
	v_min_u32_e32 v116, v77, v116
	v_max_u32_e32 v77, v83, v88
	v_min_u32_e32 v88, v83, v88
	v_max_u32_e32 v83, v102, v92
	v_min_u32_e32 v92, v102, v92
	v_max_u32_e32 v102, v110, v87
	v_min_u32_e32 v87, v110, v87
	v_max_u32_e32 v110, v89, v113
	v_min_u32_e32 v113, v89, v113
	v_max_u32_e32 v89, v108, v111
	v_min_u32_e32 v111, v108, v111
	v_max_u32_e32 v108, v85, v81
	v_min_u32_e32 v81, v85, v81
	v_max_u32_e32 v85, v117, v96
	v_min_u32_e32 v96, v117, v96
	v_max_u32_e32 v117, v70, v83
	v_min_u32_e32 v83, v70, v83
	v_max_u32_e32 v70, v77, v102
	v_min_u32_e32 v102, v77, v102
	v_max_u32_e32 v77, v116, v92
	v_min_u32_e32 v92, v116, v92
	v_max_u32_e32 v116, v88, v87
	v_min_u32_e32 v87, v88, v87
	v_max_u32_e32 v88, v110, v108
	v_min_u32_e32 v108, v110, v108
	v_max_u32_e32 v110, v89, v85
	v_min_u32_e32 v85, v89, v85
	v_max_u32_e32 v89, v113, v81
	v_min_u32_e32 v81, v113, v81
	v_max_u32_e32 v113, v111, v96
	v_min_u32_e32 v96, v111, v96
	v_max_u32_e32 v111, v117, v70
	v_min_u32_e32 v70, v117, v70
	v_max_u32_e32 v117, v83, v102
	v_min_u32_e32 v102, v83, v102
	v_max_u32_e32 v83, v77, v116
	v_min_u32_e32 v116, v77, v116
	v_max_u32_e32 v77, v92, v87
	v_min_u32_e32 v87, v92, v87
	v_max_u32_e32 v92, v88, v110
	v_min_u32_e32 v110, v88, v110
	v_max_u32_e32 v88, v108, v85
	v_min_u32_e32 v85, v108, v85
	v_max_u32_e32 v108, v89, v113
	v_min_u32_e32 v113, v89, v113
	v_max_u32_e32 v89, v81, v96
	v_min_u32_e32 v96, v81, v96
	v_max_u32_e32 v81, v107, v96
	v_max_u32_e32 v107, v100, v89
	v_max_u32_e32 v100, v115, v113
	v_max_u32_e32 v115, v112, v108
	v_max_u32_e32 v112, v91, v85
	v_max_u32_e32 v91, v109, v88
	v_max_u32_e32 v109, v98, v110
	v_max_u32_e32 v98, v86, v92
	v_max_u32_e32 v86, v101, v87
	v_max_u32_e32 v101, v97, v77
	v_max_u32_e32 v97, v114, v116
	v_max_u32_e32 v114, v90, v83
	v_max_u32_e32 v90, v104, v102
	v_max_u32_e32 v104, v106, v117
	v_max_u32_e32 v106, v105, v70
	v_max_u32_e32 v105, v103, v111
	v_max_u32_e32 v96, v81, v86
	v_min_u32_e32 v86, v81, v86
	v_max_u32_e32 v81, v107, v101
	v_min_u32_e32 v101, v107, v101
	v_max_u32_e32 v107, v100, v97
	v_min_u32_e32 v97, v100, v97
	v_max_u32_e32 v100, v115, v114
	v_min_u32_e32 v114, v115, v114
	v_max_u32_e32 v115, v112, v90
	v_min_u32_e32 v90, v112, v90
	v_max_u32_e32 v112, v91, v104
	v_min_u32_e32 v104, v91, v104
	v_max_u32_e32 v91, v109, v106
	v_min_u32_e32 v106, v109, v106
	v_max_u32_e32 v109, v98, v105
	v_min_u32_e32 v105, v98, v105
	v_max_u32_e32 v98, v96, v115
	v_min_u32_e32 v115, v96, v115
	v_max_u32_e32 v96, v81, v112
	v_min_u32_e32 v112, v81, v112
	v_max_u32_e32 v81, v107, v91
	v_min_u32_e32 v91, v107, v91
	v_max_u32_e32 v107, v100, v109
	v_min_u32_e32 v109, v100, v109
	v_max_u32_e32 v100, v86, v90
	v_min_u32_e32 v90, v86, v90
	v_max_u32_e32 v86, v101, v104
	v_min_u32_e32 v104, v101, v104
	v_max_u32_e32 v101, v97, v106
	v_min_u32_e32 v106, v97, v106
	v_max_u32_e32 v97, v114, v105
	v_min_u32_e32 v105, v114, v105
	v_max_u32_e32 v114, v98, v81
	v_min_u32_e32 v81, v98, v81
	v_max_u32_e32 v98, v96, v107
	v_min_u32_e32 v107, v96, v107
	v_max_u32_e32 v96, v115, v91
	v_min_u32_e32 v91, v115, v91
	v_max_u32_e32 v115, v112, v109
	v_min_u32_e32 v109, v112, v109
	v_max_u32_e32 v112, v100, v101
	v_min_u32_e32 v101, v100, v101
	v_max_u32_e32 v100, v86, v97
	v_min_u32_e32 v97, v86, v97
	v_max_u32_e32 v86, v90, v106
	v_min_u32_e32 v106, v90, v106
; #define MFMA32(a, b, c) __builtin_amdgcn_mfma_f32_32x32x16_bf16((a), (b), (c), 0, 0, 0)
; DI int crow(int i, int hh) { return (i & 3) + 8 * (i >> 2) + 4 * hh; }
; DI void merge_top16(unsigned (&a)[16], const unsigned (&b)[16]) {
; #pragma unroll
;   for (int i = 0; i < 16; ++i) a[i] = max(a[i], b[15 - i]);
; #pragma unroll
;     ...
; #pragma unroll
;     for (int i = 0; i < 16; ++i) {
;       const int j = 1 << js, l = i ^ j;
;       if (l > i) {
;         const unsigned x = a[i], y = a[l];
;         a[i] = max(x, y);
;         a[l] = min(x, y);
;       }
;     }
; }
; DI void peer_top16(const u16* __restrict__ PQrow, const u16* __restrict__ SK, unsigned (&top)[16], int lr, int hh) {
;     ...
;   for (int kt = 0; kt < 4; ++kt) {
;     f32x16 acc;
; #pragma unroll
;     for (int e = 0; e < 16; ++e) acc[e] = 0.f;
; #pragma unroll
;     for (int ks = 0; ks < 8; ++ks) {
;       bf16x8 a = *(const bf16x8*)(SK + (size_t)(kt * 32 + lr) * 128 + ks * 16 + hh * 8);
;       acc = MFMA32(a, qf[ks], acc);
;     }
; #pragma unroll
;     for (int e = 0; e < 16; ++e) {
;       int kidx = kt * 32 + crow(e, hh);
;       g[kt][e] = (f2ord(acc[e]) & ~127u) | (unsigned)(127 - kidx);
;     }
	v_max_u32_e32 v90, v104, v105
	v_min_u32_e32 v105, v104, v105
	v_max_u32_e32 v104, v114, v98
	v_min_u32_e32 v98, v114, v98
	v_max_u32_e32 v114, v81, v107
	v_min_u32_e32 v107, v81, v107
	v_max_u32_e32 v81, v96, v115
	v_min_u32_e32 v115, v96, v115
	v_max_u32_e32 v96, v91, v109
	v_min_u32_e32 v109, v91, v109
	v_max_u32_e32 v91, v112, v100
	v_min_u32_e32 v100, v112, v100
	v_max_u32_e32 v112, v101, v97
	v_min_u32_e32 v97, v101, v97
	v_max_u32_e32 v101, v86, v90
	v_min_u32_e32 v90, v86, v90
	v_max_u32_e32 v86, v106, v105
	v_min_u32_e32 v105, v106, v105
	v_mov_b32_e32 v16, v104
	v_mov_b32_e32 v17, v98
	v_mov_b32_e32 v18, v114
	v_mov_b32_e32 v19, v107
	v_mov_b32_e32 v20, v81
	v_mov_b32_e32 v21, v115
	v_mov_b32_e32 v22, v96
	v_mov_b32_e32 v23, v109
	v_mov_b32_e32 v24, v91
	v_mov_b32_e32 v25, v100
	v_mov_b32_e32 v26, v112
	v_mov_b32_e32 v27, v97
	v_mov_b32_e32 v28, v101
	v_mov_b32_e32 v29, v90
	v_mov_b32_e32 v30, v86
	v_mov_b32_e32 v31, v105
	v_sub_u32_e32 v213, 127, v245
	v_sub_u32_e32 v214, 126, v245
	v_sub_u32_e32 v215, 125, v245
	v_sub_u32_e32 v216, 124, v245
	v_sub_u32_e32 v217, 119, v245
	v_sub_u32_e32 v218, 118, v245
	v_sub_u32_e32 v219, 117, v245
	v_sub_u32_e32 v220, 116, v245
	v_sub_u32_e32 v221, 111, v245
	v_sub_u32_e32 v222, 110, v245
	v_sub_u32_e32 v223, 109, v245
	v_sub_u32_e32 v224, 108, v245
	v_sub_u32_e32 v225, 103, v245
	v_sub_u32_e32 v226, 102, v245
	v_sub_u32_e32 v227, 101, v245
	v_sub_u32_e32 v228, 100, v245
	s_waitcnt vmcnt(7)
	v_mfma_f32_32x32x16_bf16 v[128:143], v[144:147], v[176:179], 0
	s_waitcnt vmcnt(6)
	v_mfma_f32_32x32x16_bf16 v[128:143], v[148:151], v[180:183], v[128:143]
	s_waitcnt vmcnt(5)
	v_mfma_f32_32x32x16_bf16 v[128:143], v[152:155], v[184:187], v[128:143]
	s_waitcnt vmcnt(4)
	v_mfma_f32_32x32x16_bf16 v[128:143], v[156:159], v[188:191], v[128:143]
	s_waitcnt vmcnt(3)
	v_mfma_f32_32x32x16_bf16 v[128:143], v[160:163], v[192:195], v[128:143]
	s_waitcnt vmcnt(2)
	v_mfma_f32_32x32x16_bf16 v[128:143], v[164:167], v[196:199], v[128:143]
	s_waitcnt vmcnt(1)
	v_mfma_f32_32x32x16_bf16 v[128:143], v[168:171], v[200:203], v[128:143]
	s_waitcnt vmcnt(0)
	v_mfma_f32_32x32x16_bf16 v[128:143], v[172:175], v[204:207], v[128:143]
	s_add_u32 s4, s0, 73728
	s_addc_u32 s5, s1, 0
	global_load_dwordx4 v[144:147], v238, s[4:5] offset:0
	global_load_dwordx4 v[148:151], v238, s[4:5] offset:32
	global_load_dwordx4 v[152:155], v238, s[4:5] offset:64
	global_load_dwordx4 v[156:159], v238, s[4:5] offset:96
	global_load_dwordx4 v[160:163], v238, s[4:5] offset:128
	global_load_dwordx4 v[164:167], v238, s[4:5] offset:160
	global_load_dwordx4 v[168:171], v238, s[4:5] offset:192
	global_load_dwordx4 v[172:175], v238, s[4:5] offset:224
	s_nop 7
	s_nop 3
	v_ashrrev_i32_e32 v230, 31, v128
	v_or_b32_e32 v230, 0x80000000, v230
	v_xor_b32_e32 v229, v230, v128
	v_and_b32_e32 v229, 0xffffff80, v229
	v_or_b32_e32 v105, v229, v213
	v_ashrrev_i32_e32 v230, 31, v129
	v_or_b32_e32 v230, 0x80000000, v230
	v_xor_b32_e32 v229, v230, v129
	v_and_b32_e32 v229, 0xffffff80, v229
	v_or_b32_e32 v86, v229, v214
	v_ashrrev_i32_e32 v230, 31, v130
	v_or_b32_e32 v230, 0x80000000, v230
	v_xor_b32_e32 v229, v230, v130
	v_and_b32_e32 v229, 0xffffff80, v229
	v_or_b32_e32 v90, v229, v215
	v_ashrrev_i32_e32 v230, 31, v131
	v_or_b32_e32 v230, 0x80000000, v230
	v_xor_b32_e32 v229, v230, v131
	v_and_b32_e32 v229, 0xffffff80, v229
	v_or_b32_e32 v101, v229, v216
	v_ashrrev_i32_e32 v230, 31, v132
	v_or_b32_e32 v230, 0x80000000, v230
	v_xor_b32_e32 v229, v230, v132
	v_and_b32_e32 v229, 0xffffff80, v229
	v_or_b32_e32 v97, v229, v217
	v_ashrrev_i32_e32 v230, 31, v133
	v_or_b32_e32 v230, 0x80000000, v230
	v_xor_b32_e32 v229, v230, v133
	v_and_b32_e32 v229, 0xffffff80, v229
	v_or_b32_e32 v112, v229, v218
	v_ashrrev_i32_e32 v230, 31, v134
	v_or_b32_e32 v230, 0x80000000, v230
	v_xor_b32_e32 v229, v230, v134
	v_and_b32_e32 v229, 0xffffff80, v229
	v_or_b32_e32 v100, v229, v219
	v_ashrrev_i32_e32 v230, 31, v135
	v_or_b32_e32 v230, 0x80000000, v230
	v_xor_b32_e32 v229, v230, v135
	v_and_b32_e32 v229, 0xffffff80, v229
	v_or_b32_e32 v91, v229, v220
	v_ashrrev_i32_e32 v230, 31, v136
	v_or_b32_e32 v230, 0x80000000, v230
	v_xor_b32_e32 v229, v230, v136
	v_and_b32_e32 v229, 0xffffff80, v229
	v_or_b32_e32 v109, v229, v221
	v_ashrrev_i32_e32 v230, 31, v137
	v_or_b32_e32 v230, 0x80000000, v230
	v_xor_b32_e32 v229, v230, v137
	v_and_b32_e32 v229, 0xffffff80, v229
	v_or_b32_e32 v96, v229, v222
	v_ashrrev_i32_e32 v230, 31, v138
	v_or_b32_e32 v230, 0x80000000, v230
	v_xor_b32_e32 v229, v230, v138
	v_and_b32_e32 v229, 0xffffff80, v229
	v_or_b32_e32 v115, v229, v223
	v_ashrrev_i32_e32 v230, 31, v139
	v_or_b32_e32 v230, 0x80000000, v230
	v_xor_b32_e32 v229, v230, v139
	v_and_b32_e32 v229, 0xffffff80, v229
	v_or_b32_e32 v81, v229, v224
	v_ashrrev_i32_e32 v230, 31, v140
	v_or_b32_e32 v230, 0x80000000, v230
	v_xor_b32_e32 v229, v230, v140
	v_and_b32_e32 v229, 0xffffff80, v229
	v_or_b32_e32 v107, v229, v225
	v_ashrrev_i32_e32 v230, 31, v141
	v_or_b32_e32 v230, 0x80000000, v230
	v_xor_b32_e32 v229, v230, v141
	v_and_b32_e32 v229, 0xffffff80, v229
	v_or_b32_e32 v114, v229, v226
	v_ashrrev_i32_e32 v230, 31, v142
	v_or_b32_e32 v230, 0x80000000, v230
	v_xor_b32_e32 v229, v230, v142
	v_and_b32_e32 v229, 0xffffff80, v229
	v_or_b32_e32 v98, v229, v227
	v_ashrrev_i32_e32 v230, 31, v143
	v_or_b32_e32 v230, 0x80000000, v230
	v_xor_b32_e32 v229, v230, v143
	v_and_b32_e32 v229, 0xffffff80, v229
	v_or_b32_e32 v104, v229, v228
	v_subrev_u32_e32 v213, 32, v213
	v_subrev_u32_e32 v214, 32, v214
	v_subrev_u32_e32 v215, 32, v215
	v_subrev_u32_e32 v216, 32, v216
	v_subrev_u32_e32 v217, 32, v217
	v_subrev_u32_e32 v218, 32, v218
; template <int LOGN>
; DI void bitonic_sort_desc(unsigned (&a)[1 << LOGN]) {
;   constexpr int N = 1 << LOGN;
; #pragma unroll
;   for (int ks = 1; ks <= LOGN; ++ks)
; #pragma unroll
;     ...
; #pragma unroll
;       for (int i = 0; i < N; ++i) {
;         const int k = 1 << ks, j = 1 << js, l = i ^ j;
;         if (l > i) {
;           const bool desc = ((i & k) == 0) || (ks == LOGN);
;           const unsigned x = a[i], y = a[l];
;           const unsigned hi = max(x, y), lo = min(x, y);
;           a[i] = desc ? hi : lo;
;           a[l] = desc ? lo : hi;
;         }
;       }
; }
	v_subrev_u32_e32 v219, 32, v219
	v_subrev_u32_e32 v220, 32, v220
	v_subrev_u32_e32 v221, 32, v221
	v_subrev_u32_e32 v222, 32, v222
	v_subrev_u32_e32 v223, 32, v223
	v_subrev_u32_e32 v224, 32, v224
	v_subrev_u32_e32 v225, 32, v225
	v_subrev_u32_e32 v226, 32, v226
	v_subrev_u32_e32 v227, 32, v227
	v_subrev_u32_e32 v228, 32, v228
	v_max_u32_e32 v106, v105, v86
	v_min_u32_e32 v86, v105, v86
	v_min_u32_e32 v105, v90, v101
	v_max_u32_e32 v101, v90, v101
	v_max_u32_e32 v90, v97, v112
	v_min_u32_e32 v112, v97, v112
	v_min_u32_e32 v97, v100, v91
	v_max_u32_e32 v91, v100, v91
	v_max_u32_e32 v100, v109, v96
	v_min_u32_e32 v96, v109, v96
	v_min_u32_e32 v109, v115, v81
	v_max_u32_e32 v81, v115, v81
	v_max_u32_e32 v115, v107, v114
	v_min_u32_e32 v114, v107, v114
	v_min_u32_e32 v107, v98, v104
	v_max_u32_e32 v104, v98, v104
	v_max_u32_e32 v98, v106, v105
	v_min_u32_e32 v105, v106, v105
	v_max_u32_e32 v106, v86, v101
	v_min_u32_e32 v101, v86, v101
	v_min_u32_e32 v86, v90, v97
	v_max_u32_e32 v97, v90, v97
	v_min_u32_e32 v90, v112, v91
	v_max_u32_e32 v91, v112, v91
	v_max_u32_e32 v112, v100, v109
	v_min_u32_e32 v109, v100, v109
	v_max_u32_e32 v100, v96, v81
	v_min_u32_e32 v81, v96, v81
	v_min_u32_e32 v96, v115, v107
	v_max_u32_e32 v107, v115, v107
	v_min_u32_e32 v115, v114, v104
	v_max_u32_e32 v104, v114, v104
	v_max_u32_e32 v114, v98, v106
	v_min_u32_e32 v106, v98, v106
	v_max_u32_e32 v98, v105, v101
	v_min_u32_e32 v101, v105, v101
	v_min_u32_e32 v105, v86, v90
	v_max_u32_e32 v90, v86, v90
	v_min_u32_e32 v86, v97, v91
	v_max_u32_e32 v91, v97, v91
	v_max_u32_e32 v97, v112, v100
	v_min_u32_e32 v100, v112, v100
	v_max_u32_e32 v112, v109, v81
	v_min_u32_e32 v81, v109, v81
	v_min_u32_e32 v109, v96, v115
	v_max_u32_e32 v115, v96, v115
	v_min_u32_e32 v96, v107, v104
	v_max_u32_e32 v104, v107, v104
	v_max_u32_e32 v107, v114, v105
	v_min_u32_e32 v105, v114, v105
	v_max_u32_e32 v114, v106, v90
	v_min_u32_e32 v90, v106, v90
	v_max_u32_e32 v106, v98, v86
	v_min_u32_e32 v86, v98, v86
	v_max_u32_e32 v98, v101, v91
	v_min_u32_e32 v91, v101, v91
	v_min_u32_e32 v101, v97, v109
	v_max_u32_e32 v109, v97, v109
	v_min_u32_e32 v97, v100, v115
	v_max_u32_e32 v115, v100, v115
	v_min_u32_e32 v100, v112, v96
	v_max_u32_e32 v96, v112, v96
	v_min_u32_e32 v112, v81, v104
	v_max_u32_e32 v104, v81, v104
	v_max_u32_e32 v81, v107, v106
	v_min_u32_e32 v106, v107, v106
	v_max_u32_e32 v107, v114, v98
	v_min_u32_e32 v98, v114, v98
	v_max_u32_e32 v114, v105, v86
	v_min_u32_e32 v86, v105, v86
	v_max_u32_e32 v105, v90, v91
	v_min_u32_e32 v91, v90, v91
	v_min_u32_e32 v90, v101, v100
	v_max_u32_e32 v100, v101, v100
	v_min_u32_e32 v101, v97, v112
	v_max_u32_e32 v112, v97, v112
	v_min_u32_e32 v97, v109, v96
	v_max_u32_e32 v96, v109, v96
	v_min_u32_e32 v109, v115, v104
	v_max_u32_e32 v104, v115, v104
	v_max_u32_e32 v115, v81, v107
	v_min_u32_e32 v107, v81, v107
	v_max_u32_e32 v81, v106, v98
	v_min_u32_e32 v98, v106, v98
	v_max_u32_e32 v106, v114, v105
	v_min_u32_e32 v105, v114, v105
	v_max_u32_e32 v114, v86, v91
	v_min_u32_e32 v91, v86, v91
	v_min_u32_e32 v86, v90, v101
	v_max_u32_e32 v101, v90, v101
	v_min_u32_e32 v90, v100, v112
	v_max_u32_e32 v112, v100, v112
	v_min_u32_e32 v100, v97, v109
	v_max_u32_e32 v109, v97, v109
	v_min_u32_e32 v97, v96, v104
	v_max_u32_e32 v104, v96, v104
	v_max_u32_e32 v96, v115, v86
	v_min_u32_e32 v86, v115, v86
	v_max_u32_e32 v115, v107, v101
	v_min_u32_e32 v101, v107, v101
	v_max_u32_e32 v107, v81, v90
	v_min_u32_e32 v90, v81, v90
	v_max_u32_e32 v81, v98, v112
	v_min_u32_e32 v112, v98, v112
	v_max_u32_e32 v98, v106, v100
	v_min_u32_e32 v100, v106, v100
	v_max_u32_e32 v106, v105, v109
	v_min_u32_e32 v109, v105, v109
	v_max_u32_e32 v105, v114, v97
	v_min_u32_e32 v97, v114, v97
	v_max_u32_e32 v114, v91, v104
	v_min_u32_e32 v104, v91, v104
	v_max_u32_e32 v91, v96, v98
	v_min_u32_e32 v98, v96, v98
	v_max_u32_e32 v96, v115, v106
	v_min_u32_e32 v106, v115, v106
	v_max_u32_e32 v115, v107, v105
	v_min_u32_e32 v105, v107, v105
	v_max_u32_e32 v107, v81, v114
	v_min_u32_e32 v114, v81, v114
	v_max_u32_e32 v81, v86, v100
	v_min_u32_e32 v100, v86, v100
	v_max_u32_e32 v86, v101, v109
	v_min_u32_e32 v109, v101, v109
	v_max_u32_e32 v101, v90, v97
	v_min_u32_e32 v97, v90, v97
	v_max_u32_e32 v90, v112, v104
	v_min_u32_e32 v104, v112, v104
	v_max_u32_e32 v112, v91, v115
	v_min_u32_e32 v115, v91, v115
	v_max_u32_e32 v91, v96, v107
	v_min_u32_e32 v107, v96, v107
	v_max_u32_e32 v96, v98, v105
	v_min_u32_e32 v105, v98, v105
	v_max_u32_e32 v98, v106, v114
	v_min_u32_e32 v114, v106, v114
	v_max_u32_e32 v106, v81, v101
	v_min_u32_e32 v101, v81, v101
	v_max_u32_e32 v81, v86, v90
	v_min_u32_e32 v90, v86, v90
	v_max_u32_e32 v86, v100, v97
	v_min_u32_e32 v97, v100, v97
	v_max_u32_e32 v100, v109, v104
	v_min_u32_e32 v104, v109, v104
	v_max_u32_e32 v109, v112, v91
	v_min_u32_e32 v91, v112, v91
	v_max_u32_e32 v112, v115, v107
	v_min_u32_e32 v107, v115, v107
	v_max_u32_e32 v115, v96, v98
	v_min_u32_e32 v98, v96, v98
	v_max_u32_e32 v96, v105, v114
	v_min_u32_e32 v114, v105, v114
	v_max_u32_e32 v105, v106, v81
	v_min_u32_e32 v81, v106, v81
	v_max_u32_e32 v106, v101, v90
	v_min_u32_e32 v90, v101, v90
	v_max_u32_e32 v101, v86, v100
	v_min_u32_e32 v100, v86, v100
	v_max_u32_e32 v86, v97, v104
	v_min_u32_e32 v104, v97, v104
	s_waitcnt vmcnt(7)
	v_mfma_f32_32x32x16_bf16 v[128:143], v[144:147], v[176:179], 0
	s_waitcnt vmcnt(6)
	v_mfma_f32_32x32x16_bf16 v[128:143], v[148:151], v[180:183], v[128:143]
	s_waitcnt vmcnt(5)
	v_mfma_f32_32x32x16_bf16 v[128:143], v[152:155], v[184:187], v[128:143]
	s_waitcnt vmcnt(4)
	v_mfma_f32_32x32x16_bf16 v[128:143], v[156:159], v[188:191], v[128:143]
	s_waitcnt vmcnt(3)
; #define MFMA32(a, b, c) __builtin_amdgcn_mfma_f32_32x32x16_bf16((a), (b), (c), 0, 0, 0)
; DI int crow(int i, int hh) { return (i & 3) + 8 * (i >> 2) + 4 * hh; }
; DI void peer_top16(const u16* __restrict__ PQrow, const u16* __restrict__ SK, unsigned (&top)[16], int lr, int hh) {
;     ...
;   for (int kt = 0; kt < 4; ++kt) {
;     f32x16 acc;
; #pragma unroll
;     for (int e = 0; e < 16; ++e) acc[e] = 0.f;
; #pragma unroll
;     for (int ks = 0; ks < 8; ++ks) {
;       bf16x8 a = *(const bf16x8*)(SK + (size_t)(kt * 32 + lr) * 128 + ks * 16 + hh * 8);
;       acc = MFMA32(a, qf[ks], acc);
;     }
; #pragma unroll
;     for (int e = 0; e < 16; ++e) {
;       int kidx = kt * 32 + crow(e, hh);
;       g[kt][e] = (f2ord(acc[e]) & ~127u) | (unsigned)(127 - kidx);
;     }
	v_mfma_f32_32x32x16_bf16 v[128:143], v[160:163], v[192:195], v[128:143]
	s_waitcnt vmcnt(2)
	v_mfma_f32_32x32x16_bf16 v[128:143], v[164:167], v[196:199], v[128:143]
	s_waitcnt vmcnt(1)
	v_mfma_f32_32x32x16_bf16 v[128:143], v[168:171], v[200:203], v[128:143]
	s_waitcnt vmcnt(0)
	v_mfma_f32_32x32x16_bf16 v[128:143], v[172:175], v[204:207], v[128:143]
	s_add_u32 s4, s0, 81920
	s_addc_u32 s5, s1, 0
	global_load_dwordx4 v[144:147], v238, s[4:5] offset:0
	global_load_dwordx4 v[148:151], v238, s[4:5] offset:32
	global_load_dwordx4 v[152:155], v238, s[4:5] offset:64
	global_load_dwordx4 v[156:159], v238, s[4:5] offset:96
	global_load_dwordx4 v[160:163], v238, s[4:5] offset:128
	global_load_dwordx4 v[164:167], v238, s[4:5] offset:160
	global_load_dwordx4 v[168:171], v238, s[4:5] offset:192
	global_load_dwordx4 v[172:175], v238, s[4:5] offset:224
	s_nop 7
	s_nop 3
	v_ashrrev_i32_e32 v230, 31, v128
	v_or_b32_e32 v230, 0x80000000, v230
	v_xor_b32_e32 v229, v230, v128
	v_and_b32_e32 v229, 0xffffff80, v229
	v_or_b32_e32 v97, v229, v213
	v_ashrrev_i32_e32 v230, 31, v129
	v_or_b32_e32 v230, 0x80000000, v230
	v_xor_b32_e32 v229, v230, v129
	v_and_b32_e32 v229, 0xffffff80, v229
	v_or_b32_e32 v89, v229, v214
	v_ashrrev_i32_e32 v230, 31, v130
	v_or_b32_e32 v230, 0x80000000, v230
	v_xor_b32_e32 v229, v230, v130
	v_and_b32_e32 v229, 0xffffff80, v229
	v_or_b32_e32 v113, v229, v215
	v_ashrrev_i32_e32 v230, 31, v131
	v_or_b32_e32 v230, 0x80000000, v230
	v_xor_b32_e32 v229, v230, v131
	v_and_b32_e32 v229, 0xffffff80, v229
	v_or_b32_e32 v108, v229, v216
	v_ashrrev_i32_e32 v230, 31, v132
	v_or_b32_e32 v230, 0x80000000, v230
	v_xor_b32_e32 v229, v230, v132
	v_and_b32_e32 v229, 0xffffff80, v229
	v_or_b32_e32 v85, v229, v217
	v_ashrrev_i32_e32 v230, 31, v133
	v_or_b32_e32 v230, 0x80000000, v230
	v_xor_b32_e32 v229, v230, v133
	v_and_b32_e32 v229, 0xffffff80, v229
	v_or_b32_e32 v88, v229, v218
	v_ashrrev_i32_e32 v230, 31, v134
	v_or_b32_e32 v230, 0x80000000, v230
	v_xor_b32_e32 v229, v230, v134
	v_and_b32_e32 v229, 0xffffff80, v229
	v_or_b32_e32 v110, v229, v219
	v_ashrrev_i32_e32 v230, 31, v135
	v_or_b32_e32 v230, 0x80000000, v230
	v_xor_b32_e32 v229, v230, v135
	v_and_b32_e32 v229, 0xffffff80, v229
	v_or_b32_e32 v92, v229, v220
	v_ashrrev_i32_e32 v230, 31, v136
	v_or_b32_e32 v230, 0x80000000, v230
	v_xor_b32_e32 v229, v230, v136
	v_and_b32_e32 v229, 0xffffff80, v229
	v_or_b32_e32 v87, v229, v221
	v_ashrrev_i32_e32 v230, 31, v137
	v_or_b32_e32 v230, 0x80000000, v230
	v_xor_b32_e32 v229, v230, v137
	v_and_b32_e32 v229, 0xffffff80, v229
	v_or_b32_e32 v77, v229, v222
	v_ashrrev_i32_e32 v230, 31, v138
	v_or_b32_e32 v230, 0x80000000, v230
	v_xor_b32_e32 v229, v230, v138
	v_and_b32_e32 v229, 0xffffff80, v229
	v_or_b32_e32 v116, v229, v223
	v_ashrrev_i32_e32 v230, 31, v139
	v_or_b32_e32 v230, 0x80000000, v230
	v_xor_b32_e32 v229, v230, v139
	v_and_b32_e32 v229, 0xffffff80, v229
	v_or_b32_e32 v83, v229, v224
	v_ashrrev_i32_e32 v230, 31, v140
	v_or_b32_e32 v230, 0x80000000, v230
	v_xor_b32_e32 v229, v230, v140
	v_and_b32_e32 v229, 0xffffff80, v229
	v_or_b32_e32 v102, v229, v225
	v_ashrrev_i32_e32 v230, 31, v141
	v_or_b32_e32 v230, 0x80000000, v230
	v_xor_b32_e32 v229, v230, v141
	v_and_b32_e32 v229, 0xffffff80, v229
	v_or_b32_e32 v117, v229, v226
	v_ashrrev_i32_e32 v230, 31, v142
	v_or_b32_e32 v230, 0x80000000, v230
	v_xor_b32_e32 v229, v230, v142
	v_and_b32_e32 v229, 0xffffff80, v229
	v_or_b32_e32 v70, v229, v227
	v_ashrrev_i32_e32 v230, 31, v143
	v_or_b32_e32 v230, 0x80000000, v230
	v_xor_b32_e32 v229, v230, v143
	v_and_b32_e32 v229, 0xffffff80, v229
	v_or_b32_e32 v111, v229, v228
	v_subrev_u32_e32 v213, 32, v213
	v_subrev_u32_e32 v214, 32, v214
	v_subrev_u32_e32 v215, 32, v215
	v_subrev_u32_e32 v216, 32, v216
	v_subrev_u32_e32 v217, 32, v217
	v_subrev_u32_e32 v218, 32, v218
	v_subrev_u32_e32 v219, 32, v219
	v_subrev_u32_e32 v220, 32, v220
	v_subrev_u32_e32 v221, 32, v221
	v_subrev_u32_e32 v222, 32, v222
	v_subrev_u32_e32 v223, 32, v223
	v_subrev_u32_e32 v224, 32, v224
	v_subrev_u32_e32 v225, 32, v225
	v_subrev_u32_e32 v226, 32, v226
	v_subrev_u32_e32 v227, 32, v227
	v_subrev_u32_e32 v228, 32, v228
	v_max_u32_e32 v103, v97, v89
	v_min_u32_e32 v89, v97, v89
	v_min_u32_e32 v97, v113, v108
	v_max_u32_e32 v108, v113, v108
	v_max_u32_e32 v113, v85, v88
	v_min_u32_e32 v88, v85, v88
	v_min_u32_e32 v85, v110, v92
	v_max_u32_e32 v92, v110, v92
	v_max_u32_e32 v110, v87, v77
	v_min_u32_e32 v77, v87, v77
	v_min_u32_e32 v87, v116, v83
	v_max_u32_e32 v83, v116, v83
	v_max_u32_e32 v116, v102, v117
	v_min_u32_e32 v117, v102, v117
	v_min_u32_e32 v102, v70, v111
	v_max_u32_e32 v111, v70, v111
	v_max_u32_e32 v70, v103, v97
	v_min_u32_e32 v97, v103, v97
	v_max_u32_e32 v103, v89, v108
	v_min_u32_e32 v108, v89, v108
	v_min_u32_e32 v89, v113, v85
	v_max_u32_e32 v85, v113, v85
	v_min_u32_e32 v113, v88, v92
	v_max_u32_e32 v92, v88, v92
	v_max_u32_e32 v88, v110, v87
	v_min_u32_e32 v87, v110, v87
	v_max_u32_e32 v110, v77, v83
	v_min_u32_e32 v83, v77, v83
	v_min_u32_e32 v77, v116, v102
	v_max_u32_e32 v102, v116, v102
	v_min_u32_e32 v116, v117, v111
	v_max_u32_e32 v111, v117, v111
	v_max_u32_e32 v117, v70, v103
	v_min_u32_e32 v103, v70, v103
	v_max_u32_e32 v70, v97, v108
	v_min_u32_e32 v108, v97, v108
	v_min_u32_e32 v97, v89, v113
	v_max_u32_e32 v113, v89, v113
	v_min_u32_e32 v89, v85, v92
	v_max_u32_e32 v92, v85, v92
	v_max_u32_e32 v85, v88, v110
	v_min_u32_e32 v110, v88, v110
	v_max_u32_e32 v88, v87, v83
	v_min_u32_e32 v83, v87, v83
	v_min_u32_e32 v87, v77, v116
	v_max_u32_e32 v116, v77, v116
	v_min_u32_e32 v77, v102, v111
	v_max_u32_e32 v111, v102, v111
	v_max_u32_e32 v102, v117, v97
; template <int LOGN>
; DI void bitonic_sort_desc(unsigned (&a)[1 << LOGN]) {
;   constexpr int N = 1 << LOGN;
; #pragma unroll
;   for (int ks = 1; ks <= LOGN; ++ks)
; #pragma unroll
;     ...
; #pragma unroll
;       for (int i = 0; i < N; ++i) {
;         const int k = 1 << ks, j = 1 << js, l = i ^ j;
;         if (l > i) {
;           const bool desc = ((i & k) == 0) || (ks == LOGN);
;           const unsigned x = a[i], y = a[l];
;           const unsigned hi = max(x, y), lo = min(x, y);
;           a[i] = desc ? hi : lo;
;           a[l] = desc ? lo : hi;
;         }
;       }
; }
; DI void merge_top16(unsigned (&a)[16], const unsigned (&b)[16]) {
; #pragma unroll
;   for (int i = 0; i < 16; ++i) a[i] = max(a[i], b[15 - i]);
; #pragma unroll
;     ...
; #pragma unroll
;     for (int i = 0; i < 16; ++i) {
;       const int j = 1 << js, l = i ^ j;
;       if (l > i) {
;         const unsigned x = a[i], y = a[l];
;         a[i] = max(x, y);
;         a[l] = min(x, y);
;       }
;     }
; }
	v_min_u32_e32 v97, v117, v97
	v_max_u32_e32 v117, v103, v113
	v_min_u32_e32 v113, v103, v113
	v_max_u32_e32 v103, v70, v89
	v_min_u32_e32 v89, v70, v89
	v_max_u32_e32 v70, v108, v92
	v_min_u32_e32 v92, v108, v92
	v_min_u32_e32 v108, v85, v87
	v_max_u32_e32 v87, v85, v87
	v_min_u32_e32 v85, v110, v116
	v_max_u32_e32 v116, v110, v116
	v_min_u32_e32 v110, v88, v77
	v_max_u32_e32 v77, v88, v77
	v_min_u32_e32 v88, v83, v111
	v_max_u32_e32 v111, v83, v111
	v_max_u32_e32 v83, v102, v103
	v_min_u32_e32 v103, v102, v103
	v_max_u32_e32 v102, v117, v70
	v_min_u32_e32 v70, v117, v70
	v_max_u32_e32 v117, v97, v89
	v_min_u32_e32 v89, v97, v89
	v_max_u32_e32 v97, v113, v92
	v_min_u32_e32 v92, v113, v92
	v_min_u32_e32 v113, v108, v110
	v_max_u32_e32 v110, v108, v110
	v_min_u32_e32 v108, v85, v88
	v_max_u32_e32 v88, v85, v88
	v_min_u32_e32 v85, v87, v77
	v_max_u32_e32 v77, v87, v77
	v_min_u32_e32 v87, v116, v111
	v_max_u32_e32 v111, v116, v111
	v_max_u32_e32 v116, v83, v102
	v_min_u32_e32 v102, v83, v102
	v_max_u32_e32 v83, v103, v70
	v_min_u32_e32 v70, v103, v70
	v_max_u32_e32 v103, v117, v97
	v_min_u32_e32 v97, v117, v97
	v_max_u32_e32 v117, v89, v92
	v_min_u32_e32 v92, v89, v92
	v_min_u32_e32 v89, v113, v108
	v_max_u32_e32 v108, v113, v108
	v_min_u32_e32 v113, v110, v88
	v_max_u32_e32 v88, v110, v88
	v_min_u32_e32 v110, v85, v87
	v_max_u32_e32 v87, v85, v87
	v_min_u32_e32 v85, v77, v111
	v_max_u32_e32 v111, v77, v111
	v_max_u32_e32 v77, v116, v89
	v_min_u32_e32 v89, v116, v89
	v_max_u32_e32 v116, v102, v108
	v_min_u32_e32 v108, v102, v108
	v_max_u32_e32 v102, v83, v113
	v_min_u32_e32 v113, v83, v113
	v_max_u32_e32 v83, v70, v88
	v_min_u32_e32 v88, v70, v88
	v_max_u32_e32 v70, v103, v110
	v_min_u32_e32 v110, v103, v110
	v_max_u32_e32 v103, v97, v87
	v_min_u32_e32 v87, v97, v87
	v_max_u32_e32 v97, v117, v85
	v_min_u32_e32 v85, v117, v85
	v_max_u32_e32 v117, v92, v111
	v_min_u32_e32 v111, v92, v111
	v_max_u32_e32 v92, v77, v70
	v_min_u32_e32 v70, v77, v70
	v_max_u32_e32 v77, v116, v103
	v_min_u32_e32 v103, v116, v103
	v_max_u32_e32 v116, v102, v97
	v_min_u32_e32 v97, v102, v97
	v_max_u32_e32 v102, v83, v117
	v_min_u32_e32 v117, v83, v117
	v_max_u32_e32 v83, v89, v110
	v_min_u32_e32 v110, v89, v110
	v_max_u32_e32 v89, v108, v87
	v_min_u32_e32 v87, v108, v87
	v_max_u32_e32 v108, v113, v85
	v_min_u32_e32 v85, v113, v85
	v_max_u32_e32 v113, v88, v111
	v_min_u32_e32 v111, v88, v111
	v_max_u32_e32 v88, v92, v116
	v_min_u32_e32 v116, v92, v116
	v_max_u32_e32 v92, v77, v102
	v_min_u32_e32 v102, v77, v102
	v_max_u32_e32 v77, v70, v97
	v_min_u32_e32 v97, v70, v97
	v_max_u32_e32 v70, v103, v117
	v_min_u32_e32 v117, v103, v117
	v_max_u32_e32 v103, v83, v108
	v_min_u32_e32 v108, v83, v108
	v_max_u32_e32 v83, v89, v113
	v_min_u32_e32 v113, v89, v113
	v_max_u32_e32 v89, v110, v85
	v_min_u32_e32 v85, v110, v85
	v_max_u32_e32 v110, v87, v111
	v_min_u32_e32 v111, v87, v111
	v_max_u32_e32 v87, v88, v92
	v_min_u32_e32 v92, v88, v92
	v_max_u32_e32 v88, v116, v102
	v_min_u32_e32 v102, v116, v102
	v_max_u32_e32 v116, v77, v70
	v_min_u32_e32 v70, v77, v70
	v_max_u32_e32 v77, v97, v117
	v_min_u32_e32 v117, v97, v117
	v_max_u32_e32 v97, v103, v83
	v_min_u32_e32 v83, v103, v83
	v_max_u32_e32 v103, v108, v113
	v_min_u32_e32 v113, v108, v113
	v_max_u32_e32 v108, v89, v110
	v_min_u32_e32 v110, v89, v110
	v_max_u32_e32 v89, v85, v111
	v_min_u32_e32 v111, v85, v111
	v_max_u32_e32 v85, v109, v111
	v_max_u32_e32 v109, v91, v89
	v_max_u32_e32 v91, v112, v110
	v_max_u32_e32 v112, v107, v108
	v_max_u32_e32 v107, v115, v113
	v_max_u32_e32 v115, v98, v103
	v_max_u32_e32 v98, v96, v83
	v_max_u32_e32 v96, v114, v97
	v_max_u32_e32 v114, v105, v117
	v_max_u32_e32 v105, v81, v77
	v_max_u32_e32 v81, v106, v70
	v_max_u32_e32 v106, v90, v116
	v_max_u32_e32 v90, v101, v102
	v_max_u32_e32 v101, v100, v88
	v_max_u32_e32 v100, v86, v92
	v_max_u32_e32 v86, v104, v87
	v_max_u32_e32 v111, v85, v114
	v_min_u32_e32 v114, v85, v114
	v_max_u32_e32 v85, v109, v105
	v_min_u32_e32 v105, v109, v105
	v_max_u32_e32 v109, v91, v81
	v_min_u32_e32 v81, v91, v81
	v_max_u32_e32 v91, v112, v106
	v_min_u32_e32 v106, v112, v106
	v_max_u32_e32 v112, v107, v90
	v_min_u32_e32 v90, v107, v90
	v_max_u32_e32 v107, v115, v101
	v_min_u32_e32 v101, v115, v101
	v_max_u32_e32 v115, v98, v100
	v_min_u32_e32 v100, v98, v100
	v_max_u32_e32 v98, v96, v86
	v_min_u32_e32 v86, v96, v86
	v_max_u32_e32 v96, v111, v112
	v_min_u32_e32 v112, v111, v112
	v_max_u32_e32 v111, v85, v107
	v_min_u32_e32 v107, v85, v107
	v_max_u32_e32 v85, v109, v115
	v_min_u32_e32 v115, v109, v115
	v_max_u32_e32 v109, v91, v98
	v_min_u32_e32 v98, v91, v98
	v_max_u32_e32 v91, v114, v90
	v_min_u32_e32 v90, v114, v90
	v_max_u32_e32 v114, v105, v101
	v_min_u32_e32 v101, v105, v101
	v_max_u32_e32 v105, v81, v100
	v_min_u32_e32 v100, v81, v100
	v_max_u32_e32 v81, v106, v86
	v_min_u32_e32 v86, v106, v86
	v_max_u32_e32 v106, v96, v85
	v_min_u32_e32 v85, v96, v85
	v_max_u32_e32 v96, v111, v109
	v_min_u32_e32 v109, v111, v109
	v_max_u32_e32 v111, v112, v115
	v_min_u32_e32 v115, v112, v115
	v_max_u32_e32 v112, v107, v98
	v_min_u32_e32 v98, v107, v98
	v_max_u32_e32 v107, v91, v105
	v_min_u32_e32 v105, v91, v105
	v_max_u32_e32 v91, v114, v81
	v_min_u32_e32 v81, v114, v81
	v_max_u32_e32 v114, v90, v100
	v_min_u32_e32 v100, v90, v100
	v_max_u32_e32 v90, v101, v86
	v_min_u32_e32 v86, v101, v86
	v_max_u32_e32 v101, v106, v96
	v_min_u32_e32 v96, v106, v96
	v_max_u32_e32 v106, v85, v109
	v_min_u32_e32 v109, v85, v109
	v_max_u32_e32 v85, v111, v112
	v_min_u32_e32 v112, v111, v112
	v_max_u32_e32 v111, v115, v98
	v_min_u32_e32 v98, v115, v98
	v_max_u32_e32 v115, v107, v91
	v_min_u32_e32 v91, v107, v91
	v_max_u32_e32 v107, v105, v81
	v_min_u32_e32 v81, v105, v81
	v_max_u32_e32 v105, v114, v90
	v_min_u32_e32 v90, v114, v90
	v_max_u32_e32 v114, v100, v86
	v_min_u32_e32 v86, v100, v86
	s_waitcnt vmcnt(7)
; #define MFMA32(a, b, c) __builtin_amdgcn_mfma_f32_32x32x16_bf16((a), (b), (c), 0, 0, 0)
; DI int crow(int i, int hh) { return (i & 3) + 8 * (i >> 2) + 4 * hh; }
; DI void peer_top16(const u16* __restrict__ PQrow, const u16* __restrict__ SK, unsigned (&top)[16], int lr, int hh) {
;     ...
;   for (int kt = 0; kt < 4; ++kt) {
;     f32x16 acc;
; #pragma unroll
;     for (int e = 0; e < 16; ++e) acc[e] = 0.f;
; #pragma unroll
;     for (int ks = 0; ks < 8; ++ks) {
;       bf16x8 a = *(const bf16x8*)(SK + (size_t)(kt * 32 + lr) * 128 + ks * 16 + hh * 8);
;       acc = MFMA32(a, qf[ks], acc);
;     }
; #pragma unroll
;     for (int e = 0; e < 16; ++e) {
;       int kidx = kt * 32 + crow(e, hh);
;       g[kt][e] = (f2ord(acc[e]) & ~127u) | (unsigned)(127 - kidx);
;     }
	v_mfma_f32_32x32x16_bf16 v[128:143], v[144:147], v[176:179], 0
	s_waitcnt vmcnt(6)
	v_mfma_f32_32x32x16_bf16 v[128:143], v[148:151], v[180:183], v[128:143]
	s_waitcnt vmcnt(5)
	v_mfma_f32_32x32x16_bf16 v[128:143], v[152:155], v[184:187], v[128:143]
	s_waitcnt vmcnt(4)
	v_mfma_f32_32x32x16_bf16 v[128:143], v[156:159], v[188:191], v[128:143]
	s_waitcnt vmcnt(3)
	v_mfma_f32_32x32x16_bf16 v[128:143], v[160:163], v[192:195], v[128:143]
	s_waitcnt vmcnt(2)
	v_mfma_f32_32x32x16_bf16 v[128:143], v[164:167], v[196:199], v[128:143]
	s_waitcnt vmcnt(1)
	v_mfma_f32_32x32x16_bf16 v[128:143], v[168:171], v[200:203], v[128:143]
	s_waitcnt vmcnt(0)
	v_mfma_f32_32x32x16_bf16 v[128:143], v[172:175], v[204:207], v[128:143]
	s_add_u32 s4, s0, 90112
	s_addc_u32 s5, s1, 0
	global_load_dwordx4 v[144:147], v238, s[4:5] offset:0
	global_load_dwordx4 v[148:151], v238, s[4:5] offset:32
	global_load_dwordx4 v[152:155], v238, s[4:5] offset:64
	global_load_dwordx4 v[156:159], v238, s[4:5] offset:96
	global_load_dwordx4 v[160:163], v238, s[4:5] offset:128
	global_load_dwordx4 v[164:167], v238, s[4:5] offset:160
	global_load_dwordx4 v[168:171], v238, s[4:5] offset:192
	global_load_dwordx4 v[172:175], v238, s[4:5] offset:224
	s_nop 7
	s_nop 3
	v_ashrrev_i32_e32 v230, 31, v128
	v_or_b32_e32 v230, 0x80000000, v230
	v_xor_b32_e32 v229, v230, v128
	v_and_b32_e32 v229, 0xffffff80, v229
	v_or_b32_e32 v100, v229, v213
	v_ashrrev_i32_e32 v230, 31, v129
	v_or_b32_e32 v230, 0x80000000, v230
	v_xor_b32_e32 v229, v230, v129
	v_and_b32_e32 v229, 0xffffff80, v229
	v_or_b32_e32 v89, v229, v214
	v_ashrrev_i32_e32 v230, 31, v130
	v_or_b32_e32 v230, 0x80000000, v230
	v_xor_b32_e32 v229, v230, v130
	v_and_b32_e32 v229, 0xffffff80, v229
	v_or_b32_e32 v110, v229, v215
	v_ashrrev_i32_e32 v230, 31, v131
	v_or_b32_e32 v230, 0x80000000, v230
	v_xor_b32_e32 v229, v230, v131
	v_and_b32_e32 v229, 0xffffff80, v229
	v_or_b32_e32 v108, v229, v216
	v_ashrrev_i32_e32 v230, 31, v132
	v_or_b32_e32 v230, 0x80000000, v230
	v_xor_b32_e32 v229, v230, v132
	v_and_b32_e32 v229, 0xffffff80, v229
	v_or_b32_e32 v113, v229, v217
	v_ashrrev_i32_e32 v230, 31, v133
	v_or_b32_e32 v230, 0x80000000, v230
	v_xor_b32_e32 v229, v230, v133
	v_and_b32_e32 v229, 0xffffff80, v229
	v_or_b32_e32 v103, v229, v218
	v_ashrrev_i32_e32 v230, 31, v134
	v_or_b32_e32 v230, 0x80000000, v230
	v_xor_b32_e32 v229, v230, v134
	v_and_b32_e32 v229, 0xffffff80, v229
	v_or_b32_e32 v83, v229, v219
	v_ashrrev_i32_e32 v230, 31, v135
	v_or_b32_e32 v230, 0x80000000, v230
	v_xor_b32_e32 v229, v230, v135
	v_and_b32_e32 v229, 0xffffff80, v229
	v_or_b32_e32 v97, v229, v220
	v_ashrrev_i32_e32 v230, 31, v136
	v_or_b32_e32 v230, 0x80000000, v230
	v_xor_b32_e32 v229, v230, v136
	v_and_b32_e32 v229, 0xffffff80, v229
	v_or_b32_e32 v117, v229, v221
	v_ashrrev_i32_e32 v230, 31, v137
	v_or_b32_e32 v230, 0x80000000, v230
	v_xor_b32_e32 v229, v230, v137
	v_and_b32_e32 v229, 0xffffff80, v229
	v_or_b32_e32 v77, v229, v222
	v_ashrrev_i32_e32 v230, 31, v138
	v_or_b32_e32 v230, 0x80000000, v230
	v_xor_b32_e32 v229, v230, v138
	v_and_b32_e32 v229, 0xffffff80, v229
	v_or_b32_e32 v70, v229, v223
	v_ashrrev_i32_e32 v230, 31, v139
	v_or_b32_e32 v230, 0x80000000, v230
	v_xor_b32_e32 v229, v230, v139
	v_and_b32_e32 v229, 0xffffff80, v229
	v_or_b32_e32 v116, v229, v224
	v_ashrrev_i32_e32 v230, 31, v140
	v_or_b32_e32 v230, 0x80000000, v230
	v_xor_b32_e32 v229, v230, v140
	v_and_b32_e32 v229, 0xffffff80, v229
	v_or_b32_e32 v102, v229, v225
	v_ashrrev_i32_e32 v230, 31, v141
	v_or_b32_e32 v230, 0x80000000, v230
	v_xor_b32_e32 v229, v230, v141
	v_and_b32_e32 v229, 0xffffff80, v229
	v_or_b32_e32 v88, v229, v226
	v_ashrrev_i32_e32 v230, 31, v142
	v_or_b32_e32 v230, 0x80000000, v230
	v_xor_b32_e32 v229, v230, v142
	v_and_b32_e32 v229, 0xffffff80, v229
	v_or_b32_e32 v92, v229, v227
	v_ashrrev_i32_e32 v230, 31, v143
	v_or_b32_e32 v230, 0x80000000, v230
	v_xor_b32_e32 v229, v230, v143
	v_and_b32_e32 v229, 0xffffff80, v229
	v_or_b32_e32 v87, v229, v228
	v_subrev_u32_e32 v213, 32, v213
	v_subrev_u32_e32 v214, 32, v214
	v_subrev_u32_e32 v215, 32, v215
	v_subrev_u32_e32 v216, 32, v216
	v_subrev_u32_e32 v217, 32, v217
	v_subrev_u32_e32 v218, 32, v218
	v_subrev_u32_e32 v219, 32, v219
	v_subrev_u32_e32 v220, 32, v220
	v_subrev_u32_e32 v221, 32, v221
	v_subrev_u32_e32 v222, 32, v222
	v_subrev_u32_e32 v223, 32, v223
	v_subrev_u32_e32 v224, 32, v224
	v_subrev_u32_e32 v225, 32, v225
	v_subrev_u32_e32 v226, 32, v226
	v_subrev_u32_e32 v227, 32, v227
	v_subrev_u32_e32 v228, 32, v228
	v_max_u32_e32 v104, v100, v89
	v_min_u32_e32 v89, v100, v89
	v_min_u32_e32 v100, v110, v108
	v_max_u32_e32 v108, v110, v108
	v_max_u32_e32 v110, v113, v103
	v_min_u32_e32 v103, v113, v103
	v_min_u32_e32 v113, v83, v97
	v_max_u32_e32 v97, v83, v97
	v_max_u32_e32 v83, v117, v77
	v_min_u32_e32 v77, v117, v77
	v_min_u32_e32 v117, v70, v116
	v_max_u32_e32 v116, v70, v116
	v_max_u32_e32 v70, v102, v88
	v_min_u32_e32 v88, v102, v88
	v_min_u32_e32 v102, v92, v87
	v_max_u32_e32 v87, v92, v87
	v_max_u32_e32 v92, v104, v100
	v_min_u32_e32 v100, v104, v100
	v_max_u32_e32 v104, v89, v108
	v_min_u32_e32 v108, v89, v108
	v_min_u32_e32 v89, v110, v113
	v_max_u32_e32 v113, v110, v113
	v_min_u32_e32 v110, v103, v97
	v_max_u32_e32 v97, v103, v97
	v_max_u32_e32 v103, v83, v117
	v_min_u32_e32 v117, v83, v117
	v_max_u32_e32 v83, v77, v116
	v_min_u32_e32 v116, v77, v116
	v_min_u32_e32 v77, v70, v102
	v_max_u32_e32 v102, v70, v102
	v_min_u32_e32 v70, v88, v87
	v_max_u32_e32 v87, v88, v87
	v_max_u32_e32 v88, v92, v104
	v_min_u32_e32 v104, v92, v104
	v_max_u32_e32 v92, v100, v108
	v_min_u32_e32 v108, v100, v108
	v_min_u32_e32 v100, v89, v110
; template <int LOGN>
; DI void bitonic_sort_desc(unsigned (&a)[1 << LOGN]) {
;   constexpr int N = 1 << LOGN;
; #pragma unroll
;   for (int ks = 1; ks <= LOGN; ++ks)
; #pragma unroll
;     ...
; #pragma unroll
;       for (int i = 0; i < N; ++i) {
;         const int k = 1 << ks, j = 1 << js, l = i ^ j;
;         if (l > i) {
;           const bool desc = ((i & k) == 0) || (ks == LOGN);
;           const unsigned x = a[i], y = a[l];
;           const unsigned hi = max(x, y), lo = min(x, y);
;           a[i] = desc ? hi : lo;
;           a[l] = desc ? lo : hi;
;         }
;       }
; }
	v_max_u32_e32 v110, v89, v110
	v_min_u32_e32 v89, v113, v97
	v_max_u32_e32 v97, v113, v97
	v_max_u32_e32 v113, v103, v83
	v_min_u32_e32 v83, v103, v83
	v_max_u32_e32 v103, v117, v116
	v_min_u32_e32 v116, v117, v116
	v_min_u32_e32 v117, v77, v70
	v_max_u32_e32 v70, v77, v70
	v_min_u32_e32 v77, v102, v87
	v_max_u32_e32 v87, v102, v87
	v_max_u32_e32 v102, v88, v100
	v_min_u32_e32 v100, v88, v100
	v_max_u32_e32 v88, v104, v110
	v_min_u32_e32 v110, v104, v110
	v_max_u32_e32 v104, v92, v89
	v_min_u32_e32 v89, v92, v89
	v_max_u32_e32 v92, v108, v97
	v_min_u32_e32 v97, v108, v97
	v_min_u32_e32 v108, v113, v117
	v_max_u32_e32 v117, v113, v117
	v_min_u32_e32 v113, v83, v70
	v_max_u32_e32 v70, v83, v70
	v_min_u32_e32 v83, v103, v77
	v_max_u32_e32 v77, v103, v77
	v_min_u32_e32 v103, v116, v87
	v_max_u32_e32 v87, v116, v87
	v_max_u32_e32 v116, v102, v104
	v_min_u32_e32 v104, v102, v104
	v_max_u32_e32 v102, v88, v92
	v_min_u32_e32 v92, v88, v92
	v_max_u32_e32 v88, v100, v89
	v_min_u32_e32 v89, v100, v89
	v_max_u32_e32 v100, v110, v97
	v_min_u32_e32 v97, v110, v97
	v_min_u32_e32 v110, v108, v83
	v_max_u32_e32 v83, v108, v83
	v_min_u32_e32 v108, v113, v103
	v_max_u32_e32 v103, v113, v103
	v_min_u32_e32 v113, v117, v77
	v_max_u32_e32 v77, v117, v77
	v_min_u32_e32 v117, v70, v87
	v_max_u32_e32 v87, v70, v87
	v_max_u32_e32 v70, v116, v102
	v_min_u32_e32 v102, v116, v102
	v_max_u32_e32 v116, v104, v92
	v_min_u32_e32 v92, v104, v92
	v_max_u32_e32 v104, v88, v100
	v_min_u32_e32 v100, v88, v100
	v_max_u32_e32 v88, v89, v97
	v_min_u32_e32 v97, v89, v97
	v_min_u32_e32 v89, v110, v108
	v_max_u32_e32 v108, v110, v108
	v_min_u32_e32 v110, v83, v103
	v_max_u32_e32 v103, v83, v103
	v_min_u32_e32 v83, v113, v117
	v_max_u32_e32 v117, v113, v117
	v_min_u32_e32 v113, v77, v87
	v_max_u32_e32 v87, v77, v87
	v_max_u32_e32 v77, v70, v89
	v_min_u32_e32 v89, v70, v89
	v_max_u32_e32 v70, v102, v108
	v_min_u32_e32 v108, v102, v108
	v_max_u32_e32 v102, v116, v110
	v_min_u32_e32 v110, v116, v110
	v_max_u32_e32 v116, v92, v103
	v_min_u32_e32 v103, v92, v103
	v_max_u32_e32 v92, v104, v83
	v_min_u32_e32 v83, v104, v83
	v_max_u32_e32 v104, v100, v117
	v_min_u32_e32 v117, v100, v117
	v_max_u32_e32 v100, v88, v113
	v_min_u32_e32 v113, v88, v113
	v_max_u32_e32 v88, v97, v87
	v_min_u32_e32 v87, v97, v87
	v_max_u32_e32 v97, v77, v92
	v_min_u32_e32 v92, v77, v92
	v_max_u32_e32 v77, v70, v104
	v_min_u32_e32 v104, v70, v104
	v_max_u32_e32 v70, v102, v100
	v_min_u32_e32 v100, v102, v100
	v_max_u32_e32 v102, v116, v88
	v_min_u32_e32 v88, v116, v88
	v_max_u32_e32 v116, v89, v83
	v_min_u32_e32 v83, v89, v83
	v_max_u32_e32 v89, v108, v117
	v_min_u32_e32 v117, v108, v117
	v_max_u32_e32 v108, v110, v113
	v_min_u32_e32 v113, v110, v113
	v_max_u32_e32 v110, v103, v87
	v_min_u32_e32 v87, v103, v87
	v_max_u32_e32 v103, v97, v70
	v_min_u32_e32 v70, v97, v70
	v_max_u32_e32 v97, v77, v102
	v_min_u32_e32 v102, v77, v102
	v_max_u32_e32 v77, v92, v100
	v_min_u32_e32 v100, v92, v100
	v_max_u32_e32 v92, v104, v88
	v_min_u32_e32 v88, v104, v88
	v_max_u32_e32 v104, v116, v108
	v_min_u32_e32 v108, v116, v108
	v_max_u32_e32 v116, v89, v110
	v_min_u32_e32 v110, v89, v110
	v_max_u32_e32 v89, v83, v113
	v_min_u32_e32 v113, v83, v113
	v_max_u32_e32 v83, v117, v87
	v_min_u32_e32 v87, v117, v87
	v_max_u32_e32 v117, v103, v97
	v_min_u32_e32 v97, v103, v97
	v_max_u32_e32 v103, v70, v102
	v_min_u32_e32 v102, v70, v102
	v_max_u32_e32 v70, v77, v92
	v_min_u32_e32 v92, v77, v92
	v_max_u32_e32 v77, v100, v88
	v_min_u32_e32 v88, v100, v88
	v_max_u32_e32 v100, v104, v116
	v_min_u32_e32 v116, v104, v116
	v_max_u32_e32 v104, v108, v110
	v_min_u32_e32 v110, v108, v110
	v_max_u32_e32 v108, v89, v83
	v_min_u32_e32 v83, v89, v83
	v_max_u32_e32 v89, v113, v87
	v_min_u32_e32 v87, v113, v87
	s_waitcnt vmcnt(7)
	v_mfma_f32_32x32x16_bf16 v[128:143], v[144:147], v[176:179], 0
	s_waitcnt vmcnt(6)
	v_mfma_f32_32x32x16_bf16 v[128:143], v[148:151], v[180:183], v[128:143]
	s_waitcnt vmcnt(5)
	v_mfma_f32_32x32x16_bf16 v[128:143], v[152:155], v[184:187], v[128:143]
	s_waitcnt vmcnt(4)
	v_mfma_f32_32x32x16_bf16 v[128:143], v[156:159], v[188:191], v[128:143]
	s_waitcnt vmcnt(3)
	v_mfma_f32_32x32x16_bf16 v[128:143], v[160:163], v[192:195], v[128:143]
	s_waitcnt vmcnt(2)
	v_mfma_f32_32x32x16_bf16 v[128:143], v[164:167], v[196:199], v[128:143]
	s_waitcnt vmcnt(1)
	v_mfma_f32_32x32x16_bf16 v[128:143], v[168:171], v[200:203], v[128:143]
	s_waitcnt vmcnt(0)
; #define MFMA32(a, b, c) __builtin_amdgcn_mfma_f32_32x32x16_bf16((a), (b), (c), 0, 0, 0)
; DI int crow(int i, int hh) { return (i & 3) + 8 * (i >> 2) + 4 * hh; }
; DI void peer_top16(const u16* __restrict__ PQrow, const u16* __restrict__ SK, unsigned (&top)[16], int lr, int hh) {
;   bf16x8 qf[8];
; #pragma unroll
;   for (int ks = 0; ks < 8; ++ks) qf[ks] = *(const bf16x8*)(PQrow + ks * 16 + hh * 8);
;   unsigned g[4][16];
; #pragma unroll
;   for (int kt = 0; kt < 4; ++kt) {
;     f32x16 acc;
; #pragma unroll
;     for (int e = 0; e < 16; ++e) acc[e] = 0.f;
; #pragma unroll
;     for (int ks = 0; ks < 8; ++ks) {
;       bf16x8 a = *(const bf16x8*)(SK + (size_t)(kt * 32 + lr) * 128 + ks * 16 + hh * 8);
;       acc = MFMA32(a, qf[ks], acc);
;     }
; #pragma unroll
;     for (int e = 0; e < 16; ++e) {
;       int kidx = kt * 32 + crow(e, hh);
;       g[kt][e] = (f2ord(acc[e]) & ~127u) | (unsigned)(127 - kidx);
;     }
	v_mfma_f32_32x32x16_bf16 v[128:143], v[172:175], v[204:207], v[128:143]
	global_load_dwordx4 v[176:179], v239, s[2:3] offset:768
	global_load_dwordx4 v[180:183], v239, s[2:3] offset:800
	global_load_dwordx4 v[184:187], v239, s[2:3] offset:832
	global_load_dwordx4 v[188:191], v239, s[2:3] offset:864
	global_load_dwordx4 v[192:195], v239, s[2:3] offset:896
	global_load_dwordx4 v[196:199], v239, s[2:3] offset:928
	global_load_dwordx4 v[200:203], v239, s[2:3] offset:960
	global_load_dwordx4 v[204:207], v239, s[2:3] offset:992
	s_add_u32 s4, s0, 98304
	s_addc_u32 s5, s1, 0
	global_load_dwordx4 v[144:147], v238, s[4:5] offset:0
	global_load_dwordx4 v[148:151], v238, s[4:5] offset:32
	global_load_dwordx4 v[152:155], v238, s[4:5] offset:64
	global_load_dwordx4 v[156:159], v238, s[4:5] offset:96
	global_load_dwordx4 v[160:163], v238, s[4:5] offset:128
	global_load_dwordx4 v[164:167], v238, s[4:5] offset:160
	global_load_dwordx4 v[168:171], v238, s[4:5] offset:192
	global_load_dwordx4 v[172:175], v238, s[4:5] offset:224
	s_nop 7
	s_nop 3
	v_ashrrev_i32_e32 v230, 31, v128
	v_or_b32_e32 v230, 0x80000000, v230
	v_xor_b32_e32 v229, v230, v128
	v_and_b32_e32 v229, 0xffffff80, v229
	v_or_b32_e32 v113, v229, v213
	v_ashrrev_i32_e32 v230, 31, v129
	v_or_b32_e32 v230, 0x80000000, v230
	v_xor_b32_e32 v229, v230, v129
	v_and_b32_e32 v229, 0xffffff80, v229
	v_or_b32_e32 v84, v229, v214
	v_ashrrev_i32_e32 v230, 31, v130
	v_or_b32_e32 v230, 0x80000000, v230
	v_xor_b32_e32 v229, v230, v130
	v_and_b32_e32 v229, 0xffffff80, v229
	v_or_b32_e32 v74, v229, v215
	v_ashrrev_i32_e32 v230, 31, v131
	v_or_b32_e32 v230, 0x80000000, v230
	v_xor_b32_e32 v229, v230, v131
	v_and_b32_e32 v229, 0xffffff80, v229
	v_or_b32_e32 v82, v229, v216
	v_ashrrev_i32_e32 v230, 31, v132
	v_or_b32_e32 v230, 0x80000000, v230
	v_xor_b32_e32 v229, v230, v132
	v_and_b32_e32 v229, 0xffffff80, v229
	v_or_b32_e32 v79, v229, v217
	v_ashrrev_i32_e32 v230, 31, v133
	v_or_b32_e32 v230, 0x80000000, v230
	v_xor_b32_e32 v229, v230, v133
	v_and_b32_e32 v229, 0xffffff80, v229
	v_or_b32_e32 v93, v229, v218
	v_ashrrev_i32_e32 v230, 31, v134
	v_or_b32_e32 v230, 0x80000000, v230
	v_xor_b32_e32 v229, v230, v134
	v_and_b32_e32 v229, 0xffffff80, v229
	v_or_b32_e32 v75, v229, v219
	v_ashrrev_i32_e32 v230, 31, v135
	v_or_b32_e32 v230, 0x80000000, v230
	v_xor_b32_e32 v229, v230, v135
	v_and_b32_e32 v229, 0xffffff80, v229
	v_or_b32_e32 v95, v229, v220
	v_ashrrev_i32_e32 v230, 31, v136
	v_or_b32_e32 v230, 0x80000000, v230
	v_xor_b32_e32 v229, v230, v136
	v_and_b32_e32 v229, 0xffffff80, v229
	v_or_b32_e32 v80, v229, v221
	v_ashrrev_i32_e32 v230, 31, v137
	v_or_b32_e32 v230, 0x80000000, v230
	v_xor_b32_e32 v229, v230, v137
	v_and_b32_e32 v229, 0xffffff80, v229
	v_or_b32_e32 v76, v229, v222
	v_ashrrev_i32_e32 v230, 31, v138
	v_or_b32_e32 v230, 0x80000000, v230
	v_xor_b32_e32 v229, v230, v138
	v_and_b32_e32 v229, 0xffffff80, v229
	v_or_b32_e32 v78, v229, v223
	v_ashrrev_i32_e32 v230, 31, v139
	v_or_b32_e32 v230, 0x80000000, v230
	v_xor_b32_e32 v229, v230, v139
	v_and_b32_e32 v229, 0xffffff80, v229
	v_or_b32_e32 v71, v229, v224
	v_ashrrev_i32_e32 v230, 31, v140
	v_or_b32_e32 v230, 0x80000000, v230
	v_xor_b32_e32 v229, v230, v140
	v_and_b32_e32 v229, 0xffffff80, v229
	v_or_b32_e32 v73, v229, v225
	v_ashrrev_i32_e32 v230, 31, v141
	v_or_b32_e32 v230, 0x80000000, v230
	v_xor_b32_e32 v229, v230, v141
	v_and_b32_e32 v229, 0xffffff80, v229
	v_or_b32_e32 v69, v229, v226
	v_ashrrev_i32_e32 v230, 31, v142
	v_or_b32_e32 v230, 0x80000000, v230
	v_xor_b32_e32 v229, v230, v142
	v_and_b32_e32 v229, 0xffffff80, v229
	v_or_b32_e32 v99, v229, v227
	v_ashrrev_i32_e32 v230, 31, v143
	v_or_b32_e32 v230, 0x80000000, v230
	v_xor_b32_e32 v229, v230, v143
	v_and_b32_e32 v229, 0xffffff80, v229
	v_or_b32_e32 v72, v229, v228
	v_max_u32_e32 v94, v113, v84
	v_min_u32_e32 v84, v113, v84
	v_min_u32_e32 v113, v74, v82
	v_max_u32_e32 v82, v74, v82
	v_max_u32_e32 v74, v79, v93
	v_min_u32_e32 v93, v79, v93
	v_min_u32_e32 v79, v75, v95
	v_max_u32_e32 v95, v75, v95
	v_max_u32_e32 v75, v80, v76
	v_min_u32_e32 v76, v80, v76
	v_min_u32_e32 v80, v78, v71
	v_max_u32_e32 v71, v78, v71
	v_max_u32_e32 v78, v73, v69
	v_min_u32_e32 v69, v73, v69
	v_min_u32_e32 v73, v99, v72
	v_max_u32_e32 v72, v99, v72
	v_max_u32_e32 v99, v94, v113
	v_min_u32_e32 v113, v94, v113
	v_max_u32_e32 v94, v84, v82
	v_min_u32_e32 v82, v84, v82
	v_min_u32_e32 v84, v74, v79
	v_max_u32_e32 v79, v74, v79
	v_min_u32_e32 v74, v93, v95
	v_max_u32_e32 v95, v93, v95
	v_max_u32_e32 v93, v75, v80
	v_min_u32_e32 v80, v75, v80
	v_max_u32_e32 v75, v76, v71
	v_min_u32_e32 v71, v76, v71
	v_min_u32_e32 v76, v78, v73
	v_max_u32_e32 v73, v78, v73
	v_min_u32_e32 v78, v69, v72
	v_max_u32_e32 v72, v69, v72
	v_max_u32_e32 v69, v99, v94
	v_min_u32_e32 v94, v99, v94
	v_max_u32_e32 v99, v113, v82
	v_min_u32_e32 v82, v113, v82
	v_min_u32_e32 v113, v84, v74
	v_max_u32_e32 v74, v84, v74
	v_min_u32_e32 v84, v79, v95
	v_max_u32_e32 v95, v79, v95
	v_max_u32_e32 v79, v93, v75
	v_min_u32_e32 v75, v93, v75
	v_max_u32_e32 v93, v80, v71
	v_min_u32_e32 v71, v80, v71
	v_min_u32_e32 v80, v76, v78
	v_max_u32_e32 v78, v76, v78
	v_min_u32_e32 v76, v73, v72
	v_max_u32_e32 v72, v73, v72
	v_max_u32_e32 v73, v69, v113
	v_min_u32_e32 v113, v69, v113
	v_max_u32_e32 v69, v94, v74
	v_min_u32_e32 v74, v94, v74
	v_max_u32_e32 v94, v99, v84
	v_min_u32_e32 v84, v99, v84
	v_max_u32_e32 v99, v82, v95
	v_min_u32_e32 v95, v82, v95
	v_min_u32_e32 v82, v79, v80
	v_max_u32_e32 v80, v79, v80
	v_min_u32_e32 v79, v75, v78
	v_max_u32_e32 v78, v75, v78
	v_min_u32_e32 v75, v93, v76
	v_max_u32_e32 v76, v93, v76
	v_min_u32_e32 v93, v71, v72
	v_max_u32_e32 v72, v71, v72
; template <int LOGN>
; DI void bitonic_sort_desc(unsigned (&a)[1 << LOGN]) {
;   constexpr int N = 1 << LOGN;
; #pragma unroll
;   for (int ks = 1; ks <= LOGN; ++ks)
; #pragma unroll
;     ...
; #pragma unroll
;       for (int i = 0; i < N; ++i) {
;         const int k = 1 << ks, j = 1 << js, l = i ^ j;
;         if (l > i) {
;           const bool desc = ((i & k) == 0) || (ks == LOGN);
;           const unsigned x = a[i], y = a[l];
;           const unsigned hi = max(x, y), lo = min(x, y);
;           a[i] = desc ? hi : lo;
;           a[l] = desc ? lo : hi;
;         }
;       }
; }
; DI void merge_top16(unsigned (&a)[16], const unsigned (&b)[16]) {
; #pragma unroll
;   for (int i = 0; i < 16; ++i) a[i] = max(a[i], b[15 - i]);
; #pragma unroll
;     ...
; #pragma unroll
;     for (int i = 0; i < 16; ++i) {
;       const int j = 1 << js, l = i ^ j;
;       if (l > i) {
;         const unsigned x = a[i], y = a[l];
;         a[i] = max(x, y);
;         a[l] = min(x, y);
;       }
;     }
; }
	v_max_u32_e32 v71, v73, v94
	v_min_u32_e32 v94, v73, v94
	v_max_u32_e32 v73, v69, v99
	v_min_u32_e32 v99, v69, v99
	v_max_u32_e32 v69, v113, v84
	v_min_u32_e32 v84, v113, v84
	v_max_u32_e32 v113, v74, v95
	v_min_u32_e32 v95, v74, v95
	v_min_u32_e32 v74, v82, v75
	v_max_u32_e32 v75, v82, v75
	v_min_u32_e32 v82, v79, v93
	v_max_u32_e32 v93, v79, v93
	v_min_u32_e32 v79, v80, v76
	v_max_u32_e32 v76, v80, v76
	v_min_u32_e32 v80, v78, v72
	v_max_u32_e32 v72, v78, v72
	v_max_u32_e32 v78, v71, v73
	v_min_u32_e32 v73, v71, v73
	v_max_u32_e32 v71, v94, v99
	v_min_u32_e32 v99, v94, v99
	v_max_u32_e32 v94, v69, v113
	v_min_u32_e32 v113, v69, v113
	v_max_u32_e32 v69, v84, v95
	v_min_u32_e32 v95, v84, v95
	v_min_u32_e32 v84, v74, v82
	v_max_u32_e32 v82, v74, v82
	v_min_u32_e32 v74, v75, v93
	v_max_u32_e32 v93, v75, v93
	v_min_u32_e32 v75, v79, v80
	v_max_u32_e32 v80, v79, v80
	v_min_u32_e32 v79, v76, v72
	v_max_u32_e32 v72, v76, v72
	v_max_u32_e32 v76, v78, v84
	v_min_u32_e32 v84, v78, v84
	v_max_u32_e32 v78, v73, v82
	v_min_u32_e32 v82, v73, v82
	v_max_u32_e32 v73, v71, v74
	v_min_u32_e32 v74, v71, v74
	v_max_u32_e32 v71, v99, v93
	v_min_u32_e32 v93, v99, v93
	v_max_u32_e32 v99, v94, v75
	v_min_u32_e32 v75, v94, v75
	v_max_u32_e32 v94, v113, v80
	v_min_u32_e32 v80, v113, v80
	v_max_u32_e32 v113, v69, v79
	v_min_u32_e32 v79, v69, v79
	v_max_u32_e32 v69, v95, v72
	v_min_u32_e32 v72, v95, v72
	v_max_u32_e32 v95, v76, v99
	v_min_u32_e32 v99, v76, v99
	v_max_u32_e32 v76, v78, v94
	v_min_u32_e32 v94, v78, v94
	v_max_u32_e32 v78, v73, v113
	v_min_u32_e32 v113, v73, v113
	v_max_u32_e32 v73, v71, v69
	v_min_u32_e32 v69, v71, v69
	v_max_u32_e32 v71, v84, v75
	v_min_u32_e32 v75, v84, v75
	v_max_u32_e32 v84, v82, v80
	v_min_u32_e32 v80, v82, v80
	v_max_u32_e32 v82, v74, v79
	v_min_u32_e32 v79, v74, v79
	v_max_u32_e32 v74, v93, v72
	v_min_u32_e32 v72, v93, v72
	v_max_u32_e32 v93, v95, v78
	v_min_u32_e32 v78, v95, v78
	v_max_u32_e32 v95, v76, v73
	v_min_u32_e32 v73, v76, v73
	v_max_u32_e32 v76, v99, v113
	v_min_u32_e32 v113, v99, v113
	v_max_u32_e32 v99, v94, v69
	v_min_u32_e32 v69, v94, v69
	v_max_u32_e32 v94, v71, v82
	v_min_u32_e32 v82, v71, v82
	v_max_u32_e32 v71, v84, v74
	v_min_u32_e32 v74, v84, v74
	v_max_u32_e32 v84, v75, v79
	v_min_u32_e32 v79, v75, v79
	v_max_u32_e32 v75, v80, v72
	v_min_u32_e32 v72, v80, v72
	v_max_u32_e32 v80, v93, v95
	v_min_u32_e32 v95, v93, v95
	v_max_u32_e32 v93, v78, v73
	v_min_u32_e32 v73, v78, v73
	v_max_u32_e32 v78, v76, v99
	v_min_u32_e32 v99, v76, v99
	v_max_u32_e32 v76, v113, v69
	v_min_u32_e32 v69, v113, v69
	v_max_u32_e32 v113, v94, v71
	v_min_u32_e32 v71, v94, v71
	v_max_u32_e32 v94, v82, v74
	v_min_u32_e32 v74, v82, v74
	v_max_u32_e32 v82, v84, v75
	v_min_u32_e32 v75, v84, v75
	v_max_u32_e32 v84, v79, v72
	v_min_u32_e32 v72, v79, v72
	v_max_u32_e32 v79, v117, v72
	v_max_u32_e32 v117, v97, v84
	v_max_u32_e32 v97, v103, v75
	v_max_u32_e32 v103, v102, v82
	v_max_u32_e32 v102, v70, v74
	v_max_u32_e32 v70, v92, v94
	v_max_u32_e32 v92, v77, v71
	v_max_u32_e32 v77, v88, v113
	v_max_u32_e32 v88, v100, v69
	v_max_u32_e32 v100, v116, v76
	v_max_u32_e32 v116, v104, v99
	v_max_u32_e32 v104, v110, v78
	v_max_u32_e32 v110, v108, v73
	v_max_u32_e32 v108, v83, v93
	v_max_u32_e32 v83, v89, v95
	v_max_u32_e32 v89, v87, v80
	v_max_u32_e32 v72, v79, v88
	v_min_u32_e32 v88, v79, v88
	v_max_u32_e32 v79, v117, v100
	v_min_u32_e32 v100, v117, v100
	v_max_u32_e32 v117, v97, v116
	v_min_u32_e32 v116, v97, v116
	v_max_u32_e32 v97, v103, v104
	v_min_u32_e32 v104, v103, v104
	v_max_u32_e32 v103, v102, v110
	v_min_u32_e32 v110, v102, v110
	v_max_u32_e32 v102, v70, v108
	v_min_u32_e32 v108, v70, v108
	v_max_u32_e32 v70, v92, v83
	v_min_u32_e32 v83, v92, v83
	v_max_u32_e32 v92, v77, v89
	v_min_u32_e32 v89, v77, v89
	v_max_u32_e32 v77, v72, v103
	v_min_u32_e32 v103, v72, v103
	v_max_u32_e32 v72, v79, v102
	v_min_u32_e32 v102, v79, v102
	v_max_u32_e32 v79, v117, v70
	v_min_u32_e32 v70, v117, v70
	v_max_u32_e32 v117, v97, v92
	v_min_u32_e32 v92, v97, v92
	v_max_u32_e32 v97, v88, v110
	v_min_u32_e32 v110, v88, v110
	v_max_u32_e32 v88, v100, v108
	v_min_u32_e32 v108, v100, v108
	v_max_u32_e32 v100, v116, v83
	v_min_u32_e32 v83, v116, v83
	v_max_u32_e32 v116, v104, v89
	v_min_u32_e32 v89, v104, v89
	v_max_u32_e32 v104, v77, v79
	v_min_u32_e32 v79, v77, v79
	v_max_u32_e32 v77, v72, v117
	v_min_u32_e32 v117, v72, v117
	v_max_u32_e32 v72, v103, v70
	v_min_u32_e32 v70, v103, v70
	v_max_u32_e32 v103, v102, v92
	v_min_u32_e32 v92, v102, v92
	v_max_u32_e32 v102, v97, v100
	v_min_u32_e32 v100, v97, v100
	v_max_u32_e32 v97, v88, v116
	v_min_u32_e32 v116, v88, v116
	v_max_u32_e32 v88, v110, v83
	v_min_u32_e32 v83, v110, v83
	v_max_u32_e32 v110, v108, v89
	v_min_u32_e32 v89, v108, v89
	v_max_u32_e32 v108, v104, v77
	v_min_u32_e32 v77, v104, v77
	v_max_u32_e32 v104, v79, v117
	v_min_u32_e32 v117, v79, v117
	v_max_u32_e32 v79, v72, v103
	v_min_u32_e32 v103, v72, v103
	v_max_u32_e32 v72, v70, v92
	v_min_u32_e32 v92, v70, v92
	v_max_u32_e32 v70, v102, v97
	v_min_u32_e32 v97, v102, v97
	v_max_u32_e32 v102, v100, v116
	v_min_u32_e32 v116, v100, v116
	v_max_u32_e32 v100, v88, v110
	v_min_u32_e32 v110, v88, v110
	v_max_u32_e32 v88, v83, v89
	v_min_u32_e32 v89, v83, v89
	v_max_u32_e32 v83, v101, v89
	v_max_u32_e32 v101, v96, v88
	v_max_u32_e32 v96, v106, v110
	v_max_u32_e32 v106, v109, v100
	v_max_u32_e32 v109, v85, v116
	v_max_u32_e32 v85, v112, v102
	v_max_u32_e32 v112, v111, v97
	v_max_u32_e32 v111, v98, v70
	v_max_u32_e32 v98, v115, v92
	v_max_u32_e32 v115, v91, v72
	v_max_u32_e32 v91, v107, v103
	v_max_u32_e32 v107, v81, v79
	v_max_u32_e32 v81, v105, v117
; #define MFMA32(a, b, c) __builtin_amdgcn_mfma_f32_32x32x16_bf16((a), (b), (c), 0, 0, 0)
; DI int crow(int i, int hh) { return (i & 3) + 8 * (i >> 2) + 4 * hh; }
; DI void merge_top16(unsigned (&a)[16], const unsigned (&b)[16]) {
; #pragma unroll
;   for (int i = 0; i < 16; ++i) a[i] = max(a[i], b[15 - i]);
; #pragma unroll
;     ...
; #pragma unroll
;     for (int i = 0; i < 16; ++i) {
;       const int j = 1 << js, l = i ^ j;
;       if (l > i) {
;         const unsigned x = a[i], y = a[l];
;         a[i] = max(x, y);
;         a[l] = min(x, y);
;       }
;     }
; }
; DI void peer_top16(const u16* __restrict__ PQrow, const u16* __restrict__ SK, unsigned (&top)[16], int lr, int hh) {
;     ...
;   for (int kt = 0; kt < 4; ++kt) {
;     f32x16 acc;
; #pragma unroll
;     for (int e = 0; e < 16; ++e) acc[e] = 0.f;
; #pragma unroll
;     for (int ks = 0; ks < 8; ++ks) {
;       bf16x8 a = *(const bf16x8*)(SK + (size_t)(kt * 32 + lr) * 128 + ks * 16 + hh * 8);
;       acc = MFMA32(a, qf[ks], acc);
;     }
; #pragma unroll
;     for (int e = 0; e < 16; ++e) {
;       int kidx = kt * 32 + crow(e, hh);
;       g[kt][e] = (f2ord(acc[e]) & ~127u) | (unsigned)(127 - kidx);
;     }
	v_max_u32_e32 v105, v90, v104
	v_max_u32_e32 v90, v114, v77
	v_max_u32_e32 v114, v86, v108
	v_max_u32_e32 v89, v83, v98
	v_min_u32_e32 v98, v83, v98
	v_max_u32_e32 v83, v101, v115
	v_min_u32_e32 v115, v101, v115
	v_max_u32_e32 v101, v96, v91
	v_min_u32_e32 v91, v96, v91
	v_max_u32_e32 v96, v106, v107
	v_min_u32_e32 v107, v106, v107
	v_max_u32_e32 v106, v109, v81
	v_min_u32_e32 v81, v109, v81
	v_max_u32_e32 v109, v85, v105
	v_min_u32_e32 v105, v85, v105
	v_max_u32_e32 v85, v112, v90
	v_min_u32_e32 v90, v112, v90
	v_max_u32_e32 v112, v111, v114
	v_min_u32_e32 v114, v111, v114
	v_max_u32_e32 v111, v89, v106
	v_min_u32_e32 v106, v89, v106
	v_max_u32_e32 v89, v83, v109
	v_min_u32_e32 v109, v83, v109
	v_max_u32_e32 v83, v101, v85
	v_min_u32_e32 v85, v101, v85
	v_max_u32_e32 v101, v96, v112
	v_min_u32_e32 v112, v96, v112
	v_max_u32_e32 v96, v98, v81
	v_min_u32_e32 v81, v98, v81
	v_max_u32_e32 v98, v115, v105
	v_min_u32_e32 v105, v115, v105
	v_max_u32_e32 v115, v91, v90
	v_min_u32_e32 v90, v91, v90
	v_max_u32_e32 v91, v107, v114
	v_min_u32_e32 v114, v107, v114
	v_max_u32_e32 v107, v111, v83
	v_min_u32_e32 v83, v111, v83
	v_max_u32_e32 v111, v89, v101
	v_min_u32_e32 v101, v89, v101
	v_max_u32_e32 v89, v106, v85
	v_min_u32_e32 v85, v106, v85
	v_max_u32_e32 v106, v109, v112
	v_min_u32_e32 v112, v109, v112
	v_max_u32_e32 v109, v96, v115
	v_min_u32_e32 v115, v96, v115
	v_max_u32_e32 v96, v98, v91
	v_min_u32_e32 v91, v98, v91
	v_max_u32_e32 v98, v81, v90
	v_min_u32_e32 v90, v81, v90
	v_max_u32_e32 v81, v105, v114
	v_min_u32_e32 v114, v105, v114
	v_max_u32_e32 v105, v107, v111
	v_min_u32_e32 v111, v107, v111
	v_max_u32_e32 v107, v83, v101
	v_min_u32_e32 v101, v83, v101
	v_max_u32_e32 v83, v89, v106
	v_min_u32_e32 v106, v89, v106
	v_max_u32_e32 v89, v85, v112
	v_min_u32_e32 v112, v85, v112
	v_max_u32_e32 v85, v109, v96
	v_min_u32_e32 v96, v109, v96
	v_max_u32_e32 v109, v115, v91
	v_min_u32_e32 v91, v115, v91
	v_max_u32_e32 v115, v98, v81
	v_min_u32_e32 v81, v98, v81
	v_max_u32_e32 v98, v90, v114
	v_min_u32_e32 v114, v90, v114
	v_mov_b32_e32 v32, v105
	v_mov_b32_e32 v33, v111
	v_mov_b32_e32 v34, v107
	v_mov_b32_e32 v35, v101
	v_mov_b32_e32 v36, v83
	v_mov_b32_e32 v37, v106
	v_mov_b32_e32 v38, v89
	v_mov_b32_e32 v39, v112
	v_mov_b32_e32 v40, v85
	v_mov_b32_e32 v41, v96
	v_mov_b32_e32 v42, v109
	v_mov_b32_e32 v43, v91
	v_mov_b32_e32 v44, v115
	v_mov_b32_e32 v45, v81
	v_mov_b32_e32 v46, v98
	v_mov_b32_e32 v47, v114
	v_sub_u32_e32 v213, 127, v245
	v_sub_u32_e32 v214, 126, v245
	v_sub_u32_e32 v215, 125, v245
	v_sub_u32_e32 v216, 124, v245
	v_sub_u32_e32 v217, 119, v245
	v_sub_u32_e32 v218, 118, v245
	v_sub_u32_e32 v219, 117, v245
	v_sub_u32_e32 v220, 116, v245
	v_sub_u32_e32 v221, 111, v245
	v_sub_u32_e32 v222, 110, v245
	v_sub_u32_e32 v223, 109, v245
	v_sub_u32_e32 v224, 108, v245
	v_sub_u32_e32 v225, 103, v245
	v_sub_u32_e32 v226, 102, v245
	v_sub_u32_e32 v227, 101, v245
	v_sub_u32_e32 v228, 100, v245
	s_waitcnt vmcnt(7)
	v_mfma_f32_32x32x16_bf16 v[128:143], v[144:147], v[176:179], 0
	s_waitcnt vmcnt(6)
	v_mfma_f32_32x32x16_bf16 v[128:143], v[148:151], v[180:183], v[128:143]
	s_waitcnt vmcnt(5)
	v_mfma_f32_32x32x16_bf16 v[128:143], v[152:155], v[184:187], v[128:143]
	s_waitcnt vmcnt(4)
	v_mfma_f32_32x32x16_bf16 v[128:143], v[156:159], v[188:191], v[128:143]
	s_waitcnt vmcnt(3)
	v_mfma_f32_32x32x16_bf16 v[128:143], v[160:163], v[192:195], v[128:143]
	s_waitcnt vmcnt(2)
	v_mfma_f32_32x32x16_bf16 v[128:143], v[164:167], v[196:199], v[128:143]
	s_waitcnt vmcnt(1)
	v_mfma_f32_32x32x16_bf16 v[128:143], v[168:171], v[200:203], v[128:143]
	s_waitcnt vmcnt(0)
	v_mfma_f32_32x32x16_bf16 v[128:143], v[172:175], v[204:207], v[128:143]
	s_add_u32 s4, s0, 106496
	s_addc_u32 s5, s1, 0
	global_load_dwordx4 v[144:147], v238, s[4:5] offset:0
	global_load_dwordx4 v[148:151], v238, s[4:5] offset:32
	global_load_dwordx4 v[152:155], v238, s[4:5] offset:64
	global_load_dwordx4 v[156:159], v238, s[4:5] offset:96
	global_load_dwordx4 v[160:163], v238, s[4:5] offset:128
	global_load_dwordx4 v[164:167], v238, s[4:5] offset:160
	global_load_dwordx4 v[168:171], v238, s[4:5] offset:192
	global_load_dwordx4 v[172:175], v238, s[4:5] offset:224
	s_nop 7
	s_nop 3
	v_ashrrev_i32_e32 v230, 31, v128
	v_or_b32_e32 v230, 0x80000000, v230
	v_xor_b32_e32 v229, v230, v128
	v_and_b32_e32 v229, 0xffffff80, v229
	v_or_b32_e32 v114, v229, v213
	v_ashrrev_i32_e32 v230, 31, v129
	v_or_b32_e32 v230, 0x80000000, v230
	v_xor_b32_e32 v229, v230, v129
	v_and_b32_e32 v229, 0xffffff80, v229
	v_or_b32_e32 v98, v229, v214
	v_ashrrev_i32_e32 v230, 31, v130
	v_or_b32_e32 v230, 0x80000000, v230
	v_xor_b32_e32 v229, v230, v130
	v_and_b32_e32 v229, 0xffffff80, v229
	v_or_b32_e32 v81, v229, v215
	v_ashrrev_i32_e32 v230, 31, v131
	v_or_b32_e32 v230, 0x80000000, v230
	v_xor_b32_e32 v229, v230, v131
	v_and_b32_e32 v229, 0xffffff80, v229
	v_or_b32_e32 v115, v229, v216
	v_ashrrev_i32_e32 v230, 31, v132
	v_or_b32_e32 v230, 0x80000000, v230
	v_xor_b32_e32 v229, v230, v132
	v_and_b32_e32 v229, 0xffffff80, v229
	v_or_b32_e32 v91, v229, v217
	v_ashrrev_i32_e32 v230, 31, v133
	v_or_b32_e32 v230, 0x80000000, v230
	v_xor_b32_e32 v229, v230, v133
	v_and_b32_e32 v229, 0xffffff80, v229
	v_or_b32_e32 v109, v229, v218
	v_ashrrev_i32_e32 v230, 31, v134
	v_or_b32_e32 v230, 0x80000000, v230
	v_xor_b32_e32 v229, v230, v134
	v_and_b32_e32 v229, 0xffffff80, v229
	v_or_b32_e32 v96, v229, v219
	v_ashrrev_i32_e32 v230, 31, v135
	v_or_b32_e32 v230, 0x80000000, v230
	v_xor_b32_e32 v229, v230, v135
	v_and_b32_e32 v229, 0xffffff80, v229
	v_or_b32_e32 v85, v229, v220
	v_ashrrev_i32_e32 v230, 31, v136
	v_or_b32_e32 v230, 0x80000000, v230
; DI int crow(int i, int hh) { return (i & 3) + 8 * (i >> 2) + 4 * hh; }
; template <int LOGN>
; DI void bitonic_sort_desc(unsigned (&a)[1 << LOGN]) {
;   constexpr int N = 1 << LOGN;
; #pragma unroll
;   for (int ks = 1; ks <= LOGN; ++ks)
; #pragma unroll
;     ...
; #pragma unroll
;       for (int i = 0; i < N; ++i) {
;         const int k = 1 << ks, j = 1 << js, l = i ^ j;
;         if (l > i) {
;           const bool desc = ((i & k) == 0) || (ks == LOGN);
;           const unsigned x = a[i], y = a[l];
;           const unsigned hi = max(x, y), lo = min(x, y);
;           a[i] = desc ? hi : lo;
;           a[l] = desc ? lo : hi;
;         }
;       }
; }
; DI void peer_top16(const u16* __restrict__ PQrow, const u16* __restrict__ SK, unsigned (&top)[16], int lr, int hh) {
;     ...
;     for (int e = 0; e < 16; ++e) {
;       int kidx = kt * 32 + crow(e, hh);
;       g[kt][e] = (f2ord(acc[e]) & ~127u) | (unsigned)(127 - kidx);
;     }
	v_xor_b32_e32 v229, v230, v136
	v_and_b32_e32 v229, 0xffffff80, v229
	v_or_b32_e32 v112, v229, v221
	v_ashrrev_i32_e32 v230, 31, v137
	v_or_b32_e32 v230, 0x80000000, v230
	v_xor_b32_e32 v229, v230, v137
	v_and_b32_e32 v229, 0xffffff80, v229
	v_or_b32_e32 v89, v229, v222
	v_ashrrev_i32_e32 v230, 31, v138
	v_or_b32_e32 v230, 0x80000000, v230
	v_xor_b32_e32 v229, v230, v138
	v_and_b32_e32 v229, 0xffffff80, v229
	v_or_b32_e32 v106, v229, v223
	v_ashrrev_i32_e32 v230, 31, v139
	v_or_b32_e32 v230, 0x80000000, v230
	v_xor_b32_e32 v229, v230, v139
	v_and_b32_e32 v229, 0xffffff80, v229
	v_or_b32_e32 v83, v229, v224
	v_ashrrev_i32_e32 v230, 31, v140
	v_or_b32_e32 v230, 0x80000000, v230
	v_xor_b32_e32 v229, v230, v140
	v_and_b32_e32 v229, 0xffffff80, v229
	v_or_b32_e32 v101, v229, v225
	v_ashrrev_i32_e32 v230, 31, v141
	v_or_b32_e32 v230, 0x80000000, v230
	v_xor_b32_e32 v229, v230, v141
	v_and_b32_e32 v229, 0xffffff80, v229
	v_or_b32_e32 v107, v229, v226
	v_ashrrev_i32_e32 v230, 31, v142
	v_or_b32_e32 v230, 0x80000000, v230
	v_xor_b32_e32 v229, v230, v142
	v_and_b32_e32 v229, 0xffffff80, v229
	v_or_b32_e32 v111, v229, v227
	v_ashrrev_i32_e32 v230, 31, v143
	v_or_b32_e32 v230, 0x80000000, v230
	v_xor_b32_e32 v229, v230, v143
	v_and_b32_e32 v229, 0xffffff80, v229
	v_or_b32_e32 v105, v229, v228
	v_subrev_u32_e32 v213, 32, v213
	v_subrev_u32_e32 v214, 32, v214
	v_subrev_u32_e32 v215, 32, v215
	v_subrev_u32_e32 v216, 32, v216
	v_subrev_u32_e32 v217, 32, v217
	v_subrev_u32_e32 v218, 32, v218
	v_subrev_u32_e32 v219, 32, v219
	v_subrev_u32_e32 v220, 32, v220
	v_subrev_u32_e32 v221, 32, v221
	v_subrev_u32_e32 v222, 32, v222
	v_subrev_u32_e32 v223, 32, v223
	v_subrev_u32_e32 v224, 32, v224
	v_subrev_u32_e32 v225, 32, v225
	v_subrev_u32_e32 v226, 32, v226
	v_subrev_u32_e32 v227, 32, v227
	v_subrev_u32_e32 v228, 32, v228
	v_max_u32_e32 v90, v114, v98
	v_min_u32_e32 v98, v114, v98
	v_min_u32_e32 v114, v81, v115
	v_max_u32_e32 v115, v81, v115
	v_max_u32_e32 v81, v91, v109
	v_min_u32_e32 v109, v91, v109
	v_min_u32_e32 v91, v96, v85
	v_max_u32_e32 v85, v96, v85
	v_max_u32_e32 v96, v112, v89
	v_min_u32_e32 v89, v112, v89
	v_min_u32_e32 v112, v106, v83
	v_max_u32_e32 v83, v106, v83
	v_max_u32_e32 v106, v101, v107
	v_min_u32_e32 v107, v101, v107
	v_min_u32_e32 v101, v111, v105
	v_max_u32_e32 v105, v111, v105
	v_max_u32_e32 v111, v90, v114
	v_min_u32_e32 v114, v90, v114
	v_max_u32_e32 v90, v98, v115
	v_min_u32_e32 v115, v98, v115
	v_min_u32_e32 v98, v81, v91
	v_max_u32_e32 v91, v81, v91
	v_min_u32_e32 v81, v109, v85
	v_max_u32_e32 v85, v109, v85
	v_max_u32_e32 v109, v96, v112
	v_min_u32_e32 v112, v96, v112
	v_max_u32_e32 v96, v89, v83
	v_min_u32_e32 v83, v89, v83
	v_min_u32_e32 v89, v106, v101
	v_max_u32_e32 v101, v106, v101
	v_min_u32_e32 v106, v107, v105
	v_max_u32_e32 v105, v107, v105
	v_max_u32_e32 v107, v111, v90
	v_min_u32_e32 v90, v111, v90
	v_max_u32_e32 v111, v114, v115
	v_min_u32_e32 v115, v114, v115
	v_min_u32_e32 v114, v98, v81
	v_max_u32_e32 v81, v98, v81
	v_min_u32_e32 v98, v91, v85
	v_max_u32_e32 v85, v91, v85
	v_max_u32_e32 v91, v109, v96
	v_min_u32_e32 v96, v109, v96
	v_max_u32_e32 v109, v112, v83
	v_min_u32_e32 v83, v112, v83
	v_min_u32_e32 v112, v89, v106
	v_max_u32_e32 v106, v89, v106
	v_min_u32_e32 v89, v101, v105
	v_max_u32_e32 v105, v101, v105
	v_max_u32_e32 v101, v107, v114
	v_min_u32_e32 v114, v107, v114
	v_max_u32_e32 v107, v90, v81
	v_min_u32_e32 v81, v90, v81
	v_max_u32_e32 v90, v111, v98
	v_min_u32_e32 v98, v111, v98
	v_max_u32_e32 v111, v115, v85
	v_min_u32_e32 v85, v115, v85
	v_min_u32_e32 v115, v91, v112
	v_max_u32_e32 v112, v91, v112
	v_min_u32_e32 v91, v96, v106
	v_max_u32_e32 v106, v96, v106
	v_min_u32_e32 v96, v109, v89
	v_max_u32_e32 v89, v109, v89
	v_min_u32_e32 v109, v83, v105
	v_max_u32_e32 v105, v83, v105
	v_max_u32_e32 v83, v101, v90
	v_min_u32_e32 v90, v101, v90
	v_max_u32_e32 v101, v107, v111
	v_min_u32_e32 v111, v107, v111
	v_max_u32_e32 v107, v114, v98
	v_min_u32_e32 v98, v114, v98
	v_max_u32_e32 v114, v81, v85
	v_min_u32_e32 v85, v81, v85
	v_min_u32_e32 v81, v115, v96
	v_max_u32_e32 v96, v115, v96
	v_min_u32_e32 v115, v91, v109
	v_max_u32_e32 v109, v91, v109
	v_min_u32_e32 v91, v112, v89
	v_max_u32_e32 v89, v112, v89
	v_min_u32_e32 v112, v106, v105
	v_max_u32_e32 v105, v106, v105
	v_max_u32_e32 v106, v83, v101
	v_min_u32_e32 v101, v83, v101
	v_max_u32_e32 v83, v90, v111
	v_min_u32_e32 v111, v90, v111
	v_max_u32_e32 v90, v107, v114
	v_min_u32_e32 v114, v107, v114
	v_max_u32_e32 v107, v98, v85
	v_min_u32_e32 v85, v98, v85
	v_min_u32_e32 v98, v81, v115
	v_max_u32_e32 v115, v81, v115
	v_min_u32_e32 v81, v96, v109
	v_max_u32_e32 v109, v96, v109
	v_min_u32_e32 v96, v91, v112
	v_max_u32_e32 v112, v91, v112
	v_min_u32_e32 v91, v89, v105
	v_max_u32_e32 v105, v89, v105
	v_max_u32_e32 v89, v106, v98
	v_min_u32_e32 v98, v106, v98
	v_max_u32_e32 v106, v101, v115
	v_min_u32_e32 v115, v101, v115
	v_max_u32_e32 v101, v83, v81
	v_min_u32_e32 v81, v83, v81
	v_max_u32_e32 v83, v111, v109
	v_min_u32_e32 v109, v111, v109
	v_max_u32_e32 v111, v90, v96
	v_min_u32_e32 v96, v90, v96
	v_max_u32_e32 v90, v114, v112
	v_min_u32_e32 v112, v114, v112
	v_max_u32_e32 v114, v107, v91
	v_min_u32_e32 v91, v107, v91
	v_max_u32_e32 v107, v85, v105
	v_min_u32_e32 v105, v85, v105
	v_max_u32_e32 v85, v89, v111
	v_min_u32_e32 v111, v89, v111
	v_max_u32_e32 v89, v106, v90
	v_min_u32_e32 v90, v106, v90
	v_max_u32_e32 v106, v101, v114
	v_min_u32_e32 v114, v101, v114
	v_max_u32_e32 v101, v83, v107
	v_min_u32_e32 v107, v83, v107
	v_max_u32_e32 v83, v98, v96
	v_min_u32_e32 v96, v98, v96
	v_max_u32_e32 v98, v115, v112
	v_min_u32_e32 v112, v115, v112
	v_max_u32_e32 v115, v81, v91
	v_min_u32_e32 v91, v81, v91
	v_max_u32_e32 v81, v109, v105
	v_min_u32_e32 v105, v109, v105
	v_max_u32_e32 v109, v85, v106
	v_min_u32_e32 v106, v85, v106
	v_max_u32_e32 v85, v89, v101
	v_min_u32_e32 v101, v89, v101
	v_max_u32_e32 v89, v111, v114
	v_min_u32_e32 v114, v111, v114
	v_max_u32_e32 v111, v90, v107
	v_min_u32_e32 v107, v90, v107
	v_max_u32_e32 v90, v83, v115
	v_min_u32_e32 v115, v83, v115
	v_max_u32_e32 v83, v98, v81
	v_min_u32_e32 v81, v98, v81
	v_max_u32_e32 v98, v96, v91
	v_min_u32_e32 v91, v96, v91
	v_max_u32_e32 v96, v112, v105
	v_min_u32_e32 v105, v112, v105
	v_max_u32_e32 v112, v109, v85
	v_min_u32_e32 v85, v109, v85
	v_max_u32_e32 v109, v106, v101
	v_min_u32_e32 v101, v106, v101
	v_max_u32_e32 v106, v89, v111
	v_min_u32_e32 v111, v89, v111
	v_max_u32_e32 v89, v114, v107
	v_min_u32_e32 v107, v114, v107
	v_max_u32_e32 v114, v90, v83
	v_min_u32_e32 v83, v90, v83
	v_max_u32_e32 v90, v115, v81
	v_min_u32_e32 v81, v115, v81
	v_max_u32_e32 v115, v98, v96
	v_min_u32_e32 v96, v98, v96
	v_max_u32_e32 v98, v91, v105
	v_min_u32_e32 v105, v91, v105
	s_waitcnt vmcnt(7)
; #define MFMA32(a, b, c) __builtin_amdgcn_mfma_f32_32x32x16_bf16((a), (b), (c), 0, 0, 0)
; DI int crow(int i, int hh) { return (i & 3) + 8 * (i >> 2) + 4 * hh; }
; DI void peer_top16(const u16* __restrict__ PQrow, const u16* __restrict__ SK, unsigned (&top)[16], int lr, int hh) {
;     ...
;   for (int kt = 0; kt < 4; ++kt) {
;     f32x16 acc;
; #pragma unroll
;     for (int e = 0; e < 16; ++e) acc[e] = 0.f;
; #pragma unroll
;     for (int ks = 0; ks < 8; ++ks) {
;       bf16x8 a = *(const bf16x8*)(SK + (size_t)(kt * 32 + lr) * 128 + ks * 16 + hh * 8);
;       acc = MFMA32(a, qf[ks], acc);
;     }
; #pragma unroll
;     for (int e = 0; e < 16; ++e) {
;       int kidx = kt * 32 + crow(e, hh);
;       g[kt][e] = (f2ord(acc[e]) & ~127u) | (unsigned)(127 - kidx);
;     }
	v_mfma_f32_32x32x16_bf16 v[128:143], v[144:147], v[176:179], 0
	s_waitcnt vmcnt(6)
	v_mfma_f32_32x32x16_bf16 v[128:143], v[148:151], v[180:183], v[128:143]
	s_waitcnt vmcnt(5)
	v_mfma_f32_32x32x16_bf16 v[128:143], v[152:155], v[184:187], v[128:143]
	s_waitcnt vmcnt(4)
	v_mfma_f32_32x32x16_bf16 v[128:143], v[156:159], v[188:191], v[128:143]
	s_waitcnt vmcnt(3)
	v_mfma_f32_32x32x16_bf16 v[128:143], v[160:163], v[192:195], v[128:143]
	s_waitcnt vmcnt(2)
	v_mfma_f32_32x32x16_bf16 v[128:143], v[164:167], v[196:199], v[128:143]
	s_waitcnt vmcnt(1)
	v_mfma_f32_32x32x16_bf16 v[128:143], v[168:171], v[200:203], v[128:143]
	s_waitcnt vmcnt(0)
	v_mfma_f32_32x32x16_bf16 v[128:143], v[172:175], v[204:207], v[128:143]
	s_add_u32 s4, s0, 114688
	s_addc_u32 s5, s1, 0
	global_load_dwordx4 v[144:147], v238, s[4:5] offset:0
	global_load_dwordx4 v[148:151], v238, s[4:5] offset:32
	global_load_dwordx4 v[152:155], v238, s[4:5] offset:64
	global_load_dwordx4 v[156:159], v238, s[4:5] offset:96
	global_load_dwordx4 v[160:163], v238, s[4:5] offset:128
	global_load_dwordx4 v[164:167], v238, s[4:5] offset:160
	global_load_dwordx4 v[168:171], v238, s[4:5] offset:192
	global_load_dwordx4 v[172:175], v238, s[4:5] offset:224
	s_nop 7
	s_nop 3
	v_ashrrev_i32_e32 v230, 31, v128
	v_or_b32_e32 v230, 0x80000000, v230
	v_xor_b32_e32 v229, v230, v128
	v_and_b32_e32 v229, 0xffffff80, v229
	v_or_b32_e32 v91, v229, v213
	v_ashrrev_i32_e32 v230, 31, v129
	v_or_b32_e32 v230, 0x80000000, v230
	v_xor_b32_e32 v229, v230, v129
	v_and_b32_e32 v229, 0xffffff80, v229
	v_or_b32_e32 v88, v229, v214
	v_ashrrev_i32_e32 v230, 31, v130
	v_or_b32_e32 v230, 0x80000000, v230
	v_xor_b32_e32 v229, v230, v130
	v_and_b32_e32 v229, 0xffffff80, v229
	v_or_b32_e32 v110, v229, v215
	v_ashrrev_i32_e32 v230, 31, v131
	v_or_b32_e32 v230, 0x80000000, v230
	v_xor_b32_e32 v229, v230, v131
	v_and_b32_e32 v229, 0xffffff80, v229
	v_or_b32_e32 v100, v229, v216
	v_ashrrev_i32_e32 v230, 31, v132
	v_or_b32_e32 v230, 0x80000000, v230
	v_xor_b32_e32 v229, v230, v132
	v_and_b32_e32 v229, 0xffffff80, v229
	v_or_b32_e32 v116, v229, v217
	v_ashrrev_i32_e32 v230, 31, v133
	v_or_b32_e32 v230, 0x80000000, v230
	v_xor_b32_e32 v229, v230, v133
	v_and_b32_e32 v229, 0xffffff80, v229
	v_or_b32_e32 v102, v229, v218
	v_ashrrev_i32_e32 v230, 31, v134
	v_or_b32_e32 v230, 0x80000000, v230
	v_xor_b32_e32 v229, v230, v134
	v_and_b32_e32 v229, 0xffffff80, v229
	v_or_b32_e32 v97, v229, v219
	v_ashrrev_i32_e32 v230, 31, v135
	v_or_b32_e32 v230, 0x80000000, v230
	v_xor_b32_e32 v229, v230, v135
	v_and_b32_e32 v229, 0xffffff80, v229
	v_or_b32_e32 v70, v229, v220
	v_ashrrev_i32_e32 v230, 31, v136
	v_or_b32_e32 v230, 0x80000000, v230
	v_xor_b32_e32 v229, v230, v136
	v_and_b32_e32 v229, 0xffffff80, v229
	v_or_b32_e32 v92, v229, v221
	v_ashrrev_i32_e32 v230, 31, v137
	v_or_b32_e32 v230, 0x80000000, v230
	v_xor_b32_e32 v229, v230, v137
	v_and_b32_e32 v229, 0xffffff80, v229
	v_or_b32_e32 v72, v229, v222
	v_ashrrev_i32_e32 v230, 31, v138
	v_or_b32_e32 v230, 0x80000000, v230
	v_xor_b32_e32 v229, v230, v138
	v_and_b32_e32 v229, 0xffffff80, v229
	v_or_b32_e32 v103, v229, v223
	v_ashrrev_i32_e32 v230, 31, v139
	v_or_b32_e32 v230, 0x80000000, v230
	v_xor_b32_e32 v229, v230, v139
	v_and_b32_e32 v229, 0xffffff80, v229
	v_or_b32_e32 v79, v229, v224
	v_ashrrev_i32_e32 v230, 31, v140
	v_or_b32_e32 v230, 0x80000000, v230
	v_xor_b32_e32 v229, v230, v140
	v_and_b32_e32 v229, 0xffffff80, v229
	v_or_b32_e32 v117, v229, v225
	v_ashrrev_i32_e32 v230, 31, v141
	v_or_b32_e32 v230, 0x80000000, v230
	v_xor_b32_e32 v229, v230, v141
	v_and_b32_e32 v229, 0xffffff80, v229
	v_or_b32_e32 v104, v229, v226
	v_ashrrev_i32_e32 v230, 31, v142
	v_or_b32_e32 v230, 0x80000000, v230
	v_xor_b32_e32 v229, v230, v142
	v_and_b32_e32 v229, 0xffffff80, v229
	v_or_b32_e32 v77, v229, v227
	v_ashrrev_i32_e32 v230, 31, v143
	v_or_b32_e32 v230, 0x80000000, v230
	v_xor_b32_e32 v229, v230, v143
	v_and_b32_e32 v229, 0xffffff80, v229
	v_or_b32_e32 v108, v229, v228
	v_subrev_u32_e32 v213, 32, v213
	v_subrev_u32_e32 v214, 32, v214
	v_subrev_u32_e32 v215, 32, v215
	v_subrev_u32_e32 v216, 32, v216
	v_subrev_u32_e32 v217, 32, v217
	v_subrev_u32_e32 v218, 32, v218
	v_subrev_u32_e32 v219, 32, v219
	v_subrev_u32_e32 v220, 32, v220
	v_subrev_u32_e32 v221, 32, v221
	v_subrev_u32_e32 v222, 32, v222
	v_subrev_u32_e32 v223, 32, v223
	v_subrev_u32_e32 v224, 32, v224
	v_subrev_u32_e32 v225, 32, v225
	v_subrev_u32_e32 v226, 32, v226
	v_subrev_u32_e32 v227, 32, v227
	v_subrev_u32_e32 v228, 32, v228
	v_max_u32_e32 v86, v91, v88
	v_min_u32_e32 v88, v91, v88
	v_min_u32_e32 v91, v110, v100
	v_max_u32_e32 v100, v110, v100
	v_max_u32_e32 v110, v116, v102
	v_min_u32_e32 v102, v116, v102
	v_min_u32_e32 v116, v97, v70
	v_max_u32_e32 v70, v97, v70
	v_max_u32_e32 v97, v92, v72
	v_min_u32_e32 v72, v92, v72
	v_min_u32_e32 v92, v103, v79
	v_max_u32_e32 v79, v103, v79
	v_max_u32_e32 v103, v117, v104
	v_min_u32_e32 v104, v117, v104
	v_min_u32_e32 v117, v77, v108
	v_max_u32_e32 v108, v77, v108
	v_max_u32_e32 v77, v86, v91
	v_min_u32_e32 v91, v86, v91
	v_max_u32_e32 v86, v88, v100
	v_min_u32_e32 v100, v88, v100
	v_min_u32_e32 v88, v110, v116
	v_max_u32_e32 v116, v110, v116
	v_min_u32_e32 v110, v102, v70
	v_max_u32_e32 v70, v102, v70
	v_max_u32_e32 v102, v97, v92
	v_min_u32_e32 v92, v97, v92
	v_max_u32_e32 v97, v72, v79
	v_min_u32_e32 v79, v72, v79
	v_min_u32_e32 v72, v103, v117
	v_max_u32_e32 v117, v103, v117
	v_min_u32_e32 v103, v104, v108
	v_max_u32_e32 v108, v104, v108
	v_max_u32_e32 v104, v77, v86
	v_min_u32_e32 v86, v77, v86
	v_max_u32_e32 v77, v91, v100
	v_min_u32_e32 v100, v91, v100
	v_min_u32_e32 v91, v88, v110
; template <int LOGN>
; DI void bitonic_sort_desc(unsigned (&a)[1 << LOGN]) {
;   constexpr int N = 1 << LOGN;
; #pragma unroll
;   for (int ks = 1; ks <= LOGN; ++ks)
; #pragma unroll
;     ...
; #pragma unroll
;       for (int i = 0; i < N; ++i) {
;         const int k = 1 << ks, j = 1 << js, l = i ^ j;
;         if (l > i) {
;           const bool desc = ((i & k) == 0) || (ks == LOGN);
;           const unsigned x = a[i], y = a[l];
;           const unsigned hi = max(x, y), lo = min(x, y);
;           a[i] = desc ? hi : lo;
;           a[l] = desc ? lo : hi;
;         }
;       }
; }
; DI void merge_top16(unsigned (&a)[16], const unsigned (&b)[16]) {
; #pragma unroll
;   for (int i = 0; i < 16; ++i) a[i] = max(a[i], b[15 - i]);
; #pragma unroll
;     ...
; #pragma unroll
;     for (int i = 0; i < 16; ++i) {
;       const int j = 1 << js, l = i ^ j;
;       if (l > i) {
;         const unsigned x = a[i], y = a[l];
;         a[i] = max(x, y);
;         a[l] = min(x, y);
;       }
;     }
; }
	v_max_u32_e32 v110, v88, v110
	v_min_u32_e32 v88, v116, v70
	v_max_u32_e32 v70, v116, v70
	v_max_u32_e32 v116, v102, v97
	v_min_u32_e32 v97, v102, v97
	v_max_u32_e32 v102, v92, v79
	v_min_u32_e32 v79, v92, v79
	v_min_u32_e32 v92, v72, v103
	v_max_u32_e32 v103, v72, v103
	v_min_u32_e32 v72, v117, v108
	v_max_u32_e32 v108, v117, v108
	v_max_u32_e32 v117, v104, v91
	v_min_u32_e32 v91, v104, v91
	v_max_u32_e32 v104, v86, v110
	v_min_u32_e32 v110, v86, v110
	v_max_u32_e32 v86, v77, v88
	v_min_u32_e32 v88, v77, v88
	v_max_u32_e32 v77, v100, v70
	v_min_u32_e32 v70, v100, v70
	v_min_u32_e32 v100, v116, v92
	v_max_u32_e32 v92, v116, v92
	v_min_u32_e32 v116, v97, v103
	v_max_u32_e32 v103, v97, v103
	v_min_u32_e32 v97, v102, v72
	v_max_u32_e32 v72, v102, v72
	v_min_u32_e32 v102, v79, v108
	v_max_u32_e32 v108, v79, v108
	v_max_u32_e32 v79, v117, v86
	v_min_u32_e32 v86, v117, v86
	v_max_u32_e32 v117, v104, v77
	v_min_u32_e32 v77, v104, v77
	v_max_u32_e32 v104, v91, v88
	v_min_u32_e32 v88, v91, v88
	v_max_u32_e32 v91, v110, v70
	v_min_u32_e32 v70, v110, v70
	v_min_u32_e32 v110, v100, v97
	v_max_u32_e32 v97, v100, v97
	v_min_u32_e32 v100, v116, v102
	v_max_u32_e32 v102, v116, v102
	v_min_u32_e32 v116, v92, v72
	v_max_u32_e32 v72, v92, v72
	v_min_u32_e32 v92, v103, v108
	v_max_u32_e32 v108, v103, v108
	v_max_u32_e32 v103, v79, v117
	v_min_u32_e32 v117, v79, v117
	v_max_u32_e32 v79, v86, v77
	v_min_u32_e32 v77, v86, v77
	v_max_u32_e32 v86, v104, v91
	v_min_u32_e32 v91, v104, v91
	v_max_u32_e32 v104, v88, v70
	v_min_u32_e32 v70, v88, v70
	v_min_u32_e32 v88, v110, v100
	v_max_u32_e32 v100, v110, v100
	v_min_u32_e32 v110, v97, v102
	v_max_u32_e32 v102, v97, v102
	v_min_u32_e32 v97, v116, v92
	v_max_u32_e32 v92, v116, v92
	v_min_u32_e32 v116, v72, v108
	v_max_u32_e32 v108, v72, v108
	v_max_u32_e32 v72, v103, v88
	v_min_u32_e32 v88, v103, v88
	v_max_u32_e32 v103, v117, v100
	v_min_u32_e32 v100, v117, v100
	v_max_u32_e32 v117, v79, v110
	v_min_u32_e32 v110, v79, v110
	v_max_u32_e32 v79, v77, v102
	v_min_u32_e32 v102, v77, v102
	v_max_u32_e32 v77, v86, v97
	v_min_u32_e32 v97, v86, v97
	v_max_u32_e32 v86, v91, v92
	v_min_u32_e32 v92, v91, v92
	v_max_u32_e32 v91, v104, v116
	v_min_u32_e32 v116, v104, v116
	v_max_u32_e32 v104, v70, v108
	v_min_u32_e32 v108, v70, v108
	v_max_u32_e32 v70, v72, v77
	v_min_u32_e32 v77, v72, v77
	v_max_u32_e32 v72, v103, v86
	v_min_u32_e32 v86, v103, v86
	v_max_u32_e32 v103, v117, v91
	v_min_u32_e32 v91, v117, v91
	v_max_u32_e32 v117, v79, v104
	v_min_u32_e32 v104, v79, v104
	v_max_u32_e32 v79, v88, v97
	v_min_u32_e32 v97, v88, v97
	v_max_u32_e32 v88, v100, v92
	v_min_u32_e32 v92, v100, v92
	v_max_u32_e32 v100, v110, v116
	v_min_u32_e32 v116, v110, v116
	v_max_u32_e32 v110, v102, v108
	v_min_u32_e32 v108, v102, v108
	v_max_u32_e32 v102, v70, v103
	v_min_u32_e32 v103, v70, v103
	v_max_u32_e32 v70, v72, v117
	v_min_u32_e32 v117, v72, v117
	v_max_u32_e32 v72, v77, v91
	v_min_u32_e32 v91, v77, v91
	v_max_u32_e32 v77, v86, v104
	v_min_u32_e32 v104, v86, v104
	v_max_u32_e32 v86, v79, v100
	v_min_u32_e32 v100, v79, v100
	v_max_u32_e32 v79, v88, v110
	v_min_u32_e32 v110, v88, v110
	v_max_u32_e32 v88, v97, v116
	v_min_u32_e32 v116, v97, v116
	v_max_u32_e32 v97, v92, v108
	v_min_u32_e32 v108, v92, v108
	v_max_u32_e32 v92, v102, v70
	v_min_u32_e32 v70, v102, v70
	v_max_u32_e32 v102, v103, v117
	v_min_u32_e32 v117, v103, v117
	v_max_u32_e32 v103, v72, v77
	v_min_u32_e32 v77, v72, v77
	v_max_u32_e32 v72, v91, v104
	v_min_u32_e32 v104, v91, v104
	v_max_u32_e32 v91, v86, v79
	v_min_u32_e32 v79, v86, v79
	v_max_u32_e32 v86, v100, v110
	v_min_u32_e32 v110, v100, v110
	v_max_u32_e32 v100, v88, v97
	v_min_u32_e32 v97, v88, v97
	v_max_u32_e32 v88, v116, v108
	v_min_u32_e32 v108, v116, v108
	v_max_u32_e32 v116, v112, v108
	v_max_u32_e32 v112, v85, v88
	v_max_u32_e32 v85, v109, v97
	v_max_u32_e32 v109, v101, v100
	v_max_u32_e32 v101, v106, v110
	v_max_u32_e32 v106, v111, v86
	v_max_u32_e32 v111, v89, v79
	v_max_u32_e32 v89, v107, v91
	v_max_u32_e32 v107, v114, v104
	v_max_u32_e32 v114, v83, v72
	v_max_u32_e32 v83, v90, v77
	v_max_u32_e32 v90, v81, v103
	v_max_u32_e32 v81, v115, v117
	v_max_u32_e32 v115, v96, v102
	v_max_u32_e32 v96, v98, v70
	v_max_u32_e32 v98, v105, v92
	v_max_u32_e32 v108, v116, v107
	v_min_u32_e32 v107, v116, v107
	v_max_u32_e32 v116, v112, v114
	v_min_u32_e32 v114, v112, v114
	v_max_u32_e32 v112, v85, v83
	v_min_u32_e32 v83, v85, v83
	v_max_u32_e32 v85, v109, v90
	v_min_u32_e32 v90, v109, v90
	v_max_u32_e32 v109, v101, v81
	v_min_u32_e32 v81, v101, v81
	v_max_u32_e32 v101, v106, v115
	v_min_u32_e32 v115, v106, v115
	v_max_u32_e32 v106, v111, v96
	v_min_u32_e32 v96, v111, v96
	v_max_u32_e32 v111, v89, v98
	v_min_u32_e32 v98, v89, v98
	v_max_u32_e32 v89, v108, v109
	v_min_u32_e32 v109, v108, v109
	v_max_u32_e32 v108, v116, v101
	v_min_u32_e32 v101, v116, v101
	v_max_u32_e32 v116, v112, v106
	v_min_u32_e32 v106, v112, v106
	v_max_u32_e32 v112, v85, v111
	v_min_u32_e32 v111, v85, v111
	v_max_u32_e32 v85, v107, v81
	v_min_u32_e32 v81, v107, v81
	v_max_u32_e32 v107, v114, v115
	v_min_u32_e32 v115, v114, v115
	v_max_u32_e32 v114, v83, v96
	v_min_u32_e32 v96, v83, v96
	v_max_u32_e32 v83, v90, v98
	v_min_u32_e32 v98, v90, v98
	v_max_u32_e32 v90, v89, v116
	v_min_u32_e32 v116, v89, v116
	v_max_u32_e32 v89, v108, v112
	v_min_u32_e32 v112, v108, v112
	v_max_u32_e32 v108, v109, v106
	v_min_u32_e32 v106, v109, v106
	v_max_u32_e32 v109, v101, v111
	v_min_u32_e32 v111, v101, v111
	v_max_u32_e32 v101, v85, v114
	v_min_u32_e32 v114, v85, v114
	v_max_u32_e32 v85, v107, v83
	v_min_u32_e32 v83, v107, v83
	v_max_u32_e32 v107, v81, v96
	v_min_u32_e32 v96, v81, v96
	v_max_u32_e32 v81, v115, v98
	v_min_u32_e32 v98, v115, v98
	v_max_u32_e32 v115, v90, v89
	v_min_u32_e32 v89, v90, v89
	v_max_u32_e32 v90, v116, v112
	v_min_u32_e32 v112, v116, v112
	v_max_u32_e32 v116, v108, v109
	v_min_u32_e32 v109, v108, v109
	v_max_u32_e32 v108, v106, v111
	v_min_u32_e32 v111, v106, v111
	v_max_u32_e32 v106, v101, v85
	v_min_u32_e32 v85, v101, v85
	v_max_u32_e32 v101, v114, v83
	v_min_u32_e32 v83, v114, v83
	v_max_u32_e32 v114, v107, v81
	v_min_u32_e32 v81, v107, v81
	v_max_u32_e32 v107, v96, v98
	v_min_u32_e32 v98, v96, v98
	s_waitcnt vmcnt(7)
; #define MFMA32(a, b, c) __builtin_amdgcn_mfma_f32_32x32x16_bf16((a), (b), (c), 0, 0, 0)
; DI int crow(int i, int hh) { return (i & 3) + 8 * (i >> 2) + 4 * hh; }
; DI void peer_top16(const u16* __restrict__ PQrow, const u16* __restrict__ SK, unsigned (&top)[16], int lr, int hh) {
;     ...
;   for (int kt = 0; kt < 4; ++kt) {
;     f32x16 acc;
; #pragma unroll
;     for (int e = 0; e < 16; ++e) acc[e] = 0.f;
; #pragma unroll
;     for (int ks = 0; ks < 8; ++ks) {
;       bf16x8 a = *(const bf16x8*)(SK + (size_t)(kt * 32 + lr) * 128 + ks * 16 + hh * 8);
;       acc = MFMA32(a, qf[ks], acc);
;     }
; #pragma unroll
;     for (int e = 0; e < 16; ++e) {
;       int kidx = kt * 32 + crow(e, hh);
;       g[kt][e] = (f2ord(acc[e]) & ~127u) | (unsigned)(127 - kidx);
;     }
	v_mfma_f32_32x32x16_bf16 v[128:143], v[144:147], v[176:179], 0
	s_waitcnt vmcnt(6)
	v_mfma_f32_32x32x16_bf16 v[128:143], v[148:151], v[180:183], v[128:143]
	s_waitcnt vmcnt(5)
	v_mfma_f32_32x32x16_bf16 v[128:143], v[152:155], v[184:187], v[128:143]
	s_waitcnt vmcnt(4)
	v_mfma_f32_32x32x16_bf16 v[128:143], v[156:159], v[188:191], v[128:143]
	s_waitcnt vmcnt(3)
	v_mfma_f32_32x32x16_bf16 v[128:143], v[160:163], v[192:195], v[128:143]
	s_waitcnt vmcnt(2)
	v_mfma_f32_32x32x16_bf16 v[128:143], v[164:167], v[196:199], v[128:143]
	s_waitcnt vmcnt(1)
	v_mfma_f32_32x32x16_bf16 v[128:143], v[168:171], v[200:203], v[128:143]
	s_waitcnt vmcnt(0)
	v_mfma_f32_32x32x16_bf16 v[128:143], v[172:175], v[204:207], v[128:143]
	s_add_u32 s4, s0, 122880
	s_addc_u32 s5, s1, 0
	global_load_dwordx4 v[144:147], v238, s[4:5] offset:0
	global_load_dwordx4 v[148:151], v238, s[4:5] offset:32
	global_load_dwordx4 v[152:155], v238, s[4:5] offset:64
	global_load_dwordx4 v[156:159], v238, s[4:5] offset:96
	global_load_dwordx4 v[160:163], v238, s[4:5] offset:128
	global_load_dwordx4 v[164:167], v238, s[4:5] offset:160
	global_load_dwordx4 v[168:171], v238, s[4:5] offset:192
	global_load_dwordx4 v[172:175], v238, s[4:5] offset:224
	s_nop 7
	s_nop 3
	v_ashrrev_i32_e32 v230, 31, v128
	v_or_b32_e32 v230, 0x80000000, v230
	v_xor_b32_e32 v229, v230, v128
	v_and_b32_e32 v229, 0xffffff80, v229
	v_or_b32_e32 v96, v229, v213
	v_ashrrev_i32_e32 v230, 31, v129
	v_or_b32_e32 v230, 0x80000000, v230
	v_xor_b32_e32 v229, v230, v129
	v_and_b32_e32 v229, 0xffffff80, v229
	v_or_b32_e32 v88, v229, v214
	v_ashrrev_i32_e32 v230, 31, v130
	v_or_b32_e32 v230, 0x80000000, v230
	v_xor_b32_e32 v229, v230, v130
	v_and_b32_e32 v229, 0xffffff80, v229
	v_or_b32_e32 v97, v229, v215
	v_ashrrev_i32_e32 v230, 31, v131
	v_or_b32_e32 v230, 0x80000000, v230
	v_xor_b32_e32 v229, v230, v131
	v_and_b32_e32 v229, 0xffffff80, v229
	v_or_b32_e32 v100, v229, v216
	v_ashrrev_i32_e32 v230, 31, v132
	v_or_b32_e32 v230, 0x80000000, v230
	v_xor_b32_e32 v229, v230, v132
	v_and_b32_e32 v229, 0xffffff80, v229
	v_or_b32_e32 v110, v229, v217
	v_ashrrev_i32_e32 v230, 31, v133
	v_or_b32_e32 v230, 0x80000000, v230
	v_xor_b32_e32 v229, v230, v133
	v_and_b32_e32 v229, 0xffffff80, v229
	v_or_b32_e32 v86, v229, v218
	v_ashrrev_i32_e32 v230, 31, v134
	v_or_b32_e32 v230, 0x80000000, v230
	v_xor_b32_e32 v229, v230, v134
	v_and_b32_e32 v229, 0xffffff80, v229
	v_or_b32_e32 v79, v229, v219
	v_ashrrev_i32_e32 v230, 31, v135
	v_or_b32_e32 v230, 0x80000000, v230
	v_xor_b32_e32 v229, v230, v135
	v_and_b32_e32 v229, 0xffffff80, v229
	v_or_b32_e32 v91, v229, v220
	v_ashrrev_i32_e32 v230, 31, v136
	v_or_b32_e32 v230, 0x80000000, v230
	v_xor_b32_e32 v229, v230, v136
	v_and_b32_e32 v229, 0xffffff80, v229
	v_or_b32_e32 v104, v229, v221
	v_ashrrev_i32_e32 v230, 31, v137
	v_or_b32_e32 v230, 0x80000000, v230
	v_xor_b32_e32 v229, v230, v137
	v_and_b32_e32 v229, 0xffffff80, v229
	v_or_b32_e32 v72, v229, v222
	v_ashrrev_i32_e32 v230, 31, v138
	v_or_b32_e32 v230, 0x80000000, v230
	v_xor_b32_e32 v229, v230, v138
	v_and_b32_e32 v229, 0xffffff80, v229
	v_or_b32_e32 v77, v229, v223
	v_ashrrev_i32_e32 v230, 31, v139
	v_or_b32_e32 v230, 0x80000000, v230
	v_xor_b32_e32 v229, v230, v139
	v_and_b32_e32 v229, 0xffffff80, v229
	v_or_b32_e32 v103, v229, v224
	v_ashrrev_i32_e32 v230, 31, v140
	v_or_b32_e32 v230, 0x80000000, v230
	v_xor_b32_e32 v229, v230, v140
	v_and_b32_e32 v229, 0xffffff80, v229
	v_or_b32_e32 v117, v229, v225
	v_ashrrev_i32_e32 v230, 31, v141
	v_or_b32_e32 v230, 0x80000000, v230
	v_xor_b32_e32 v229, v230, v141
	v_and_b32_e32 v229, 0xffffff80, v229
	v_or_b32_e32 v102, v229, v226
	v_ashrrev_i32_e32 v230, 31, v142
	v_or_b32_e32 v230, 0x80000000, v230
	v_xor_b32_e32 v229, v230, v142
	v_and_b32_e32 v229, 0xffffff80, v229
	v_or_b32_e32 v70, v229, v227
	v_ashrrev_i32_e32 v230, 31, v143
	v_or_b32_e32 v230, 0x80000000, v230
	v_xor_b32_e32 v229, v230, v143
	v_and_b32_e32 v229, 0xffffff80, v229
	v_or_b32_e32 v92, v229, v228
	v_subrev_u32_e32 v213, 32, v213
	v_subrev_u32_e32 v214, 32, v214
	v_subrev_u32_e32 v215, 32, v215
	v_subrev_u32_e32 v216, 32, v216
	v_subrev_u32_e32 v217, 32, v217
	v_subrev_u32_e32 v218, 32, v218
	v_subrev_u32_e32 v219, 32, v219
	v_subrev_u32_e32 v220, 32, v220
	v_subrev_u32_e32 v221, 32, v221
	v_subrev_u32_e32 v222, 32, v222
	v_subrev_u32_e32 v223, 32, v223
	v_subrev_u32_e32 v224, 32, v224
	v_subrev_u32_e32 v225, 32, v225
	v_subrev_u32_e32 v226, 32, v226
	v_subrev_u32_e32 v227, 32, v227
	v_subrev_u32_e32 v228, 32, v228
	v_max_u32_e32 v105, v96, v88
	v_min_u32_e32 v88, v96, v88
	v_min_u32_e32 v96, v97, v100
	v_max_u32_e32 v100, v97, v100
	v_max_u32_e32 v97, v110, v86
	v_min_u32_e32 v86, v110, v86
	v_min_u32_e32 v110, v79, v91
	v_max_u32_e32 v91, v79, v91
	v_max_u32_e32 v79, v104, v72
	v_min_u32_e32 v72, v104, v72
	v_min_u32_e32 v104, v77, v103
	v_max_u32_e32 v103, v77, v103
	v_max_u32_e32 v77, v117, v102
	v_min_u32_e32 v102, v117, v102
	v_min_u32_e32 v117, v70, v92
	v_max_u32_e32 v92, v70, v92
	v_max_u32_e32 v70, v105, v96
	v_min_u32_e32 v96, v105, v96
	v_max_u32_e32 v105, v88, v100
	v_min_u32_e32 v100, v88, v100
	v_min_u32_e32 v88, v97, v110
	v_max_u32_e32 v110, v97, v110
	v_min_u32_e32 v97, v86, v91
	v_max_u32_e32 v91, v86, v91
	v_max_u32_e32 v86, v79, v104
	v_min_u32_e32 v104, v79, v104
	v_max_u32_e32 v79, v72, v103
	v_min_u32_e32 v103, v72, v103
	v_min_u32_e32 v72, v77, v117
	v_max_u32_e32 v117, v77, v117
	v_min_u32_e32 v77, v102, v92
	v_max_u32_e32 v92, v102, v92
	v_max_u32_e32 v102, v70, v105
	v_min_u32_e32 v105, v70, v105
	v_max_u32_e32 v70, v96, v100
	v_min_u32_e32 v100, v96, v100
	v_min_u32_e32 v96, v88, v97
	v_max_u32_e32 v97, v88, v97
; template <int LOGN>
; DI void bitonic_sort_desc(unsigned (&a)[1 << LOGN]) {
;   constexpr int N = 1 << LOGN;
; #pragma unroll
;   for (int ks = 1; ks <= LOGN; ++ks)
; #pragma unroll
;     ...
; #pragma unroll
;       for (int i = 0; i < N; ++i) {
;         const int k = 1 << ks, j = 1 << js, l = i ^ j;
;         if (l > i) {
;           const bool desc = ((i & k) == 0) || (ks == LOGN);
;           const unsigned x = a[i], y = a[l];
;           const unsigned hi = max(x, y), lo = min(x, y);
;           a[i] = desc ? hi : lo;
;           a[l] = desc ? lo : hi;
;         }
;       }
; }
	v_min_u32_e32 v88, v110, v91
	v_max_u32_e32 v91, v110, v91
	v_max_u32_e32 v110, v86, v79
	v_min_u32_e32 v79, v86, v79
	v_max_u32_e32 v86, v104, v103
	v_min_u32_e32 v103, v104, v103
	v_min_u32_e32 v104, v72, v77
	v_max_u32_e32 v77, v72, v77
	v_min_u32_e32 v72, v117, v92
	v_max_u32_e32 v92, v117, v92
	v_max_u32_e32 v117, v102, v96
	v_min_u32_e32 v96, v102, v96
	v_max_u32_e32 v102, v105, v97
	v_min_u32_e32 v97, v105, v97
	v_max_u32_e32 v105, v70, v88
	v_min_u32_e32 v88, v70, v88
	v_max_u32_e32 v70, v100, v91
	v_min_u32_e32 v91, v100, v91
	v_min_u32_e32 v100, v110, v104
	v_max_u32_e32 v104, v110, v104
	v_min_u32_e32 v110, v79, v77
	v_max_u32_e32 v77, v79, v77
	v_min_u32_e32 v79, v86, v72
	v_max_u32_e32 v72, v86, v72
	v_min_u32_e32 v86, v103, v92
	v_max_u32_e32 v92, v103, v92
	v_max_u32_e32 v103, v117, v105
	v_min_u32_e32 v105, v117, v105
	v_max_u32_e32 v117, v102, v70
	v_min_u32_e32 v70, v102, v70
	v_max_u32_e32 v102, v96, v88
	v_min_u32_e32 v88, v96, v88
	v_max_u32_e32 v96, v97, v91
	v_min_u32_e32 v91, v97, v91
	v_min_u32_e32 v97, v100, v79
	v_max_u32_e32 v79, v100, v79
	v_min_u32_e32 v100, v110, v86
	v_max_u32_e32 v86, v110, v86
	v_min_u32_e32 v110, v104, v72
	v_max_u32_e32 v72, v104, v72
	v_min_u32_e32 v104, v77, v92
	v_max_u32_e32 v92, v77, v92
	v_max_u32_e32 v77, v103, v117
	v_min_u32_e32 v117, v103, v117
	v_max_u32_e32 v103, v105, v70
	v_min_u32_e32 v70, v105, v70
	v_max_u32_e32 v105, v102, v96
	v_min_u32_e32 v96, v102, v96
	v_max_u32_e32 v102, v88, v91
	v_min_u32_e32 v91, v88, v91
	v_min_u32_e32 v88, v97, v100
	v_max_u32_e32 v100, v97, v100
	v_min_u32_e32 v97, v79, v86
	v_max_u32_e32 v86, v79, v86
	v_min_u32_e32 v79, v110, v104
	v_max_u32_e32 v104, v110, v104
	v_min_u32_e32 v110, v72, v92
	v_max_u32_e32 v92, v72, v92
	v_max_u32_e32 v72, v77, v88
	v_min_u32_e32 v88, v77, v88
	v_max_u32_e32 v77, v117, v100
	v_min_u32_e32 v100, v117, v100
	v_max_u32_e32 v117, v103, v97
	v_min_u32_e32 v97, v103, v97
	v_max_u32_e32 v103, v70, v86
	v_min_u32_e32 v86, v70, v86
	v_max_u32_e32 v70, v105, v79
	v_min_u32_e32 v79, v105, v79
	v_max_u32_e32 v105, v96, v104
	v_min_u32_e32 v104, v96, v104
	v_max_u32_e32 v96, v102, v110
	v_min_u32_e32 v110, v102, v110
	v_max_u32_e32 v102, v91, v92
	v_min_u32_e32 v92, v91, v92
	v_max_u32_e32 v91, v72, v70
	v_min_u32_e32 v70, v72, v70
	v_max_u32_e32 v72, v77, v105
	v_min_u32_e32 v105, v77, v105
	v_max_u32_e32 v77, v117, v96
	v_min_u32_e32 v96, v117, v96
	v_max_u32_e32 v117, v103, v102
	v_min_u32_e32 v102, v103, v102
	v_max_u32_e32 v103, v88, v79
	v_min_u32_e32 v79, v88, v79
	v_max_u32_e32 v88, v100, v104
	v_min_u32_e32 v104, v100, v104
	v_max_u32_e32 v100, v97, v110
	v_min_u32_e32 v110, v97, v110
	v_max_u32_e32 v97, v86, v92
	v_min_u32_e32 v92, v86, v92
	v_max_u32_e32 v86, v91, v77
	v_min_u32_e32 v77, v91, v77
	v_max_u32_e32 v91, v72, v117
	v_min_u32_e32 v117, v72, v117
	v_max_u32_e32 v72, v70, v96
	v_min_u32_e32 v96, v70, v96
	v_max_u32_e32 v70, v105, v102
	v_min_u32_e32 v102, v105, v102
	v_max_u32_e32 v105, v103, v100
	v_min_u32_e32 v100, v103, v100
	v_max_u32_e32 v103, v88, v97
	v_min_u32_e32 v97, v88, v97
	v_max_u32_e32 v88, v79, v110
	v_min_u32_e32 v110, v79, v110
	v_max_u32_e32 v79, v104, v92
	v_min_u32_e32 v92, v104, v92
	v_max_u32_e32 v104, v86, v91
	v_min_u32_e32 v91, v86, v91
	v_max_u32_e32 v86, v77, v117
	v_min_u32_e32 v117, v77, v117
	v_max_u32_e32 v77, v72, v70
	v_min_u32_e32 v70, v72, v70
	v_max_u32_e32 v72, v96, v102
	v_min_u32_e32 v102, v96, v102
	v_max_u32_e32 v96, v105, v103
	v_min_u32_e32 v103, v105, v103
	v_max_u32_e32 v105, v100, v97
	v_min_u32_e32 v97, v100, v97
	v_max_u32_e32 v100, v88, v79
	v_min_u32_e32 v79, v88, v79
	v_max_u32_e32 v88, v110, v92
	v_min_u32_e32 v92, v110, v92
	s_waitcnt vmcnt(7)
	v_mfma_f32_32x32x16_bf16 v[128:143], v[144:147], v[176:179], 0
	s_waitcnt vmcnt(6)
	v_mfma_f32_32x32x16_bf16 v[128:143], v[148:151], v[180:183], v[128:143]
	s_waitcnt vmcnt(5)
	v_mfma_f32_32x32x16_bf16 v[128:143], v[152:155], v[184:187], v[128:143]
	s_waitcnt vmcnt(4)
	v_mfma_f32_32x32x16_bf16 v[128:143], v[156:159], v[188:191], v[128:143]
	s_waitcnt vmcnt(3)
	v_mfma_f32_32x32x16_bf16 v[128:143], v[160:163], v[192:195], v[128:143]
	s_waitcnt vmcnt(2)
	v_mfma_f32_32x32x16_bf16 v[128:143], v[164:167], v[196:199], v[128:143]
	s_waitcnt vmcnt(1)
	v_mfma_f32_32x32x16_bf16 v[128:143], v[168:171], v[200:203], v[128:143]
	s_waitcnt vmcnt(0)
; DI int crow(int i, int hh) { return (i & 3) + 8 * (i >> 2) + 4 * hh; }
; template <int LOGN>
; DI void bitonic_sort_desc(unsigned (&a)[1 << LOGN]) {
;   constexpr int N = 1 << LOGN;
; #pragma unroll
;   for (int ks = 1; ks <= LOGN; ++ks)
; #pragma unroll
;     ...
; #pragma unroll
;       for (int i = 0; i < N; ++i) {
;         const int k = 1 << ks, j = 1 << js, l = i ^ j;
;         if (l > i) {
;           const bool desc = ((i & k) == 0) || (ks == LOGN);
;           const unsigned x = a[i], y = a[l];
;           const unsigned hi = max(x, y), lo = min(x, y);
;           a[i] = desc ? hi : lo;
;           a[l] = desc ? lo : hi;
;         }
;       }
; }
; DI void peer_top16(const u16* __restrict__ PQrow, const u16* __restrict__ SK, unsigned (&top)[16], int lr, int hh) {
;     ...
; #pragma unroll
;     for (int e = 0; e < 16; ++e) {
;       int kidx = kt * 32 + crow(e, hh);
;       g[kt][e] = (f2ord(acc[e]) & ~127u) | (unsigned)(127 - kidx);
;     }
	v_mfma_f32_32x32x16_bf16 v[128:143], v[172:175], v[204:207], v[128:143]
	s_nop 7
	s_nop 3
	v_ashrrev_i32_e32 v230, 31, v128
	v_or_b32_e32 v230, 0x80000000, v230
	v_xor_b32_e32 v229, v230, v128
	v_and_b32_e32 v229, 0xffffff80, v229
	v_or_b32_e32 v110, v229, v213
	v_ashrrev_i32_e32 v230, 31, v129
	v_or_b32_e32 v230, 0x80000000, v230
	v_xor_b32_e32 v229, v230, v129
	v_and_b32_e32 v229, 0xffffff80, v229
	v_or_b32_e32 v84, v229, v214
	v_ashrrev_i32_e32 v230, 31, v130
	v_or_b32_e32 v230, 0x80000000, v230
	v_xor_b32_e32 v229, v230, v130
	v_and_b32_e32 v229, 0xffffff80, v229
	v_or_b32_e32 v75, v229, v215
	v_ashrrev_i32_e32 v230, 31, v131
	v_or_b32_e32 v230, 0x80000000, v230
	v_xor_b32_e32 v229, v230, v131
	v_and_b32_e32 v229, 0xffffff80, v229
	v_or_b32_e32 v82, v229, v216
	v_ashrrev_i32_e32 v230, 31, v132
	v_or_b32_e32 v230, 0x80000000, v230
	v_xor_b32_e32 v229, v230, v132
	v_and_b32_e32 v229, 0xffffff80, v229
	v_or_b32_e32 v74, v229, v217
	v_ashrrev_i32_e32 v230, 31, v133
	v_or_b32_e32 v230, 0x80000000, v230
	v_xor_b32_e32 v229, v230, v133
	v_and_b32_e32 v229, 0xffffff80, v229
	v_or_b32_e32 v94, v229, v218
	v_ashrrev_i32_e32 v230, 31, v134
	v_or_b32_e32 v230, 0x80000000, v230
	v_xor_b32_e32 v229, v230, v134
	v_and_b32_e32 v229, 0xffffff80, v229
	v_or_b32_e32 v71, v229, v219
	v_ashrrev_i32_e32 v230, 31, v135
	v_or_b32_e32 v230, 0x80000000, v230
	v_xor_b32_e32 v229, v230, v135
	v_and_b32_e32 v229, 0xffffff80, v229
	v_or_b32_e32 v113, v229, v220
	v_ashrrev_i32_e32 v230, 31, v136
	v_or_b32_e32 v230, 0x80000000, v230
	v_xor_b32_e32 v229, v230, v136
	v_and_b32_e32 v229, 0xffffff80, v229
	v_or_b32_e32 v69, v229, v221
	v_ashrrev_i32_e32 v230, 31, v137
	v_or_b32_e32 v230, 0x80000000, v230
	v_xor_b32_e32 v229, v230, v137
	v_and_b32_e32 v229, 0xffffff80, v229
	v_or_b32_e32 v76, v229, v222
	v_ashrrev_i32_e32 v230, 31, v138
	v_or_b32_e32 v230, 0x80000000, v230
	v_xor_b32_e32 v229, v230, v138
	v_and_b32_e32 v229, 0xffffff80, v229
	v_or_b32_e32 v99, v229, v223
	v_ashrrev_i32_e32 v230, 31, v139
	v_or_b32_e32 v230, 0x80000000, v230
	v_xor_b32_e32 v229, v230, v139
	v_and_b32_e32 v229, 0xffffff80, v229
	v_or_b32_e32 v78, v229, v224
	v_ashrrev_i32_e32 v230, 31, v140
	v_or_b32_e32 v230, 0x80000000, v230
	v_xor_b32_e32 v229, v230, v140
	v_and_b32_e32 v229, 0xffffff80, v229
	v_or_b32_e32 v73, v229, v225
	v_ashrrev_i32_e32 v230, 31, v141
	v_or_b32_e32 v230, 0x80000000, v230
	v_xor_b32_e32 v229, v230, v141
	v_and_b32_e32 v229, 0xffffff80, v229
	v_or_b32_e32 v93, v229, v226
	v_ashrrev_i32_e32 v230, 31, v142
	v_or_b32_e32 v230, 0x80000000, v230
	v_xor_b32_e32 v229, v230, v142
	v_and_b32_e32 v229, 0xffffff80, v229
	v_or_b32_e32 v95, v229, v227
	v_ashrrev_i32_e32 v230, 31, v143
	v_or_b32_e32 v230, 0x80000000, v230
	v_xor_b32_e32 v229, v230, v143
	v_and_b32_e32 v229, 0xffffff80, v229
	v_or_b32_e32 v80, v229, v228
	v_max_u32_e32 v87, v110, v84
	v_min_u32_e32 v84, v110, v84
	v_min_u32_e32 v110, v75, v82
	v_max_u32_e32 v82, v75, v82
	v_max_u32_e32 v75, v74, v94
	v_min_u32_e32 v94, v74, v94
	v_min_u32_e32 v74, v71, v113
	v_max_u32_e32 v113, v71, v113
	v_max_u32_e32 v71, v69, v76
	v_min_u32_e32 v76, v69, v76
	v_min_u32_e32 v69, v99, v78
	v_max_u32_e32 v78, v99, v78
	v_max_u32_e32 v99, v73, v93
	v_min_u32_e32 v93, v73, v93
	v_min_u32_e32 v73, v95, v80
	v_max_u32_e32 v80, v95, v80
	v_max_u32_e32 v95, v87, v110
	v_min_u32_e32 v110, v87, v110
	v_max_u32_e32 v87, v84, v82
	v_min_u32_e32 v82, v84, v82
	v_min_u32_e32 v84, v75, v74
	v_max_u32_e32 v74, v75, v74
	v_min_u32_e32 v75, v94, v113
	v_max_u32_e32 v113, v94, v113
	v_max_u32_e32 v94, v71, v69
	v_min_u32_e32 v69, v71, v69
	v_max_u32_e32 v71, v76, v78
	v_min_u32_e32 v78, v76, v78
	v_min_u32_e32 v76, v99, v73
	v_max_u32_e32 v73, v99, v73
	v_min_u32_e32 v99, v93, v80
	v_max_u32_e32 v80, v93, v80
	v_max_u32_e32 v93, v95, v87
	v_min_u32_e32 v87, v95, v87
	v_max_u32_e32 v95, v110, v82
	v_min_u32_e32 v82, v110, v82
	v_min_u32_e32 v110, v84, v75
	v_max_u32_e32 v75, v84, v75
	v_min_u32_e32 v84, v74, v113
	v_max_u32_e32 v113, v74, v113
	v_max_u32_e32 v74, v94, v71
	v_min_u32_e32 v71, v94, v71
	v_max_u32_e32 v94, v69, v78
	v_min_u32_e32 v78, v69, v78
	v_min_u32_e32 v69, v76, v99
	v_max_u32_e32 v99, v76, v99
	v_min_u32_e32 v76, v73, v80
	v_max_u32_e32 v80, v73, v80
	v_max_u32_e32 v73, v93, v110
	v_min_u32_e32 v110, v93, v110
	v_max_u32_e32 v93, v87, v75
	v_min_u32_e32 v75, v87, v75
	v_max_u32_e32 v87, v95, v84
	v_min_u32_e32 v84, v95, v84
	v_max_u32_e32 v95, v82, v113
	v_min_u32_e32 v113, v82, v113
	v_min_u32_e32 v82, v74, v69
	v_max_u32_e32 v69, v74, v69
	v_min_u32_e32 v74, v71, v99
	v_max_u32_e32 v99, v71, v99
	v_min_u32_e32 v71, v94, v76
	v_max_u32_e32 v76, v94, v76
	v_min_u32_e32 v94, v78, v80
	v_max_u32_e32 v80, v78, v80
	v_max_u32_e32 v78, v73, v87
	v_min_u32_e32 v87, v73, v87
	v_max_u32_e32 v73, v93, v95
	v_min_u32_e32 v95, v93, v95
	v_max_u32_e32 v93, v110, v84
	v_min_u32_e32 v84, v110, v84
	v_max_u32_e32 v110, v75, v113
	v_min_u32_e32 v113, v75, v113
	v_min_u32_e32 v75, v82, v71
	v_max_u32_e32 v71, v82, v71
	v_min_u32_e32 v82, v74, v94
	v_max_u32_e32 v94, v74, v94
	v_min_u32_e32 v74, v69, v76
	v_max_u32_e32 v76, v69, v76
	v_min_u32_e32 v69, v99, v80
	v_max_u32_e32 v80, v99, v80
	v_max_u32_e32 v99, v78, v73
	v_min_u32_e32 v73, v78, v73
	v_max_u32_e32 v78, v87, v95
	v_min_u32_e32 v95, v87, v95
	v_max_u32_e32 v87, v93, v110
	v_min_u32_e32 v110, v93, v110
	v_max_u32_e32 v93, v84, v113
	v_min_u32_e32 v113, v84, v113
	v_min_u32_e32 v84, v75, v82
	v_max_u32_e32 v82, v75, v82
	v_min_u32_e32 v75, v71, v94
	v_max_u32_e32 v94, v71, v94
	v_min_u32_e32 v71, v74, v69
	v_max_u32_e32 v69, v74, v69
	v_min_u32_e32 v74, v76, v80
	v_max_u32_e32 v80, v76, v80
; template <int LOGN>
; DI void bitonic_sort_desc(unsigned (&a)[1 << LOGN]) {
;   constexpr int N = 1 << LOGN;
; #pragma unroll
;   for (int ks = 1; ks <= LOGN; ++ks)
; #pragma unroll
;     ...
; #pragma unroll
;       for (int i = 0; i < N; ++i) {
;         const int k = 1 << ks, j = 1 << js, l = i ^ j;
;         if (l > i) {
;           const bool desc = ((i & k) == 0) || (ks == LOGN);
;           const unsigned x = a[i], y = a[l];
;           const unsigned hi = max(x, y), lo = min(x, y);
;           a[i] = desc ? hi : lo;
;           a[l] = desc ? lo : hi;
;         }
;       }
; }
; DI void merge_top16(unsigned (&a)[16], const unsigned (&b)[16]) {
; #pragma unroll
;   for (int i = 0; i < 16; ++i) a[i] = max(a[i], b[15 - i]);
; #pragma unroll
;     ...
; #pragma unroll
;     for (int i = 0; i < 16; ++i) {
;       const int j = 1 << js, l = i ^ j;
;       if (l > i) {
;         const unsigned x = a[i], y = a[l];
;         a[i] = max(x, y);
;         a[l] = min(x, y);
;       }
;     }
; }
	v_max_u32_e32 v76, v99, v84
	v_min_u32_e32 v84, v99, v84
	v_max_u32_e32 v99, v73, v82
	v_min_u32_e32 v82, v73, v82
	v_max_u32_e32 v73, v78, v75
	v_min_u32_e32 v75, v78, v75
	v_max_u32_e32 v78, v95, v94
	v_min_u32_e32 v94, v95, v94
	v_max_u32_e32 v95, v87, v71
	v_min_u32_e32 v71, v87, v71
	v_max_u32_e32 v87, v110, v69
	v_min_u32_e32 v69, v110, v69
	v_max_u32_e32 v110, v93, v74
	v_min_u32_e32 v74, v93, v74
	v_max_u32_e32 v93, v113, v80
	v_min_u32_e32 v80, v113, v80
	v_max_u32_e32 v113, v76, v95
	v_min_u32_e32 v95, v76, v95
	v_max_u32_e32 v76, v99, v87
	v_min_u32_e32 v87, v99, v87
	v_max_u32_e32 v99, v73, v110
	v_min_u32_e32 v110, v73, v110
	v_max_u32_e32 v73, v78, v93
	v_min_u32_e32 v93, v78, v93
	v_max_u32_e32 v78, v84, v71
	v_min_u32_e32 v71, v84, v71
	v_max_u32_e32 v84, v82, v69
	v_min_u32_e32 v69, v82, v69
	v_max_u32_e32 v82, v75, v74
	v_min_u32_e32 v74, v75, v74
	v_max_u32_e32 v75, v94, v80
	v_min_u32_e32 v80, v94, v80
	v_max_u32_e32 v94, v113, v99
	v_min_u32_e32 v99, v113, v99
	v_max_u32_e32 v113, v76, v73
	v_min_u32_e32 v73, v76, v73
	v_max_u32_e32 v76, v95, v110
	v_min_u32_e32 v110, v95, v110
	v_max_u32_e32 v95, v87, v93
	v_min_u32_e32 v93, v87, v93
	v_max_u32_e32 v87, v78, v82
	v_min_u32_e32 v82, v78, v82
	v_max_u32_e32 v78, v84, v75
	v_min_u32_e32 v75, v84, v75
	v_max_u32_e32 v84, v71, v74
	v_min_u32_e32 v74, v71, v74
	v_max_u32_e32 v71, v69, v80
	v_min_u32_e32 v80, v69, v80
	v_max_u32_e32 v69, v94, v113
	v_min_u32_e32 v113, v94, v113
	v_max_u32_e32 v94, v99, v73
	v_min_u32_e32 v73, v99, v73
	v_max_u32_e32 v99, v76, v95
	v_min_u32_e32 v95, v76, v95
	v_max_u32_e32 v76, v110, v93
	v_min_u32_e32 v93, v110, v93
	v_max_u32_e32 v110, v87, v78
	v_min_u32_e32 v78, v87, v78
	v_max_u32_e32 v87, v82, v75
	v_min_u32_e32 v75, v82, v75
	v_max_u32_e32 v82, v84, v71
	v_min_u32_e32 v71, v84, v71
	v_max_u32_e32 v84, v74, v80
	v_min_u32_e32 v80, v74, v80
	v_max_u32_e32 v74, v104, v80
	v_max_u32_e32 v104, v91, v84
	v_max_u32_e32 v91, v86, v71
	v_max_u32_e32 v86, v117, v82
	v_max_u32_e32 v117, v77, v75
	v_max_u32_e32 v77, v70, v87
	v_max_u32_e32 v70, v72, v78
	v_max_u32_e32 v72, v102, v110
	v_max_u32_e32 v102, v96, v93
	v_max_u32_e32 v96, v103, v76
	v_max_u32_e32 v103, v105, v95
	v_max_u32_e32 v105, v97, v99
	v_max_u32_e32 v97, v100, v73
	v_max_u32_e32 v100, v79, v94
	v_max_u32_e32 v79, v88, v113
	v_max_u32_e32 v88, v92, v69
	v_max_u32_e32 v80, v74, v102
	v_min_u32_e32 v102, v74, v102
	v_max_u32_e32 v74, v104, v96
	v_min_u32_e32 v96, v104, v96
	v_max_u32_e32 v104, v91, v103
	v_min_u32_e32 v103, v91, v103
	v_max_u32_e32 v91, v86, v105
	v_min_u32_e32 v105, v86, v105
	v_max_u32_e32 v86, v117, v97
	v_min_u32_e32 v97, v117, v97
	v_max_u32_e32 v117, v77, v100
	v_min_u32_e32 v100, v77, v100
	v_max_u32_e32 v77, v70, v79
	v_min_u32_e32 v79, v70, v79
	v_max_u32_e32 v70, v72, v88
	v_min_u32_e32 v88, v72, v88
	v_max_u32_e32 v72, v80, v86
	v_min_u32_e32 v86, v80, v86
	v_max_u32_e32 v80, v74, v117
	v_min_u32_e32 v117, v74, v117
	v_max_u32_e32 v74, v104, v77
	v_min_u32_e32 v77, v104, v77
	v_max_u32_e32 v104, v91, v70
	v_min_u32_e32 v70, v91, v70
	v_max_u32_e32 v91, v102, v97
	v_min_u32_e32 v97, v102, v97
	v_max_u32_e32 v102, v96, v100
	v_min_u32_e32 v100, v96, v100
	v_max_u32_e32 v96, v103, v79
	v_min_u32_e32 v79, v103, v79
	v_max_u32_e32 v103, v105, v88
	v_min_u32_e32 v88, v105, v88
	v_max_u32_e32 v105, v72, v74
	v_min_u32_e32 v74, v72, v74
	v_max_u32_e32 v72, v80, v104
	v_min_u32_e32 v104, v80, v104
	v_max_u32_e32 v80, v86, v77
	v_min_u32_e32 v77, v86, v77
	v_max_u32_e32 v86, v117, v70
	v_min_u32_e32 v70, v117, v70
	v_max_u32_e32 v117, v91, v96
	v_min_u32_e32 v96, v91, v96
	v_max_u32_e32 v91, v102, v103
	v_min_u32_e32 v103, v102, v103
	v_max_u32_e32 v102, v97, v79
	v_min_u32_e32 v79, v97, v79
	v_max_u32_e32 v97, v100, v88
	v_min_u32_e32 v88, v100, v88
	v_max_u32_e32 v100, v105, v72
	v_min_u32_e32 v72, v105, v72
	v_max_u32_e32 v105, v74, v104
	v_min_u32_e32 v104, v74, v104
	v_max_u32_e32 v74, v80, v86
	v_min_u32_e32 v86, v80, v86
	v_max_u32_e32 v80, v77, v70
	v_min_u32_e32 v70, v77, v70
	v_max_u32_e32 v77, v117, v91
	v_min_u32_e32 v91, v117, v91
	v_max_u32_e32 v117, v96, v103
	v_min_u32_e32 v103, v96, v103
	v_max_u32_e32 v96, v102, v97
	v_min_u32_e32 v97, v102, v97
	v_max_u32_e32 v102, v79, v88
	v_min_u32_e32 v88, v79, v88
	v_max_u32_e32 v79, v115, v88
	v_max_u32_e32 v115, v89, v102
	v_max_u32_e32 v89, v90, v97
	v_max_u32_e32 v90, v112, v96
	v_max_u32_e32 v112, v116, v103
	v_max_u32_e32 v116, v109, v117
	v_max_u32_e32 v109, v108, v91
	v_max_u32_e32 v108, v111, v77
	v_max_u32_e32 v111, v106, v70
	v_max_u32_e32 v106, v85, v80
	v_max_u32_e32 v85, v101, v86
	v_max_u32_e32 v101, v83, v74
	v_max_u32_e32 v83, v114, v104
	v_max_u32_e32 v114, v81, v105
	v_max_u32_e32 v81, v107, v72
	v_max_u32_e32 v107, v98, v100
	v_max_u32_e32 v88, v79, v111
	v_min_u32_e32 v111, v79, v111
	v_max_u32_e32 v79, v115, v106
	v_min_u32_e32 v106, v115, v106
	v_max_u32_e32 v115, v89, v85
	v_min_u32_e32 v85, v89, v85
	v_max_u32_e32 v89, v90, v101
	v_min_u32_e32 v101, v90, v101
	v_max_u32_e32 v90, v112, v83
	v_min_u32_e32 v83, v112, v83
	v_max_u32_e32 v112, v116, v114
	v_min_u32_e32 v114, v116, v114
	v_max_u32_e32 v116, v109, v81
	v_min_u32_e32 v81, v109, v81
	v_max_u32_e32 v109, v108, v107
	v_min_u32_e32 v107, v108, v107
	v_max_u32_e32 v108, v88, v90
	v_min_u32_e32 v90, v88, v90
	v_max_u32_e32 v88, v79, v112
	v_min_u32_e32 v112, v79, v112
	v_max_u32_e32 v79, v115, v116
	v_min_u32_e32 v116, v115, v116
	v_max_u32_e32 v115, v89, v109
	v_min_u32_e32 v109, v89, v109
	v_max_u32_e32 v89, v111, v83
	v_min_u32_e32 v83, v111, v83
	v_max_u32_e32 v111, v106, v114
	v_min_u32_e32 v114, v106, v114
; DI void merge_top16(unsigned (&a)[16], const unsigned (&b)[16]) {
; #pragma unroll
;   for (int i = 0; i < 16; ++i) a[i] = max(a[i], b[15 - i]);
; #pragma unroll
;     ...
; #pragma unroll
;     for (int i = 0; i < 16; ++i) {
;       const int j = 1 << js, l = i ^ j;
;       if (l > i) {
;         const unsigned x = a[i], y = a[l];
;         a[i] = max(x, y);
;         a[l] = min(x, y);
;       }
;     }
; }
; DI void peer_top16(const u16* __restrict__ PQrow, const u16* __restrict__ SK, unsigned (&top)[16], int lr, int hh) {
;     ...
;   merge_top16(g[0], g[1]);
;   merge_top16(g[2], g[3]);
;   merge_top16(g[0], g[2]);
;   unsigned other[16];
; #pragma unroll
;   for (int i = 0; i < 16; ++i) other[i] = (unsigned)__shfl_xor((int)g[0][i], 32);
;   merge_top16(g[0], other);
	v_max_u32_e32 v106, v85, v81
	v_min_u32_e32 v81, v85, v81
	v_max_u32_e32 v85, v101, v107
	v_min_u32_e32 v107, v101, v107
	v_max_u32_e32 v101, v108, v79
	v_min_u32_e32 v79, v108, v79
	v_max_u32_e32 v108, v88, v115
	v_min_u32_e32 v115, v88, v115
	v_max_u32_e32 v88, v90, v116
	v_min_u32_e32 v116, v90, v116
	v_max_u32_e32 v90, v112, v109
	v_min_u32_e32 v109, v112, v109
	v_max_u32_e32 v112, v89, v106
	v_min_u32_e32 v106, v89, v106
	v_max_u32_e32 v89, v111, v85
	v_min_u32_e32 v85, v111, v85
	v_max_u32_e32 v111, v83, v81
	v_min_u32_e32 v81, v83, v81
	v_max_u32_e32 v83, v114, v107
	v_min_u32_e32 v107, v114, v107
	v_max_u32_e32 v114, v101, v108
	v_min_u32_e32 v108, v101, v108
	v_max_u32_e32 v101, v79, v115
	v_min_u32_e32 v115, v79, v115
	v_max_u32_e32 v79, v88, v90
	v_min_u32_e32 v90, v88, v90
	v_max_u32_e32 v88, v116, v109
	v_min_u32_e32 v109, v116, v109
	v_max_u32_e32 v116, v112, v89
	v_min_u32_e32 v89, v112, v89
	v_max_u32_e32 v112, v106, v85
	v_min_u32_e32 v85, v106, v85
	v_max_u32_e32 v106, v111, v83
	v_min_u32_e32 v83, v111, v83
	v_max_u32_e32 v111, v81, v107
	v_min_u32_e32 v107, v81, v107
	v_mov_b32_e32 v48, v114
	v_mov_b32_e32 v49, v108
	v_mov_b32_e32 v50, v101
	v_mov_b32_e32 v51, v115
	v_mov_b32_e32 v52, v79
	v_mov_b32_e32 v53, v90
	v_mov_b32_e32 v54, v88
	v_mov_b32_e32 v55, v109
	v_mov_b32_e32 v56, v116
	v_mov_b32_e32 v57, v89
	v_mov_b32_e32 v58, v112
	v_mov_b32_e32 v59, v85
	v_mov_b32_e32 v60, v106
	v_mov_b32_e32 v61, v83
	v_mov_b32_e32 v62, v111
	v_mov_b32_e32 v63, v107
	s_nop 1
	v_permlane32_swap_b32_e32 v0, v32
	v_permlane32_swap_b32_e32 v1, v33
	v_permlane32_swap_b32_e32 v2, v34
	v_permlane32_swap_b32_e32 v3, v35
	v_permlane32_swap_b32_e32 v4, v36
	v_permlane32_swap_b32_e32 v5, v37
	v_permlane32_swap_b32_e32 v6, v38
	v_permlane32_swap_b32_e32 v7, v39
	v_permlane32_swap_b32_e32 v8, v40
	v_permlane32_swap_b32_e32 v9, v41
	v_permlane32_swap_b32_e32 v10, v42
	v_permlane32_swap_b32_e32 v11, v43
	v_permlane32_swap_b32_e32 v12, v44
	v_permlane32_swap_b32_e32 v13, v45
	v_permlane32_swap_b32_e32 v14, v46
	v_permlane32_swap_b32_e32 v15, v47
	v_permlane32_swap_b32_e32 v16, v48
	v_permlane32_swap_b32_e32 v17, v49
	v_permlane32_swap_b32_e32 v18, v50
	v_permlane32_swap_b32_e32 v19, v51
	v_permlane32_swap_b32_e32 v20, v52
	v_permlane32_swap_b32_e32 v21, v53
	v_permlane32_swap_b32_e32 v22, v54
	v_permlane32_swap_b32_e32 v23, v55
	v_permlane32_swap_b32_e32 v24, v56
	v_permlane32_swap_b32_e32 v25, v57
	v_permlane32_swap_b32_e32 v26, v58
	v_permlane32_swap_b32_e32 v27, v59
	v_permlane32_swap_b32_e32 v28, v60
	v_permlane32_swap_b32_e32 v29, v61
	v_permlane32_swap_b32_e32 v30, v62
	v_permlane32_swap_b32_e32 v31, v63
	v_max_u32_e32 v107, v0, v47
	v_max_u32_e32 v0, v1, v46
	v_max_u32_e32 v1, v2, v45
	v_max_u32_e32 v2, v3, v44
	v_max_u32_e32 v3, v4, v43
	v_max_u32_e32 v4, v5, v42
	v_max_u32_e32 v5, v6, v41
	v_max_u32_e32 v6, v7, v40
	v_max_u32_e32 v7, v8, v39
	v_max_u32_e32 v8, v9, v38
	v_max_u32_e32 v9, v10, v37
	v_max_u32_e32 v10, v11, v36
	v_max_u32_e32 v11, v12, v35
	v_max_u32_e32 v12, v13, v34
	v_max_u32_e32 v13, v14, v33
	v_max_u32_e32 v14, v15, v32
	v_max_u32_e32 v47, v107, v7
	v_min_u32_e32 v7, v107, v7
	v_max_u32_e32 v107, v0, v8
	v_min_u32_e32 v8, v0, v8
	v_max_u32_e32 v0, v1, v9
	v_min_u32_e32 v9, v1, v9
	v_max_u32_e32 v1, v2, v10
	v_min_u32_e32 v10, v2, v10
	v_max_u32_e32 v2, v3, v11
	v_min_u32_e32 v11, v3, v11
	v_max_u32_e32 v3, v4, v12
	v_min_u32_e32 v12, v4, v12
	v_max_u32_e32 v4, v5, v13
	v_min_u32_e32 v13, v5, v13
	v_max_u32_e32 v5, v6, v14
	v_min_u32_e32 v14, v6, v14
	v_max_u32_e32 v6, v47, v2
	v_min_u32_e32 v2, v47, v2
	v_max_u32_e32 v47, v107, v3
	v_min_u32_e32 v3, v107, v3
	v_max_u32_e32 v107, v0, v4
	v_min_u32_e32 v4, v0, v4
	v_max_u32_e32 v0, v1, v5
	v_min_u32_e32 v5, v1, v5
	v_max_u32_e32 v1, v7, v11
	v_min_u32_e32 v11, v7, v11
	v_max_u32_e32 v7, v8, v12
	v_min_u32_e32 v12, v8, v12
	v_max_u32_e32 v8, v9, v13
	v_min_u32_e32 v13, v9, v13
	v_max_u32_e32 v9, v10, v14
	v_min_u32_e32 v14, v10, v14
	v_max_u32_e32 v10, v6, v107
	v_min_u32_e32 v107, v6, v107
	v_max_u32_e32 v6, v47, v0
	v_min_u32_e32 v0, v47, v0
	v_max_u32_e32 v47, v2, v4
	v_min_u32_e32 v4, v2, v4
	v_max_u32_e32 v2, v3, v5
	v_min_u32_e32 v5, v3, v5
	v_max_u32_e32 v3, v1, v8
	v_min_u32_e32 v8, v1, v8
	v_max_u32_e32 v1, v7, v9
	v_min_u32_e32 v9, v7, v9
	v_max_u32_e32 v7, v11, v13
	v_min_u32_e32 v13, v11, v13
	v_max_u32_e32 v11, v12, v14
	v_min_u32_e32 v14, v12, v14
	v_max_u32_e32 v12, v10, v6
	v_min_u32_e32 v6, v10, v6
	v_max_u32_e32 v10, v107, v0
	v_min_u32_e32 v0, v107, v0
	v_max_u32_e32 v107, v47, v2
	v_min_u32_e32 v2, v47, v2
	v_max_u32_e32 v47, v4, v5
	v_min_u32_e32 v5, v4, v5
	v_max_u32_e32 v4, v3, v1
	v_min_u32_e32 v1, v3, v1
	v_max_u32_e32 v3, v8, v9
	v_min_u32_e32 v9, v8, v9
	v_max_u32_e32 v8, v7, v11
	v_min_u32_e32 v11, v7, v11
	v_max_u32_e32 v7, v13, v14
	v_min_u32_e32 v14, v13, v14
	v_max_u32_e32 v13, v16, v63
	v_max_u32_e32 v16, v17, v62
	v_max_u32_e32 v17, v18, v61
	v_max_u32_e32 v18, v19, v60
	v_max_u32_e32 v19, v20, v59
	v_max_u32_e32 v20, v21, v58
	v_max_u32_e32 v21, v22, v57
	v_max_u32_e32 v22, v23, v56
	v_max_u32_e32 v23, v24, v55
	v_max_u32_e32 v24, v25, v54
	v_max_u32_e32 v25, v26, v53
	v_max_u32_e32 v26, v27, v52
	v_max_u32_e32 v27, v28, v51
	v_max_u32_e32 v28, v29, v50
	v_max_u32_e32 v29, v30, v49
	v_max_u32_e32 v30, v31, v48
	v_max_u32_e32 v63, v13, v23
	v_min_u32_e32 v23, v13, v23
	v_max_u32_e32 v13, v16, v24
	v_min_u32_e32 v24, v16, v24
	v_max_u32_e32 v16, v17, v25
	v_min_u32_e32 v25, v17, v25
	v_max_u32_e32 v17, v18, v26
	v_min_u32_e32 v26, v18, v26
	v_max_u32_e32 v18, v19, v27
	v_min_u32_e32 v27, v19, v27
	v_max_u32_e32 v19, v20, v28
; DI float ord2f(unsigned u) { return __uint_as_float((u & 0x80000000u) ? (u ^ 0x80000000u) : ~u); }
; DI void merge_top16(unsigned (&a)[16], const unsigned (&b)[16]) {
; #pragma unroll
;   for (int i = 0; i < 16; ++i) a[i] = max(a[i], b[15 - i]);
; #pragma unroll
;     ...
; #pragma unroll
;     for (int i = 0; i < 16; ++i) {
;       const int j = 1 << js, l = i ^ j;
;       if (l > i) {
;         const unsigned x = a[i], y = a[l];
;         a[i] = max(x, y);
;         a[l] = min(x, y);
;       }
;     }
; }
; template <bool STORE>
; DI void peer_item(const Params& p, int item, char* smem) {
;     ...
; #pragma unroll
;     for (int a = 0; a < 16; ++a)
; #pragma unroll
;       for (int bq = 0; bq < 16; ++bq)
;         if ((a + 1) * (bq + 1) <= 16)
;           ckey[a][bq] = (f2ord(ord2f(top1[a] & ~127u) + ord2f(top2[bq] & ~127u)) & ~255u) | (unsigned)(255 - (a * 16 + bq));
	v_min_u32_e32 v28, v20, v28
	v_max_u32_e32 v20, v21, v29
	v_min_u32_e32 v29, v21, v29
	v_max_u32_e32 v21, v22, v30
	v_min_u32_e32 v30, v22, v30
	v_max_u32_e32 v22, v63, v18
	v_min_u32_e32 v18, v63, v18
	v_max_u32_e32 v63, v13, v19
	v_min_u32_e32 v19, v13, v19
	v_max_u32_e32 v13, v16, v20
	v_min_u32_e32 v20, v16, v20
	v_max_u32_e32 v16, v17, v21
	v_min_u32_e32 v21, v17, v21
	v_max_u32_e32 v17, v23, v27
	v_min_u32_e32 v27, v23, v27
	v_max_u32_e32 v23, v24, v28
	v_min_u32_e32 v28, v24, v28
	v_max_u32_e32 v24, v25, v29
	v_min_u32_e32 v29, v25, v29
	v_max_u32_e32 v25, v26, v30
	v_min_u32_e32 v30, v26, v30
	v_max_u32_e32 v26, v22, v13
	v_min_u32_e32 v13, v22, v13
	v_max_u32_e32 v22, v63, v16
	v_min_u32_e32 v16, v63, v16
	v_max_u32_e32 v63, v18, v20
	v_min_u32_e32 v20, v18, v20
	v_max_u32_e32 v18, v19, v21
	v_min_u32_e32 v21, v19, v21
	v_max_u32_e32 v19, v17, v24
	v_min_u32_e32 v24, v17, v24
	v_max_u32_e32 v17, v23, v25
	v_min_u32_e32 v25, v23, v25
	v_max_u32_e32 v23, v27, v29
	v_min_u32_e32 v29, v27, v29
	v_max_u32_e32 v27, v28, v30
	v_min_u32_e32 v30, v28, v30
	v_max_u32_e32 v28, v26, v22
	v_min_u32_e32 v22, v26, v22
	v_max_u32_e32 v26, v13, v16
	v_min_u32_e32 v16, v13, v16
	v_max_u32_e32 v13, v63, v18
	v_min_u32_e32 v18, v63, v18
	v_max_u32_e32 v63, v20, v21
	v_min_u32_e32 v21, v20, v21
	v_max_u32_e32 v20, v19, v17
	v_min_u32_e32 v17, v19, v17
	v_max_u32_e32 v19, v24, v25
	v_min_u32_e32 v25, v24, v25
	v_max_u32_e32 v24, v23, v27
	v_min_u32_e32 v27, v23, v27
	v_max_u32_e32 v23, v29, v30
	v_min_u32_e32 v30, v29, v30
	v_xor_b32_e32 v229, 0x7f, v12
	v_and_b32_e32 v229, 0x7f, v229
	v_mov_b32_e32 v29, v229
	v_xor_b32_e32 v229, 0x7f, v6
	v_and_b32_e32 v229, 0x7f, v229
	v_lshl_or_b32 v29, v229, 8, v29
	v_xor_b32_e32 v229, 0x7f, v10
	v_and_b32_e32 v229, 0x7f, v229
	v_lshl_or_b32 v29, v229, 16, v29
	v_xor_b32_e32 v229, 0x7f, v0
	v_and_b32_e32 v229, 0x7f, v229
	v_lshl_or_b32 v29, v229, 24, v29
	v_xor_b32_e32 v229, 0x7f, v107
	v_and_b32_e32 v229, 0x7f, v229
	v_mov_b32_e32 v62, v229
	v_xor_b32_e32 v229, 0x7f, v2
	v_and_b32_e32 v229, 0x7f, v229
	v_lshl_or_b32 v62, v229, 8, v62
	v_xor_b32_e32 v229, 0x7f, v47
	v_and_b32_e32 v229, 0x7f, v229
	v_lshl_or_b32 v62, v229, 16, v62
	v_xor_b32_e32 v229, 0x7f, v5
	v_and_b32_e32 v229, 0x7f, v229
	v_lshl_or_b32 v62, v229, 24, v62
	v_xor_b32_e32 v229, 0x7f, v4
	v_and_b32_e32 v229, 0x7f, v229
	v_mov_b32_e32 v61, v229
	v_xor_b32_e32 v229, 0x7f, v1
	v_and_b32_e32 v229, 0x7f, v229
	v_lshl_or_b32 v61, v229, 8, v61
	v_xor_b32_e32 v229, 0x7f, v3
	v_and_b32_e32 v229, 0x7f, v229
	v_lshl_or_b32 v61, v229, 16, v61
	v_xor_b32_e32 v229, 0x7f, v9
	v_and_b32_e32 v229, 0x7f, v229
	v_lshl_or_b32 v61, v229, 24, v61
	v_xor_b32_e32 v229, 0x7f, v8
	v_and_b32_e32 v229, 0x7f, v229
	v_mov_b32_e32 v60, v229
	v_xor_b32_e32 v229, 0x7f, v11
	v_and_b32_e32 v229, 0x7f, v229
	v_lshl_or_b32 v60, v229, 8, v60
	v_xor_b32_e32 v229, 0x7f, v7
	v_and_b32_e32 v229, 0x7f, v229
	v_lshl_or_b32 v60, v229, 16, v60
	v_xor_b32_e32 v229, 0x7f, v14
	v_and_b32_e32 v229, 0x7f, v229
	v_lshl_or_b32 v60, v229, 24, v60
	v_xor_b32_e32 v229, 0x7f, v28
	v_and_b32_e32 v229, 0x7f, v229
	v_mov_b32_e32 v59, v229
	v_xor_b32_e32 v229, 0x7f, v22
	v_and_b32_e32 v229, 0x7f, v229
	v_lshl_or_b32 v59, v229, 8, v59
	v_xor_b32_e32 v229, 0x7f, v26
	v_and_b32_e32 v229, 0x7f, v229
	v_lshl_or_b32 v59, v229, 16, v59
	v_xor_b32_e32 v229, 0x7f, v16
	v_and_b32_e32 v229, 0x7f, v229
	v_lshl_or_b32 v59, v229, 24, v59
	v_xor_b32_e32 v229, 0x7f, v13
	v_and_b32_e32 v229, 0x7f, v229
	v_mov_b32_e32 v58, v229
	v_xor_b32_e32 v229, 0x7f, v18
	v_and_b32_e32 v229, 0x7f, v229
	v_lshl_or_b32 v58, v229, 8, v58
	v_xor_b32_e32 v229, 0x7f, v63
	v_and_b32_e32 v229, 0x7f, v229
	v_lshl_or_b32 v58, v229, 16, v58
	v_xor_b32_e32 v229, 0x7f, v21
	v_and_b32_e32 v229, 0x7f, v229
	v_lshl_or_b32 v58, v229, 24, v58
	v_xor_b32_e32 v229, 0x7f, v20
	v_and_b32_e32 v229, 0x7f, v229
	v_mov_b32_e32 v57, v229
	v_xor_b32_e32 v229, 0x7f, v17
	v_and_b32_e32 v229, 0x7f, v229
	v_lshl_or_b32 v57, v229, 8, v57
	v_xor_b32_e32 v229, 0x7f, v19
	v_and_b32_e32 v229, 0x7f, v229
	v_lshl_or_b32 v57, v229, 16, v57
	v_xor_b32_e32 v229, 0x7f, v25
	v_and_b32_e32 v229, 0x7f, v229
	v_lshl_or_b32 v57, v229, 24, v57
	v_xor_b32_e32 v229, 0x7f, v24
	v_and_b32_e32 v229, 0x7f, v229
	v_mov_b32_e32 v56, v229
	v_xor_b32_e32 v229, 0x7f, v27
	v_and_b32_e32 v229, 0x7f, v229
	v_lshl_or_b32 v56, v229, 8, v56
	v_xor_b32_e32 v229, 0x7f, v23
	v_and_b32_e32 v229, 0x7f, v229
	v_lshl_or_b32 v56, v229, 16, v56
	v_xor_b32_e32 v229, 0x7f, v30
	v_and_b32_e32 v229, 0x7f, v229
	v_lshl_or_b32 v56, v229, 24, v56
	ds_write_b32 v241, v29 offset:0
	ds_write_b32 v241, v62 offset:4
	ds_write_b32 v241, v61 offset:8
	ds_write_b32 v241, v60 offset:12
	ds_write_b32 v241, v59 offset:16
	ds_write_b32 v241, v58 offset:20
	ds_write_b32 v241, v57 offset:24
	ds_write_b32 v241, v56 offset:28
	v_and_b32_e32 v229, 0xffffff80, v12
	v_ashrrev_i32_e32 v230, 31, v229
	v_not_b32_e32 v230, v230
	v_or_b32_e32 v230, 0x80000000, v230
	v_xor_b32_e32 v56, v230, v229
	v_and_b32_e32 v229, 0xffffff80, v6
	v_ashrrev_i32_e32 v230, 31, v229
	v_not_b32_e32 v230, v230
	v_or_b32_e32 v230, 0x80000000, v230
	v_xor_b32_e32 v57, v230, v229
	v_and_b32_e32 v229, 0xffffff80, v10
	v_ashrrev_i32_e32 v230, 31, v229
	v_not_b32_e32 v230, v230
	v_or_b32_e32 v230, 0x80000000, v230
	v_xor_b32_e32 v58, v230, v229
	v_and_b32_e32 v229, 0xffffff80, v0
	v_ashrrev_i32_e32 v230, 31, v229
	v_not_b32_e32 v230, v230
	v_or_b32_e32 v230, 0x80000000, v230
	v_xor_b32_e32 v59, v230, v229
	v_and_b32_e32 v229, 0xffffff80, v107
	v_ashrrev_i32_e32 v230, 31, v229
	v_not_b32_e32 v230, v230
	v_or_b32_e32 v230, 0x80000000, v230
	v_xor_b32_e32 v60, v230, v229
; DI float ord2f(unsigned u) { return __uint_as_float((u & 0x80000000u) ? (u ^ 0x80000000u) : ~u); }
; template <bool STORE>
; DI void peer_item(const Params& p, int item, char* smem) {
;     ...
; #pragma unroll
;     for (int a = 0; a < 16; ++a)
; #pragma unroll
;       for (int bq = 0; bq < 16; ++bq)
;         if ((a + 1) * (bq + 1) <= 16)
;           ckey[a][bq] = (f2ord(ord2f(top1[a] & ~127u) + ord2f(top2[bq] & ~127u)) & ~255u) | (unsigned)(255 - (a * 16 + bq));
	v_and_b32_e32 v229, 0xffffff80, v2
	v_ashrrev_i32_e32 v230, 31, v229
	v_not_b32_e32 v230, v230
	v_or_b32_e32 v230, 0x80000000, v230
	v_xor_b32_e32 v61, v230, v229
	v_and_b32_e32 v229, 0xffffff80, v47
	v_ashrrev_i32_e32 v230, 31, v229
	v_not_b32_e32 v230, v230
	v_or_b32_e32 v230, 0x80000000, v230
	v_xor_b32_e32 v62, v230, v229
	v_and_b32_e32 v229, 0xffffff80, v5
	v_ashrrev_i32_e32 v230, 31, v229
	v_not_b32_e32 v230, v230
	v_or_b32_e32 v230, 0x80000000, v230
	v_xor_b32_e32 v29, v230, v229
	v_and_b32_e32 v229, 0xffffff80, v4
	v_ashrrev_i32_e32 v230, 31, v229
	v_not_b32_e32 v230, v230
	v_or_b32_e32 v230, 0x80000000, v230
	v_xor_b32_e32 v55, v230, v229
	v_and_b32_e32 v229, 0xffffff80, v1
	v_ashrrev_i32_e32 v230, 31, v229
	v_not_b32_e32 v230, v230
	v_or_b32_e32 v230, 0x80000000, v230
	v_xor_b32_e32 v54, v230, v229
	v_and_b32_e32 v229, 0xffffff80, v3
	v_ashrrev_i32_e32 v230, 31, v229
	v_not_b32_e32 v230, v230
	v_or_b32_e32 v230, 0x80000000, v230
	v_xor_b32_e32 v53, v230, v229
	v_and_b32_e32 v229, 0xffffff80, v9
	v_ashrrev_i32_e32 v230, 31, v229
	v_not_b32_e32 v230, v230
	v_or_b32_e32 v230, 0x80000000, v230
	v_xor_b32_e32 v52, v230, v229
	v_and_b32_e32 v229, 0xffffff80, v8
	v_ashrrev_i32_e32 v230, 31, v229
	v_not_b32_e32 v230, v230
	v_or_b32_e32 v230, 0x80000000, v230
	v_xor_b32_e32 v51, v230, v229
	v_and_b32_e32 v229, 0xffffff80, v11
	v_ashrrev_i32_e32 v230, 31, v229
	v_not_b32_e32 v230, v230
	v_or_b32_e32 v230, 0x80000000, v230
	v_xor_b32_e32 v50, v230, v229
	v_and_b32_e32 v229, 0xffffff80, v7
	v_ashrrev_i32_e32 v230, 31, v229
	v_not_b32_e32 v230, v230
	v_or_b32_e32 v230, 0x80000000, v230
	v_xor_b32_e32 v49, v230, v229
	v_and_b32_e32 v229, 0xffffff80, v14
	v_ashrrev_i32_e32 v230, 31, v229
	v_not_b32_e32 v230, v230
	v_or_b32_e32 v230, 0x80000000, v230
	v_xor_b32_e32 v48, v230, v229
	v_and_b32_e32 v229, 0xffffff80, v28
	v_ashrrev_i32_e32 v230, 31, v229
	v_not_b32_e32 v230, v230
	v_or_b32_e32 v230, 0x80000000, v230
	v_xor_b32_e32 v31, v230, v229
	v_and_b32_e32 v229, 0xffffff80, v22
	v_ashrrev_i32_e32 v230, 31, v229
	v_not_b32_e32 v230, v230
	v_or_b32_e32 v230, 0x80000000, v230
	v_xor_b32_e32 v46, v230, v229
	v_and_b32_e32 v229, 0xffffff80, v26
	v_ashrrev_i32_e32 v230, 31, v229
	v_not_b32_e32 v230, v230
	v_or_b32_e32 v230, 0x80000000, v230
	v_xor_b32_e32 v45, v230, v229
	v_and_b32_e32 v229, 0xffffff80, v16
	v_ashrrev_i32_e32 v230, 31, v229
	v_not_b32_e32 v230, v230
	v_or_b32_e32 v230, 0x80000000, v230
	v_xor_b32_e32 v44, v230, v229
	v_and_b32_e32 v229, 0xffffff80, v13
	v_ashrrev_i32_e32 v230, 31, v229
	v_not_b32_e32 v230, v230
	v_or_b32_e32 v230, 0x80000000, v230
	v_xor_b32_e32 v43, v230, v229
	v_and_b32_e32 v229, 0xffffff80, v18
	v_ashrrev_i32_e32 v230, 31, v229
	v_not_b32_e32 v230, v230
	v_or_b32_e32 v230, 0x80000000, v230
	v_xor_b32_e32 v42, v230, v229
	v_and_b32_e32 v229, 0xffffff80, v63
	v_ashrrev_i32_e32 v230, 31, v229
	v_not_b32_e32 v230, v230
	v_or_b32_e32 v230, 0x80000000, v230
	v_xor_b32_e32 v41, v230, v229
	v_and_b32_e32 v229, 0xffffff80, v21
	v_ashrrev_i32_e32 v230, 31, v229
	v_not_b32_e32 v230, v230
	v_or_b32_e32 v230, 0x80000000, v230
	v_xor_b32_e32 v40, v230, v229
	v_and_b32_e32 v229, 0xffffff80, v20
	v_ashrrev_i32_e32 v230, 31, v229
	v_not_b32_e32 v230, v230
	v_or_b32_e32 v230, 0x80000000, v230
	v_xor_b32_e32 v39, v230, v229
	v_and_b32_e32 v229, 0xffffff80, v17
	v_ashrrev_i32_e32 v230, 31, v229
	v_not_b32_e32 v230, v230
	v_or_b32_e32 v230, 0x80000000, v230
	v_xor_b32_e32 v38, v230, v229
	v_and_b32_e32 v229, 0xffffff80, v19
	v_ashrrev_i32_e32 v230, 31, v229
	v_not_b32_e32 v230, v230
	v_or_b32_e32 v230, 0x80000000, v230
	v_xor_b32_e32 v37, v230, v229
	v_and_b32_e32 v229, 0xffffff80, v25
	v_ashrrev_i32_e32 v230, 31, v229
	v_not_b32_e32 v230, v230
	v_or_b32_e32 v230, 0x80000000, v230
	v_xor_b32_e32 v36, v230, v229
	v_and_b32_e32 v229, 0xffffff80, v24
	v_ashrrev_i32_e32 v230, 31, v229
	v_not_b32_e32 v230, v230
	v_or_b32_e32 v230, 0x80000000, v230
	v_xor_b32_e32 v35, v230, v229
	v_and_b32_e32 v229, 0xffffff80, v27
	v_ashrrev_i32_e32 v230, 31, v229
	v_not_b32_e32 v230, v230
	v_or_b32_e32 v230, 0x80000000, v230
	v_xor_b32_e32 v34, v230, v229
	v_and_b32_e32 v229, 0xffffff80, v23
	v_ashrrev_i32_e32 v230, 31, v229
	v_not_b32_e32 v230, v230
	v_or_b32_e32 v230, 0x80000000, v230
	v_xor_b32_e32 v33, v230, v229
	v_and_b32_e32 v229, 0xffffff80, v30
	v_ashrrev_i32_e32 v230, 31, v229
	v_not_b32_e32 v230, v230
	v_or_b32_e32 v230, 0x80000000, v230
	v_xor_b32_e32 v32, v230, v229
	v_add_f32_e32 v229, v56, v31
	v_ashrrev_i32_e32 v230, 31, v229
	v_or_b32_e32 v230, 0x80000000, v230
	v_xor_b32_e32 v231, v230, v229
	v_and_b32_e32 v231, 0xffffff00, v231
	v_or_b32_e32 v15, 0xff, v231
	v_add_f32_e32 v229, v56, v46
	v_ashrrev_i32_e32 v230, 31, v229
	v_or_b32_e32 v230, 0x80000000, v230
	v_xor_b32_e32 v231, v230, v229
	v_and_b32_e32 v231, 0xffffff00, v231
	v_or_b32_e32 v111, 0xfe, v231
	v_add_f32_e32 v229, v56, v45
	v_ashrrev_i32_e32 v230, 31, v229
	v_or_b32_e32 v230, 0x80000000, v230
	v_xor_b32_e32 v231, v230, v229
	v_and_b32_e32 v231, 0xffffff00, v231
	v_or_b32_e32 v83, 0xfd, v231
	v_add_f32_e32 v229, v56, v44
	v_ashrrev_i32_e32 v230, 31, v229
	v_or_b32_e32 v230, 0x80000000, v230
	v_xor_b32_e32 v231, v230, v229
	v_and_b32_e32 v231, 0xffffff00, v231
	v_or_b32_e32 v106, 0xfc, v231
	v_add_f32_e32 v229, v56, v43
	v_ashrrev_i32_e32 v230, 31, v229
	v_or_b32_e32 v230, 0x80000000, v230
	v_xor_b32_e32 v231, v230, v229
	v_and_b32_e32 v231, 0xffffff00, v231
	v_or_b32_e32 v85, 0xfb, v231
	v_add_f32_e32 v229, v56, v42
	v_ashrrev_i32_e32 v230, 31, v229
	v_or_b32_e32 v230, 0x80000000, v230
	v_xor_b32_e32 v231, v230, v229
	v_and_b32_e32 v231, 0xffffff00, v231
; DI float ord2f(unsigned u) { return __uint_as_float((u & 0x80000000u) ? (u ^ 0x80000000u) : ~u); }
; template <int LOGN>
; DI void bitonic_sort_desc(unsigned (&a)[1 << LOGN]) {
;   constexpr int N = 1 << LOGN;
; #pragma unroll
;   for (int ks = 1; ks <= LOGN; ++ks)
; #pragma unroll
;     ...
; #pragma unroll
;       for (int i = 0; i < N; ++i) {
;         const int k = 1 << ks, j = 1 << js, l = i ^ j;
;         if (l > i) {
;           const bool desc = ((i & k) == 0) || (ks == LOGN);
;           const unsigned x = a[i], y = a[l];
;           const unsigned hi = max(x, y), lo = min(x, y);
;           a[i] = desc ? hi : lo;
;           a[l] = desc ? lo : hi;
;         }
;       }
; }
; template <bool STORE>
; DI void peer_item(const Params& p, int item, char* smem) {
;     ...
; #pragma unroll
;     for (int a = 0; a < 16; ++a)
; #pragma unroll
;       for (int bq = 0; bq < 16; ++bq)
;         if ((a + 1) * (bq + 1) <= 16)
;           ckey[a][bq] = (f2ord(ord2f(top1[a] & ~127u) + ord2f(top2[bq] & ~127u)) & ~255u) | (unsigned)(255 - (a * 16 + bq));
	v_or_b32_e32 v112, 0xfa, v231
	v_add_f32_e32 v229, v56, v41
	v_ashrrev_i32_e32 v230, 31, v229
	v_or_b32_e32 v230, 0x80000000, v230
	v_xor_b32_e32 v231, v230, v229
	v_and_b32_e32 v231, 0xffffff00, v231
	v_or_b32_e32 v89, 0xf9, v231
	v_add_f32_e32 v229, v56, v40
	v_ashrrev_i32_e32 v230, 31, v229
	v_or_b32_e32 v230, 0x80000000, v230
	v_xor_b32_e32 v231, v230, v229
	v_and_b32_e32 v231, 0xffffff00, v231
	v_or_b32_e32 v116, 0xf8, v231
	v_add_f32_e32 v229, v56, v39
	v_ashrrev_i32_e32 v230, 31, v229
	v_or_b32_e32 v230, 0x80000000, v230
	v_xor_b32_e32 v231, v230, v229
	v_and_b32_e32 v231, 0xffffff00, v231
	v_or_b32_e32 v109, 0xf7, v231
	v_add_f32_e32 v229, v56, v38
	v_ashrrev_i32_e32 v230, 31, v229
	v_or_b32_e32 v230, 0x80000000, v230
	v_xor_b32_e32 v231, v230, v229
	v_and_b32_e32 v231, 0xffffff00, v231
	v_or_b32_e32 v88, 0xf6, v231
	v_add_f32_e32 v229, v56, v37
	v_ashrrev_i32_e32 v230, 31, v229
	v_or_b32_e32 v230, 0x80000000, v230
	v_xor_b32_e32 v231, v230, v229
	v_and_b32_e32 v231, 0xffffff00, v231
	v_or_b32_e32 v90, 0xf5, v231
	v_add_f32_e32 v229, v56, v36
	v_ashrrev_i32_e32 v230, 31, v229
	v_or_b32_e32 v230, 0x80000000, v230
	v_xor_b32_e32 v231, v230, v229
	v_and_b32_e32 v231, 0xffffff00, v231
	v_or_b32_e32 v79, 0xf4, v231
	v_add_f32_e32 v229, v56, v35
	v_ashrrev_i32_e32 v230, 31, v229
	v_or_b32_e32 v230, 0x80000000, v230
	v_xor_b32_e32 v231, v230, v229
	v_and_b32_e32 v231, 0xffffff00, v231
	v_or_b32_e32 v115, 0xf3, v231
	v_add_f32_e32 v229, v56, v34
	v_ashrrev_i32_e32 v230, 31, v229
	v_or_b32_e32 v230, 0x80000000, v230
	v_xor_b32_e32 v231, v230, v229
	v_and_b32_e32 v231, 0xffffff00, v231
	v_or_b32_e32 v101, 0xf2, v231
	v_add_f32_e32 v229, v56, v33
	v_ashrrev_i32_e32 v230, 31, v229
	v_or_b32_e32 v230, 0x80000000, v230
	v_xor_b32_e32 v231, v230, v229
	v_and_b32_e32 v231, 0xffffff00, v231
	v_or_b32_e32 v108, 0xf1, v231
	v_add_f32_e32 v229, v56, v32
	v_ashrrev_i32_e32 v230, 31, v229
	v_or_b32_e32 v230, 0x80000000, v230
	v_xor_b32_e32 v231, v230, v229
	v_and_b32_e32 v231, 0xffffff00, v231
	v_or_b32_e32 v114, 0xf0, v231
	v_add_f32_e32 v229, v57, v31
	v_ashrrev_i32_e32 v230, 31, v229
	v_or_b32_e32 v230, 0x80000000, v230
	v_xor_b32_e32 v231, v230, v229
	v_and_b32_e32 v231, 0xffffff00, v231
	v_or_b32_e32 v81, 0xef, v231
	v_add_f32_e32 v229, v57, v46
	v_ashrrev_i32_e32 v230, 31, v229
	v_or_b32_e32 v230, 0x80000000, v230
	v_xor_b32_e32 v231, v230, v229
	v_and_b32_e32 v231, 0xffffff00, v231
	v_or_b32_e32 v102, 0xee, v231
	v_add_f32_e32 v229, v57, v45
	v_ashrrev_i32_e32 v230, 31, v229
	v_or_b32_e32 v230, 0x80000000, v230
	v_xor_b32_e32 v231, v230, v229
	v_and_b32_e32 v231, 0xffffff00, v231
	v_or_b32_e32 v97, 0xed, v231
	v_add_f32_e32 v229, v57, v44
	v_ashrrev_i32_e32 v230, 31, v229
	v_or_b32_e32 v230, 0x80000000, v230
	v_xor_b32_e32 v231, v230, v229
	v_and_b32_e32 v231, 0xffffff00, v231
	v_or_b32_e32 v96, 0xec, v231
	v_add_f32_e32 v229, v57, v43
	v_ashrrev_i32_e32 v230, 31, v229
	v_or_b32_e32 v230, 0x80000000, v230
	v_xor_b32_e32 v231, v230, v229
	v_and_b32_e32 v231, 0xffffff00, v231
	v_or_b32_e32 v103, 0xeb, v231
	v_add_f32_e32 v229, v57, v42
	v_ashrrev_i32_e32 v230, 31, v229
	v_or_b32_e32 v230, 0x80000000, v230
	v_xor_b32_e32 v231, v230, v229
	v_and_b32_e32 v231, 0xffffff00, v231
	v_or_b32_e32 v117, 0xea, v231
	v_add_f32_e32 v229, v57, v41
	v_ashrrev_i32_e32 v230, 31, v229
	v_or_b32_e32 v230, 0x80000000, v230
	v_xor_b32_e32 v231, v230, v229
	v_and_b32_e32 v231, 0xffffff00, v231
	v_or_b32_e32 v91, 0xe9, v231
	v_add_f32_e32 v229, v57, v40
	v_ashrrev_i32_e32 v230, 31, v229
	v_or_b32_e32 v230, 0x80000000, v230
	v_xor_b32_e32 v231, v230, v229
	v_and_b32_e32 v231, 0xffffff00, v231
	v_or_b32_e32 v77, 0xe8, v231
	v_add_f32_e32 v229, v58, v31
	v_ashrrev_i32_e32 v230, 31, v229
	v_or_b32_e32 v230, 0x80000000, v230
	v_xor_b32_e32 v231, v230, v229
	v_and_b32_e32 v231, 0xffffff00, v231
	v_or_b32_e32 v70, 0xdf, v231
	v_add_f32_e32 v229, v58, v46
	v_ashrrev_i32_e32 v230, 31, v229
	v_or_b32_e32 v230, 0x80000000, v230
	v_xor_b32_e32 v231, v230, v229
	v_and_b32_e32 v231, 0xffffff00, v231
	v_or_b32_e32 v80, 0xde, v231
	v_add_f32_e32 v229, v58, v45
	v_ashrrev_i32_e32 v230, 31, v229
	v_or_b32_e32 v230, 0x80000000, v230
	v_xor_b32_e32 v231, v230, v229
	v_and_b32_e32 v231, 0xffffff00, v231
	v_or_b32_e32 v86, 0xdd, v231
	v_add_f32_e32 v229, v58, v44
	v_ashrrev_i32_e32 v230, 31, v229
	v_or_b32_e32 v230, 0x80000000, v230
	v_xor_b32_e32 v231, v230, v229
	v_and_b32_e32 v231, 0xffffff00, v231
	v_or_b32_e32 v74, 0xdc, v231
	v_add_f32_e32 v229, v58, v43
	v_ashrrev_i32_e32 v230, 31, v229
	v_or_b32_e32 v230, 0x80000000, v230
	v_xor_b32_e32 v231, v230, v229
	v_and_b32_e32 v231, 0xffffff00, v231
	v_or_b32_e32 v104, 0xdb, v231
	v_add_f32_e32 v229, v59, v31
	v_ashrrev_i32_e32 v230, 31, v229
	v_or_b32_e32 v230, 0x80000000, v230
	v_xor_b32_e32 v231, v230, v229
	v_and_b32_e32 v231, 0xffffff00, v231
	v_or_b32_e32 v105, 0xcf, v231
	v_add_f32_e32 v229, v59, v46
	v_ashrrev_i32_e32 v230, 31, v229
	v_or_b32_e32 v230, 0x80000000, v230
	v_xor_b32_e32 v231, v230, v229
	v_and_b32_e32 v231, 0xffffff00, v231
	v_or_b32_e32 v72, 0xce, v231
	v_add_f32_e32 v229, v59, v45
	v_ashrrev_i32_e32 v230, 31, v229
	v_or_b32_e32 v230, 0x80000000, v230
	v_xor_b32_e32 v231, v230, v229
	v_and_b32_e32 v231, 0xffffff00, v231
	v_or_b32_e32 v100, 0xcd, v231
	v_max_u32_e32 v98, v81, v102
	v_min_u32_e32 v102, v81, v102
	v_min_u32_e32 v81, v97, v96
	v_max_u32_e32 v96, v97, v96
	v_max_u32_e32 v97, v103, v117
	v_min_u32_e32 v117, v103, v117
	v_min_u32_e32 v103, v91, v77
	v_max_u32_e32 v77, v91, v77
	v_max_u32_e32 v91, v70, v80
	v_min_u32_e32 v80, v70, v80
	v_min_u32_e32 v70, v86, v74
	v_max_u32_e32 v74, v86, v74
; DI void merge_top16(unsigned (&a)[16], const unsigned (&b)[16]) {
; #pragma unroll
;   for (int i = 0; i < 16; ++i) a[i] = max(a[i], b[15 - i]);
; #pragma unroll
;     ...
; #pragma unroll
;     for (int i = 0; i < 16; ++i) {
;       const int j = 1 << js, l = i ^ j;
;       if (l > i) {
;         const unsigned x = a[i], y = a[l];
;         a[i] = max(x, y);
;         a[l] = min(x, y);
;       }
;     }
; }
; template <bool STORE>
; DI void peer_item(const Params& p, int item, char* smem) {
;     ...
;     for (int r = 0; r < 16; ++r) {
;       unsigned mx = 0u;
; #pragma unroll
;       for (int a = 0; a < 16; ++a)
; #pragma unroll
;         for (int bq = 0; bq < 16; ++bq)
;           if ((a + 1) * (bq + 1) <= 16) mx = max(mx, ckey[a][bq]);
; #pragma unroll
;       for (int a = 0; a < 16; ++a)
; #pragma unroll
;         for (int bq = 0; bq < 16; ++bq)
;           if ((a + 1) * (bq + 1) <= 16) ckey[a][bq] = (ckey[a][bq] == mx) ? 0u : ckey[a][bq];
;       wkey[r] = mx;
	v_max_u32_e32 v86, v104, v105
	v_min_u32_e32 v105, v104, v105
	v_min_u32_e32 v104, v72, v100
	v_max_u32_e32 v100, v72, v100
	v_max_u32_e32 v72, v98, v81
	v_min_u32_e32 v81, v98, v81
	v_max_u32_e32 v98, v102, v96
	v_min_u32_e32 v96, v102, v96
	v_min_u32_e32 v102, v97, v103
	v_max_u32_e32 v103, v97, v103
	v_min_u32_e32 v97, v117, v77
	v_max_u32_e32 v77, v117, v77
	v_max_u32_e32 v117, v91, v70
	v_min_u32_e32 v70, v91, v70
	v_max_u32_e32 v91, v80, v74
	v_min_u32_e32 v74, v80, v74
	v_min_u32_e32 v80, v86, v104
	v_max_u32_e32 v104, v86, v104
	v_min_u32_e32 v86, v105, v100
	v_max_u32_e32 v100, v105, v100
	v_max_u32_e32 v105, v72, v98
	v_min_u32_e32 v98, v72, v98
	v_max_u32_e32 v72, v81, v96
	v_min_u32_e32 v96, v81, v96
	v_min_u32_e32 v81, v102, v97
	v_max_u32_e32 v97, v102, v97
	v_min_u32_e32 v102, v103, v77
	v_max_u32_e32 v77, v103, v77
	v_max_u32_e32 v103, v117, v91
	v_min_u32_e32 v91, v117, v91
	v_max_u32_e32 v117, v70, v74
	v_min_u32_e32 v74, v70, v74
	v_min_u32_e32 v70, v80, v86
	v_max_u32_e32 v86, v80, v86
	v_min_u32_e32 v80, v104, v100
	v_max_u32_e32 v100, v104, v100
	v_max_u32_e32 v104, v105, v81
	v_min_u32_e32 v81, v105, v81
	v_max_u32_e32 v105, v98, v97
	v_min_u32_e32 v97, v98, v97
	v_max_u32_e32 v98, v72, v102
	v_min_u32_e32 v102, v72, v102
	v_max_u32_e32 v72, v96, v77
	v_min_u32_e32 v77, v96, v77
	v_min_u32_e32 v96, v103, v70
	v_max_u32_e32 v70, v103, v70
	v_min_u32_e32 v103, v91, v86
	v_max_u32_e32 v86, v91, v86
	v_min_u32_e32 v91, v117, v80
	v_max_u32_e32 v80, v117, v80
	v_min_u32_e32 v117, v74, v100
	v_max_u32_e32 v100, v74, v100
	v_max_u32_e32 v74, v104, v98
	v_min_u32_e32 v98, v104, v98
	v_max_u32_e32 v104, v105, v72
	v_min_u32_e32 v72, v105, v72
	v_max_u32_e32 v105, v81, v102
	v_min_u32_e32 v102, v81, v102
	v_max_u32_e32 v81, v97, v77
	v_min_u32_e32 v77, v97, v77
	v_min_u32_e32 v97, v96, v91
	v_max_u32_e32 v91, v96, v91
	v_min_u32_e32 v96, v103, v117
	v_max_u32_e32 v117, v103, v117
	v_min_u32_e32 v103, v70, v80
	v_max_u32_e32 v80, v70, v80
	v_min_u32_e32 v70, v86, v100
	v_max_u32_e32 v100, v86, v100
	v_max_u32_e32 v86, v74, v104
	v_min_u32_e32 v104, v74, v104
	v_max_u32_e32 v74, v98, v72
	v_min_u32_e32 v72, v98, v72
	v_max_u32_e32 v98, v105, v81
	v_min_u32_e32 v81, v105, v81
	v_max_u32_e32 v105, v102, v77
	v_min_u32_e32 v77, v102, v77
	v_min_u32_e32 v102, v97, v96
	v_max_u32_e32 v96, v97, v96
	v_min_u32_e32 v97, v91, v117
	v_max_u32_e32 v117, v91, v117
	v_min_u32_e32 v91, v103, v70
	v_max_u32_e32 v70, v103, v70
	v_min_u32_e32 v103, v80, v100
	v_max_u32_e32 v100, v80, v100
	v_max_u32_e32 v80, v86, v102
	v_min_u32_e32 v102, v86, v102
	v_max_u32_e32 v86, v104, v96
	v_min_u32_e32 v96, v104, v96
	v_max_u32_e32 v104, v74, v97
	v_min_u32_e32 v97, v74, v97
	v_max_u32_e32 v74, v72, v117
	v_min_u32_e32 v117, v72, v117
	v_max_u32_e32 v72, v98, v91
	v_min_u32_e32 v91, v98, v91
	v_max_u32_e32 v98, v81, v70
	v_min_u32_e32 v70, v81, v70
	v_max_u32_e32 v81, v105, v103
	v_min_u32_e32 v103, v105, v103
	v_max_u32_e32 v105, v77, v100
	v_min_u32_e32 v100, v77, v100
	v_max_u32_e32 v77, v80, v72
	v_min_u32_e32 v72, v80, v72
	v_max_u32_e32 v80, v86, v98
	v_min_u32_e32 v98, v86, v98
	v_max_u32_e32 v86, v104, v81
	v_min_u32_e32 v81, v104, v81
	v_max_u32_e32 v104, v74, v105
	v_min_u32_e32 v105, v74, v105
	v_max_u32_e32 v74, v102, v91
	v_min_u32_e32 v91, v102, v91
	v_max_u32_e32 v102, v96, v70
	v_min_u32_e32 v70, v96, v70
	v_max_u32_e32 v96, v97, v103
	v_min_u32_e32 v103, v97, v103
	v_max_u32_e32 v97, v117, v100
	v_min_u32_e32 v100, v117, v100
	v_max_u32_e32 v117, v77, v86
	v_min_u32_e32 v86, v77, v86
	v_max_u32_e32 v77, v80, v104
	v_min_u32_e32 v104, v80, v104
	v_max_u32_e32 v80, v72, v81
	v_min_u32_e32 v81, v72, v81
	v_max_u32_e32 v72, v98, v105
	v_min_u32_e32 v105, v98, v105
	v_max_u32_e32 v98, v74, v96
	v_min_u32_e32 v96, v74, v96
	v_max_u32_e32 v74, v102, v97
	v_min_u32_e32 v97, v102, v97
	v_max_u32_e32 v102, v91, v103
	v_min_u32_e32 v103, v91, v103
	v_max_u32_e32 v91, v70, v100
	v_min_u32_e32 v100, v70, v100
	v_max_u32_e32 v70, v117, v77
	v_min_u32_e32 v77, v117, v77
	v_max_u32_e32 v117, v86, v104
	v_min_u32_e32 v104, v86, v104
	v_max_u32_e32 v86, v80, v72
	v_min_u32_e32 v72, v80, v72
	v_max_u32_e32 v80, v81, v105
	v_min_u32_e32 v105, v81, v105
	v_max_u32_e32 v81, v98, v74
	v_min_u32_e32 v74, v98, v74
	v_max_u32_e32 v98, v96, v97
	v_min_u32_e32 v97, v96, v97
	v_max_u32_e32 v96, v102, v91
	v_min_u32_e32 v91, v102, v91
	v_max_u32_e32 v102, v103, v100
	v_min_u32_e32 v100, v103, v100
	v_max_u32_e32 v103, v15, v100
	v_max_u32_e32 v15, v111, v102
	v_max_u32_e32 v111, v83, v91
	v_max_u32_e32 v83, v106, v96
	v_max_u32_e32 v106, v85, v97
	v_max_u32_e32 v85, v112, v98
	v_max_u32_e32 v112, v89, v74
	v_max_u32_e32 v89, v116, v81
	v_max_u32_e32 v116, v109, v105
	v_max_u32_e32 v109, v88, v80
	v_max_u32_e32 v88, v90, v72
	v_max_u32_e32 v90, v79, v86
	v_max_u32_e32 v79, v115, v104
	v_max_u32_e32 v115, v101, v117
	v_max_u32_e32 v101, v108, v77
	v_max_u32_e32 v108, v114, v70
	v_max_u32_e32 v100, v103, v116
	v_min_u32_e32 v116, v103, v116
	v_max_u32_e32 v103, v15, v109
	v_min_u32_e32 v109, v15, v109
	v_max_u32_e32 v15, v111, v88
	v_min_u32_e32 v88, v111, v88
	v_max_u32_e32 v111, v83, v90
	v_min_u32_e32 v90, v83, v90
	v_max_u32_e32 v83, v106, v79
	v_min_u32_e32 v79, v106, v79
	v_max_u32_e32 v106, v85, v115
	v_min_u32_e32 v115, v85, v115
	v_max_u32_e32 v85, v112, v101
	v_min_u32_e32 v101, v112, v101
	v_max_u32_e32 v112, v89, v108
	v_min_u32_e32 v108, v89, v108
	v_max_u32_e32 v89, v100, v83
	v_min_u32_e32 v83, v100, v83
	v_max_u32_e32 v100, v103, v106
	v_min_u32_e32 v106, v103, v106
	v_max_u32_e32 v103, v15, v85
	v_min_u32_e32 v85, v15, v85
	v_max_u32_e32 v15, v111, v112
; DI float ord2f(unsigned u) { return __uint_as_float((u & 0x80000000u) ? (u ^ 0x80000000u) : ~u); }
; template <bool STORE>
; DI void peer_item(const Params& p, int item, char* smem) {
;     ...
;     unsigned ckey[16][16];
; #pragma unroll
;     for (int a = 0; a < 16; ++a)
; #pragma unroll
;       for (int bq = 0; bq < 16; ++bq)
;         if ((a + 1) * (bq + 1) <= 16)
;           ckey[a][bq] = (f2ord(ord2f(top1[a] & ~127u) + ord2f(top2[bq] & ~127u)) & ~255u) | (unsigned)(255 - (a * 16 + bq));
;     unsigned wkey[16];
;     int we[16];
; #pragma unroll
;     for (int r = 0; r < 16; ++r) {
;       unsigned mx = 0u;
; #pragma unroll
;       for (int a = 0; a < 16; ++a)
; #pragma unroll
;         for (int bq = 0; bq < 16; ++bq)
;           if ((a + 1) * (bq + 1) <= 16) mx = max(mx, ckey[a][bq]);
; #pragma unroll
;       for (int a = 0; a < 16; ++a)
; #pragma unroll
;         for (int bq = 0; bq < 16; ++bq)
;           if ((a + 1) * (bq + 1) <= 16) ckey[a][bq] = (ckey[a][bq] == mx) ? 0u : ckey[a][bq];
;       wkey[r] = mx;
	v_min_u32_e32 v112, v111, v112
	v_max_u32_e32 v111, v116, v79
	v_min_u32_e32 v79, v116, v79
	v_max_u32_e32 v116, v109, v115
	v_min_u32_e32 v115, v109, v115
	v_max_u32_e32 v109, v88, v101
	v_min_u32_e32 v101, v88, v101
	v_max_u32_e32 v88, v90, v108
	v_min_u32_e32 v108, v90, v108
	v_max_u32_e32 v90, v89, v103
	v_min_u32_e32 v103, v89, v103
	v_max_u32_e32 v89, v100, v15
	v_min_u32_e32 v15, v100, v15
	v_max_u32_e32 v100, v83, v85
	v_min_u32_e32 v85, v83, v85
	v_max_u32_e32 v83, v106, v112
	v_min_u32_e32 v112, v106, v112
	v_max_u32_e32 v106, v111, v109
	v_min_u32_e32 v109, v111, v109
	v_max_u32_e32 v111, v116, v88
	v_min_u32_e32 v88, v116, v88
	v_max_u32_e32 v116, v79, v101
	v_min_u32_e32 v101, v79, v101
	v_max_u32_e32 v79, v115, v108
	v_min_u32_e32 v108, v115, v108
	v_max_u32_e32 v115, v90, v89
	v_min_u32_e32 v89, v90, v89
	v_max_u32_e32 v90, v103, v15
	v_min_u32_e32 v15, v103, v15
	v_max_u32_e32 v103, v100, v83
	v_min_u32_e32 v83, v100, v83
	v_max_u32_e32 v100, v85, v112
	v_min_u32_e32 v112, v85, v112
	v_max_u32_e32 v85, v106, v111
	v_min_u32_e32 v111, v106, v111
	v_max_u32_e32 v106, v109, v88
	v_min_u32_e32 v88, v109, v88
	v_max_u32_e32 v109, v116, v79
	v_min_u32_e32 v79, v116, v79
	v_max_u32_e32 v116, v101, v108
	v_min_u32_e32 v108, v101, v108
	v_add_f32_e32 v229, v59, v44
	v_ashrrev_i32_e32 v230, 31, v229
	v_or_b32_e32 v230, 0x80000000, v230
	v_xor_b32_e32 v231, v230, v229
	v_and_b32_e32 v231, 0xffffff00, v231
	v_or_b32_e32 v101, 0xcc, v231
	v_add_f32_e32 v229, v60, v31
	v_ashrrev_i32_e32 v230, 31, v229
	v_or_b32_e32 v230, 0x80000000, v230
	v_xor_b32_e32 v231, v230, v229
	v_and_b32_e32 v231, 0xffffff00, v231
	v_or_b32_e32 v102, 0xbf, v231
	v_add_f32_e32 v229, v60, v46
	v_ashrrev_i32_e32 v230, 31, v229
	v_or_b32_e32 v230, 0x80000000, v230
	v_xor_b32_e32 v231, v230, v229
	v_and_b32_e32 v231, 0xffffff00, v231
	v_or_b32_e32 v91, 0xbe, v231
	v_add_f32_e32 v229, v60, v45
	v_ashrrev_i32_e32 v230, 31, v229
	v_or_b32_e32 v230, 0x80000000, v230
	v_xor_b32_e32 v231, v230, v229
	v_and_b32_e32 v231, 0xffffff00, v231
	v_or_b32_e32 v96, 0xbd, v231
	v_add_f32_e32 v229, v61, v31
	v_ashrrev_i32_e32 v230, 31, v229
	v_or_b32_e32 v230, 0x80000000, v230
	v_xor_b32_e32 v231, v230, v229
	v_and_b32_e32 v231, 0xffffff00, v231
	v_or_b32_e32 v97, 0xaf, v231
	v_add_f32_e32 v229, v61, v46
	v_ashrrev_i32_e32 v230, 31, v229
	v_or_b32_e32 v230, 0x80000000, v230
	v_xor_b32_e32 v231, v230, v229
	v_and_b32_e32 v231, 0xffffff00, v231
	v_or_b32_e32 v98, 0xae, v231
	v_add_f32_e32 v229, v62, v31
	v_ashrrev_i32_e32 v230, 31, v229
	v_or_b32_e32 v230, 0x80000000, v230
	v_xor_b32_e32 v231, v230, v229
	v_and_b32_e32 v231, 0xffffff00, v231
	v_or_b32_e32 v74, 0x9f, v231
	v_add_f32_e32 v229, v62, v46
	v_ashrrev_i32_e32 v230, 31, v229
	v_or_b32_e32 v230, 0x80000000, v230
	v_xor_b32_e32 v231, v230, v229
	v_and_b32_e32 v231, 0xffffff00, v231
	v_or_b32_e32 v81, 0x9e, v231
	v_add_f32_e32 v229, v29, v31
	v_ashrrev_i32_e32 v230, 31, v229
	v_or_b32_e32 v230, 0x80000000, v230
	v_xor_b32_e32 v231, v230, v229
	v_and_b32_e32 v231, 0xffffff00, v231
	v_or_b32_e32 v105, 0x8f, v231
	v_add_f32_e32 v229, v29, v46
	v_ashrrev_i32_e32 v230, 31, v229
	v_or_b32_e32 v230, 0x80000000, v230
	v_xor_b32_e32 v231, v230, v229
	v_and_b32_e32 v231, 0xffffff00, v231
	v_or_b32_e32 v80, 0x8e, v231
	v_add_f32_e32 v229, v55, v31
	v_ashrrev_i32_e32 v230, 31, v229
	v_or_b32_e32 v230, 0x80000000, v230
	v_xor_b32_e32 v231, v230, v229
	v_and_b32_e32 v231, 0xffffff00, v231
	v_or_b32_e32 v72, 0x7f, v231
	v_add_f32_e32 v229, v54, v31
	v_ashrrev_i32_e32 v230, 31, v229
	v_or_b32_e32 v230, 0x80000000, v230
	v_xor_b32_e32 v231, v230, v229
	v_and_b32_e32 v231, 0xffffff00, v231
	v_or_b32_e32 v86, 0x6f, v231
	v_add_f32_e32 v229, v53, v31
	v_ashrrev_i32_e32 v230, 31, v229
	v_or_b32_e32 v230, 0x80000000, v230
	v_xor_b32_e32 v231, v230, v229
	v_and_b32_e32 v231, 0xffffff00, v231
	v_or_b32_e32 v104, 0x5f, v231
	v_add_f32_e32 v229, v52, v31
	v_ashrrev_i32_e32 v230, 31, v229
	v_or_b32_e32 v230, 0x80000000, v230
	v_xor_b32_e32 v231, v230, v229
	v_and_b32_e32 v231, 0xffffff00, v231
	v_or_b32_e32 v117, 0x4f, v231
	v_add_f32_e32 v229, v51, v31
	v_ashrrev_i32_e32 v230, 31, v229
	v_or_b32_e32 v230, 0x80000000, v230
	v_xor_b32_e32 v231, v230, v229
	v_and_b32_e32 v231, 0xffffff00, v231
	v_or_b32_e32 v77, 0x3f, v231
	v_add_f32_e32 v229, v50, v31
	v_ashrrev_i32_e32 v230, 31, v229
	v_or_b32_e32 v230, 0x80000000, v230
	v_xor_b32_e32 v231, v230, v229
	v_and_b32_e32 v231, 0xffffff00, v231
	v_or_b32_e32 v70, 0x2f, v231
	v_max_u32_e32 v114, v101, v102
	v_min_u32_e32 v102, v101, v102
	v_min_u32_e32 v101, v91, v96
	v_max_u32_e32 v96, v91, v96
	v_max_u32_e32 v91, v97, v98
	v_min_u32_e32 v98, v97, v98
	v_min_u32_e32 v97, v74, v81
	v_max_u32_e32 v81, v74, v81
	v_max_u32_e32 v74, v105, v80
	v_min_u32_e32 v80, v105, v80
	v_min_u32_e32 v105, v72, v86
	v_max_u32_e32 v86, v72, v86
	v_max_u32_e32 v72, v104, v117
	v_min_u32_e32 v117, v104, v117
	v_min_u32_e32 v104, v77, v70
	v_max_u32_e32 v70, v77, v70
	v_max_u32_e32 v77, v114, v101
	v_min_u32_e32 v101, v114, v101
	v_max_u32_e32 v114, v102, v96
	v_min_u32_e32 v96, v102, v96
	v_min_u32_e32 v102, v91, v97
	v_max_u32_e32 v97, v91, v97
	v_min_u32_e32 v91, v98, v81
	v_max_u32_e32 v81, v98, v81
	v_max_u32_e32 v98, v74, v105
	v_min_u32_e32 v105, v74, v105
	v_max_u32_e32 v74, v80, v86
	v_min_u32_e32 v86, v80, v86
	v_min_u32_e32 v80, v72, v104
	v_max_u32_e32 v104, v72, v104
	v_min_u32_e32 v72, v117, v70
	v_max_u32_e32 v70, v117, v70
	v_max_u32_e32 v117, v77, v114
	v_min_u32_e32 v114, v77, v114
	v_max_u32_e32 v77, v101, v96
	v_min_u32_e32 v96, v101, v96
	v_min_u32_e32 v101, v102, v91
	v_max_u32_e32 v91, v102, v91
; DI float ord2f(unsigned u) { return __uint_as_float((u & 0x80000000u) ? (u ^ 0x80000000u) : ~u); }
; template <bool STORE>
; DI void peer_item(const Params& p, int item, char* smem) {
;     ...
;     unsigned ckey[16][16];
; #pragma unroll
;     for (int a = 0; a < 16; ++a)
; #pragma unroll
;       for (int bq = 0; bq < 16; ++bq)
;         if ((a + 1) * (bq + 1) <= 16)
;           ckey[a][bq] = (f2ord(ord2f(top1[a] & ~127u) + ord2f(top2[bq] & ~127u)) & ~255u) | (unsigned)(255 - (a * 16 + bq));
;     unsigned wkey[16];
;     int we[16];
; #pragma unroll
;     for (int r = 0; r < 16; ++r) {
;       unsigned mx = 0u;
; #pragma unroll
;       for (int a = 0; a < 16; ++a)
; #pragma unroll
;         for (int bq = 0; bq < 16; ++bq)
;           if ((a + 1) * (bq + 1) <= 16) mx = max(mx, ckey[a][bq]);
; #pragma unroll
;       for (int a = 0; a < 16; ++a)
; #pragma unroll
;         for (int bq = 0; bq < 16; ++bq)
;           if ((a + 1) * (bq + 1) <= 16) ckey[a][bq] = (ckey[a][bq] == mx) ? 0u : ckey[a][bq];
;       wkey[r] = mx;
	v_min_u32_e32 v102, v97, v81
	v_max_u32_e32 v81, v97, v81
	v_max_u32_e32 v97, v98, v74
	v_min_u32_e32 v74, v98, v74
	v_max_u32_e32 v98, v105, v86
	v_min_u32_e32 v86, v105, v86
	v_min_u32_e32 v105, v80, v72
	v_max_u32_e32 v72, v80, v72
	v_min_u32_e32 v80, v104, v70
	v_max_u32_e32 v70, v104, v70
	v_max_u32_e32 v104, v117, v101
	v_min_u32_e32 v101, v117, v101
	v_max_u32_e32 v117, v114, v91
	v_min_u32_e32 v91, v114, v91
	v_max_u32_e32 v114, v77, v102
	v_min_u32_e32 v102, v77, v102
	v_max_u32_e32 v77, v96, v81
	v_min_u32_e32 v81, v96, v81
	v_min_u32_e32 v96, v97, v105
	v_max_u32_e32 v105, v97, v105
	v_min_u32_e32 v97, v74, v72
	v_max_u32_e32 v72, v74, v72
	v_min_u32_e32 v74, v98, v80
	v_max_u32_e32 v80, v98, v80
	v_min_u32_e32 v98, v86, v70
	v_max_u32_e32 v70, v86, v70
	v_max_u32_e32 v86, v104, v114
	v_min_u32_e32 v114, v104, v114
	v_max_u32_e32 v104, v117, v77
	v_min_u32_e32 v77, v117, v77
	v_max_u32_e32 v117, v101, v102
	v_min_u32_e32 v102, v101, v102
	v_max_u32_e32 v101, v91, v81
	v_min_u32_e32 v81, v91, v81
	v_min_u32_e32 v91, v96, v74
	v_max_u32_e32 v74, v96, v74
	v_min_u32_e32 v96, v97, v98
	v_max_u32_e32 v98, v97, v98
	v_min_u32_e32 v97, v105, v80
	v_max_u32_e32 v80, v105, v80
	v_min_u32_e32 v105, v72, v70
	v_max_u32_e32 v70, v72, v70
	v_max_u32_e32 v72, v86, v104
	v_min_u32_e32 v104, v86, v104
	v_max_u32_e32 v86, v114, v77
	v_min_u32_e32 v77, v114, v77
	v_max_u32_e32 v114, v117, v101
	v_min_u32_e32 v101, v117, v101
	v_max_u32_e32 v117, v102, v81
	v_min_u32_e32 v81, v102, v81
	v_min_u32_e32 v102, v91, v96
	v_max_u32_e32 v96, v91, v96
	v_min_u32_e32 v91, v74, v98
	v_max_u32_e32 v98, v74, v98
	v_min_u32_e32 v74, v97, v105
	v_max_u32_e32 v105, v97, v105
	v_min_u32_e32 v97, v80, v70
	v_max_u32_e32 v70, v80, v70
	v_max_u32_e32 v80, v72, v102
	v_min_u32_e32 v102, v72, v102
	v_max_u32_e32 v72, v104, v96
	v_min_u32_e32 v96, v104, v96
	v_max_u32_e32 v104, v86, v91
	v_min_u32_e32 v91, v86, v91
	v_max_u32_e32 v86, v77, v98
	v_min_u32_e32 v98, v77, v98
	v_max_u32_e32 v77, v114, v74
	v_min_u32_e32 v74, v114, v74
	v_max_u32_e32 v114, v101, v105
	v_min_u32_e32 v105, v101, v105
	v_max_u32_e32 v101, v117, v97
	v_min_u32_e32 v97, v117, v97
	v_max_u32_e32 v117, v81, v70
	v_min_u32_e32 v70, v81, v70
	v_max_u32_e32 v81, v80, v77
	v_min_u32_e32 v77, v80, v77
	v_max_u32_e32 v80, v72, v114
	v_min_u32_e32 v114, v72, v114
	v_max_u32_e32 v72, v104, v101
	v_min_u32_e32 v101, v104, v101
	v_max_u32_e32 v104, v86, v117
	v_min_u32_e32 v117, v86, v117
	v_max_u32_e32 v86, v102, v74
	v_min_u32_e32 v74, v102, v74
	v_max_u32_e32 v102, v96, v105
	v_min_u32_e32 v105, v96, v105
	v_max_u32_e32 v96, v91, v97
	v_min_u32_e32 v97, v91, v97
	v_max_u32_e32 v91, v98, v70
	v_min_u32_e32 v70, v98, v70
	v_max_u32_e32 v98, v81, v72
	v_min_u32_e32 v72, v81, v72
	v_max_u32_e32 v81, v80, v104
	v_min_u32_e32 v104, v80, v104
	v_max_u32_e32 v80, v77, v101
	v_min_u32_e32 v101, v77, v101
	v_max_u32_e32 v77, v114, v117
	v_min_u32_e32 v117, v114, v117
	v_max_u32_e32 v114, v86, v96
	v_min_u32_e32 v96, v86, v96
	v_max_u32_e32 v86, v102, v91
	v_min_u32_e32 v91, v102, v91
	v_max_u32_e32 v102, v74, v97
	v_min_u32_e32 v97, v74, v97
	v_max_u32_e32 v74, v105, v70
	v_min_u32_e32 v70, v105, v70
	v_max_u32_e32 v105, v98, v81
	v_min_u32_e32 v81, v98, v81
	v_max_u32_e32 v98, v72, v104
	v_min_u32_e32 v104, v72, v104
	v_max_u32_e32 v72, v80, v77
	v_min_u32_e32 v77, v80, v77
	v_max_u32_e32 v80, v101, v117
	v_min_u32_e32 v117, v101, v117
	v_max_u32_e32 v101, v114, v86
	v_min_u32_e32 v86, v114, v86
	v_max_u32_e32 v114, v96, v91
	v_min_u32_e32 v91, v96, v91
	v_max_u32_e32 v96, v102, v74
	v_min_u32_e32 v74, v102, v74
	v_max_u32_e32 v102, v97, v70
	v_min_u32_e32 v70, v97, v70
	v_add_f32_e32 v229, v49, v31
	v_ashrrev_i32_e32 v230, 31, v229
	v_or_b32_e32 v230, 0x80000000, v230
	v_xor_b32_e32 v231, v230, v229
	v_and_b32_e32 v231, 0xffffff00, v231
	v_or_b32_e32 v97, 0x1f, v231
	v_add_f32_e32 v229, v48, v31
	v_ashrrev_i32_e32 v230, 31, v229
	v_or_b32_e32 v230, 0x80000000, v230
	v_xor_b32_e32 v231, v230, v229
	v_and_b32_e32 v231, 0xffffff00, v231
	v_or_b32_e32 v84, 0xf, v231
	v_mov_b32_e32 v71, 0
	v_mov_b32_e32 v82, 0
	v_mov_b32_e32 v75, 0
	v_mov_b32_e32 v87, 0
	v_mov_b32_e32 v78, 0
	v_mov_b32_e32 v110, 0
	v_mov_b32_e32 v93, 0
	v_mov_b32_e32 v76, 0
	v_mov_b32_e32 v95, 0
	v_mov_b32_e32 v99, 0
	v_mov_b32_e32 v73, 0
	v_mov_b32_e32 v94, 0
	v_mov_b32_e32 v113, 0
	v_mov_b32_e32 v69, 0
	v_max_u32_e32 v92, v97, v84
	v_min_u32_e32 v84, v97, v84
	v_max_u32_e32 v97, v105, v69
	v_max_u32_e32 v105, v81, v113
	v_max_u32_e32 v81, v98, v94
	v_max_u32_e32 v98, v104, v73
	v_max_u32_e32 v104, v72, v99
	v_max_u32_e32 v72, v77, v95
	v_max_u32_e32 v77, v80, v76
	v_max_u32_e32 v80, v117, v93
	v_max_u32_e32 v117, v101, v110
	v_max_u32_e32 v101, v86, v78
	v_max_u32_e32 v86, v114, v87
	v_max_u32_e32 v114, v91, v75
	v_max_u32_e32 v91, v96, v82
	v_max_u32_e32 v96, v74, v71
	v_max_u32_e32 v74, v102, v84
	v_max_u32_e32 v102, v70, v92
	v_max_u32_e32 v69, v97, v117
	v_min_u32_e32 v117, v97, v117
	v_max_u32_e32 v97, v105, v101
	v_min_u32_e32 v101, v105, v101
	v_max_u32_e32 v105, v81, v86
	v_min_u32_e32 v86, v81, v86
	v_max_u32_e32 v81, v98, v114
	v_min_u32_e32 v114, v98, v114
	v_max_u32_e32 v98, v104, v91
	v_min_u32_e32 v91, v104, v91
	v_max_u32_e32 v104, v72, v96
	v_min_u32_e32 v96, v72, v96
	v_max_u32_e32 v72, v77, v74
	v_min_u32_e32 v74, v77, v74
	v_max_u32_e32 v77, v80, v102
	v_min_u32_e32 v102, v80, v102
	v_max_u32_e32 v80, v69, v98
	v_min_u32_e32 v98, v69, v98
	v_max_u32_e32 v69, v97, v104
	v_min_u32_e32 v104, v97, v104
	v_max_u32_e32 v97, v105, v72
	v_min_u32_e32 v72, v105, v72
	v_max_u32_e32 v105, v81, v77
	v_min_u32_e32 v77, v81, v77
; template <bool STORE>
; DI void peer_item(const Params& p, int item, char* smem) {
;     ...
;     unsigned wkey[16];
;     int we[16];
; #pragma unroll
;     for (int r = 0; r < 16; ++r) {
;       unsigned mx = 0u;
; #pragma unroll
;       for (int a = 0; a < 16; ++a)
; #pragma unroll
;         for (int bq = 0; bq < 16; ++bq)
;           if ((a + 1) * (bq + 1) <= 16) mx = max(mx, ckey[a][bq]);
; #pragma unroll
;       for (int a = 0; a < 16; ++a)
; #pragma unroll
;         for (int bq = 0; bq < 16; ++bq)
;           if ((a + 1) * (bq + 1) <= 16) ckey[a][bq] = (ckey[a][bq] == mx) ? 0u : ckey[a][bq];
;       wkey[r] = mx;
;       const int cidx = 255 - (int)(mx & 255u);
;       const int wa = cidx >> 4, wb = cidx & 15;
;       unsigned t1 = top1[0], t2 = top2[0];
; #pragma unroll
;       for (int a = 1; a < 16; ++a) { t1 = (wa == a) ? top1[a] : t1; t2 = (wb == a) ? top2[a] : t2; }
;       we[r] = (127 - (int)(t1 & 127u)) * 128 + (127 - (int)(t2 & 127u));
	v_max_u32_e32 v81, v117, v91
	v_min_u32_e32 v91, v117, v91
	v_max_u32_e32 v117, v101, v96
	v_min_u32_e32 v96, v101, v96
	v_max_u32_e32 v101, v86, v74
	v_min_u32_e32 v74, v86, v74
	v_max_u32_e32 v86, v114, v102
	v_min_u32_e32 v102, v114, v102
	v_max_u32_e32 v114, v80, v97
	v_min_u32_e32 v97, v80, v97
	v_max_u32_e32 v80, v69, v105
	v_min_u32_e32 v105, v69, v105
	v_max_u32_e32 v69, v98, v72
	v_min_u32_e32 v72, v98, v72
	v_max_u32_e32 v98, v104, v77
	v_min_u32_e32 v77, v104, v77
	v_max_u32_e32 v104, v81, v101
	v_min_u32_e32 v101, v81, v101
	v_max_u32_e32 v81, v117, v86
	v_min_u32_e32 v86, v117, v86
	v_max_u32_e32 v117, v91, v74
	v_min_u32_e32 v74, v91, v74
	v_max_u32_e32 v91, v96, v102
	v_min_u32_e32 v102, v96, v102
	v_max_u32_e32 v96, v114, v80
	v_min_u32_e32 v80, v114, v80
	v_max_u32_e32 v114, v97, v105
	v_min_u32_e32 v105, v97, v105
	v_max_u32_e32 v97, v69, v98
	v_min_u32_e32 v98, v69, v98
	v_max_u32_e32 v69, v72, v77
	v_min_u32_e32 v77, v72, v77
	v_max_u32_e32 v72, v104, v81
	v_min_u32_e32 v81, v104, v81
	v_max_u32_e32 v104, v101, v86
	v_min_u32_e32 v86, v101, v86
	v_max_u32_e32 v101, v117, v91
	v_min_u32_e32 v91, v117, v91
	v_max_u32_e32 v117, v74, v102
	v_min_u32_e32 v102, v74, v102
	v_max_u32_e32 v74, v115, v102
	v_max_u32_e32 v115, v89, v117
	v_max_u32_e32 v89, v90, v91
	v_max_u32_e32 v90, v15, v101
	v_max_u32_e32 v15, v103, v86
	v_max_u32_e32 v103, v83, v104
	v_max_u32_e32 v83, v100, v81
	v_max_u32_e32 v100, v112, v72
	v_max_u32_e32 v112, v85, v77
	v_max_u32_e32 v85, v111, v69
	v_max_u32_e32 v111, v106, v98
	v_max_u32_e32 v106, v88, v97
	v_max_u32_e32 v88, v109, v105
	v_max_u32_e32 v109, v79, v114
	v_max_u32_e32 v79, v116, v80
	v_max_u32_e32 v116, v108, v96
	v_max_u32_e32 v102, v74, v112
	v_min_u32_e32 v112, v74, v112
	v_max_u32_e32 v74, v115, v85
	v_min_u32_e32 v85, v115, v85
	v_max_u32_e32 v115, v89, v111
	v_min_u32_e32 v111, v89, v111
	v_max_u32_e32 v89, v90, v106
	v_min_u32_e32 v106, v90, v106
	v_max_u32_e32 v90, v15, v88
	v_min_u32_e32 v88, v15, v88
	v_max_u32_e32 v15, v103, v109
	v_min_u32_e32 v109, v103, v109
	v_max_u32_e32 v103, v83, v79
	v_min_u32_e32 v79, v83, v79
	v_max_u32_e32 v83, v100, v116
	v_min_u32_e32 v116, v100, v116
	v_max_u32_e32 v100, v102, v90
	v_min_u32_e32 v90, v102, v90
	v_max_u32_e32 v102, v74, v15
	v_min_u32_e32 v15, v74, v15
	v_max_u32_e32 v74, v115, v103
	v_min_u32_e32 v103, v115, v103
	v_max_u32_e32 v115, v89, v83
	v_min_u32_e32 v83, v89, v83
	v_max_u32_e32 v89, v112, v88
	v_min_u32_e32 v88, v112, v88
	v_max_u32_e32 v112, v85, v109
	v_min_u32_e32 v109, v85, v109
	v_max_u32_e32 v85, v111, v79
	v_min_u32_e32 v79, v111, v79
	v_max_u32_e32 v111, v106, v116
	v_min_u32_e32 v116, v106, v116
	v_max_u32_e32 v106, v100, v74
	v_min_u32_e32 v74, v100, v74
	v_max_u32_e32 v100, v102, v115
	v_min_u32_e32 v115, v102, v115
	v_max_u32_e32 v102, v90, v103
	v_min_u32_e32 v103, v90, v103
	v_max_u32_e32 v90, v15, v83
	v_min_u32_e32 v83, v15, v83
	v_max_u32_e32 v15, v89, v85
	v_min_u32_e32 v85, v89, v85
	v_max_u32_e32 v89, v112, v111
	v_min_u32_e32 v111, v112, v111
	v_max_u32_e32 v112, v88, v79
	v_min_u32_e32 v79, v88, v79
	v_max_u32_e32 v88, v109, v116
	v_min_u32_e32 v116, v109, v116
	v_max_u32_e32 v109, v106, v100
	v_min_u32_e32 v100, v106, v100
	v_max_u32_e32 v106, v74, v115
	v_min_u32_e32 v115, v74, v115
	v_max_u32_e32 v74, v102, v90
	v_min_u32_e32 v90, v102, v90
	v_max_u32_e32 v102, v103, v83
	v_min_u32_e32 v83, v103, v83
	v_max_u32_e32 v103, v15, v89
	v_min_u32_e32 v89, v15, v89
	v_max_u32_e32 v15, v85, v111
	v_min_u32_e32 v111, v85, v111
	v_max_u32_e32 v85, v112, v88
	v_min_u32_e32 v88, v112, v88
	v_max_u32_e32 v112, v79, v116
	v_min_u32_e32 v116, v79, v116
	s_waitcnt lgkmcnt(0)
	v_not_b32_e32 v229, v109
	v_bfe_u32 v230, v229, 4, 4
	v_and_b32_e32 v231, 15, v229
	v_add_u32_e32 v230, v241, v230
	v_add_u32_e32 v231, v241, v231
	ds_read_u8 v79, v230
	ds_read_u8 v108, v231 offset:16
	v_not_b32_e32 v229, v100
	v_bfe_u32 v230, v229, 4, 4
	v_and_b32_e32 v231, 15, v229
	v_add_u32_e32 v230, v241, v230
	v_add_u32_e32 v231, v241, v231
	ds_read_u8 v117, v230
	ds_read_u8 v113, v231 offset:16
	v_not_b32_e32 v229, v106
	v_bfe_u32 v230, v229, 4, 4
	v_and_b32_e32 v231, 15, v229
	v_add_u32_e32 v230, v241, v230
	v_add_u32_e32 v231, v241, v231
	ds_read_u8 v91, v230
	ds_read_u8 v94, v231 offset:16
	v_not_b32_e32 v229, v115
	v_bfe_u32 v230, v229, 4, 4
	v_and_b32_e32 v231, 15, v229
	v_add_u32_e32 v230, v241, v230
	v_add_u32_e32 v231, v241, v231
	ds_read_u8 v101, v230
	ds_read_u8 v73, v231 offset:16
	v_not_b32_e32 v229, v74
	v_bfe_u32 v230, v229, 4, 4
	v_and_b32_e32 v231, 15, v229
	v_add_u32_e32 v230, v241, v230
	v_add_u32_e32 v231, v241, v231
	ds_read_u8 v86, v230
	ds_read_u8 v99, v231 offset:16
	v_not_b32_e32 v229, v90
	v_bfe_u32 v230, v229, 4, 4
	v_and_b32_e32 v231, 15, v229
	v_add_u32_e32 v230, v241, v230
	v_add_u32_e32 v231, v241, v231
	ds_read_u8 v104, v230
	ds_read_u8 v95, v231 offset:16
	v_not_b32_e32 v229, v102
	v_bfe_u32 v230, v229, 4, 4
	v_and_b32_e32 v231, 15, v229
	v_add_u32_e32 v230, v241, v230
	v_add_u32_e32 v231, v241, v231
	ds_read_u8 v81, v230
	ds_read_u8 v76, v231 offset:16
	v_not_b32_e32 v229, v83
	v_bfe_u32 v230, v229, 4, 4
	v_and_b32_e32 v231, 15, v229
	v_add_u32_e32 v230, v241, v230
	v_add_u32_e32 v231, v241, v231
	ds_read_u8 v72, v230
	ds_read_u8 v93, v231 offset:16
	v_not_b32_e32 v229, v103
	v_bfe_u32 v230, v229, 4, 4
	v_and_b32_e32 v231, 15, v229
	v_add_u32_e32 v230, v241, v230
	v_add_u32_e32 v231, v241, v231
	ds_read_u8 v77, v230
	ds_read_u8 v110, v231 offset:16
	v_not_b32_e32 v229, v89
	v_bfe_u32 v230, v229, 4, 4
	v_and_b32_e32 v231, 15, v229
	v_add_u32_e32 v230, v241, v230
	v_add_u32_e32 v231, v241, v231
; DI float ord2f(unsigned u) { return __uint_as_float((u & 0x80000000u) ? (u ^ 0x80000000u) : ~u); }
; template <bool STORE>
; DI void peer_item(const Params& p, int item, char* smem) {
;     ...
;       const int cidx = 255 - (int)(mx & 255u);
;       const int wa = cidx >> 4, wb = cidx & 15;
;       unsigned t1 = top1[0], t2 = top2[0];
; #pragma unroll
;       for (int a = 1; a < 16; ++a) { t1 = (wa == a) ? top1[a] : t1; t2 = (wb == a) ? top2[a] : t2; }
;       we[r] = (127 - (int)(t1 & 127u)) * 128 + (127 - (int)(t2 & 127u));
;     }
;     float cs0 = ord2f(wkey[0] & ~255u);
;     float ex[16], sum = 0.f;
; #pragma unroll
;     for (int r = 0; r < 16; ++r) { ex[r] = __expf(ord2f(wkey[r] & ~255u) - cs0); sum += ex[r]; }
;     float inv = 1.f / sum;
	ds_read_u8 v69, v230
	ds_read_u8 v78, v231 offset:16
	v_not_b32_e32 v229, v15
	v_bfe_u32 v230, v229, 4, 4
	v_and_b32_e32 v231, 15, v229
	v_add_u32_e32 v230, v241, v230
	v_add_u32_e32 v231, v241, v231
	ds_read_u8 v98, v230
	ds_read_u8 v87, v231 offset:16
	v_not_b32_e32 v229, v111
	v_bfe_u32 v230, v229, 4, 4
	v_and_b32_e32 v231, 15, v229
	v_add_u32_e32 v230, v241, v230
	v_add_u32_e32 v231, v241, v231
	ds_read_u8 v97, v230
	ds_read_u8 v75, v231 offset:16
	v_not_b32_e32 v229, v85
	v_bfe_u32 v230, v229, 4, 4
	v_and_b32_e32 v231, 15, v229
	v_add_u32_e32 v230, v241, v230
	v_add_u32_e32 v231, v241, v231
	ds_read_u8 v105, v230
	ds_read_u8 v82, v231 offset:16
	v_not_b32_e32 v229, v88
	v_bfe_u32 v230, v229, 4, 4
	v_and_b32_e32 v231, 15, v229
	v_add_u32_e32 v230, v241, v230
	v_add_u32_e32 v231, v241, v231
	ds_read_u8 v114, v230
	ds_read_u8 v71, v231 offset:16
	v_not_b32_e32 v229, v112
	v_bfe_u32 v230, v229, 4, 4
	v_and_b32_e32 v231, 15, v229
	v_add_u32_e32 v230, v241, v230
	v_add_u32_e32 v231, v241, v231
	ds_read_u8 v80, v230
	ds_read_u8 v84, v231 offset:16
	v_not_b32_e32 v229, v116
	v_bfe_u32 v230, v229, 4, 4
	v_and_b32_e32 v231, 15, v229
	v_add_u32_e32 v230, v241, v230
	v_add_u32_e32 v231, v241, v231
	ds_read_u8 v96, v230
	ds_read_u8 v92, v231 offset:16
	v_and_b32_e32 v229, 0xffffff00, v109
	v_ashrrev_i32_e32 v230, 31, v229
	v_not_b32_e32 v230, v230
	v_or_b32_e32 v230, 0x80000000, v230
	v_xor_b32_e32 v48, v230, v229
	v_and_b32_e32 v229, 0xffffff00, v100
	v_ashrrev_i32_e32 v230, 31, v229
	v_not_b32_e32 v230, v230
	v_or_b32_e32 v230, 0x80000000, v230
	v_xor_b32_e32 v49, v230, v229
	v_and_b32_e32 v229, 0xffffff00, v106
	v_ashrrev_i32_e32 v230, 31, v229
	v_not_b32_e32 v230, v230
	v_or_b32_e32 v230, 0x80000000, v230
	v_xor_b32_e32 v50, v230, v229
	v_and_b32_e32 v229, 0xffffff00, v115
	v_ashrrev_i32_e32 v230, 31, v229
	v_not_b32_e32 v230, v230
	v_or_b32_e32 v230, 0x80000000, v230
	v_xor_b32_e32 v51, v230, v229
	v_and_b32_e32 v229, 0xffffff00, v74
	v_ashrrev_i32_e32 v230, 31, v229
	v_not_b32_e32 v230, v230
	v_or_b32_e32 v230, 0x80000000, v230
	v_xor_b32_e32 v52, v230, v229
	v_and_b32_e32 v229, 0xffffff00, v90
	v_ashrrev_i32_e32 v230, 31, v229
	v_not_b32_e32 v230, v230
	v_or_b32_e32 v230, 0x80000000, v230
	v_xor_b32_e32 v53, v230, v229
	v_and_b32_e32 v229, 0xffffff00, v102
	v_ashrrev_i32_e32 v230, 31, v229
	v_not_b32_e32 v230, v230
	v_or_b32_e32 v230, 0x80000000, v230
	v_xor_b32_e32 v54, v230, v229
	v_and_b32_e32 v229, 0xffffff00, v83
	v_ashrrev_i32_e32 v230, 31, v229
	v_not_b32_e32 v230, v230
	v_or_b32_e32 v230, 0x80000000, v230
	v_xor_b32_e32 v55, v230, v229
	v_and_b32_e32 v229, 0xffffff00, v103
	v_ashrrev_i32_e32 v230, 31, v229
	v_not_b32_e32 v230, v230
	v_or_b32_e32 v230, 0x80000000, v230
	v_xor_b32_e32 v29, v230, v229
	v_and_b32_e32 v229, 0xffffff00, v89
	v_ashrrev_i32_e32 v230, 31, v229
	v_not_b32_e32 v230, v230
	v_or_b32_e32 v230, 0x80000000, v230
	v_xor_b32_e32 v62, v230, v229
	v_and_b32_e32 v229, 0xffffff00, v15
	v_ashrrev_i32_e32 v230, 31, v229
	v_not_b32_e32 v230, v230
	v_or_b32_e32 v230, 0x80000000, v230
	v_xor_b32_e32 v61, v230, v229
	v_and_b32_e32 v229, 0xffffff00, v111
	v_ashrrev_i32_e32 v230, 31, v229
	v_not_b32_e32 v230, v230
	v_or_b32_e32 v230, 0x80000000, v230
	v_xor_b32_e32 v60, v230, v229
	v_and_b32_e32 v229, 0xffffff00, v85
	v_ashrrev_i32_e32 v230, 31, v229
	v_not_b32_e32 v230, v230
	v_or_b32_e32 v230, 0x80000000, v230
	v_xor_b32_e32 v59, v230, v229
	v_and_b32_e32 v229, 0xffffff00, v88
	v_ashrrev_i32_e32 v230, 31, v229
	v_not_b32_e32 v230, v230
	v_or_b32_e32 v230, 0x80000000, v230
	v_xor_b32_e32 v58, v230, v229
	v_and_b32_e32 v229, 0xffffff00, v112
	v_ashrrev_i32_e32 v230, 31, v229
	v_not_b32_e32 v230, v230
	v_or_b32_e32 v230, 0x80000000, v230
	v_xor_b32_e32 v57, v230, v229
	v_and_b32_e32 v229, 0xffffff00, v116
	v_ashrrev_i32_e32 v230, 31, v229
	v_not_b32_e32 v230, v230
	v_or_b32_e32 v230, 0x80000000, v230
	v_xor_b32_e32 v56, v230, v229
	v_sub_f32_e32 v56, v56, v48
	v_sub_f32_e32 v57, v57, v48
	v_sub_f32_e32 v58, v58, v48
	v_sub_f32_e32 v59, v59, v48
	v_sub_f32_e32 v60, v60, v48
	v_sub_f32_e32 v61, v61, v48
	v_sub_f32_e32 v62, v62, v48
	v_sub_f32_e32 v29, v29, v48
	v_sub_f32_e32 v55, v55, v48
	v_sub_f32_e32 v54, v54, v48
	v_sub_f32_e32 v53, v53, v48
	v_sub_f32_e32 v52, v52, v48
	v_sub_f32_e32 v51, v51, v48
	v_sub_f32_e32 v50, v50, v48
	v_sub_f32_e32 v49, v49, v48
	v_sub_f32_e32 v48, v48, v48
	v_mul_f32_e32 v48, 0x3fb8aa3b, v48
	v_mul_f32_e32 v49, 0x3fb8aa3b, v49
	v_mul_f32_e32 v50, 0x3fb8aa3b, v50
	v_mul_f32_e32 v51, 0x3fb8aa3b, v51
	v_mul_f32_e32 v52, 0x3fb8aa3b, v52
	v_mul_f32_e32 v53, 0x3fb8aa3b, v53
	v_mul_f32_e32 v54, 0x3fb8aa3b, v54
	v_mul_f32_e32 v55, 0x3fb8aa3b, v55
	v_mul_f32_e32 v29, 0x3fb8aa3b, v29
	v_mul_f32_e32 v62, 0x3fb8aa3b, v62
	v_mul_f32_e32 v61, 0x3fb8aa3b, v61
	v_mul_f32_e32 v60, 0x3fb8aa3b, v60
	v_mul_f32_e32 v59, 0x3fb8aa3b, v59
	v_mul_f32_e32 v58, 0x3fb8aa3b, v58
	v_mul_f32_e32 v57, 0x3fb8aa3b, v57
	v_mul_f32_e32 v56, 0x3fb8aa3b, v56
	v_exp_f32_e32 v48, v48
	v_exp_f32_e32 v49, v49
	v_exp_f32_e32 v50, v50
	v_exp_f32_e32 v51, v51
	v_exp_f32_e32 v52, v52
	v_exp_f32_e32 v53, v53
	v_exp_f32_e32 v54, v54
	v_exp_f32_e32 v55, v55
	v_exp_f32_e32 v29, v29
	v_exp_f32_e32 v62, v62
	v_exp_f32_e32 v61, v61
	v_exp_f32_e32 v60, v60
	v_exp_f32_e32 v59, v59
	v_exp_f32_e32 v58, v58
	v_exp_f32_e32 v57, v57
	v_exp_f32_e32 v56, v56
	s_nop 0
	v_add_f32_e32 v232, v48, v49
	v_add_f32_e32 v232, v232, v50
	v_add_f32_e32 v232, v232, v51
	v_add_f32_e32 v232, v232, v52
	v_add_f32_e32 v232, v232, v53
	v_add_f32_e32 v232, v232, v54
	v_add_f32_e32 v232, v232, v55
	v_add_f32_e32 v232, v232, v29
	v_add_f32_e32 v232, v232, v62
	v_add_f32_e32 v232, v232, v61
	v_add_f32_e32 v232, v232, v60
	v_add_f32_e32 v232, v232, v59
	v_add_f32_e32 v232, v232, v58
	v_add_f32_e32 v232, v232, v57
	v_add_f32_e32 v232, v232, v56
	v_div_scale_f32 v246, s[8:9], v232, v232, 1.0
	v_rcp_f32_e32 v247, v246
	s_nop 0
	v_fma_f32 v248, -v246, v247, 1.0
	v_fmac_f32_e32 v247, v248, v247
	v_div_scale_f32 v249, vcc, 1.0, v232, 1.0
	v_mul_f32_e32 v250, v249, v247
	v_fma_f32 v251, -v246, v250, v249
	v_fmac_f32_e32 v250, v251, v247
	v_fma_f32 v246, -v246, v250, v249
	s_nop 1
	v_div_fmas_f32 v246, v246, v247, v250
	v_div_fixup_f32 v247, v246, v232, 1.0
	v_mul_f32_e32 v48, v48, v247
	v_mul_f32_e32 v49, v49, v247
	v_mul_f32_e32 v50, v50, v247
	v_mul_f32_e32 v51, v51, v247
	v_mul_f32_e32 v52, v52, v247
	v_mul_f32_e32 v53, v53, v247
	v_mul_f32_e32 v54, v54, v247
	v_mul_f32_e32 v55, v55, v247
	v_mul_f32_e32 v29, v29, v247
	v_mul_f32_e32 v62, v62, v247
	v_mul_f32_e32 v61, v61, v247
	v_mul_f32_e32 v60, v60, v247
	v_mul_f32_e32 v59, v59, v247
	v_mul_f32_e32 v58, v58, v247
	v_mul_f32_e32 v57, v57, v247
	v_mul_f32_e32 v56, v56, v247
	s_waitcnt lgkmcnt(0)
; DI float ord2f(unsigned u) { return __uint_as_float((u & 0x80000000u) ? (u ^ 0x80000000u) : ~u); }
; template <bool STORE>
; DI void peer_item(const Params& p, int item, char* smem) {
;     ...
;       we[r] = (127 - (int)(t1 & 127u)) * 128 + (127 - (int)(t2 & 127u));
;     }
;     float cs0 = ord2f(wkey[0] & ~255u);
;     float ex[16], sum = 0.f;
; #pragma unroll
;     for (int r = 0; r < 16; ++r) { ex[r] = __expf(ord2f(wkey[r] & ~255u) - cs0); sum += ex[r]; }
;     float inv = 1.f / sum;
;     if (hh == 0) {
; #pragma unroll
;       for (int r = 0; r < 16; ++r) {
;         e_s[lr * 128 + hd * 16 + r] = we[r];
;         g_s[lr * 128 + hd * 16 + r] = ex[r] * inv;
;       }
;     }
	v_lshl_or_b32 v32, v79, 7, v108
	v_lshl_or_b32 v33, v117, 7, v113
	v_lshl_or_b32 v34, v91, 7, v94
	v_lshl_or_b32 v35, v101, 7, v73
	v_lshl_or_b32 v36, v86, 7, v99
	v_lshl_or_b32 v37, v104, 7, v95
	v_lshl_or_b32 v38, v81, 7, v76
	v_lshl_or_b32 v39, v72, 7, v93
	v_lshl_or_b32 v40, v77, 7, v110
	v_lshl_or_b32 v41, v69, 7, v78
	v_lshl_or_b32 v42, v98, 7, v87
	v_lshl_or_b32 v43, v97, 7, v75
	v_lshl_or_b32 v44, v105, 7, v82
	v_lshl_or_b32 v45, v114, 7, v71
	v_lshl_or_b32 v46, v80, 7, v84
	v_lshl_or_b32 v31, v96, 7, v92
	ds_write_b32 v242, v32 offset:0
	ds_write_b32 v242, v48 offset:16384
	ds_write_b32 v242, v33 offset:4
	ds_write_b32 v242, v49 offset:16388
	ds_write_b32 v242, v34 offset:8
	ds_write_b32 v242, v50 offset:16392
	ds_write_b32 v242, v35 offset:12
	ds_write_b32 v242, v51 offset:16396
	ds_write_b32 v242, v36 offset:16
	ds_write_b32 v242, v52 offset:16400
	ds_write_b32 v242, v37 offset:20
	ds_write_b32 v242, v53 offset:16404
	ds_write_b32 v242, v38 offset:24
	ds_write_b32 v242, v54 offset:16408
	ds_write_b32 v242, v39 offset:28
	ds_write_b32 v242, v55 offset:16412
	ds_write_b32 v242, v40 offset:32
	ds_write_b32 v242, v29 offset:16416
	ds_write_b32 v242, v41 offset:36
	ds_write_b32 v242, v62 offset:16420
	ds_write_b32 v242, v42 offset:40
	ds_write_b32 v242, v61 offset:16424
	ds_write_b32 v242, v43 offset:44
	ds_write_b32 v242, v60 offset:16428
	ds_write_b32 v242, v44 offset:48
	ds_write_b32 v242, v59 offset:16432
	ds_write_b32 v242, v45 offset:52
	ds_write_b32 v242, v58 offset:16436
	ds_write_b32 v242, v46 offset:56
	ds_write_b32 v242, v57 offset:16440
	ds_write_b32 v242, v31 offset:60
	ds_write_b32 v242, v56 offset:16444
	ds_read_b32 v3, v240 offset:512
	ds_read_b32 v53, v240 offset:768
	ds_read_b32 v64, v240 offset:1024
	ds_read_b32 v65, v240 offset:1280
	ds_read_b32 v66, v240 offset:1536
	ds_read_b32 v67, v240 offset:1792
	ds_read_b32 v68, v240 offset:2048
	ds_read_b32 v69, v240 offset:2304
	ds_read_b32 v70, v240 offset:2560
	ds_read_b32 v71, v240 offset:2816
	ds_read_b32 v72, v240 offset:3072
	ds_read_b32 v73, v240 offset:3328
	ds_read_b32 v74, v240 offset:3584
	ds_read_b32 v75, v240 offset:3840
	ds_read_b32 v76, v240 offset:4096
	ds_read_b32 v77, v240 offset:4352
	ds_read_b32 v78, v240 offset:4608
	ds_read_b32 v79, v240 offset:4864
	ds_read_b32 v80, v240 offset:5120
	ds_read_b32 v81, v240 offset:5376
	ds_read_b32 v82, v240 offset:5632
	ds_read_b32 v83, v240 offset:5888
	ds_read_b32 v84, v240 offset:6144
	ds_read_b32 v96, v240 offset:6400
	v_readlane_b32 s6, v254, 0
	v_readlane_b32 s7, v254, 1
	v_readlane_b32 s12, v254, 2
	v_readlane_b32 s13, v254, 3
	v_readlane_b32 s14, v254, 4
	v_readlane_b32 s15, v254, 5
	v_readlane_b32 s16, v254, 6
	v_readlane_b32 s17, v254, 7
	v_readlane_b32 s18, v254, 8
	v_readlane_b32 s19, v254, 9
	v_readlane_b32 s20, v254, 10
	v_readlane_b32 s21, v254, 11
	v_readlane_b32 s22, v254, 12
	v_readlane_b32 s23, v254, 13
	v_readlane_b32 s24, v254, 14
	v_readlane_b32 s25, v254, 15
	v_readlane_b32 s26, v254, 16
	v_readlane_b32 s27, v254, 17
	v_readlane_b32 s28, v254, 18
	v_readlane_b32 s29, v254, 19
	v_readlane_b32 s30, v254, 20
	v_readlane_b32 s31, v254, 21
	v_readlane_b32 s33, v254, 22
	v_readlane_b32 s34, v254, 23
	v_readlane_b32 s35, v254, 24
	v_readlane_b32 s36, v254, 25
	v_readlane_b32 s37, v254, 26
	v_readlane_b32 s38, v254, 27
	v_readlane_b32 s39, v254, 28
	v_readlane_b32 s40, v254, 29
	v_readlane_b32 s41, v254, 30
	v_readlane_b32 s42, v254, 31
	v_readlane_b32 s44, v254, 32
	v_readlane_b32 s45, v254, 33
	v_readlane_b32 s48, v254, 34
	v_readlane_b32 s49, v254, 35
	v_readlane_b32 s50, v254, 36
	v_readlane_b32 s51, v254, 37
	v_readlane_b32 s52, v254, 38
	v_readlane_b32 s53, v254, 39
	v_readlane_b32 s55, v254, 40
	v_readlane_b32 s60, v254, 41
	v_readlane_b32 s61, v254, 42
	v_readlane_b32 s62, v254, 43
	v_readlane_b32 s63, v254, 44
	v_readlane_b32 s66, v254, 45
	v_readlane_b32 s67, v254, 46
	v_readlane_b32 s68, v254, 47
	v_readlane_b32 s69, v254, 48
	v_readlane_b32 s74, v254, 49
	v_readlane_b32 s75, v254, 50
	v_readlane_b32 s76, v254, 51
	v_readlane_b32 s77, v254, 52
	v_readlane_b32 s78, v254, 53
	v_readlane_b32 s79, v254, 54
	v_readlane_b32 s88, v254, 55
	s_waitcnt vmcnt(0) lgkmcnt(0)
	s_nop 3

; DI float bflo(unsigned u) { return __uint_as_float(u << 16); }
; DI float bfhi(unsigned u) { return __uint_as_float(u & 0xffff0000u); }
; template <bool STORE>
; DI void peer_item(const Params& p, int item, char* smem) {
;     ...
;   const unsigned char* U8 = (const unsigned char*)(ws + WS_UBF);
;   const float* SU = (const float*)(ws + WS_SU);
;   const float* SV = (const float*)(ws + WS_SV);
;   int* EG = (int*)(ws + WS_XN);
;   float* AG = (float*)(ws + WS_XN + (size_t)T_TOK * 128 * 4);
;   const bool b5 = (lane & 32) != 0, b4 = (lane & 16) != 0, b3 = (lane & 8) != 0;
; #pragma unroll 1
;   for (int ti = 0; ti < 8; ++ti) {
;     const int tl = wave * 8 + ti;
;     const size_t tok = (size_t)tok0 + tl;
;     float xf[16];
;     {
; #pragma unroll
;       for (int i = 0; i < 4; ++i) {
;         const uint2 xv = *(const uint2*)(XN2 + tok * 1024 + 256 * i + lane * 4);
;         xf[4 * i] = bflo(xv.x); xf[4 * i + 1] = bfhi(xv.x); xf[4 * i + 2] = bflo(xv.y); xf[4 * i + 3] = bfhi(xv.y);
;       }
;     }
.LBB0_1058:
	s_or_b64 exec, exec, s[0:1]
	s_waitcnt vmcnt(0) lgkmcnt(0)
	v_writelane_b32 v254, s6, 0
	v_writelane_b32 v254, s7, 1
	v_writelane_b32 v254, s12, 2
	v_writelane_b32 v254, s13, 3
	v_writelane_b32 v254, s14, 4
	v_writelane_b32 v254, s15, 5
	v_writelane_b32 v254, s16, 6
	v_writelane_b32 v254, s17, 7
	v_writelane_b32 v254, s18, 8
	v_writelane_b32 v254, s19, 9
	v_writelane_b32 v254, s20, 10
	v_writelane_b32 v254, s21, 11
	v_writelane_b32 v254, s22, 12
	v_writelane_b32 v254, s23, 13
	v_writelane_b32 v254, s24, 14
	v_writelane_b32 v254, s25, 15
	v_writelane_b32 v254, s26, 16
	v_writelane_b32 v254, s27, 17
	v_writelane_b32 v254, s28, 18
	v_writelane_b32 v254, s29, 19
	v_writelane_b32 v254, s30, 20
	v_writelane_b32 v254, s31, 21
	v_writelane_b32 v254, s33, 22
	v_writelane_b32 v254, s34, 23
	v_writelane_b32 v254, s35, 24
	v_writelane_b32 v254, s36, 25
	v_writelane_b32 v254, s37, 26
	v_writelane_b32 v254, s38, 27
	v_writelane_b32 v254, s39, 28
	v_writelane_b32 v254, s40, 29
	v_writelane_b32 v254, s41, 30
	v_writelane_b32 v254, s42, 31
	v_writelane_b32 v254, s44, 32
	v_writelane_b32 v254, s45, 33
	v_writelane_b32 v254, s48, 34
	v_writelane_b32 v254, s49, 35
	v_writelane_b32 v254, s50, 36
	v_writelane_b32 v254, s51, 37
	v_writelane_b32 v254, s52, 38
	v_writelane_b32 v254, s53, 39
	v_writelane_b32 v254, s55, 40
	v_writelane_b32 v254, s60, 41
	v_writelane_b32 v254, s61, 42
	v_writelane_b32 v254, s62, 43
	v_writelane_b32 v254, s63, 44
	v_writelane_b32 v254, s66, 45
	v_writelane_b32 v254, s67, 46
	v_writelane_b32 v254, s68, 47
	v_writelane_b32 v254, s69, 48
	v_writelane_b32 v254, s74, 49
	v_writelane_b32 v254, s75, 50
	v_writelane_b32 v254, s76, 51
	v_writelane_b32 v254, s77, 52
	v_writelane_b32 v254, s78, 53
	v_writelane_b32 v254, s79, 54
	v_writelane_b32 v254, s88, 55
	s_mov_b32 s16, s33
	s_mov_b32 s14, s42
	v_readlane_b32 s56, v253, 48
	v_readlane_b32 s57, v253, 49
	v_readfirstlane_b32 s13, v211
	v_mbcnt_lo_u32_b32 v213, -1, 0
	v_mbcnt_hi_u32_b32 v213, -1, v213
	s_nop 3
	s_bfe_u32 s17, s13, 0x20006
	s_add_u32 s0, s56, 0x1200200
	s_addc_u32 s1, s57, 0
	s_add_u32 s2, s56, 0x7200200
	s_addc_u32 s3, s57, 0
	s_add_u32 s4, s56, 0x5200200
	s_addc_u32 s5, s57, 0
	s_add_u32 s6, s56, 0x5a00200
	s_addc_u32 s7, s57, 0
	s_add_u32 s8, s56, 0x2200200
	s_addc_u32 s9, s57, 0
	s_add_u32 s10, s56, 0x4200200
	s_addc_u32 s11, s57, 0
	s_lshl_b32 s13, s17, 3
	s_add_u32 s14, s14, s13
	s_mul_i32 s18, s17, 7680
	s_add_u32 s18, s18, s16
	s_add_u32 s18, s18, 49152
	s_lshl_b32 s19, s17, 12
	s_add_u32 s19, s19, s16
	v_lshlrev_b32_e32 v238, 2, v213
	v_lshlrev_b32_e32 v234, 4, v213
	v_add_u32_e32 v236, s18, v238
	v_add_u32_e32 v237, s19, v238
	ds_write_b32 v236, v3 offset:512
	ds_write_b32 v236, v53 offset:768
	ds_write_b32 v236, v64 offset:1024
	ds_write_b32 v236, v65 offset:1280
	ds_write_b32 v236, v66 offset:1536
	ds_write_b32 v236, v67 offset:1792
	ds_write_b32 v236, v68 offset:2048
	ds_write_b32 v236, v69 offset:2304
	ds_write_b32 v236, v70 offset:2560
	ds_write_b32 v236, v71 offset:2816
	ds_write_b32 v236, v72 offset:3072
	ds_write_b32 v236, v73 offset:3328
	ds_write_b32 v236, v74 offset:3584
	ds_write_b32 v236, v75 offset:3840
	ds_write_b32 v236, v76 offset:4096
	ds_write_b32 v236, v77 offset:4352
	ds_write_b32 v236, v78 offset:4608
	ds_write_b32 v236, v79 offset:4864
	ds_write_b32 v236, v80 offset:5120
	ds_write_b32 v236, v81 offset:5376
	ds_write_b32 v236, v82 offset:5632
	ds_write_b32 v236, v83 offset:5888
	ds_write_b32 v236, v96 offset:6144
	ds_write_b32 v236, v210 offset:6400
	ds_write_b32 v236, v211 offset:6656
	ds_write_b32 v236, v212 offset:6912
	s_mov_b32 s24, 0xff00ff00
	s_mov_b32 s25, 0xff00ff00
	s_mov_b32 s80, 0x378e98ab
	s_mov_b32 s81, 0x3b7cd369
	s_mov_b32 s82, 0xbcc618b2
	s_mov_b32 s83, 0x3dda74e4
	s_mov_b32 s84, 0x3f228afd
	s_mov_b32 s85, 0x3e03c728
	s_mov_b32 s86, 0xbfb8aa3b
	s_mov_b32 s87, 0x42ce8ed0
	s_mov_b32 s88, 0xc2b17218
	s_mov_b32 s89, 0x7fffffff
	s_waitcnt lgkmcnt(0)
	s_lshl_b32 s13, s14, 11
	s_add_u32 s32, s2, s13
	s_addc_u32 s33, s3, 0
	v_lshlrev_b32_e32 v239, 3, v213
	global_load_dwordx2 v[2:3], v239, s[32:33] offset:0
	global_load_dwordx2 v[6:7], v239, s[32:33] offset:512
	global_load_dwordx2 v[10:11], v239, s[32:33] offset:1024
	global_load_dwordx2 v[14:15], v239, s[32:33] offset:1536
	global_load_dwordx2 v[18:19], v239, s[32:33] offset:2048
	global_load_dwordx2 v[22:23], v239, s[32:33] offset:2560
	global_load_dwordx2 v[26:27], v239, s[32:33] offset:3072
	global_load_dwordx2 v[30:31], v239, s[32:33] offset:3584
	s_add_u32 s32, s32, 4096
	s_addc_u32 s33, s33, 0
	global_load_dwordx2 v[34:35], v239, s[32:33] offset:0
	global_load_dwordx2 v[38:39], v239, s[32:33] offset:512
	global_load_dwordx2 v[42:43], v239, s[32:33] offset:1024
	global_load_dwordx2 v[46:47], v239, s[32:33] offset:1536
	global_load_dwordx2 v[50:51], v239, s[32:33] offset:2048
	global_load_dwordx2 v[54:55], v239, s[32:33] offset:2560
	global_load_dwordx2 v[58:59], v239, s[32:33] offset:3072
	global_load_dwordx2 v[62:63], v239, s[32:33] offset:3584
	s_add_u32 s32, s32, 4096
	s_addc_u32 s33, s33, 0
	global_load_dwordx2 v[66:67], v239, s[32:33] offset:0
	global_load_dwordx2 v[70:71], v239, s[32:33] offset:512
	global_load_dwordx2 v[74:75], v239, s[32:33] offset:1024
	global_load_dwordx2 v[78:79], v239, s[32:33] offset:1536
	global_load_dwordx2 v[82:83], v239, s[32:33] offset:2048
	global_load_dwordx2 v[86:87], v239, s[32:33] offset:2560
	global_load_dwordx2 v[90:91], v239, s[32:33] offset:3072
	global_load_dwordx2 v[94:95], v239, s[32:33] offset:3584
	s_add_u32 s32, s32, 4096
	s_addc_u32 s33, s33, 0
	global_load_dwordx2 v[98:99], v239, s[32:33] offset:0
; template <bool STORE>
; DI void peer_item(const Params& p, int item, char* smem) {
;     ...
; #pragma unroll 2
;     for (int k = 0; k < 128; k += 8) {
;       u32x4 uq[8];
;       const int emine = e_s[tl * 128 + k + (lane >> 3)];
;       const float gmine = g_s[tl * 128 + k + (lane >> 3)];
;       const float su = SU[emine], sv = SV[emine];
; #pragma unroll
;       for (int u = 0; u < 8; ++u) {
;         int e = e_s[tl * 128 + k + u];
;         uq[u] = *(const u32x4*)(U8 + (size_t)e * 1024 + lane * 16);
	global_load_dwordx2 v[102:103], v239, s[32:33] offset:512
	global_load_dwordx2 v[106:107], v239, s[32:33] offset:1024
	global_load_dwordx2 v[110:111], v239, s[32:33] offset:1536
	global_load_dwordx2 v[114:115], v239, s[32:33] offset:2048
	global_load_dwordx2 v[118:119], v239, s[32:33] offset:2560
	global_load_dwordx2 v[122:123], v239, s[32:33] offset:3072
	global_load_dwordx2 v[126:127], v239, s[32:33] offset:3584
	v_mov_b32_e32 v144, v236
	v_mov_b32_e32 v145, 0
	v_mov_b32_e32 v146, 1
	v_lshrrev_b32_e32 v147, 3, v213
	v_and_b32_e32 v148, 7, v213
	v_lshlrev_b32_e32 v147, 6, v147
	v_lshl_add_u32 v147, v148, 2, v147
	v_add_u32_e32 v147, s19, v147
	v_subrev_u32_e32 v149, 1, v213
	v_subrev_u32_e32 v150, 2, v213
	v_subrev_u32_e32 v151, 4, v213
	v_subrev_u32_e32 v152, 8, v213
	v_subrev_u32_e32 v153, 16, v213
	v_subrev_u32_e32 v154, 32, v213
	v_lshlrev_b32_e32 v149, 2, v149
	v_lshlrev_b32_e32 v150, 2, v150
	v_lshlrev_b32_e32 v151, 2, v151
	v_lshlrev_b32_e32 v152, 2, v152
	v_lshlrev_b32_e32 v153, 2, v153
	v_lshlrev_b32_e32 v154, 2, v154
	ds_read_b32 v166, v237 offset:0
	ds_read_b32 v167, v237 offset:256
	ds_read_b32 v168, v237 offset:16384
	ds_read_b32 v169, v237 offset:16640
	ds_write_b32 v144, v145 offset:0
	ds_write_b32 v144, v145 offset:256
	ds_read_b32 v180, v237 offset:512
	ds_read_b32 v181, v237 offset:768
	ds_read_b32 v182, v237 offset:16896
	ds_read_b32 v183, v237 offset:17152
	ds_write_b32 v144, v145 offset:7168
	ds_write_b32 v144, v145 offset:7424
	s_waitcnt lgkmcnt(0)
	v_lshrrev_b32_e32 v156, 5, v166
	v_and_b32_e32 v156, 0x1fc, v156
	v_add_u32_e32 v156, s18, v156
	v_lshrrev_b32_e32 v157, 5, v167
	v_and_b32_e32 v157, 0x1fc, v157
	v_add_u32_e32 v157, s18, v157
	v_lshrrev_b32_e32 v170, 5, v180
	v_and_b32_e32 v170, 0x1fc, v170
	v_add_u32_e32 v170, s18, v170
	v_add_u32_e32 v170, 7168, v170
	v_lshrrev_b32_e32 v171, 5, v181
	v_and_b32_e32 v171, 0x1fc, v171
	v_add_u32_e32 v171, s18, v171
	v_add_u32_e32 v171, 7168, v171
	ds_add_rtn_u32 v158, v156, v146
	ds_add_rtn_u32 v159, v157, v146
	ds_add_rtn_u32 v172, v170, v146
	ds_add_rtn_u32 v173, v171, v146
	ds_read_b32 v160, v144 offset:0
	ds_read_b32 v161, v144 offset:256
	ds_read_b32 v174, v144 offset:7168
	ds_read_b32 v175, v144 offset:7424
	s_waitcnt lgkmcnt(0)
	v_mov_b32_e32 v164, v160
	v_mov_b32_e32 v165, v161
	v_mov_b32_e32 v178, v174
	v_mov_b32_e32 v179, v175
	v_cmp_le_u32_e32 vcc, 1, v213
	ds_bpermute_b32 v162, v149, v164
	ds_bpermute_b32 v163, v149, v165
	ds_bpermute_b32 v176, v149, v178
	ds_bpermute_b32 v177, v149, v179
	s_waitcnt lgkmcnt(0)
	v_cndmask_b32_e32 v162, 0, v162, vcc
	v_cndmask_b32_e32 v163, 0, v163, vcc
	v_add_u32_e32 v164, v164, v162
	v_add_u32_e32 v165, v165, v163
	v_cndmask_b32_e32 v176, 0, v176, vcc
	v_cndmask_b32_e32 v177, 0, v177, vcc
	v_add_u32_e32 v178, v178, v176
	v_add_u32_e32 v179, v179, v177
	v_cmp_le_u32_e32 vcc, 2, v213
	ds_bpermute_b32 v162, v150, v164
	ds_bpermute_b32 v163, v150, v165
	ds_bpermute_b32 v176, v150, v178
	ds_bpermute_b32 v177, v150, v179
	s_waitcnt lgkmcnt(0)
	v_cndmask_b32_e32 v162, 0, v162, vcc
	v_cndmask_b32_e32 v163, 0, v163, vcc
	v_add_u32_e32 v164, v164, v162
	v_add_u32_e32 v165, v165, v163
	v_cndmask_b32_e32 v176, 0, v176, vcc
	v_cndmask_b32_e32 v177, 0, v177, vcc
	v_add_u32_e32 v178, v178, v176
	v_add_u32_e32 v179, v179, v177
	v_cmp_le_u32_e32 vcc, 4, v213
	ds_bpermute_b32 v162, v151, v164
	ds_bpermute_b32 v163, v151, v165
	ds_bpermute_b32 v176, v151, v178
	ds_bpermute_b32 v177, v151, v179
	s_waitcnt lgkmcnt(0)
	v_cndmask_b32_e32 v162, 0, v162, vcc
	v_cndmask_b32_e32 v163, 0, v163, vcc
	v_add_u32_e32 v164, v164, v162
	v_add_u32_e32 v165, v165, v163
	v_cndmask_b32_e32 v176, 0, v176, vcc
	v_cndmask_b32_e32 v177, 0, v177, vcc
	v_add_u32_e32 v178, v178, v176
	v_add_u32_e32 v179, v179, v177
	v_cmp_le_u32_e32 vcc, 8, v213
	ds_bpermute_b32 v162, v152, v164
	ds_bpermute_b32 v163, v152, v165
	ds_bpermute_b32 v176, v152, v178
	ds_bpermute_b32 v177, v152, v179
	s_waitcnt lgkmcnt(0)
	v_cndmask_b32_e32 v162, 0, v162, vcc
	v_cndmask_b32_e32 v163, 0, v163, vcc
	v_add_u32_e32 v164, v164, v162
	v_add_u32_e32 v165, v165, v163
	v_cndmask_b32_e32 v176, 0, v176, vcc
	v_cndmask_b32_e32 v177, 0, v177, vcc
	v_add_u32_e32 v178, v178, v176
	v_add_u32_e32 v179, v179, v177
	v_cmp_le_u32_e32 vcc, 16, v213
	ds_bpermute_b32 v162, v153, v164
	ds_bpermute_b32 v163, v153, v165
	ds_bpermute_b32 v176, v153, v178
	ds_bpermute_b32 v177, v153, v179
	s_waitcnt lgkmcnt(0)
	v_cndmask_b32_e32 v162, 0, v162, vcc
	v_cndmask_b32_e32 v163, 0, v163, vcc
	v_add_u32_e32 v164, v164, v162
	v_add_u32_e32 v165, v165, v163
	v_cndmask_b32_e32 v176, 0, v176, vcc
	v_cndmask_b32_e32 v177, 0, v177, vcc
	v_add_u32_e32 v178, v178, v176
	v_add_u32_e32 v179, v179, v177
	v_cmp_le_u32_e32 vcc, 32, v213
	ds_bpermute_b32 v162, v154, v164
	ds_bpermute_b32 v163, v154, v165
	ds_bpermute_b32 v176, v154, v178
	ds_bpermute_b32 v177, v154, v179
	s_waitcnt lgkmcnt(0)
	v_cndmask_b32_e32 v162, 0, v162, vcc
	v_cndmask_b32_e32 v163, 0, v163, vcc
	v_add_u32_e32 v164, v164, v162
	v_add_u32_e32 v165, v165, v163
	v_cndmask_b32_e32 v176, 0, v176, vcc
	v_cndmask_b32_e32 v177, 0, v177, vcc
	v_add_u32_e32 v178, v178, v176
	v_add_u32_e32 v179, v179, v177
	s_nop 0
	v_readlane_b32 s13, v164, 63
	v_sub_u32_e32 v164, v164, v160
	v_sub_u32_e32 v165, v165, v161
	s_nop 0
	v_add_u32_e32 v165, s13, v165
	s_nop 0
	v_readlane_b32 s13, v178, 63
	v_sub_u32_e32 v178, v178, v174
	v_sub_u32_e32 v179, v179, v175
	s_nop 0
	v_add_u32_e32 v179, s13, v179
	ds_write_b32 v144, v164 offset:0
	ds_write_b32 v144, v165 offset:256
	ds_write_b32 v144, v178 offset:7168
	ds_write_b32 v144, v179 offset:7424
	ds_read_b32 v160, v156
	ds_read_b32 v161, v157
	ds_read_b32 v174, v170
	ds_read_b32 v175, v171
	s_waitcnt lgkmcnt(0)
; template <bool STORE>
; DI void peer_item(const Params& p, int item, char* smem) {
;     ...
; #pragma unroll 2
;     for (int k = 0; k < 128; k += 8) {
;       u32x4 uq[8];
;       const int emine = e_s[tl * 128 + k + (lane >> 3)];
;       const float gmine = g_s[tl * 128 + k + (lane >> 3)];
;       const float su = SU[emine], sv = SV[emine];
; #pragma unroll
;       for (int u = 0; u < 8; ++u) {
;         int e = e_s[tl * 128 + k + u];
;         uq[u] = *(const u32x4*)(U8 + (size_t)e * 1024 + lane * 16);
	v_add_u32_e32 v160, v160, v158
	v_add_u32_e32 v161, v161, v159
	v_lshl_add_u32 v160, v160, 2, s19
	v_lshl_add_u32 v161, v161, 2, s19
	v_add_u32_e32 v174, v174, v172
	v_add_u32_e32 v175, v175, v173
	v_lshl_add_u32 v174, v174, 2, s19
	v_lshl_add_u32 v175, v175, 2, s19
	ds_write_b32 v160, v166 offset:0
	ds_write_b32 v160, v168 offset:16384
	ds_write_b32 v161, v167 offset:0
	ds_write_b32 v161, v169 offset:16384
	ds_write_b32 v174, v180 offset:512
	ds_write_b32 v174, v182 offset:16896
	ds_write_b32 v175, v181 offset:512
	ds_write_b32 v175, v183 offset:16896
	ds_read_b32 v128, v147 offset:0
	ds_read_b32 v129, v147 offset:32
	ds_read_b32 v130, v147 offset:512
	ds_read_b32 v131, v147 offset:544
	s_waitcnt lgkmcnt(0)
	v_lshlrev_b32_e32 v128, 10, v128
	v_lshlrev_b32_e32 v129, 10, v129
	v_lshlrev_b32_e32 v130, 10, v130
	v_lshlrev_b32_e32 v131, 10, v131
	ds_read_b32 v166, v237 offset:1024
	ds_read_b32 v167, v237 offset:1280
	ds_read_b32 v168, v237 offset:17408
	ds_read_b32 v169, v237 offset:17664
	ds_write_b32 v144, v145 offset:0
	ds_write_b32 v144, v145 offset:256
	ds_read_b32 v180, v237 offset:1536
	ds_read_b32 v181, v237 offset:1792
	ds_read_b32 v182, v237 offset:17920
	ds_read_b32 v183, v237 offset:18176
	ds_write_b32 v144, v145 offset:7168
	ds_write_b32 v144, v145 offset:7424
	s_waitcnt lgkmcnt(0)
	v_lshrrev_b32_e32 v156, 5, v166
	v_and_b32_e32 v156, 0x1fc, v156
	v_add_u32_e32 v156, s18, v156
	v_lshrrev_b32_e32 v157, 5, v167
	v_and_b32_e32 v157, 0x1fc, v157
	v_add_u32_e32 v157, s18, v157
	v_lshrrev_b32_e32 v170, 5, v180
	v_and_b32_e32 v170, 0x1fc, v170
	v_add_u32_e32 v170, s18, v170
	v_add_u32_e32 v170, 7168, v170
	v_lshrrev_b32_e32 v171, 5, v181
	v_and_b32_e32 v171, 0x1fc, v171
	v_add_u32_e32 v171, s18, v171
	v_add_u32_e32 v171, 7168, v171
	ds_add_rtn_u32 v158, v156, v146
	ds_add_rtn_u32 v159, v157, v146
	ds_add_rtn_u32 v172, v170, v146
	ds_add_rtn_u32 v173, v171, v146
	ds_read_b32 v160, v144 offset:0
	ds_read_b32 v161, v144 offset:256
	ds_read_b32 v174, v144 offset:7168
	ds_read_b32 v175, v144 offset:7424
	s_waitcnt lgkmcnt(0)
	v_mov_b32_e32 v164, v160
	v_mov_b32_e32 v165, v161
	v_mov_b32_e32 v178, v174
	v_mov_b32_e32 v179, v175
	v_cmp_le_u32_e32 vcc, 1, v213
	ds_bpermute_b32 v162, v149, v164
	ds_bpermute_b32 v163, v149, v165
	ds_bpermute_b32 v176, v149, v178
	ds_bpermute_b32 v177, v149, v179
	s_waitcnt lgkmcnt(0)
	v_cndmask_b32_e32 v162, 0, v162, vcc
	v_cndmask_b32_e32 v163, 0, v163, vcc
	v_add_u32_e32 v164, v164, v162
	v_add_u32_e32 v165, v165, v163
	v_cndmask_b32_e32 v176, 0, v176, vcc
	v_cndmask_b32_e32 v177, 0, v177, vcc
	v_add_u32_e32 v178, v178, v176
	v_add_u32_e32 v179, v179, v177
	v_cmp_le_u32_e32 vcc, 2, v213
	ds_bpermute_b32 v162, v150, v164
	ds_bpermute_b32 v163, v150, v165
	ds_bpermute_b32 v176, v150, v178
	ds_bpermute_b32 v177, v150, v179
	s_waitcnt lgkmcnt(0)
	v_cndmask_b32_e32 v162, 0, v162, vcc
	v_cndmask_b32_e32 v163, 0, v163, vcc
	v_add_u32_e32 v164, v164, v162
	v_add_u32_e32 v165, v165, v163
	v_cndmask_b32_e32 v176, 0, v176, vcc
	v_cndmask_b32_e32 v177, 0, v177, vcc
	v_add_u32_e32 v178, v178, v176
	v_add_u32_e32 v179, v179, v177
	v_cmp_le_u32_e32 vcc, 4, v213
	ds_bpermute_b32 v162, v151, v164
	ds_bpermute_b32 v163, v151, v165
	ds_bpermute_b32 v176, v151, v178
	ds_bpermute_b32 v177, v151, v179
	s_waitcnt lgkmcnt(0)
	v_cndmask_b32_e32 v162, 0, v162, vcc
	v_cndmask_b32_e32 v163, 0, v163, vcc
	v_add_u32_e32 v164, v164, v162
	v_add_u32_e32 v165, v165, v163
	v_cndmask_b32_e32 v176, 0, v176, vcc
	v_cndmask_b32_e32 v177, 0, v177, vcc
	v_add_u32_e32 v178, v178, v176
	v_add_u32_e32 v179, v179, v177
	v_cmp_le_u32_e32 vcc, 8, v213
	ds_bpermute_b32 v162, v152, v164
	ds_bpermute_b32 v163, v152, v165
	ds_bpermute_b32 v176, v152, v178
	ds_bpermute_b32 v177, v152, v179
	s_waitcnt lgkmcnt(0)
	v_cndmask_b32_e32 v162, 0, v162, vcc
	v_cndmask_b32_e32 v163, 0, v163, vcc
	v_add_u32_e32 v164, v164, v162
	v_add_u32_e32 v165, v165, v163
	v_cndmask_b32_e32 v176, 0, v176, vcc
	v_cndmask_b32_e32 v177, 0, v177, vcc
	v_add_u32_e32 v178, v178, v176
	v_add_u32_e32 v179, v179, v177
	v_cmp_le_u32_e32 vcc, 16, v213
	ds_bpermute_b32 v162, v153, v164
	ds_bpermute_b32 v163, v153, v165
	ds_bpermute_b32 v176, v153, v178
	ds_bpermute_b32 v177, v153, v179
	s_waitcnt lgkmcnt(0)
	v_cndmask_b32_e32 v162, 0, v162, vcc
	v_cndmask_b32_e32 v163, 0, v163, vcc
	v_add_u32_e32 v164, v164, v162
	v_add_u32_e32 v165, v165, v163
	v_cndmask_b32_e32 v176, 0, v176, vcc
	v_cndmask_b32_e32 v177, 0, v177, vcc
	v_add_u32_e32 v178, v178, v176
	v_add_u32_e32 v179, v179, v177
	v_cmp_le_u32_e32 vcc, 32, v213
	ds_bpermute_b32 v162, v154, v164
	ds_bpermute_b32 v163, v154, v165
	ds_bpermute_b32 v176, v154, v178
	ds_bpermute_b32 v177, v154, v179
	s_waitcnt lgkmcnt(0)
	v_cndmask_b32_e32 v162, 0, v162, vcc
	v_cndmask_b32_e32 v163, 0, v163, vcc
	v_add_u32_e32 v164, v164, v162
	v_add_u32_e32 v165, v165, v163
	v_cndmask_b32_e32 v176, 0, v176, vcc
	v_cndmask_b32_e32 v177, 0, v177, vcc
	v_add_u32_e32 v178, v178, v176
	v_add_u32_e32 v179, v179, v177
	s_nop 0
	v_readlane_b32 s13, v164, 63
	v_sub_u32_e32 v164, v164, v160
	v_sub_u32_e32 v165, v165, v161
	s_nop 0
	v_add_u32_e32 v165, s13, v165
	s_nop 0
	v_readlane_b32 s13, v178, 63
	v_sub_u32_e32 v178, v178, v174
	v_sub_u32_e32 v179, v179, v175
	s_nop 0
	v_add_u32_e32 v179, s13, v179
	ds_write_b32 v144, v164 offset:0
	ds_write_b32 v144, v165 offset:256
	ds_write_b32 v144, v178 offset:7168
	ds_write_b32 v144, v179 offset:7424
	ds_read_b32 v160, v156
	ds_read_b32 v161, v157
	ds_read_b32 v174, v170
	ds_read_b32 v175, v171
	s_waitcnt lgkmcnt(0)
; template <bool STORE>
; DI void peer_item(const Params& p, int item, char* smem) {
;     ...
; #pragma unroll 2
;     for (int k = 0; k < 128; k += 8) {
;       u32x4 uq[8];
;       const int emine = e_s[tl * 128 + k + (lane >> 3)];
;       const float gmine = g_s[tl * 128 + k + (lane >> 3)];
;       const float su = SU[emine], sv = SV[emine];
; #pragma unroll
;       for (int u = 0; u < 8; ++u) {
;         int e = e_s[tl * 128 + k + u];
;         uq[u] = *(const u32x4*)(U8 + (size_t)e * 1024 + lane * 16);
	v_add_u32_e32 v160, v160, v158
	v_add_u32_e32 v161, v161, v159
	v_lshl_add_u32 v160, v160, 2, s19
	v_lshl_add_u32 v161, v161, 2, s19
	v_add_u32_e32 v174, v174, v172
	v_add_u32_e32 v175, v175, v173
	v_lshl_add_u32 v174, v174, 2, s19
	v_lshl_add_u32 v175, v175, 2, s19
	ds_write_b32 v160, v166 offset:1024
	ds_write_b32 v160, v168 offset:17408
	ds_write_b32 v161, v167 offset:1024
	ds_write_b32 v161, v169 offset:17408
	ds_write_b32 v174, v180 offset:1536
	ds_write_b32 v174, v182 offset:17920
	ds_write_b32 v175, v181 offset:1536
	ds_write_b32 v175, v183 offset:17920
	ds_read_b32 v132, v147 offset:1024
	ds_read_b32 v133, v147 offset:1056
	ds_read_b32 v134, v147 offset:1536
	ds_read_b32 v135, v147 offset:1568
	s_waitcnt lgkmcnt(0)
	v_lshlrev_b32_e32 v132, 10, v132
	v_lshlrev_b32_e32 v133, 10, v133
	v_lshlrev_b32_e32 v134, 10, v134
	v_lshlrev_b32_e32 v135, 10, v135
	ds_read_b32 v166, v237 offset:2048
	ds_read_b32 v167, v237 offset:2304
	ds_read_b32 v168, v237 offset:18432
	ds_read_b32 v169, v237 offset:18688
	ds_write_b32 v144, v145 offset:0
	ds_write_b32 v144, v145 offset:256
	ds_read_b32 v180, v237 offset:2560
	ds_read_b32 v181, v237 offset:2816
	ds_read_b32 v182, v237 offset:18944
	ds_read_b32 v183, v237 offset:19200
	ds_write_b32 v144, v145 offset:7168
	ds_write_b32 v144, v145 offset:7424
	s_waitcnt lgkmcnt(0)
	v_lshrrev_b32_e32 v156, 5, v166
	v_and_b32_e32 v156, 0x1fc, v156
	v_add_u32_e32 v156, s18, v156
	v_lshrrev_b32_e32 v157, 5, v167
	v_and_b32_e32 v157, 0x1fc, v157
	v_add_u32_e32 v157, s18, v157
	v_lshrrev_b32_e32 v170, 5, v180
	v_and_b32_e32 v170, 0x1fc, v170
	v_add_u32_e32 v170, s18, v170
	v_add_u32_e32 v170, 7168, v170
	v_lshrrev_b32_e32 v171, 5, v181
	v_and_b32_e32 v171, 0x1fc, v171
	v_add_u32_e32 v171, s18, v171
	v_add_u32_e32 v171, 7168, v171
	ds_add_rtn_u32 v158, v156, v146
	ds_add_rtn_u32 v159, v157, v146
	ds_add_rtn_u32 v172, v170, v146
	ds_add_rtn_u32 v173, v171, v146
	ds_read_b32 v160, v144 offset:0
	ds_read_b32 v161, v144 offset:256
	ds_read_b32 v174, v144 offset:7168
	ds_read_b32 v175, v144 offset:7424
	s_waitcnt lgkmcnt(0)
	v_mov_b32_e32 v164, v160
	v_mov_b32_e32 v165, v161
	v_mov_b32_e32 v178, v174
	v_mov_b32_e32 v179, v175
	v_cmp_le_u32_e32 vcc, 1, v213
	ds_bpermute_b32 v162, v149, v164
	ds_bpermute_b32 v163, v149, v165
	ds_bpermute_b32 v176, v149, v178
	ds_bpermute_b32 v177, v149, v179
	s_waitcnt lgkmcnt(0)
	v_cndmask_b32_e32 v162, 0, v162, vcc
	v_cndmask_b32_e32 v163, 0, v163, vcc
	v_add_u32_e32 v164, v164, v162
	v_add_u32_e32 v165, v165, v163
	v_cndmask_b32_e32 v176, 0, v176, vcc
	v_cndmask_b32_e32 v177, 0, v177, vcc
	v_add_u32_e32 v178, v178, v176
	v_add_u32_e32 v179, v179, v177
	v_cmp_le_u32_e32 vcc, 2, v213
	ds_bpermute_b32 v162, v150, v164
	ds_bpermute_b32 v163, v150, v165
	ds_bpermute_b32 v176, v150, v178
	ds_bpermute_b32 v177, v150, v179
	s_waitcnt lgkmcnt(0)
	v_cndmask_b32_e32 v162, 0, v162, vcc
	v_cndmask_b32_e32 v163, 0, v163, vcc
	v_add_u32_e32 v164, v164, v162
	v_add_u32_e32 v165, v165, v163
	v_cndmask_b32_e32 v176, 0, v176, vcc
	v_cndmask_b32_e32 v177, 0, v177, vcc
	v_add_u32_e32 v178, v178, v176
	v_add_u32_e32 v179, v179, v177
	v_cmp_le_u32_e32 vcc, 4, v213
	ds_bpermute_b32 v162, v151, v164
	ds_bpermute_b32 v163, v151, v165
	ds_bpermute_b32 v176, v151, v178
	ds_bpermute_b32 v177, v151, v179
	s_waitcnt lgkmcnt(0)
	v_cndmask_b32_e32 v162, 0, v162, vcc
	v_cndmask_b32_e32 v163, 0, v163, vcc
	v_add_u32_e32 v164, v164, v162
	v_add_u32_e32 v165, v165, v163
	v_cndmask_b32_e32 v176, 0, v176, vcc
	v_cndmask_b32_e32 v177, 0, v177, vcc
	v_add_u32_e32 v178, v178, v176
	v_add_u32_e32 v179, v179, v177
	v_cmp_le_u32_e32 vcc, 8, v213
	ds_bpermute_b32 v162, v152, v164
	ds_bpermute_b32 v163, v152, v165
	ds_bpermute_b32 v176, v152, v178
	ds_bpermute_b32 v177, v152, v179
	s_waitcnt lgkmcnt(0)
	v_cndmask_b32_e32 v162, 0, v162, vcc
	v_cndmask_b32_e32 v163, 0, v163, vcc
	v_add_u32_e32 v164, v164, v162
	v_add_u32_e32 v165, v165, v163
	v_cndmask_b32_e32 v176, 0, v176, vcc
	v_cndmask_b32_e32 v177, 0, v177, vcc
	v_add_u32_e32 v178, v178, v176
	v_add_u32_e32 v179, v179, v177
	v_cmp_le_u32_e32 vcc, 16, v213
	ds_bpermute_b32 v162, v153, v164
	ds_bpermute_b32 v163, v153, v165
	ds_bpermute_b32 v176, v153, v178
	ds_bpermute_b32 v177, v153, v179
	s_waitcnt lgkmcnt(0)
	v_cndmask_b32_e32 v162, 0, v162, vcc
	v_cndmask_b32_e32 v163, 0, v163, vcc
	v_add_u32_e32 v164, v164, v162
	v_add_u32_e32 v165, v165, v163
	v_cndmask_b32_e32 v176, 0, v176, vcc
	v_cndmask_b32_e32 v177, 0, v177, vcc
	v_add_u32_e32 v178, v178, v176
	v_add_u32_e32 v179, v179, v177
	v_cmp_le_u32_e32 vcc, 32, v213
	ds_bpermute_b32 v162, v154, v164
	ds_bpermute_b32 v163, v154, v165
	ds_bpermute_b32 v176, v154, v178
	ds_bpermute_b32 v177, v154, v179
	s_waitcnt lgkmcnt(0)
	v_cndmask_b32_e32 v162, 0, v162, vcc
	v_cndmask_b32_e32 v163, 0, v163, vcc
	v_add_u32_e32 v164, v164, v162
	v_add_u32_e32 v165, v165, v163
	v_cndmask_b32_e32 v176, 0, v176, vcc
	v_cndmask_b32_e32 v177, 0, v177, vcc
	v_add_u32_e32 v178, v178, v176
	v_add_u32_e32 v179, v179, v177
	s_nop 0
	v_readlane_b32 s13, v164, 63
	v_sub_u32_e32 v164, v164, v160
	v_sub_u32_e32 v165, v165, v161
	s_nop 0
	v_add_u32_e32 v165, s13, v165
	s_nop 0
	v_readlane_b32 s13, v178, 63
	v_sub_u32_e32 v178, v178, v174
	v_sub_u32_e32 v179, v179, v175
	s_nop 0
	v_add_u32_e32 v179, s13, v179
	ds_write_b32 v144, v164 offset:0
	ds_write_b32 v144, v165 offset:256
	ds_write_b32 v144, v178 offset:7168
	ds_write_b32 v144, v179 offset:7424
	ds_read_b32 v160, v156
	ds_read_b32 v161, v157
	ds_read_b32 v174, v170
	ds_read_b32 v175, v171
	s_waitcnt lgkmcnt(0)
; template <bool STORE>
; DI void peer_item(const Params& p, int item, char* smem) {
;     ...
; #pragma unroll 2
;     for (int k = 0; k < 128; k += 8) {
;       u32x4 uq[8];
;       const int emine = e_s[tl * 128 + k + (lane >> 3)];
;       const float gmine = g_s[tl * 128 + k + (lane >> 3)];
;       const float su = SU[emine], sv = SV[emine];
; #pragma unroll
;       for (int u = 0; u < 8; ++u) {
;         int e = e_s[tl * 128 + k + u];
;         uq[u] = *(const u32x4*)(U8 + (size_t)e * 1024 + lane * 16);
	v_add_u32_e32 v160, v160, v158
	v_add_u32_e32 v161, v161, v159
	v_lshl_add_u32 v160, v160, 2, s19
	v_lshl_add_u32 v161, v161, 2, s19
	v_add_u32_e32 v174, v174, v172
	v_add_u32_e32 v175, v175, v173
	v_lshl_add_u32 v174, v174, 2, s19
	v_lshl_add_u32 v175, v175, 2, s19
	ds_write_b32 v160, v166 offset:2048
	ds_write_b32 v160, v168 offset:18432
	ds_write_b32 v161, v167 offset:2048
	ds_write_b32 v161, v169 offset:18432
	ds_write_b32 v174, v180 offset:2560
	ds_write_b32 v174, v182 offset:18944
	ds_write_b32 v175, v181 offset:2560
	ds_write_b32 v175, v183 offset:18944
	ds_read_b32 v136, v147 offset:2048
	ds_read_b32 v137, v147 offset:2080
	ds_read_b32 v138, v147 offset:2560
	ds_read_b32 v139, v147 offset:2592
	s_waitcnt lgkmcnt(0)
	v_lshlrev_b32_e32 v136, 10, v136
	v_lshlrev_b32_e32 v137, 10, v137
	v_lshlrev_b32_e32 v138, 10, v138
	v_lshlrev_b32_e32 v139, 10, v139
	ds_read_b32 v166, v237 offset:3072
	ds_read_b32 v167, v237 offset:3328
	ds_read_b32 v168, v237 offset:19456
	ds_read_b32 v169, v237 offset:19712
	ds_write_b32 v144, v145 offset:0
	ds_write_b32 v144, v145 offset:256
	ds_read_b32 v180, v237 offset:3584
	ds_read_b32 v181, v237 offset:3840
	ds_read_b32 v182, v237 offset:19968
	ds_read_b32 v183, v237 offset:20224
	ds_write_b32 v144, v145 offset:7168
	ds_write_b32 v144, v145 offset:7424
	s_waitcnt lgkmcnt(0)
	v_lshrrev_b32_e32 v156, 5, v166
	v_and_b32_e32 v156, 0x1fc, v156
	v_add_u32_e32 v156, s18, v156
	v_lshrrev_b32_e32 v157, 5, v167
	v_and_b32_e32 v157, 0x1fc, v157
	v_add_u32_e32 v157, s18, v157
	v_lshrrev_b32_e32 v170, 5, v180
	v_and_b32_e32 v170, 0x1fc, v170
	v_add_u32_e32 v170, s18, v170
	v_add_u32_e32 v170, 7168, v170
	v_lshrrev_b32_e32 v171, 5, v181
	v_and_b32_e32 v171, 0x1fc, v171
	v_add_u32_e32 v171, s18, v171
	v_add_u32_e32 v171, 7168, v171
	ds_add_rtn_u32 v158, v156, v146
	ds_add_rtn_u32 v159, v157, v146
	ds_add_rtn_u32 v172, v170, v146
	ds_add_rtn_u32 v173, v171, v146
	ds_read_b32 v160, v144 offset:0
	ds_read_b32 v161, v144 offset:256
	ds_read_b32 v174, v144 offset:7168
	ds_read_b32 v175, v144 offset:7424
	s_waitcnt lgkmcnt(0)
	v_mov_b32_e32 v164, v160
	v_mov_b32_e32 v165, v161
	v_mov_b32_e32 v178, v174
	v_mov_b32_e32 v179, v175
	v_cmp_le_u32_e32 vcc, 1, v213
	ds_bpermute_b32 v162, v149, v164
	ds_bpermute_b32 v163, v149, v165
	ds_bpermute_b32 v176, v149, v178
	ds_bpermute_b32 v177, v149, v179
	s_waitcnt lgkmcnt(0)
	v_cndmask_b32_e32 v162, 0, v162, vcc
	v_cndmask_b32_e32 v163, 0, v163, vcc
	v_add_u32_e32 v164, v164, v162
	v_add_u32_e32 v165, v165, v163
	v_cndmask_b32_e32 v176, 0, v176, vcc
	v_cndmask_b32_e32 v177, 0, v177, vcc
	v_add_u32_e32 v178, v178, v176
	v_add_u32_e32 v179, v179, v177
	v_cmp_le_u32_e32 vcc, 2, v213
	ds_bpermute_b32 v162, v150, v164
	ds_bpermute_b32 v163, v150, v165
	ds_bpermute_b32 v176, v150, v178
	ds_bpermute_b32 v177, v150, v179
	s_waitcnt lgkmcnt(0)
	v_cndmask_b32_e32 v162, 0, v162, vcc
	v_cndmask_b32_e32 v163, 0, v163, vcc
	v_add_u32_e32 v164, v164, v162
	v_add_u32_e32 v165, v165, v163
	v_cndmask_b32_e32 v176, 0, v176, vcc
	v_cndmask_b32_e32 v177, 0, v177, vcc
	v_add_u32_e32 v178, v178, v176
	v_add_u32_e32 v179, v179, v177
	v_cmp_le_u32_e32 vcc, 4, v213
	ds_bpermute_b32 v162, v151, v164
	ds_bpermute_b32 v163, v151, v165
	ds_bpermute_b32 v176, v151, v178
	ds_bpermute_b32 v177, v151, v179
	s_waitcnt lgkmcnt(0)
	v_cndmask_b32_e32 v162, 0, v162, vcc
	v_cndmask_b32_e32 v163, 0, v163, vcc
	v_add_u32_e32 v164, v164, v162
	v_add_u32_e32 v165, v165, v163
	v_cndmask_b32_e32 v176, 0, v176, vcc
	v_cndmask_b32_e32 v177, 0, v177, vcc
	v_add_u32_e32 v178, v178, v176
	v_add_u32_e32 v179, v179, v177
	v_cmp_le_u32_e32 vcc, 8, v213
	ds_bpermute_b32 v162, v152, v164
	ds_bpermute_b32 v163, v152, v165
	ds_bpermute_b32 v176, v152, v178
	ds_bpermute_b32 v177, v152, v179
	s_waitcnt lgkmcnt(0)
	v_cndmask_b32_e32 v162, 0, v162, vcc
	v_cndmask_b32_e32 v163, 0, v163, vcc
	v_add_u32_e32 v164, v164, v162
	v_add_u32_e32 v165, v165, v163
	v_cndmask_b32_e32 v176, 0, v176, vcc
	v_cndmask_b32_e32 v177, 0, v177, vcc
	v_add_u32_e32 v178, v178, v176
	v_add_u32_e32 v179, v179, v177
	v_cmp_le_u32_e32 vcc, 16, v213
	ds_bpermute_b32 v162, v153, v164
	ds_bpermute_b32 v163, v153, v165
	ds_bpermute_b32 v176, v153, v178
	ds_bpermute_b32 v177, v153, v179
	s_waitcnt lgkmcnt(0)
	v_cndmask_b32_e32 v162, 0, v162, vcc
	v_cndmask_b32_e32 v163, 0, v163, vcc
	v_add_u32_e32 v164, v164, v162
	v_add_u32_e32 v165, v165, v163
	v_cndmask_b32_e32 v176, 0, v176, vcc
	v_cndmask_b32_e32 v177, 0, v177, vcc
	v_add_u32_e32 v178, v178, v176
	v_add_u32_e32 v179, v179, v177
	v_cmp_le_u32_e32 vcc, 32, v213
	ds_bpermute_b32 v162, v154, v164
	ds_bpermute_b32 v163, v154, v165
	ds_bpermute_b32 v176, v154, v178
	ds_bpermute_b32 v177, v154, v179
	s_waitcnt lgkmcnt(0)
	v_cndmask_b32_e32 v162, 0, v162, vcc
	v_cndmask_b32_e32 v163, 0, v163, vcc
	v_add_u32_e32 v164, v164, v162
	v_add_u32_e32 v165, v165, v163
	v_cndmask_b32_e32 v176, 0, v176, vcc
	v_cndmask_b32_e32 v177, 0, v177, vcc
	v_add_u32_e32 v178, v178, v176
	v_add_u32_e32 v179, v179, v177
	s_nop 0
	v_readlane_b32 s13, v164, 63
	v_sub_u32_e32 v164, v164, v160
	v_sub_u32_e32 v165, v165, v161
	s_nop 0
	v_add_u32_e32 v165, s13, v165
	s_nop 0
	v_readlane_b32 s13, v178, 63
	v_sub_u32_e32 v178, v178, v174
	v_sub_u32_e32 v179, v179, v175
	s_nop 0
	v_add_u32_e32 v179, s13, v179
	ds_write_b32 v144, v164 offset:0
	ds_write_b32 v144, v165 offset:256
	ds_write_b32 v144, v178 offset:7168
	ds_write_b32 v144, v179 offset:7424
	ds_read_b32 v160, v156
	ds_read_b32 v161, v157
	ds_read_b32 v174, v170
	ds_read_b32 v175, v171
	s_waitcnt lgkmcnt(0)
; DI float bflo(unsigned u) { return __uint_as_float(u << 16); }
; DI float bfhi(unsigned u) { return __uint_as_float(u & 0xffff0000u); }
; template <bool STORE>
; DI void peer_item(const Params& p, int item, char* smem) {
;     ...
;     float xf[16];
;     {
; #pragma unroll
;       for (int i = 0; i < 4; ++i) {
;         const uint2 xv = *(const uint2*)(XN2 + tok * 1024 + 256 * i + lane * 4);
;         xf[4 * i] = bflo(xv.x); xf[4 * i + 1] = bfhi(xv.x); xf[4 * i + 2] = bflo(xv.y); xf[4 * i + 3] = bfhi(xv.y);
;       }
;     }
; #pragma unroll 2
;     for (int k = 0; k < 128; k += 8) {
;       u32x4 uq[8];
;       const int emine = e_s[tl * 128 + k + (lane >> 3)];
;       const float gmine = g_s[tl * 128 + k + (lane >> 3)];
;       const float su = SU[emine], sv = SV[emine];
; #pragma unroll
;       for (int u = 0; u < 8; ++u) {
;         int e = e_s[tl * 128 + k + u];
;         uq[u] = *(const u32x4*)(U8 + (size_t)e * 1024 + lane * 16);
	v_add_u32_e32 v160, v160, v158
	v_add_u32_e32 v161, v161, v159
	v_lshl_add_u32 v160, v160, 2, s19
	v_lshl_add_u32 v161, v161, 2, s19
	v_add_u32_e32 v174, v174, v172
	v_add_u32_e32 v175, v175, v173
	v_lshl_add_u32 v174, v174, 2, s19
	v_lshl_add_u32 v175, v175, 2, s19
	ds_write_b32 v160, v166 offset:3072
	ds_write_b32 v160, v168 offset:19456
	ds_write_b32 v161, v167 offset:3072
	ds_write_b32 v161, v169 offset:19456
	ds_write_b32 v174, v180 offset:3584
	ds_write_b32 v174, v182 offset:19968
	ds_write_b32 v175, v181 offset:3584
	ds_write_b32 v175, v183 offset:19968
	ds_read_b32 v140, v147 offset:3072
	ds_read_b32 v141, v147 offset:3104
	ds_read_b32 v142, v147 offset:3584
	ds_read_b32 v143, v147 offset:3616
	s_waitcnt lgkmcnt(0)
	v_lshlrev_b32_e32 v140, 10, v140
	v_lshlrev_b32_e32 v141, 10, v141
	v_lshlrev_b32_e32 v142, 10, v142
	v_lshlrev_b32_e32 v143, 10, v143
	s_waitcnt vmcnt(0)
	v_lshlrev_b32_e32 v0, 16, v2
	v_and_b32_e32 v1, 0xffff0000, v2
	v_lshlrev_b32_e32 v2, 16, v3
	v_and_b32_e32 v3, 0xffff0000, v3
	v_lshlrev_b32_e32 v4, 16, v6
	v_and_b32_e32 v5, 0xffff0000, v6
	v_lshlrev_b32_e32 v6, 16, v7
	v_and_b32_e32 v7, 0xffff0000, v7
	v_lshlrev_b32_e32 v8, 16, v10
	v_and_b32_e32 v9, 0xffff0000, v10
	v_lshlrev_b32_e32 v10, 16, v11
	v_and_b32_e32 v11, 0xffff0000, v11
	v_lshlrev_b32_e32 v12, 16, v14
	v_and_b32_e32 v13, 0xffff0000, v14
	v_lshlrev_b32_e32 v14, 16, v15
	v_and_b32_e32 v15, 0xffff0000, v15
	v_lshlrev_b32_e32 v16, 16, v18
	v_and_b32_e32 v17, 0xffff0000, v18
	v_lshlrev_b32_e32 v18, 16, v19
	v_and_b32_e32 v19, 0xffff0000, v19
	v_lshlrev_b32_e32 v20, 16, v22
	v_and_b32_e32 v21, 0xffff0000, v22
	v_lshlrev_b32_e32 v22, 16, v23
	v_and_b32_e32 v23, 0xffff0000, v23
	v_lshlrev_b32_e32 v24, 16, v26
	v_and_b32_e32 v25, 0xffff0000, v26
	v_lshlrev_b32_e32 v26, 16, v27
	v_and_b32_e32 v27, 0xffff0000, v27
	v_lshlrev_b32_e32 v28, 16, v30
	v_and_b32_e32 v29, 0xffff0000, v30
	v_lshlrev_b32_e32 v30, 16, v31
	v_and_b32_e32 v31, 0xffff0000, v31
	v_lshlrev_b32_e32 v32, 16, v34
	v_and_b32_e32 v33, 0xffff0000, v34
	v_lshlrev_b32_e32 v34, 16, v35
	v_and_b32_e32 v35, 0xffff0000, v35
	v_lshlrev_b32_e32 v36, 16, v38
	v_and_b32_e32 v37, 0xffff0000, v38
	v_lshlrev_b32_e32 v38, 16, v39
	v_and_b32_e32 v39, 0xffff0000, v39
	v_lshlrev_b32_e32 v40, 16, v42
	v_and_b32_e32 v41, 0xffff0000, v42
	v_lshlrev_b32_e32 v42, 16, v43
	v_and_b32_e32 v43, 0xffff0000, v43
	v_lshlrev_b32_e32 v44, 16, v46
	v_and_b32_e32 v45, 0xffff0000, v46
	v_lshlrev_b32_e32 v46, 16, v47
	v_and_b32_e32 v47, 0xffff0000, v47
	v_lshlrev_b32_e32 v48, 16, v50
	v_and_b32_e32 v49, 0xffff0000, v50
	v_lshlrev_b32_e32 v50, 16, v51
	v_and_b32_e32 v51, 0xffff0000, v51
	v_lshlrev_b32_e32 v52, 16, v54
	v_and_b32_e32 v53, 0xffff0000, v54
	v_lshlrev_b32_e32 v54, 16, v55
	v_and_b32_e32 v55, 0xffff0000, v55
	v_lshlrev_b32_e32 v56, 16, v58
	v_and_b32_e32 v57, 0xffff0000, v58
	v_lshlrev_b32_e32 v58, 16, v59
	v_and_b32_e32 v59, 0xffff0000, v59
	v_lshlrev_b32_e32 v60, 16, v62
	v_and_b32_e32 v61, 0xffff0000, v62
	v_lshlrev_b32_e32 v62, 16, v63
	v_and_b32_e32 v63, 0xffff0000, v63
	v_lshlrev_b32_e32 v64, 16, v66
	v_and_b32_e32 v65, 0xffff0000, v66
	v_lshlrev_b32_e32 v66, 16, v67
	v_and_b32_e32 v67, 0xffff0000, v67
	v_lshlrev_b32_e32 v68, 16, v70
	v_and_b32_e32 v69, 0xffff0000, v70
	v_lshlrev_b32_e32 v70, 16, v71
	v_and_b32_e32 v71, 0xffff0000, v71
	v_lshlrev_b32_e32 v72, 16, v74
	v_and_b32_e32 v73, 0xffff0000, v74
	v_lshlrev_b32_e32 v74, 16, v75
	v_and_b32_e32 v75, 0xffff0000, v75
	v_lshlrev_b32_e32 v76, 16, v78
	v_and_b32_e32 v77, 0xffff0000, v78
	v_lshlrev_b32_e32 v78, 16, v79
	v_and_b32_e32 v79, 0xffff0000, v79
	v_lshlrev_b32_e32 v80, 16, v82
	v_and_b32_e32 v81, 0xffff0000, v82
	v_lshlrev_b32_e32 v82, 16, v83
	v_and_b32_e32 v83, 0xffff0000, v83
	v_lshlrev_b32_e32 v84, 16, v86
	v_and_b32_e32 v85, 0xffff0000, v86
	v_lshlrev_b32_e32 v86, 16, v87
	v_and_b32_e32 v87, 0xffff0000, v87
	v_lshlrev_b32_e32 v88, 16, v90
	v_and_b32_e32 v89, 0xffff0000, v90
	v_lshlrev_b32_e32 v90, 16, v91
	v_and_b32_e32 v91, 0xffff0000, v91
	v_lshlrev_b32_e32 v92, 16, v94
	v_and_b32_e32 v93, 0xffff0000, v94
	v_lshlrev_b32_e32 v94, 16, v95
	v_and_b32_e32 v95, 0xffff0000, v95
	v_lshlrev_b32_e32 v96, 16, v98
	v_and_b32_e32 v97, 0xffff0000, v98
	v_lshlrev_b32_e32 v98, 16, v99
	v_and_b32_e32 v99, 0xffff0000, v99
	v_lshlrev_b32_e32 v100, 16, v102
	v_and_b32_e32 v101, 0xffff0000, v102
	v_lshlrev_b32_e32 v102, 16, v103
	v_and_b32_e32 v103, 0xffff0000, v103
	v_lshlrev_b32_e32 v104, 16, v106
	v_and_b32_e32 v105, 0xffff0000, v106
	v_lshlrev_b32_e32 v106, 16, v107
	v_and_b32_e32 v107, 0xffff0000, v107
	v_lshlrev_b32_e32 v108, 16, v110
	v_and_b32_e32 v109, 0xffff0000, v110
	v_lshlrev_b32_e32 v110, 16, v111
	v_and_b32_e32 v111, 0xffff0000, v111
	v_lshlrev_b32_e32 v112, 16, v114
	v_and_b32_e32 v113, 0xffff0000, v114
	v_lshlrev_b32_e32 v114, 16, v115
	v_and_b32_e32 v115, 0xffff0000, v115
	v_lshlrev_b32_e32 v116, 16, v118
	v_and_b32_e32 v117, 0xffff0000, v118
	v_lshlrev_b32_e32 v118, 16, v119
	v_and_b32_e32 v119, 0xffff0000, v119
	v_lshlrev_b32_e32 v120, 16, v122
	v_and_b32_e32 v121, 0xffff0000, v122
	v_lshlrev_b32_e32 v122, 16, v123
	v_and_b32_e32 v123, 0xffff0000, v123
	v_lshlrev_b32_e32 v124, 16, v126
	v_and_b32_e32 v125, 0xffff0000, v126
	v_lshlrev_b32_e32 v126, 16, v127
	v_and_b32_e32 v127, 0xffff0000, v127
	v_lshrrev_b32_e32 v235, 3, v213
	v_lshl_add_u32 v235, v235, 2, s19
	s_mov_b32 s72, 0
	s_mov_b32 s73, 1
	s_mov_b32 s74, 2
	s_mov_b32 s75, 3
	s_mov_b32 s76, 4
	s_mov_b32 s77, 5
	s_mov_b32 s78, 6
	s_mov_b32 s79, 7
	s_nop 0
	v_readlane_b32 s48, v128, s72
	v_readlane_b32 s49, v128, s73
	v_readlane_b32 s50, v128, s74
	v_readlane_b32 s51, v128, s75
	v_readlane_b32 s52, v128, s76
	v_readlane_b32 s53, v128, s77
	v_readlane_b32 s54, v128, s78
	v_readlane_b32 s55, v128, s79
	s_add_u32 s32, s0, s48
	s_addc_u32 s33, s1, 0
	s_add_u32 s34, s0, s49
	s_addc_u32 s35, s1, 0
	s_add_u32 s36, s0, s50
	s_addc_u32 s37, s1, 0
	s_add_u32 s38, s0, s51
	s_addc_u32 s39, s1, 0
	s_add_u32 s40, s0, s52
	s_addc_u32 s41, s1, 0
	s_add_u32 s42, s0, s53
	s_addc_u32 s43, s1, 0
	s_add_u32 s44, s0, s54
	s_addc_u32 s45, s1, 0
	s_add_u32 s46, s0, s55
	s_addc_u32 s47, s1, 0
	global_load_dwordx4 v[144:147], v234, s[32:33]
	global_load_dwordx4 v[148:151], v234, s[34:35]
	global_load_dwordx4 v[152:155], v234, s[36:37]
	global_load_dwordx4 v[156:159], v234, s[38:39]
	global_load_dwordx4 v[160:163], v234, s[40:41]
	global_load_dwordx4 v[164:167], v234, s[42:43]
	global_load_dwordx4 v[168:171], v234, s[44:45]
	global_load_dwordx4 v[172:175], v234, s[46:47]
	s_mov_b32 s12, 0
